# token mixer: hand-written SGU stage (W/u/bias prefetched, 8 LDS fragment reads batched per ks block, double-buffered) on top of LN hoist
# speedup vs baseline: 1.0328x; 1.0090x over previous
; __device__ __forceinline__ void p2_block(LAS unsigned char* lds, const bf16_t* __restrict__ PROJ, bf16_t* __restrict__ ATT, bf16_t* __restrict__ SGU, const float* __restrict__ qn, const float* __restrict__ kn, ...
;     ...
;     const int b = item >> 6, n = (item >> 2) & 15, kvh = item & 3;
;     const int lane = tid & 63, w = __builtin_amdgcn_readfirstlane(tid >> 6), fr = lane & 15, fq = lane >> 4;
;     LAS unsigned char* KS = lds; LAS unsigned char* VT = lds + KS_BYTES;
;     const int g = w >> 1, rbase = (w & 1) * 64, hq = kvh * 4 + g;
;     const int kk = tid >> 1, h = tid & 1, s = n * 128 - 128 + kk, sc = s < 0 ? 0 : s;
;     const bf16_t* rowp = PROJ + (size_t)(b * pg8::SEQ + sc) * pg8::IN_W;
;     const bf16_t* kp = rowp + pg8::C_K + kvh * 64 + 16 * h;
;     const u32x4 ka = *(const u32x4*)kp, kb = *(const u32x4*)(kp + 8), kc = *(const u32x4*)(kp + 32), kd = *(const u32x4*)(kp + 40);
;     const bf16_t* vp = rowp + pg8::C_V + kvh * 64 + 32 * h;
;     u32x4 vv[4];
; #pragma unroll
;     for (int c4 = 0; c4 < 4; ++c4) vv[c4] = *(const u32x4*)(vp + 8 * c4);
;     const int sp_ = tid >> 2, q4 = tid & 3;
;     u32x4 sv[2][4];
;     const bf16_t* svsrc = PROJ + ((size_t)b * pg8::SEQ + n * 128 + sp_) * pg8::IN_W + pg8::C_VS + (2 * kvh) * 128 + 32 * q4;
; #pragma unroll
;     for (int c4 = 0; c4 < 4; ++c4) sv[0][c4] = *(const u32x4*)(svsrc + 8 * c4);
;     u32x4 qa[4], qb[4];
; #pragma unroll
;     for (int c = 0; c < 2; ++c) { const bf16_t* qp = PROJ + ((size_t)b * pg8::SEQ + n * 128 + rbase + 16 * c + fr) * pg8::IN_W + hq * 64 + 8 * fq; qa[c] = *(const u32x4*)qp; qb[c] = *(const u32x4*)(qp + 32); }
;     {
;         const float valid = s < 0 ? 0.f : 1.f;
;         float x1[16], x2[16]; unpack8(ka, x1); unpack8(kb, x1 + 8); unpack8(kc, x2); unpack8(kd, x2 + 8);
;         float ss = 0.f;
; #pragma unroll
;         for (int j = 0; j < 16; ++j) ss += x1[j] * x1[j] + x2[j] * x2[j];
;         ss += __shfl_xor(ss, 1);
;         const float rinv = rsqrtf(ss * (1.0f / 64.0f) + pg8::EPS) * valid;
;         const float* cp = COS + sc * 32 + 16 * h; const float* sp = SIN + sc * 32 + 16 * h;
;         float o1[16], o2[16];
; #pragma unroll
;         for (int j = 0; j < 16; ++j) { const float a1 = x1[j] * rinv * kn[16 * h + j], a2 = x2[j] * rinv * kn[32 + 16 * h + j], c = cp[j], sn = sp[j]; o1[j] = a1 * c - a2 * sn; o2[j] = a2 * c + a1 * sn; }
.LBB0_330:
	s_bfe_u32 s27, s2, 0x40002
	v_mov_b32_e32 v160, v204
	s_lshl_b32 s17, s27, 7
	s_add_i32 s4, s17, 0xffffff80
	v_ashrrev_i32_e32 v167, 1, v160
	v_add_u32_e32 v22, s4, v167
	s_ashr_i32 s6, s2, 6
	v_max_i32_e32 v66, 0, v22
	s_and_b32 s73, s2, 3
	v_lshl_add_u32 v0, s6, 11, v66
	s_waitcnt lgkmcnt(0)
	v_mov_b64_e32 v[2:3], s[10:11]
	v_and_b32_e32 v166, 1, v160
	v_mad_i64_i32 v[4:5], s[24:25], v0, s83, v[2:3]
	s_lshl_b32 s4, s73, 7
	v_lshl_add_u64 v[4:5], v[4:5], 0, s[4:5]
	v_lshlrev_b32_e32 v0, 5, v166
	v_lshl_add_u64 v[6:7], v[4:5], 0, v[0:1]
	global_load_dwordx4 v[50:53], v[6:7], off offset:2048
	global_load_dwordx4 v[58:61], v[6:7], off offset:2064
	global_load_dwordx4 v[54:57], v[6:7], off offset:2112
	global_load_dwordx4 v[62:65], v[6:7], off offset:2128
	v_readfirstlane_b32 s16, v160
	s_ashr_i32 s77, s16, 7
	s_lshl_b32 s7, s73, 2
	s_add_i32 s42, s77, s7
	s_ashr_i32 s7, s6, 31
	v_lshlrev_b32_e32 v74, 6, v166
	v_mov_b32_e32 v75, v1
	v_ashrrev_i32_e32 v136, 2, v160
	s_lshl_b64 s[48:49], s[6:7], 11
	v_lshl_add_u64 v[4:5], v[4:5], 0, v[74:75]
	s_or_b32 s24, s48, s17
	s_mov_b32 s25, s49
	v_ashrrev_i32_e32 v137, 31, v136
	s_waitcnt lgkmcnt(0)
	global_load_dwordx4 v[18:21], v[4:5], off offset:2560
	global_load_dwordx4 v[14:17], v[4:5], off offset:2576
	global_load_dwordx4 v[10:13], v[4:5], off offset:2592
	global_load_dwordx4 v[6:9], v[4:5], off offset:2608
	v_lshl_add_u64 v[4:5], s[24:25], 0, v[136:137]
	v_mad_u64_u32 v[2:3], s[6:7], v4, s83, v[2:3]
	v_lshlrev_b32_e32 v4, 5, v160
	v_mad_i32_i24 v3, v5, s83, v3
	s_lshl_b32 s4, s73, 9
	v_and_b32_e32 v165, 0x60, v4
	v_lshl_add_u64 v[2:3], v[2:3], 0, s[4:5]
	v_lshlrev_b32_e32 v4, 1, v165
	v_mov_b32_e32 v5, v1
	v_lshl_add_u64 v[2:3], v[2:3], 0, v[4:5]
	s_mov_b64 s[6:7], 0x1400
	v_lshl_add_u64 v[138:139], v[2:3], 0, s[6:7]
	s_lshl_b32 s6, s42, 6
	s_ashr_i32 s7, s6, 31
	s_and_b32 s26, s16, 64
	s_lshl_b64 s[6:7], s[6:7], 1
	v_bfe_u32 v162, v160, 4, 2
	s_add_u32 s28, s10, s6
	s_movk_i32 s4, 0x1000
	v_and_b32_e32 v137, 15, v160
	s_addc_u32 s29, s11, s7
	v_lshlrev_b32_e32 v132, 4, v162
	v_mov_b32_e32 v133, v1
	v_and_b32_e32 v68, 64, v211
	v_add_co_u32_e32 v2, vcc, s4, v2
	v_or_b32_e32 v161, s26, v137
	v_lshl_add_u64 v[134:135], s[28:29], 0, v[132:133]
	v_xor_b32_e32 v67, 1, v211
	v_add_u32_e32 v133, 64, v68
	v_addc_co_u32_e32 v3, vcc, 0, v3, vcc
	v_or_b32_e32 v163, s24, v161
	v_cmp_lt_i32_e64 s[40:41], v67, v133
	v_cmp_gt_i32_e32 vcc, 0, v22
	v_mad_u64_u32 v[22:23], s[28:29], v163, s83, v[134:135]
	v_cndmask_b32_e64 v67, v211, v67, s[40:41]
	v_mad_i32_i24 v23, s49, v212, v23
	v_lshlrev_b32_e32 v164, 2, v67
	v_lshlrev_b32_e32 v66, 5, v66
	v_mov_b32_e32 v67, v1
	v_readlane_b32 s44, v250, 36
	v_readlane_b32 s46, v250, 38
	global_load_dwordx4 v[46:49], v[2:3], off offset:1024
	global_load_dwordx4 v[34:37], v[138:139], off offset:48
	global_load_dwordx4 v[38:41], v[138:139], off offset:32
	global_load_dwordx4 v[42:45], v[138:139], off offset:16
	s_nop 0
	global_load_dwordx4 v[2:5], v[22:23], off
	global_load_dwordx4 v[30:33], v[22:23], off offset:64
	v_or_b32_e32 v22, 16, v163
	v_lshlrev_b64 v[66:67], 2, v[66:67]
	v_readlane_b32 s45, v250, 37
	v_readlane_b32 s47, v250, 39
	v_mad_u64_u32 v[26:27], s[28:29], v22, s83, v[134:135]
	v_lshl_add_u64 v[68:69], s[44:45], 0, v[66:67]
	v_lshl_add_u64 v[66:67], s[46:47], 0, v[66:67]
	v_mad_i32_i24 v27, s49, v212, v27
	v_lshl_add_u64 v[86:87], v[68:69], 0, v[74:75]
	v_lshl_add_u64 v[126:127], v[66:67], 0, v[74:75]
	global_load_dwordx4 v[22:25], v[26:27], off
	s_nop 0
	global_load_dwordx4 v[26:29], v[26:27], off offset:64
	s_nop 0
	global_load_dwordx4 v[66:69], v74, s[0:1] offset:48
	global_load_dwordx4 v[78:81], v74, s[0:1] offset:32
	global_load_dwordx4 v[94:97], v74, s[0:1] offset:16
	global_load_dwordx4 v[106:109], v74, s[0:1]
	global_load_dwordx4 v[70:73], v74, s[0:1] offset:176
	global_load_dwordx4 v[82:85], v74, s[0:1] offset:160
	global_load_dwordx4 v[98:101], v74, s[0:1] offset:144
	global_load_dwordx4 v[110:113], v74, s[0:1] offset:128
	s_nop 0
	global_load_dwordx4 v[74:77], v[86:87], off offset:48
	global_load_dwordx4 v[90:93], v[86:87], off offset:32
	global_load_dwordx4 v[102:105], v[86:87], off offset:16
	global_load_dwordx4 v[114:117], v[86:87], off
	s_nop 0
	global_load_dwordx4 v[86:89], v[126:127], off offset:48
	global_load_dwordx4 v[118:121], v[126:127], off offset:32
	global_load_dwordx4 v[122:125], v[126:127], off offset:16
	s_nop 0
	global_load_dwordx4 v[126:129], v[126:127], off
	v_cndmask_b32_e64 v180, 1.0, 0, vcc
	s_lshl_b32 s4, s73, 10
	s_waitcnt vmcnt(0)
; __device__ __forceinline__ void unpack8(const u32x4 w, float* f) { f[0] = bf_lo(w.x); f[1] = bf_hi(w.x); f[2] = bf_lo(w.y); f[3] = bf_hi(w.y); f[4] = bf_lo(w.z); f[5] = bf_hi(w.z); f[6] = bf_lo(w.w); f[7] = bf_hi(w.w); }
; __device__ __forceinline__ void p2_block(LAS unsigned char* lds, const bf16_t* __restrict__ PROJ, bf16_t* __restrict__ ATT, bf16_t* __restrict__ SGU, const float* __restrict__ qn, const float* __restrict__ kn, ...
;     ...
;         float x1[16], x2[16]; unpack8(ka, x1); unpack8(kb, x1 + 8); unpack8(kc, x2); unpack8(kd, x2 + 8);
;         float ss = 0.f;
; #pragma unroll
;         for (int j = 0; j < 16; ++j) ss += x1[j] * x1[j] + x2[j] * x2[j];
;         ss += __shfl_xor(ss, 1);
;         const float rinv = rsqrtf(ss * (1.0f / 64.0f) + pg8::EPS) * valid;
;         const float* cp = COS + sc * 32 + 16 * h; const float* sp = SIN + sc * 32 + 16 * h;
;         float o1[16], o2[16];
; #pragma unroll
;         for (int j = 0; j < 16; ++j) { const float a1 = x1[j] * rinv * kn[16 * h + j], a2 = x2[j] * rinv * kn[32 + 16 * h + j], c = cp[j], sn = sp[j]; o1[j] = a1 * c - a2 * sn; o2[j] = a2 * c + a1 * sn; }
	v_lshlrev_b32_e32 v226, 16, v51
	v_lshlrev_b32_e32 v142, 16, v61
	v_and_b32_e32 v140, 0xffff0000, v61
	v_lshlrev_b32_e32 v143, 16, v65
	v_and_b32_e32 v141, 0xffff0000, v65
	v_mov_b32_e32 v150, v141
	v_mov_b32_e32 v151, v143
	v_mov_b32_e32 v148, v140
	v_mov_b32_e32 v149, v142
	v_pk_mul_f32 v[150:151], v[150:151], v[150:151]
	v_and_b32_e32 v61, 0xffff0000, v64
	v_pk_fma_f32 v[182:183], v[148:149], v[148:149], v[150:151]
	v_lshlrev_b32_e32 v149, 16, v64
	v_lshlrev_b32_e32 v148, 16, v60
	v_and_b32_e32 v60, 0xffff0000, v60
	v_mov_b32_e32 v154, v61
	v_mov_b32_e32 v155, v149
	v_mov_b32_e32 v64, v60
	v_mov_b32_e32 v65, v148
	v_pk_mul_f32 v[154:155], v[154:155], v[154:155]
	v_and_b32_e32 v201, 0xffff0000, v57
	v_pk_fma_f32 v[184:185], v[64:65], v[64:65], v[154:155]
	v_lshlrev_b32_e32 v155, 16, v63
	v_and_b32_e32 v65, 0xffff0000, v63
	v_lshlrev_b32_e32 v154, 16, v59
	v_and_b32_e32 v64, 0xffff0000, v59
	v_mov_b32_e32 v188, v65
	v_mov_b32_e32 v189, v155
	v_mov_b32_e32 v186, v64
	v_mov_b32_e32 v187, v154
	v_pk_mul_f32 v[188:189], v[188:189], v[188:189]
	v_and_b32_e32 v59, 0xffff0000, v62
	v_pk_fma_f32 v[186:187], v[186:187], v[186:187], v[188:189]
	v_lshlrev_b32_e32 v189, 16, v62
	v_lshlrev_b32_e32 v188, 16, v58
	v_and_b32_e32 v58, 0xffff0000, v58
	v_mov_b32_e32 v194, v59
	v_mov_b32_e32 v195, v189
	v_mov_b32_e32 v62, v58
	v_mov_b32_e32 v63, v188
	v_pk_mul_f32 v[194:195], v[194:195], v[194:195]
	v_and_b32_e32 v234, 0xffff0000, v51
	v_pk_fma_f32 v[62:63], v[62:63], v[62:63], v[194:195]
	v_lshlrev_b32_e32 v195, 16, v57
	v_lshlrev_b32_e32 v239, 16, v54
	v_lshlrev_b32_e32 v238, 16, v50
	v_and_b32_e32 v51, 0xffff0000, v54
	v_and_b32_e32 v50, 0xffff0000, v50
	v_lshlrev_b32_e32 v194, 16, v53
	v_and_b32_e32 v200, 0xffff0000, v53
	v_mov_b32_e32 v218, v201
	v_mov_b32_e32 v219, v195
	v_lshlrev_b32_e32 v227, 16, v55
	v_and_b32_e32 v235, 0xffff0000, v55
	v_pk_mul_f32 v[240:241], v[238:239], v[238:239]
	v_pk_mul_f32 v[54:55], v[50:51], v[50:51]
	v_mov_b32_e32 v202, v200
	v_mov_b32_e32 v203, v194
	v_pk_mul_f32 v[218:219], v[218:219], v[218:219]
	v_pk_mul_f32 v[228:229], v[226:227], v[226:227]
	v_add_f32_e32 v54, v54, v55
	v_add_f32_e32 v55, v240, v241
	v_pk_fma_f32 v[202:203], v[202:203], v[202:203], v[218:219]
	v_lshlrev_b32_e32 v219, 16, v56
	v_lshlrev_b32_e32 v218, 16, v52
	v_pk_mul_f32 v[236:237], v[234:235], v[234:235]
	v_add_f32_e32 v54, v55, v54
	v_add_f32_e32 v55, v228, v229
	v_mov_b32_e32 v150, v66
	v_pk_mul_f32 v[220:221], v[218:219], v[218:219]
	v_and_b32_e32 v53, 0xffff0000, v56
	v_and_b32_e32 v52, 0xffff0000, v52
	v_add_f32_e32 v66, v236, v237
	v_add_f32_e32 v54, v55, v54
	v_pk_mul_f32 v[56:57], v[52:53], v[52:53]
	v_add_f32_e32 v54, v66, v54
	v_add_f32_e32 v55, v220, v221
	v_add_f32_e32 v54, v55, v54
	v_add_f32_e32 v55, v56, v57
	v_add_f32_e32 v54, v55, v54
	v_add_f32_e32 v54, v203, v54
	v_add_f32_e32 v54, v202, v54
	v_add_f32_e32 v54, v63, v54
	v_add_f32_e32 v54, v62, v54
	v_add_f32_e32 v54, v187, v54
	v_add_f32_e32 v54, v186, v54
	v_add_f32_e32 v54, v185, v54
	v_add_f32_e32 v54, v184, v54
	v_add_f32_e32 v54, v183, v54
	v_add_f32_e32 v54, v182, v54
	ds_bpermute_b32 v55, v164, v54
	v_mov_b32_e32 v242, v106
	v_mov_b32_e32 v243, v110
	v_mov_b32_e32 v244, v114
	v_mov_b32_e32 v245, v126
	s_waitcnt lgkmcnt(0)
	v_add_f32_e32 v54, v54, v55
	v_fmamk_f32 v54, v54, 0x3c800000, v209
	v_cmp_gt_f32_e64 s[40:41], s82, v54
	v_mul_f32_e32 v55, 0x4b800000, v54
	v_mov_b32_e32 v110, v107
	v_cndmask_b32_e64 v54, v54, v55, s[40:41]
	v_rsq_f32_e32 v54, v54
	v_mov_b32_e32 v230, v108
	v_mov_b32_e32 v231, v112
	v_mov_b32_e32 v232, v116
	v_mul_f32_e32 v55, 0x45800000, v54
	v_cndmask_b32_e64 v54, v54, v55, s[40:41]
	v_mul_f32_e32 v54, v180, v54
	v_pk_mul_f32 v[56:57], v[54:55], v[238:239] op_sel_hi:[0,1]
	v_pk_mul_f32 v[56:57], v[242:243], v[56:57]
	v_mov_b32_e32 v233, v128
	v_pk_mul_f32 v[62:63], v[244:245], v[56:57]
	v_mov_b32_e32 v144, v68
	v_sub_f32_e32 v55, v62, v63
	v_mov_b32_e32 v62, v126
	v_mov_b32_e32 v63, v114
	v_pk_mul_f32 v[50:51], v[54:55], v[50:51] op_sel_hi:[0,1]
	v_pk_mul_f32 v[56:57], v[62:63], v[56:57]
	v_pk_mul_f32 v[50:51], v[110:111], v[50:51]
	v_mov_b32_e32 v126, v115
	v_mov_b32_e32 v114, v127
	v_add_f32_e32 v62, v57, v56
	v_pk_mul_f32 v[56:57], v[126:127], v[50:51]
	v_pk_mul_f32 v[50:51], v[114:115], v[50:51]
	v_sub_f32_e32 v63, v56, v57
	v_add_f32_e32 v66, v51, v50
	v_pk_mul_f32 v[50:51], v[54:55], v[226:227] op_sel_hi:[0,1]
	v_pk_mul_f32 v[50:51], v[230:231], v[50:51]
	v_mov_b32_e32 v190, v78
	v_pk_mul_f32 v[56:57], v[232:233], v[50:51]
	v_mov_b32_e32 v112, v109
	v_sub_f32_e32 v68, v56, v57
	v_mov_b32_e32 v56, v128
	v_mov_b32_e32 v57, v116
	v_pk_mul_f32 v[50:51], v[56:57], v[50:51]
	v_mov_b32_e32 v128, v117
	v_add_f32_e32 v78, v51, v50
	v_pk_mul_f32 v[50:51], v[54:55], v[234:235] op_sel_hi:[0,1]
	v_pk_mul_f32 v[50:51], v[112:113], v[50:51]
	v_mov_b32_e32 v116, v129
	v_pk_mul_f32 v[56:57], v[128:129], v[50:51]
	v_pk_mul_f32 v[50:51], v[116:117], v[50:51]
	v_mov_b32_e32 v222, v94
	v_mov_b32_e32 v223, v98
	v_add_f32_e32 v94, v51, v50
	v_pk_mul_f32 v[50:51], v[54:55], v[218:219] op_sel_hi:[0,1]
	v_mov_b32_e32 v224, v102
	v_mov_b32_e32 v225, v122
	v_pk_mul_f32 v[50:51], v[50:51], v[222:223]
	v_mov_b32_e32 v156, v80
	v_sub_f32_e32 v80, v56, v57
	v_pk_mul_f32 v[56:57], v[50:51], v[224:225]
	v_mov_b32_e32 v196, v96
	v_sub_f32_e32 v96, v56, v57
	v_mov_b32_e32 v56, v122
	v_mov_b32_e32 v57, v102
	v_pk_mul_f32 v[50:51], v[50:51], v[56:57]
	v_mov_b32_e32 v98, v95
	v_add_f32_e32 v106, v51, v50
	v_pk_mul_f32 v[50:51], v[54:55], v[52:53] op_sel_hi:[0,1]
	v_pk_mul_f32 v[50:51], v[50:51], v[98:99]
	v_mov_b32_e32 v122, v103
	v_mov_b32_e32 v102, v123
; __device__ __forceinline__ unsigned cvt_pk_bf16(float lo, float hi) { unsigned r; asm volatile("v_cvt_pk_bf16_f32 %0, %1, %2" : "=v"(r) : "v"(lo), "v"(hi)); return r; }
; #define LAS __attribute__((address_space(3)))
; __device__ __forceinline__ void p2_block(LAS unsigned char* lds, const bf16_t* __restrict__ PROJ, bf16_t* __restrict__ ATT, bf16_t* __restrict__ SGU, const float* __restrict__ qn, const float* __restrict__ kn, ...
;     ...
;         for (int j = 0; j < 16; ++j) { const float a1 = x1[j] * rinv * kn[16 * h + j], a2 = x2[j] * rinv * kn[32 + 16 * h + j], c = cp[j], sn = sp[j]; o1[j] = a1 * c - a2 * sn; o2[j] = a2 * c + a1 * sn; }
;         LAS unsigned char* kdst = KS + kk * KS_STRIDE + 32 * h;
;         u32x4 w0, w1;
;         w0.x = cvt_pk_bf16(o1[0], o1[1]); w0.y = cvt_pk_bf16(o1[2], o1[3]); w0.z = cvt_pk_bf16(o1[4], o1[5]); w0.w = cvt_pk_bf16(o1[6], o1[7]);
;         w1.x = cvt_pk_bf16(o1[8], o1[9]); w1.y = cvt_pk_bf16(o1[10], o1[11]); w1.z = cvt_pk_bf16(o1[12], o1[13]); w1.w = cvt_pk_bf16(o1[14], o1[15]);
;         *(LAS u32x4*)kdst = w0; *(LAS u32x4*)(kdst + 16) = w1;
;         w0.x = cvt_pk_bf16(o2[0], o2[1]); w0.y = cvt_pk_bf16(o2[2], o2[3]); w0.z = cvt_pk_bf16(o2[4], o2[5]); w0.w = cvt_pk_bf16(o2[6], o2[7]);
;         w1.x = cvt_pk_bf16(o2[8], o2[9]); w1.y = cvt_pk_bf16(o2[10], o2[11]); w1.z = cvt_pk_bf16(o2[12], o2[13]); w1.w = cvt_pk_bf16(o2[14], o2[15]);
;         *(LAS u32x4*)(kdst + 64) = w0; *(LAS u32x4*)(kdst + 80) = w1;
;     ...
;         const float* gp = lng + gg * 128 + 32 * q4; const float* bp = lnb + gg * 128 + 32 * q4;
	v_pk_mul_f32 v[52:53], v[50:51], v[122:123]
	v_pk_mul_f32 v[50:51], v[50:51], v[102:103]
	v_mov_b32_e32 v197, v100
	v_add_f32_e32 v95, v51, v50
	v_pk_mul_f32 v[50:51], v[54:55], v[194:195] op_sel_hi:[0,1]
	v_mov_b32_e32 v198, v104
	v_mov_b32_e32 v199, v124
	v_pk_mul_f32 v[50:51], v[50:51], v[196:197]
	v_sub_f32_e32 v56, v52, v53
	v_pk_mul_f32 v[52:53], v[50:51], v[198:199]
	v_mov_b32_e32 v100, v97
	v_sub_f32_e32 v57, v52, v53
	v_mov_b32_e32 v52, v124
	v_mov_b32_e32 v53, v104
	v_pk_mul_f32 v[50:51], v[50:51], v[52:53]
	v_mov_b32_e32 v124, v105
	v_add_f32_e32 v98, v51, v50
	v_pk_mul_f32 v[50:51], v[54:55], v[200:201] op_sel_hi:[0,1]
	v_pk_mul_f32 v[50:51], v[50:51], v[100:101]
	v_mov_b32_e32 v104, v125
	v_pk_mul_f32 v[52:53], v[50:51], v[124:125]
	v_pk_mul_f32 v[50:51], v[50:51], v[104:105]
	v_mov_b32_e32 v191, v82
	v_add_f32_e32 v99, v51, v50
	v_pk_mul_f32 v[50:51], v[54:55], v[188:189] op_sel_hi:[0,1]
	v_mov_b32_e32 v192, v90
	v_mov_b32_e32 v193, v118
	v_pk_mul_f32 v[50:51], v[50:51], v[190:191]
	v_sub_f32_e32 v97, v52, v53
	v_pk_mul_f32 v[52:53], v[50:51], v[192:193]
	v_mov_b32_e32 v82, v79
	v_sub_f32_e32 v100, v52, v53
	v_mov_b32_e32 v52, v118
	v_mov_b32_e32 v53, v90
	v_pk_mul_f32 v[50:51], v[50:51], v[52:53]
	v_mov_b32_e32 v118, v91
	v_add_f32_e32 v101, v51, v50
	v_pk_mul_f32 v[50:51], v[54:55], v[58:59] op_sel_hi:[0,1]
	v_pk_mul_f32 v[50:51], v[50:51], v[82:83]
	v_mov_b32_e32 v90, v119
	v_pk_mul_f32 v[52:53], v[50:51], v[118:119]
	v_pk_mul_f32 v[50:51], v[50:51], v[90:91]
	v_mov_b32_e32 v157, v84
	v_add_f32_e32 v59, v51, v50
	v_pk_mul_f32 v[50:51], v[54:55], v[154:155] op_sel_hi:[0,1]
	v_mov_b32_e32 v158, v92
	v_mov_b32_e32 v159, v120
	v_pk_mul_f32 v[50:51], v[50:51], v[156:157]
	v_sub_f32_e32 v58, v52, v53
	v_pk_mul_f32 v[52:53], v[50:51], v[158:159]
	v_mov_b32_e32 v84, v81
	v_sub_f32_e32 v79, v52, v53
	v_mov_b32_e32 v52, v120
	v_mov_b32_e32 v53, v92
	v_pk_mul_f32 v[50:51], v[50:51], v[52:53]
	v_mov_b32_e32 v120, v93
	v_add_f32_e32 v82, v51, v50
	v_pk_mul_f32 v[50:51], v[54:55], v[64:65] op_sel_hi:[0,1]
	v_pk_mul_f32 v[50:51], v[50:51], v[84:85]
	v_mov_b32_e32 v92, v121
	v_pk_mul_f32 v[52:53], v[50:51], v[120:121]
	v_pk_mul_f32 v[50:51], v[50:51], v[92:93]
	v_mov_b32_e32 v151, v70
	v_add_f32_e32 v65, v51, v50
	v_pk_mul_f32 v[50:51], v[54:55], v[148:149] op_sel_hi:[0,1]
	v_mov_b32_e32 v152, v74
	v_mov_b32_e32 v153, v86
	v_pk_mul_f32 v[50:51], v[50:51], v[150:151]
	v_sub_f32_e32 v64, v52, v53
	v_pk_mul_f32 v[52:53], v[50:51], v[152:153]
	v_mov_b32_e32 v70, v67
	v_sub_f32_e32 v81, v52, v53
	v_mov_b32_e32 v52, v86
	v_mov_b32_e32 v53, v74
	v_pk_mul_f32 v[50:51], v[50:51], v[52:53]
	v_mov_b32_e32 v86, v75
	v_add_f32_e32 v83, v51, v50
	v_pk_mul_f32 v[50:51], v[54:55], v[60:61] op_sel_hi:[0,1]
	v_pk_mul_f32 v[50:51], v[50:51], v[70:71]
	v_mov_b32_e32 v74, v87
	v_pk_mul_f32 v[52:53], v[50:51], v[86:87]
	v_pk_mul_f32 v[50:51], v[50:51], v[74:75]
	v_mov_b32_e32 v145, v72
	v_add_f32_e32 v61, v51, v50
	v_pk_mul_f32 v[50:51], v[54:55], v[142:143] op_sel_hi:[0,1]
	v_mov_b32_e32 v146, v76
	v_mov_b32_e32 v147, v88
	v_pk_mul_f32 v[50:51], v[50:51], v[144:145]
	v_sub_f32_e32 v60, v52, v53
	v_pk_mul_f32 v[52:53], v[50:51], v[146:147]
	v_mov_b32_e32 v72, v69
	v_lshl_add_u32 v182, v165, 2, s4
	global_load_dwordx4 v[144:147], v182, s[36:37] offset:0
	global_load_dwordx4 v[148:151], v182, s[36:37] offset:16
	global_load_dwordx4 v[152:155], v182, s[36:37] offset:32
	global_load_dwordx4 v[156:159], v182, s[36:37] offset:48
	global_load_dwordx4 v[184:187], v182, s[36:37] offset:64
	global_load_dwordx4 v[188:191], v182, s[36:37] offset:80
	global_load_dwordx4 v[192:195], v182, s[36:37] offset:96
	global_load_dwordx4 v[196:199], v182, s[36:37] offset:112
	global_load_dwordx4 v[218:221], v182, s[18:19] offset:0
	global_load_dwordx4 v[222:225], v182, s[18:19] offset:16
	global_load_dwordx4 v[226:229], v182, s[18:19] offset:32
	global_load_dwordx4 v[230:233], v182, s[18:19] offset:48
	global_load_dwordx4 v[234:237], v182, s[18:19] offset:64
	global_load_dwordx4 v[238:241], v182, s[18:19] offset:80
	global_load_dwordx4 v[242:245], v182, s[18:19] offset:96
	global_load_dwordx4 v[200:203], v182, s[18:19] offset:112
	v_sub_f32_e32 v67, v52, v53
	v_mov_b32_e32 v52, v88
	v_mov_b32_e32 v53, v76
	v_pk_mul_f32 v[50:51], v[50:51], v[52:53]
	v_mov_b32_e32 v88, v77
	v_add_f32_e32 v70, v51, v50
	v_pk_mul_f32 v[50:51], v[54:55], v[140:141] op_sel_hi:[0,1]
	v_pk_mul_f32 v[50:51], v[50:51], v[72:73]
	v_mov_b32_e32 v76, v89
	v_pk_mul_f32 v[52:53], v[50:51], v[88:89]
	v_pk_mul_f32 v[50:51], v[50:51], v[76:77]
	v_sub_f32_e32 v69, v52, v53
	v_add_f32_e32 v71, v51, v50
	v_mul_lo_u32 v50, v167, s59
	v_add3_u32 v0, 0, v50, v0
	v_cvt_pk_bf16_f32 v50, v55, v63
	v_cvt_pk_bf16_f32 v51, v68, v80
	v_cvt_pk_bf16_f32 v52, v96, v56
	v_cvt_pk_bf16_f32 v53, v57, v97
	v_cvt_pk_bf16_f32 v54, v100, v58
	v_cvt_pk_bf16_f32 v55, v79, v64
	v_cvt_pk_bf16_f32 v56, v81, v60
	v_cvt_pk_bf16_f32 v57, v67, v69
	v_lshlrev_b32_e32 v73, 16, v46
	ds_write_b128 v0, v[50:53]
	ds_write_b128 v0, v[54:57] offset:16
	v_cvt_pk_bf16_f32 v50, v62, v66
	v_cvt_pk_bf16_f32 v51, v78, v94
	v_cvt_pk_bf16_f32 v52, v106, v95
	v_cvt_pk_bf16_f32 v53, v98, v99
	v_cvt_pk_bf16_f32 v54, v101, v59
	v_cvt_pk_bf16_f32 v55, v82, v65
	v_cvt_pk_bf16_f32 v56, v83, v61
	v_cvt_pk_bf16_f32 v57, v70, v71
	v_lshlrev_b32_e32 v70, 16, v48
	v_and_b32_e32 v69, 0xffff0000, v48
	v_lshlrev_b32_e32 v68, 16, v49
	v_and_b32_e32 v67, 0xffff0000, v49
	v_lshlrev_b32_e32 v66, 16, v42
	v_and_b32_e32 v65, 0xffff0000, v42
	v_lshlrev_b32_e32 v64, 16, v43
	v_and_b32_e32 v63, 0xffff0000, v43
	v_lshlrev_b32_e32 v62, 16, v44
	v_and_b32_e32 v61, 0xffff0000, v44
; __device__ __forceinline__ unsigned cvt_pk_bf16(float lo, float hi) { unsigned r; asm volatile("v_cvt_pk_bf16_f32 %0, %1, %2" : "=v"(r) : "v"(lo), "v"(hi)); return r; }
; __device__ __forceinline__ float gelu_f(float x) { const float y2 = 1.5957691216057308f * x * (1.0f + 0.044715f * x * x); return x * sigmoid_f(y2); }
; #define LAS __attribute__((address_space(3)))
; __device__ __forceinline__ void unpack8(const u32x4 w, float* f) { f[0] = bf_lo(w.x); f[1] = bf_hi(w.x); f[2] = bf_lo(w.y); f[3] = bf_hi(w.y); f[4] = bf_lo(w.z); f[5] = bf_hi(w.z); f[6] = bf_lo(w.w); f[7] = bf_hi(w.w); }
; __device__ __forceinline__ void p2_block(LAS unsigned char* lds, const bf16_t* __restrict__ PROJ, bf16_t* __restrict__ ATT, bf16_t* __restrict__ SGU, const float* __restrict__ qn, const float* __restrict__ kn, ...
;     ...
;         *(LAS u32x4*)kdst = w0; *(LAS u32x4*)(kdst + 16) = w1;
;         w0.x = cvt_pk_bf16(o2[0], o2[1]); w0.y = cvt_pk_bf16(o2[2], o2[3]); w0.z = cvt_pk_bf16(o2[4], o2[5]); w0.w = cvt_pk_bf16(o2[6], o2[7]);
;         w1.x = cvt_pk_bf16(o2[8], o2[9]); w1.y = cvt_pk_bf16(o2[10], o2[11]); w1.z = cvt_pk_bf16(o2[12], o2[13]); w1.w = cvt_pk_bf16(o2[14], o2[15]);
;         *(LAS u32x4*)(kdst + 64) = w0; *(LAS u32x4*)(kdst + 80) = w1;
;     ...
;         for (int c4 = 0; c4 < 4; ++c4) unpack8(sv[gi][c4], v + 8 * c4);
;         float sm = 0.f;
; #pragma unroll
;         for (int j = 0; j < 32; ++j) { v[j] = gelu_f(v[j]); sm += v[j]; }
	v_lshlrev_b32_e32 v60, 16, v45
	v_and_b32_e32 v59, 0xffff0000, v45
	v_lshlrev_b32_e32 v49, 16, v40
	v_and_b32_e32 v48, 0xffff0000, v40
	v_lshlrev_b32_e32 v45, 16, v41
	v_and_b32_e32 v44, 0xffff0000, v41
	v_lshlrev_b32_e32 v43, 16, v34
	v_and_b32_e32 v42, 0xffff0000, v34
	v_lshlrev_b32_e32 v41, 16, v35
	v_and_b32_e32 v40, 0xffff0000, v35
	v_lshlrev_b32_e32 v35, 16, v37
	v_and_b32_e32 v34, 0xffff0000, v37
	v_mul_f32_e32 v37, 0x3d372713, v73
	ds_write_b128 v0, v[50:53] offset:64
	ds_write_b128 v0, v[54:57] offset:80
	v_lshlrev_b32_e32 v58, 16, v38
	v_and_b32_e32 v57, 0xffff0000, v38
	v_lshlrev_b32_e32 v56, 16, v39
	v_and_b32_e32 v55, 0xffff0000, v39
	v_lshlrev_b32_e32 v39, 16, v36
	v_and_b32_e32 v38, 0xffff0000, v36
	v_mul_f32_e32 v36, 0x3fcc422a, v73
	v_fma_f32 v37, v37, v73, 1.0
	v_mul_f32_e32 v36, v36, v37
	v_mul_f32_e32 v36, 0xbfb8aa3b, v36
	v_exp_f32_e32 v36, v36
	v_and_b32_e32 v74, 0xffff0000, v46
	v_mul_f32_e32 v37, 0x3d372713, v74
	v_fma_f32 v37, v37, v74, 1.0
	v_add_f32_e32 v36, 1.0, v36
	v_rcp_f32_e32 v75, v36
	v_mul_f32_e32 v36, 0x3fcc422a, v74
	v_mul_f32_e32 v36, v36, v37
	v_mul_f32_e32 v36, 0xbfb8aa3b, v36
	v_exp_f32_e32 v36, v36
	v_lshlrev_b32_e32 v72, 16, v47
	v_mul_f32_e32 v37, 0x3d372713, v72
	v_fma_f32 v37, v37, v72, 1.0
	v_add_f32_e32 v36, 1.0, v36
	v_rcp_f32_e32 v76, v36
	v_mul_f32_e32 v36, 0x3fcc422a, v72
	v_mul_f32_e32 v36, v36, v37
	v_mul_f32_e32 v36, 0xbfb8aa3b, v36
	v_exp_f32_e32 v36, v36
	v_and_b32_e32 v71, 0xffff0000, v47
	v_mul_f32_e32 v37, 0x3d372713, v71
	v_fma_f32 v37, v37, v71, 1.0
	v_add_f32_e32 v36, 1.0, v36
	v_rcp_f32_e32 v77, v36
	v_mul_f32_e32 v36, 0x3fcc422a, v71
	v_mul_f32_e32 v36, v36, v37
	v_mul_f32_e32 v36, 0xbfb8aa3b, v36
	v_exp_f32_e32 v36, v36
	v_mul_f32_e32 v37, 0x3d372713, v70
	v_fma_f32 v37, v37, v70, 1.0
	v_fma_f32 v46, v75, v73, 0
	v_add_f32_e32 v36, 1.0, v36
	v_rcp_f32_e32 v78, v36
	v_mul_f32_e32 v36, 0x3fcc422a, v70
	v_mul_f32_e32 v36, v36, v37
	v_mul_f32_e32 v36, 0xbfb8aa3b, v36
	v_exp_f32_e32 v36, v36
	v_mul_f32_e32 v37, 0x3d372713, v69
	v_fma_f32 v37, v37, v69, 1.0
	v_fmac_f32_e32 v46, v76, v74
	v_add_f32_e32 v36, 1.0, v36
	v_rcp_f32_e32 v79, v36
	v_mul_f32_e32 v36, 0x3fcc422a, v69
	v_mul_f32_e32 v36, v36, v37
	v_mul_f32_e32 v36, 0xbfb8aa3b, v36
	v_exp_f32_e32 v36, v36
	v_mul_f32_e32 v37, 0x3d372713, v68
	v_fma_f32 v37, v37, v68, 1.0
	v_fmac_f32_e32 v46, v77, v72
	v_add_f32_e32 v36, 1.0, v36
	v_rcp_f32_e32 v80, v36
	v_mul_f32_e32 v36, 0x3fcc422a, v68
	v_mul_f32_e32 v36, v36, v37
	v_mul_f32_e32 v36, 0xbfb8aa3b, v36
	v_exp_f32_e32 v36, v36
	v_mul_f32_e32 v37, 0x3d372713, v67
	v_fma_f32 v37, v37, v67, 1.0
	v_fmac_f32_e32 v46, v78, v71
	v_add_f32_e32 v36, 1.0, v36
	v_rcp_f32_e32 v81, v36
	v_mul_f32_e32 v36, 0x3fcc422a, v67
	v_mul_f32_e32 v36, v36, v37
	v_mul_f32_e32 v36, 0xbfb8aa3b, v36
	v_exp_f32_e32 v36, v36
	v_mul_f32_e32 v37, 0x3d372713, v66
	v_fma_f32 v37, v37, v66, 1.0
	v_fmac_f32_e32 v46, v79, v70
	v_add_f32_e32 v36, 1.0, v36
	v_rcp_f32_e32 v82, v36
	v_mul_f32_e32 v36, 0x3fcc422a, v66
	v_mul_f32_e32 v36, v36, v37
	v_mul_f32_e32 v36, 0xbfb8aa3b, v36
	v_exp_f32_e32 v36, v36
	v_mul_f32_e32 v37, 0x3d372713, v65
	v_fma_f32 v37, v37, v65, 1.0
	v_fmac_f32_e32 v46, v80, v69
	v_add_f32_e32 v36, 1.0, v36
	v_rcp_f32_e32 v84, v36
	v_mul_f32_e32 v36, 0x3fcc422a, v65
	v_mul_f32_e32 v36, v36, v37
	v_mul_f32_e32 v36, 0xbfb8aa3b, v36
	v_exp_f32_e32 v36, v36
	v_mul_f32_e32 v37, 0x3d372713, v64
	v_fma_f32 v37, v37, v64, 1.0
	v_fmac_f32_e32 v46, v81, v68
	v_add_f32_e32 v36, 1.0, v36
	v_rcp_f32_e32 v85, v36
	v_mul_f32_e32 v36, 0x3fcc422a, v64
	v_mul_f32_e32 v36, v36, v37
	v_mul_f32_e32 v36, 0xbfb8aa3b, v36
	v_exp_f32_e32 v36, v36
	v_mul_f32_e32 v37, 0x3d372713, v63
	v_fma_f32 v37, v37, v63, 1.0
	v_fmac_f32_e32 v46, v82, v67
	v_add_f32_e32 v36, 1.0, v36
	v_rcp_f32_e32 v86, v36
	v_mul_f32_e32 v36, 0x3fcc422a, v63
	v_mul_f32_e32 v36, v36, v37
	v_mul_f32_e32 v36, 0xbfb8aa3b, v36
	v_exp_f32_e32 v36, v36
	v_mul_f32_e32 v37, 0x3d372713, v62
	v_fma_f32 v37, v37, v62, 1.0
	v_fmac_f32_e32 v46, v84, v66
	v_add_f32_e32 v36, 1.0, v36
	v_rcp_f32_e32 v87, v36
	v_mul_f32_e32 v36, 0x3fcc422a, v62
	v_mul_f32_e32 v36, v36, v37
	v_mul_f32_e32 v36, 0xbfb8aa3b, v36
	v_exp_f32_e32 v36, v36
	v_mul_f32_e32 v37, 0x3d372713, v61
	v_fma_f32 v37, v37, v61, 1.0
	v_fmac_f32_e32 v46, v85, v65
	v_add_f32_e32 v36, 1.0, v36
	v_rcp_f32_e32 v88, v36
	v_mul_f32_e32 v36, 0x3fcc422a, v61
	v_mul_f32_e32 v36, v36, v37
	v_mul_f32_e32 v36, 0xbfb8aa3b, v36
	v_exp_f32_e32 v36, v36
	v_mul_f32_e32 v37, 0x3d372713, v60
	v_fma_f32 v37, v37, v60, 1.0
	v_fmac_f32_e32 v46, v86, v64
	v_add_f32_e32 v36, 1.0, v36
	v_rcp_f32_e32 v89, v36
	v_mul_f32_e32 v36, 0x3fcc422a, v60
	v_mul_f32_e32 v36, v36, v37
	v_mul_f32_e32 v36, 0xbfb8aa3b, v36
	v_exp_f32_e32 v36, v36
	v_mul_f32_e32 v37, 0x3d372713, v59
	v_fma_f32 v37, v37, v59, 1.0
	v_mul_f32_e32 v47, 0x3d372713, v42
	v_add_f32_e32 v36, 1.0, v36
	v_rcp_f32_e32 v90, v36
	v_mul_f32_e32 v36, 0x3fcc422a, v59
	v_mul_f32_e32 v36, v36, v37
	v_mul_f32_e32 v36, 0xbfb8aa3b, v36
	v_exp_f32_e32 v36, v36
	v_mul_f32_e32 v37, 0x3d372713, v58
	v_fma_f32 v37, v37, v58, 1.0
	v_fmac_f32_e32 v46, v87, v63
	v_add_f32_e32 v36, 1.0, v36
	v_rcp_f32_e32 v91, v36
	v_mul_f32_e32 v36, 0x3fcc422a, v58
	v_mul_f32_e32 v36, v36, v37
	v_mul_f32_e32 v36, 0xbfb8aa3b, v36
	v_exp_f32_e32 v36, v36
	v_mul_f32_e32 v37, 0x3d372713, v57
	v_fma_f32 v37, v37, v57, 1.0
	v_fma_f32 v47, v47, v42, 1.0
	v_add_f32_e32 v36, 1.0, v36
	v_rcp_f32_e32 v98, v36
	v_mul_f32_e32 v36, 0x3fcc422a, v57
	v_mul_f32_e32 v36, v36, v37
	v_mul_f32_e32 v36, 0xbfb8aa3b, v36
	v_exp_f32_e32 v36, v36
	v_mul_f32_e32 v37, 0x3d372713, v56
	v_fma_f32 v37, v37, v56, 1.0
	v_fmac_f32_e32 v46, v88, v62
; __device__ __forceinline__ float gelu_f(float x) { const float y2 = 1.5957691216057308f * x * (1.0f + 0.044715f * x * x); return x * sigmoid_f(y2); }
; #define LAS __attribute__((address_space(3)))
; __device__ __forceinline__ void unpack8(const u32x4 w, float* f) { f[0] = bf_lo(w.x); f[1] = bf_hi(w.x); f[2] = bf_lo(w.y); f[3] = bf_hi(w.y); f[4] = bf_lo(w.z); f[5] = bf_hi(w.z); f[6] = bf_lo(w.w); f[7] = bf_hi(w.w); }
; __device__ __forceinline__ void p2_block(LAS unsigned char* lds, const bf16_t* __restrict__ PROJ, bf16_t* __restrict__ ATT, bf16_t* __restrict__ SGU, const float* __restrict__ qn, const float* __restrict__ kn, ...
;     ...
;         for (int c4 = 0; c4 < 4; ++c4) { u32x4 t = vv[c4]; if (s < 0) t = (u32x4){0u, 0u, 0u, 0u};
;             LAS unsigned char* vd = VT + (32 * h + 8 * c4) * VT_STRIDE + kk * 2;
;             *(LAS unsigned short*)(vd + 0 * VT_STRIDE) = (unsigned short)(t.x & 0xffffu); *(LAS unsigned short*)(vd + 1 * VT_STRIDE) = (unsigned short)(t.x >> 16);
;             *(LAS unsigned short*)(vd + 2 * VT_STRIDE) = (unsigned short)(t.y & 0xffffu); *(LAS unsigned short*)(vd + 3 * VT_STRIDE) = (unsigned short)(t.y >> 16);
;             *(LAS unsigned short*)(vd + 4 * VT_STRIDE) = (unsigned short)(t.z & 0xffffu); *(LAS unsigned short*)(vd + 5 * VT_STRIDE) = (unsigned short)(t.z >> 16);
;             *(LAS unsigned short*)(vd + 6 * VT_STRIDE) = (unsigned short)(t.w & 0xffffu); *(LAS unsigned short*)(vd + 7 * VT_STRIDE) = (unsigned short)(t.w >> 16); }
;     ...
;         for (int c4 = 0; c4 < 4; ++c4) unpack8(sv[gi][c4], v + 8 * c4);
;         float sm = 0.f;
; #pragma unroll
;         for (int j = 0; j < 32; ++j) { v[j] = gelu_f(v[j]); sm += v[j]; }
;         sm += __shfl_xor(sm, 1); sm += __shfl_xor(sm, 2);
	v_add_f32_e32 v36, 1.0, v36
	v_rcp_f32_e32 v99, v36
	v_mul_f32_e32 v36, 0x3fcc422a, v56
	v_mul_f32_e32 v36, v36, v37
	v_mul_f32_e32 v36, 0xbfb8aa3b, v36
	v_exp_f32_e32 v36, v36
	v_mul_f32_e32 v37, 0x3d372713, v55
	v_fma_f32 v37, v37, v55, 1.0
	v_fmac_f32_e32 v46, v89, v61
	v_add_f32_e32 v36, 1.0, v36
	v_rcp_f32_e32 v100, v36
	v_mul_f32_e32 v36, 0x3fcc422a, v55
	v_mul_f32_e32 v36, v36, v37
	v_mul_f32_e32 v36, 0xbfb8aa3b, v36
	v_exp_f32_e32 v36, v36
	v_mul_f32_e32 v37, 0x3d372713, v49
	v_fma_f32 v37, v37, v49, 1.0
	v_fmac_f32_e32 v46, v90, v60
	v_add_f32_e32 v36, 1.0, v36
	v_rcp_f32_e32 v101, v36
	v_mul_f32_e32 v36, 0x3fcc422a, v49
	v_mul_f32_e32 v36, v36, v37
	v_mul_f32_e32 v36, 0xbfb8aa3b, v36
	v_exp_f32_e32 v36, v36
	v_mul_f32_e32 v37, 0x3d372713, v48
	v_fma_f32 v37, v37, v48, 1.0
	v_fmac_f32_e32 v46, v91, v59
	v_add_f32_e32 v36, 1.0, v36
	v_rcp_f32_e32 v102, v36
	v_mul_f32_e32 v36, 0x3fcc422a, v48
	v_mul_f32_e32 v36, v36, v37
	v_mul_f32_e32 v36, 0xbfb8aa3b, v36
	v_exp_f32_e32 v36, v36
	v_mul_f32_e32 v37, 0x3d372713, v45
	v_fma_f32 v37, v37, v45, 1.0
	v_fmac_f32_e32 v46, v98, v58
	v_add_f32_e32 v36, 1.0, v36
	v_rcp_f32_e32 v103, v36
	v_mul_f32_e32 v36, 0x3fcc422a, v45
	v_mul_f32_e32 v36, v36, v37
	v_mul_f32_e32 v36, 0xbfb8aa3b, v36
	v_exp_f32_e32 v36, v36
	v_mul_f32_e32 v37, 0x3d372713, v44
	v_fma_f32 v37, v37, v44, 1.0
	v_fmac_f32_e32 v46, v99, v57
	v_add_f32_e32 v36, 1.0, v36
	v_rcp_f32_e32 v104, v36
	v_mul_f32_e32 v36, 0x3fcc422a, v44
	v_mul_f32_e32 v36, v36, v37
	v_mul_f32_e32 v36, 0xbfb8aa3b, v36
	v_exp_f32_e32 v36, v36
	v_mul_f32_e32 v37, 0x3d372713, v43
	v_fma_f32 v37, v37, v43, 1.0
	v_fmac_f32_e32 v46, v100, v56
	v_add_f32_e32 v36, 1.0, v36
	v_rcp_f32_e32 v105, v36
	v_mul_f32_e32 v36, 0x3fcc422a, v43
	v_mul_f32_e32 v36, v36, v37
	v_mul_f32_e32 v36, 0xbfb8aa3b, v36
	v_exp_f32_e32 v36, v36
	v_fmac_f32_e32 v46, v101, v55
	v_fmac_f32_e32 v46, v102, v49
	v_fmac_f32_e32 v46, v103, v48
	v_add_f32_e32 v36, 1.0, v36
	v_rcp_f32_e32 v37, v36
	v_mul_f32_e32 v36, 0x3fcc422a, v42
	v_mul_f32_e32 v36, v36, v47
	v_mul_f32_e32 v36, 0xbfb8aa3b, v36
	v_exp_f32_e32 v36, v36
	v_fmac_f32_e32 v46, v104, v45
	v_fmac_f32_e32 v46, v105, v44
	v_mul_f32_e32 v47, 0x3d372713, v41
	v_add_f32_e32 v36, 1.0, v36
	v_rcp_f32_e32 v36, v36
	v_fma_f32 v47, v47, v41, 1.0
	v_mul_f32_e32 v94, 0x3d372713, v38
	v_fma_f32 v94, v94, v38, 1.0
	v_pk_mul_f32 v[92:93], v[36:37], v[42:43]
	v_mul_f32_e32 v96, 0x3d372713, v34
	v_add_f32_e32 v46, v93, v46
	v_add_f32_e32 v83, v92, v46
	v_mul_f32_e32 v46, 0x3fcc422a, v41
	v_mul_f32_e32 v46, v46, v47
	v_mul_f32_e32 v46, 0xbfb8aa3b, v46
	v_exp_f32_e32 v46, v46
	v_mul_f32_e32 v92, 0x3d372713, v40
	v_fma_f32 v92, v92, v40, 1.0
	v_fma_f32 v96, v96, v34, 1.0
	v_add_f32_e32 v46, 1.0, v46
	v_rcp_f32_e32 v47, v46
	v_mul_f32_e32 v46, 0x3fcc422a, v40
	v_mul_f32_e32 v46, v46, v92
	v_mul_f32_e32 v46, 0xbfb8aa3b, v46
	v_exp_f32_e32 v46, v46
	v_and_b32_e32 v0, -2, v160
	v_mul_u32_u24_e32 v50, 0x4200, v166
	v_cndmask_b32_e64 v18, v18, 0, vcc
	v_add_f32_e32 v46, 1.0, v46
	v_rcp_f32_e32 v46, v46
	v_add3_u32 v0, 0, v0, v50
	v_cndmask_b32_e64 v14, v14, 0, vcc
	v_cndmask_b32_e64 v10, v10, 0, vcc
	v_pk_mul_f32 v[92:93], v[46:47], v[40:41]
	v_cndmask_b32_e64 v6, v6, 0, vcc
	v_add_f32_e32 v83, v93, v83
	v_mul_f32_e32 v93, 0x3d372713, v39
	v_add_f32_e32 v83, v92, v83
	v_mul_f32_e32 v92, 0x3fcc422a, v39
	v_fma_f32 v93, v93, v39, 1.0
	v_mul_f32_e32 v92, v92, v93
	v_mul_f32_e32 v92, 0xbfb8aa3b, v92
	v_exp_f32_e32 v92, v92
	v_cndmask_b32_e64 v21, v21, 0, vcc
	v_cndmask_b32_e64 v20, v20, 0, vcc
	v_cndmask_b32_e64 v19, v19, 0, vcc
	v_add_f32_e32 v92, 1.0, v92
	v_rcp_f32_e32 v93, v92
	v_mul_f32_e32 v92, 0x3fcc422a, v38
	v_mul_f32_e32 v92, v92, v94
	v_mul_f32_e32 v92, 0xbfb8aa3b, v92
	v_exp_f32_e32 v92, v92
	ds_write_b16 v0, v18 offset:36864
	ds_write_b16_d16_hi v0, v18 offset:37392
	ds_write_b16 v0, v19 offset:37920
	ds_write_b16_d16_hi v0, v19 offset:38448
	ds_write_b16 v0, v20 offset:38976
	ds_write_b16_d16_hi v0, v20 offset:39504
	ds_write_b16 v0, v21 offset:40032
	ds_write_b16_d16_hi v0, v21 offset:40560
	v_cndmask_b32_e64 v17, v17, 0, vcc
	v_cndmask_b32_e64 v16, v16, 0, vcc
	v_add_f32_e32 v92, 1.0, v92
	v_rcp_f32_e32 v92, v92
	v_cndmask_b32_e64 v15, v15, 0, vcc
	ds_write_b16 v0, v14 offset:41088
	ds_write_b16_d16_hi v0, v14 offset:41616
	ds_write_b16 v0, v15 offset:42144
	ds_write_b16_d16_hi v0, v15 offset:42672
	ds_write_b16 v0, v16 offset:43200
	ds_write_b16_d16_hi v0, v16 offset:43728
	ds_write_b16 v0, v17 offset:44256
	ds_write_b16_d16_hi v0, v17 offset:44784
	v_cndmask_b32_e64 v13, v13, 0, vcc
	v_pk_mul_f32 v[94:95], v[92:93], v[38:39]
	v_cndmask_b32_e64 v12, v12, 0, vcc
	v_add_f32_e32 v83, v95, v83
	v_mul_f32_e32 v95, 0x3d372713, v35
	v_add_f32_e32 v83, v94, v83
	v_mul_f32_e32 v94, 0x3fcc422a, v35
	v_fma_f32 v95, v95, v35, 1.0
	v_mul_f32_e32 v94, v94, v95
	v_mul_f32_e32 v94, 0xbfb8aa3b, v94
	v_exp_f32_e32 v94, v94
	v_cndmask_b32_e64 v11, v11, 0, vcc
	ds_write_b16 v0, v10 offset:45312
	ds_write_b16_d16_hi v0, v10 offset:45840
	ds_write_b16 v0, v11 offset:46368
	ds_write_b16_d16_hi v0, v11 offset:46896
	ds_write_b16 v0, v12 offset:47424
	ds_write_b16_d16_hi v0, v12 offset:47952
	ds_write_b16 v0, v13 offset:48480
	ds_write_b16_d16_hi v0, v13 offset:49008
	v_cndmask_b32_e64 v9, v9, 0, vcc
	v_add_f32_e32 v94, 1.0, v94
	v_rcp_f32_e32 v95, v94
	v_mul_f32_e32 v94, 0x3fcc422a, v34
	v_mul_f32_e32 v94, v94, v96
	v_mul_f32_e32 v94, 0xbfb8aa3b, v94
	v_exp_f32_e32 v94, v94
	v_cndmask_b32_e64 v8, v8, 0, vcc
	v_cndmask_b32_e64 v7, v7, 0, vcc
	ds_write_b16 v0, v6 offset:49536
	ds_write_b16_d16_hi v0, v6 offset:50064
	ds_write_b16 v0, v7 offset:50592
	ds_write_b16_d16_hi v0, v7 offset:51120
	ds_write_b16 v0, v8 offset:51648
	ds_write_b16_d16_hi v0, v8 offset:52176
	ds_write_b16 v0, v9 offset:52704
	ds_write_b16_d16_hi v0, v9 offset:53232
	v_add_f32_e32 v94, 1.0, v94
	v_rcp_f32_e32 v94, v94
	v_xor_b32_e32 v0, 2, v211
	v_cmp_lt_i32_e32 vcc, v0, v133
	v_lshlrev_b32_e32 v6, 1, v136
	v_pk_mul_f32 v[96:97], v[94:95], v[34:35]
	v_cndmask_b32_e32 v0, v211, v0, vcc
	v_add_f32_e32 v83, v97, v83
	v_add_f32_e32 v83, v96, v83
	ds_bpermute_b32 v96, v164, v83
	v_lshlrev_b32_e32 v54, 2, v0
	v_lshlrev_b32_e32 v0, 2, v165
	v_lshl_add_u64 v[50:51], s[36:37], 0, v[0:1]
	v_lshl_add_u64 v[52:53], s[18:19], 0, v[0:1]
	s_waitcnt lgkmcnt(0)
; __device__ __forceinline__ unsigned cvt_pk_bf16(float lo, float hi) { unsigned r; asm volatile("v_cvt_pk_bf16_f32 %0, %1, %2" : "=v"(r) : "v"(lo), "v"(hi)); return r; }
; #define LAS __attribute__((address_space(3)))
; __device__ __forceinline__ void p2_block(LAS unsigned char* lds, const bf16_t* __restrict__ PROJ, bf16_t* __restrict__ ATT, bf16_t* __restrict__ SGU, const float* __restrict__ qn, const float* __restrict__ kn, ...
;     ...
;             for (int c4 = 0; c4 < 4; ++c4) sv[1][c4] = *(const u32x4*)(svsrc + 128 + 8 * c4); }
;     ...
;         const float mu = sm * (1.0f / 128.0f); float q = 0.f;
; #pragma unroll
;         for (int j = 0; j < 32; ++j) { v[j] -= mu; q += v[j] * v[j]; }
;         q += __shfl_xor(q, 1); q += __shfl_xor(q, 2);
;         const float rstd = rsqrtf(q * (1.0f / 128.0f) + pg8::EPS);
;         const float* gp = lng + gg * 128 + 32 * q4; const float* bp = lnb + gg * 128 + 32 * q4;
;         LAS unsigned char* dst = lds + (gi ? VN_OFF1 : VN_OFF0) + (32 * q4) * VN_STRIDE + sp_ * 2;
; #pragma unroll
;         for (int j = 0; j < 32; j += 2) { const unsigned pk = cvt_pk_bf16(v[j] * rstd * gp[j] + bp[j], v[j + 1] * rstd * gp[j + 1] + bp[j + 1]);
;             *(LAS unsigned short*)(dst + j * VN_STRIDE) = (unsigned short)(pk & 0xffffu); *(LAS unsigned short*)(dst + (j + 1) * VN_STRIDE) = (unsigned short)(pk >> 16); }
	v_add_f32_e32 v83, v83, v96
	ds_bpermute_b32 v96, v54, v83
	v_mul_u32_u24_e32 v0, 0x110, v165
	v_add3_u32 v0, 0, v0, v6
	global_load_dwordx4 v[6:9], v[138:139], off offset:304
	global_load_dwordx4 v[10:13], v[138:139], off offset:288
	global_load_dwordx4 v[14:17], v[138:139], off offset:272
	global_load_dwordx4 v[18:21], v[138:139], off offset:256
	s_ashr_i32 s43, s42, 31
	s_waitcnt lgkmcnt(0)
	v_add_f32_e32 v83, v83, v96
	v_mul_f32_e32 v96, 0x3c000000, v83
	v_fma_f32 v83, v76, v74, -v96
	v_fma_f32 v97, v75, v73, -v96
	v_mul_f32_e32 v106, v83, v83
	v_fmac_f32_e32 v106, v97, v97
	v_fma_f32 v77, v77, v72, -v96
	v_fmac_f32_e32 v106, v77, v77
	v_fma_f32 v76, v78, v71, -v96
	v_fmac_f32_e32 v106, v76, v76
	v_fma_f32 v75, v79, v70, -v96
	v_fmac_f32_e32 v106, v75, v75
	v_fma_f32 v74, v80, v69, -v96
	v_fmac_f32_e32 v106, v74, v74
	v_fma_f32 v73, v81, v68, -v96
	v_fmac_f32_e32 v106, v73, v73
	v_fma_f32 v72, v82, v67, -v96
	v_fmac_f32_e32 v106, v72, v72
	v_fma_f32 v71, v84, v66, -v96
	v_fmac_f32_e32 v106, v71, v71
	v_fma_f32 v70, v85, v65, -v96
	v_fmac_f32_e32 v106, v70, v70
	v_fma_f32 v69, v86, v64, -v96
	v_fmac_f32_e32 v106, v69, v69
	v_fma_f32 v68, v87, v63, -v96
	v_fmac_f32_e32 v106, v68, v68
	v_fma_f32 v67, v88, v62, -v96
	v_fmac_f32_e32 v106, v67, v67
	v_fma_f32 v66, v89, v61, -v96
	v_fmac_f32_e32 v106, v66, v66
	v_fma_f32 v65, v90, v60, -v96
	v_fmac_f32_e32 v106, v65, v65
	v_fma_f32 v64, v91, v59, -v96
	v_fmac_f32_e32 v106, v64, v64
	v_fma_f32 v63, v98, v58, -v96
	v_fmac_f32_e32 v106, v63, v63
	v_fma_f32 v62, v99, v57, -v96
	v_fmac_f32_e32 v106, v62, v62
	v_fma_f32 v61, v100, v56, -v96
	v_fmac_f32_e32 v106, v61, v61
	v_fma_f32 v60, v101, v55, -v96
	v_fmac_f32_e32 v106, v60, v60
	v_fma_f32 v59, v102, v49, -v96
	v_fmac_f32_e32 v106, v59, v59
	v_fma_f32 v58, v103, v48, -v96
	v_fmac_f32_e32 v106, v58, v58
	v_fma_f32 v57, v104, v45, -v96
	v_fmac_f32_e32 v106, v57, v57
	v_fma_f32 v56, v105, v44, -v96
	v_pk_fma_f32 v[44:45], v[36:37], v[42:43], v[96:97] op_sel_hi:[1,1,0] neg_lo:[0,0,1] neg_hi:[0,0,1]
	v_fmac_f32_e32 v106, v56, v56
	v_pk_mul_f32 v[36:37], v[44:45], v[44:45]
	v_pk_fma_f32 v[42:43], v[46:47], v[40:41], v[96:97] op_sel_hi:[1,1,0] neg_lo:[0,0,1] neg_hi:[0,0,1]
	v_add_f32_e32 v37, v37, v106
	v_add_f32_e32 v48, v36, v37
	v_pk_mul_f32 v[36:37], v[42:43], v[42:43]
	v_pk_fma_f32 v[40:41], v[92:93], v[38:39], v[96:97] op_sel_hi:[1,1,0] neg_lo:[0,0,1] neg_hi:[0,0,1]
	v_add_f32_e32 v37, v37, v48
	v_add_f32_e32 v46, v36, v37
	v_pk_mul_f32 v[36:37], v[40:41], v[40:41]
	v_pk_fma_f32 v[38:39], v[94:95], v[34:35], v[96:97] op_sel_hi:[1,1,0] neg_lo:[0,0,1] neg_hi:[0,0,1]
	v_add_f32_e32 v37, v37, v46
	v_add_f32_e32 v36, v36, v37
	v_pk_mul_f32 v[34:35], v[38:39], v[38:39]
	v_lshlrev_b32_e32 v105, 16, v3
	v_add_f32_e32 v35, v35, v36
	v_add_f32_e32 v34, v34, v35
	ds_bpermute_b32 v35, v164, v34
	v_lshl_add_u64 v[36:37], v[52:53], 0, s[4:5]
	v_and_b32_e32 v109, 0xffff0000, v3
	v_lshlrev_b32_e32 v113, 16, v2
	v_lshlrev_b32_e32 v112, 16, v30
	s_waitcnt lgkmcnt(0)
	v_add_f32_e32 v34, v34, v35
	ds_bpermute_b32 v35, v54, v34
	v_and_b32_e32 v3, 0xffff0000, v2
	v_and_b32_e32 v2, 0xffff0000, v30
	v_and_b32_e32 v96, 0xffff0000, v33
	s_waitcnt vmcnt(1)
	v_lshlrev_b32_e32 v53, 16, v14
	s_waitcnt lgkmcnt(0)
	v_add_f32_e32 v34, v34, v35
	v_fmamk_f32 v34, v34, 0x3c000000, v209
	v_cmp_gt_f32_e32 vcc, s82, v34
	v_mul_f32_e32 v35, 0x4b800000, v34
	v_and_b32_e32 v52, 0xffff0000, v14
	v_cndmask_b32_e32 v34, v34, v35, vcc
	v_rsq_f32_e32 v34, v34
	v_and_b32_e32 v14, 0xffff0000, v6
	v_lshlrev_b32_e32 v104, 16, v31
	v_and_b32_e32 v108, 0xffff0000, v31
	v_mul_f32_e32 v35, 0x45800000, v34
	v_cndmask_b32_e32 v55, v34, v35, vcc
	v_lshl_add_u64 v[34:35], v[50:51], 0, s[4:5]
	v_mov_b64_e32 v[46:47], v[144:145]
	v_mov_b64_e32 v[48:49], v[218:219]
	v_mul_f32_e32 v51, v97, v55
	v_add_u32_e32 v50, 0x11800, v0
	v_mul_f32_e32 v45, v45, v55
	v_mul_f32_e32 v44, v44, v55
	v_mul_f32_e32 v43, v43, v55
	v_mul_f32_e32 v42, v42, v55
	v_mul_f32_e32 v41, v41, v55
	v_mul_f32_e32 v40, v40, v55
	v_mul_f32_e32 v39, v39, v55
	v_mul_f32_e32 v38, v38, v55
	v_mov_b32_e32 v116, v112
	v_mov_b32_e32 v117, v2
	v_and_b32_e32 v97, 0xffff0000, v5
	v_mov_b32_e32 v110, v108
	v_mov_b32_e32 v111, v104
	v_mov_b32_e32 v30, v113
	v_mov_b32_e32 v31, v3
	v_pk_mul_f32 v[116:117], v[116:117], v[116:117]
	v_lshlrev_b32_e32 v101, 16, v4
	v_lshlrev_b32_e32 v100, 16, v32
	v_pk_mul_f32 v[110:111], v[110:111], v[110:111]
	v_pk_fma_f32 v[30:31], v[30:31], v[30:31], v[116:117]
	v_lshlrev_b32_e32 v130, 3, v162
	v_mov_b32_e32 v131, v1
	s_mov_b32 s4, s5
	s_mov_b32 s52, 0xf149f2ca
	s_waitcnt vmcnt(0)
	v_fma_f32 v46, v46, v51, v48
	v_mul_f32_e32 v48, v83, v55
	v_fmac_f32_e32 v49, v47, v48
	v_add_u32_e32 v47, 0x11910, v0
	v_cvt_pk_bf16_f32 v46, v46, v49
	ds_write_b16 v50, v46
	ds_write_b16_d16_hi v47, v46
	v_mov_b64_e32 v[46:47], v[146:147]
	v_mov_b64_e32 v[48:49], v[220:221]
	v_mul_f32_e32 v50, v77, v55
	v_lshlrev_b32_e32 v51, 16, v15
	s_waitcnt vmcnt(0)
	v_fma_f32 v46, v46, v50, v48
	v_mul_f32_e32 v48, v76, v55
	v_fmac_f32_e32 v49, v47, v48
	v_add_u32_e32 v47, 0x11a20, v0
	v_cvt_pk_bf16_f32 v46, v46, v49
	ds_write_b16 v47, v46
	v_add_u32_e32 v47, 0x11b30, v0
	ds_write_b16_d16_hi v47, v46
	v_mov_b64_e32 v[46:47], v[148:149]
	v_mov_b64_e32 v[48:49], v[222:223]
	v_mul_f32_e32 v50, v75, v55
	s_waitcnt vmcnt(0)
	v_fma_f32 v46, v46, v50, v48
	v_mul_f32_e32 v48, v74, v55
	v_fmac_f32_e32 v49, v47, v48
	v_add_u32_e32 v47, 0x11c40, v0
	v_cvt_pk_bf16_f32 v46, v46, v49
	ds_write_b16 v47, v46
	v_add_u32_e32 v47, 0x11d50, v0
	ds_write_b16_d16_hi v47, v46
	v_mov_b64_e32 v[46:47], v[150:151]
	v_mov_b64_e32 v[48:49], v[224:225]
	v_mul_f32_e32 v50, v73, v55
	s_waitcnt vmcnt(0)
; __device__ __forceinline__ unsigned cvt_pk_bf16(float lo, float hi) { unsigned r; asm volatile("v_cvt_pk_bf16_f32 %0, %1, %2" : "=v"(r) : "v"(lo), "v"(hi)); return r; }
; #define LAS __attribute__((address_space(3)))
; __device__ __forceinline__ void p2_block(LAS unsigned char* lds, const bf16_t* __restrict__ PROJ, bf16_t* __restrict__ ATT, bf16_t* __restrict__ SGU, const float* __restrict__ qn, const float* __restrict__ kn, ...
;     ...
;         for (int j = 0; j < 32; j += 2) { const unsigned pk = cvt_pk_bf16(v[j] * rstd * gp[j] + bp[j], v[j + 1] * rstd * gp[j + 1] + bp[j + 1]);
;             *(LAS unsigned short*)(dst + j * VN_STRIDE) = (unsigned short)(pk & 0xffffu); *(LAS unsigned short*)(dst + (j + 1) * VN_STRIDE) = (unsigned short)(pk >> 16); }
	v_fma_f32 v46, v46, v50, v48
	v_mul_f32_e32 v48, v72, v55
	v_fmac_f32_e32 v49, v47, v48
	v_add_u32_e32 v47, 0x11e60, v0
	v_cvt_pk_bf16_f32 v46, v46, v49
	ds_write_b16 v47, v46
	v_add_u32_e32 v47, 0x11f70, v0
	ds_write_b16_d16_hi v47, v46
	v_mov_b64_e32 v[46:47], v[152:153]
	v_mov_b64_e32 v[48:49], v[226:227]
	v_mul_f32_e32 v50, v71, v55
	s_waitcnt vmcnt(0)
	v_fma_f32 v46, v46, v50, v48
	v_mul_f32_e32 v48, v70, v55
	v_fmac_f32_e32 v49, v47, v48
	v_add_u32_e32 v47, 0x12080, v0
	v_cvt_pk_bf16_f32 v46, v46, v49
	ds_write_b16 v47, v46
	v_add_u32_e32 v47, 0x12190, v0
	ds_write_b16_d16_hi v47, v46
	v_mov_b64_e32 v[46:47], v[154:155]
	v_mov_b64_e32 v[48:49], v[228:229]
	v_mul_f32_e32 v50, v69, v55
	s_waitcnt vmcnt(0)
	v_fma_f32 v46, v46, v50, v48
	v_mul_f32_e32 v48, v68, v55
	v_fmac_f32_e32 v49, v47, v48
	v_add_u32_e32 v47, 0x122a0, v0
	v_cvt_pk_bf16_f32 v46, v46, v49
	ds_write_b16 v47, v46
	v_add_u32_e32 v47, 0x123b0, v0
	ds_write_b16_d16_hi v47, v46
	v_mov_b64_e32 v[46:47], v[156:157]
	v_mov_b64_e32 v[48:49], v[230:231]
	v_mul_f32_e32 v50, v67, v55
	s_waitcnt vmcnt(0)
	v_fma_f32 v46, v46, v50, v48
	v_mul_f32_e32 v48, v66, v55
	v_fmac_f32_e32 v49, v48, v47
	v_add_u32_e32 v47, 0x124c0, v0
	v_cvt_pk_bf16_f32 v46, v46, v49
	ds_write_b16 v47, v46
	v_add_u32_e32 v47, 0x125d0, v0
	ds_write_b16_d16_hi v47, v46
	v_mov_b64_e32 v[46:47], v[158:159]
	v_mov_b64_e32 v[48:49], v[232:233]
	v_mul_f32_e32 v50, v65, v55
	s_waitcnt vmcnt(0)
	v_fma_f32 v46, v50, v46, v48
	v_mul_f32_e32 v48, v64, v55
	v_fmac_f32_e32 v49, v48, v47
	v_add_u32_e32 v47, 0x126e0, v0
	v_cvt_pk_bf16_f32 v46, v46, v49
	ds_write_b16 v47, v46
	v_add_u32_e32 v47, 0x127f0, v0
	ds_write_b16_d16_hi v47, v46
	v_mov_b64_e32 v[46:47], v[184:185]
	v_mov_b64_e32 v[48:49], v[234:235]
	v_mul_f32_e32 v50, v63, v55
	s_waitcnt vmcnt(0)
	v_fma_f32 v46, v50, v46, v48
	v_mul_f32_e32 v48, v62, v55
	v_fmac_f32_e32 v49, v48, v47
	v_add_u32_e32 v47, 0x12900, v0
	v_cvt_pk_bf16_f32 v46, v46, v49
	ds_write_b16 v47, v46
	v_add_u32_e32 v47, 0x12a10, v0
	ds_write_b16_d16_hi v47, v46
	v_mov_b64_e32 v[46:47], v[186:187]
	v_mov_b64_e32 v[48:49], v[236:237]
	v_mul_f32_e32 v50, v61, v55
	v_lshlrev_b32_e32 v61, 16, v18
	v_and_b32_e32 v62, 0xffff0000, v18
	s_waitcnt vmcnt(0)
	v_fma_f32 v46, v50, v46, v48
	v_mul_f32_e32 v48, v60, v55
	v_fmac_f32_e32 v49, v48, v47
	v_add_u32_e32 v47, 0x12b20, v0
	v_cvt_pk_bf16_f32 v46, v46, v49
	ds_write_b16 v47, v46
	v_add_u32_e32 v47, 0x12c30, v0
	ds_write_b16_d16_hi v47, v46
	v_mov_b64_e32 v[46:47], v[188:189]
	v_mov_b64_e32 v[48:49], v[238:239]
	v_mul_f32_e32 v50, v59, v55
	v_lshlrev_b32_e32 v60, 16, v19
	v_and_b32_e32 v59, 0xffff0000, v19
	s_waitcnt vmcnt(0)
	v_fma_f32 v46, v50, v46, v48
	v_mul_f32_e32 v48, v58, v55
	v_fmac_f32_e32 v49, v48, v47
	v_add_u32_e32 v47, 0x12d40, v0
	v_cvt_pk_bf16_f32 v46, v46, v49
	ds_write_b16 v47, v46
	v_add_u32_e32 v47, 0x12e50, v0
	ds_write_b16_d16_hi v47, v46
	v_mov_b64_e32 v[46:47], v[190:191]
	v_mov_b64_e32 v[48:49], v[240:241]
	v_mul_f32_e32 v50, v57, v55
	v_lshlrev_b32_e32 v58, 16, v20
	v_and_b32_e32 v57, 0xffff0000, v20
	s_waitcnt vmcnt(0)
	v_fma_f32 v46, v50, v46, v48
	v_mul_f32_e32 v48, v56, v55
	v_fmac_f32_e32 v49, v48, v47
	v_add_u32_e32 v47, 0x12f60, v0
	v_cvt_pk_bf16_f32 v46, v46, v49
	ds_write_b16 v47, v46
	v_add_u32_e32 v47, 0x13070, v0
	ds_write_b16_d16_hi v47, v46
	v_mov_b64_e32 v[46:47], v[192:193]
	v_mov_b64_e32 v[48:49], v[242:243]
	v_and_b32_e32 v50, 0xffff0000, v15
	v_lshlrev_b32_e32 v15, 16, v6
	v_and_b32_e32 v6, 0xffff0000, v9
	v_lshlrev_b32_e32 v56, 16, v21
	v_and_b32_e32 v55, 0xffff0000, v21
	v_mul_f32_e32 v88, 0x3d372713, v6
	v_fma_f32 v88, v88, v6, 1.0
	s_waitcnt vmcnt(0)
	v_fma_f32 v45, v45, v46, v48
	v_fmac_f32_e32 v49, v44, v47
	v_cvt_pk_bf16_f32 v44, v45, v49
	v_add_u32_e32 v45, 0x13180, v0
	ds_write_b16 v45, v44
	v_add_u32_e32 v45, 0x13290, v0
	ds_write_b16_d16_hi v45, v44
	v_mov_b64_e32 v[44:45], v[194:195]
	v_mov_b64_e32 v[46:47], v[244:245]
	v_lshlrev_b32_e32 v49, 16, v16
	v_and_b32_e32 v48, 0xffff0000, v16
	s_waitcnt vmcnt(0)
	v_fma_f32 v43, v43, v44, v46
	v_fmac_f32_e32 v47, v42, v45
	v_cvt_pk_bf16_f32 v42, v43, v47
	v_add_u32_e32 v43, 0x133a0, v0
	ds_write_b16 v43, v42
	v_add_u32_e32 v43, 0x134b0, v0
	ds_write_b16_d16_hi v43, v42
	v_mov_b64_e32 v[42:43], v[196:197]
	v_mov_b64_e32 v[44:45], v[200:201]
	v_lshlrev_b32_e32 v47, 16, v17
	v_and_b32_e32 v46, 0xffff0000, v17
	v_mul_f32_e32 v17, 0x3d372713, v14
	v_fma_f32 v17, v17, v14, 1.0
	s_waitcnt vmcnt(0)
	v_fma_f32 v41, v41, v42, v44
	v_fmac_f32_e32 v45, v40, v43
	v_cvt_pk_bf16_f32 v40, v41, v45
	v_add_u32_e32 v41, 0x135c0, v0
	ds_write_b16 v41, v40
	v_add_u32_e32 v41, 0x136d0, v0
	ds_write_b16_d16_hi v41, v40
	v_mov_b64_e32 v[40:41], v[198:199]
	v_mov_b64_e32 v[42:43], v[202:203]
	v_lshlrev_b32_e32 v45, 16, v10
	v_and_b32_e32 v44, 0xffff0000, v10
	v_and_b32_e32 v10, 0xffff0000, v8
	s_waitcnt vmcnt(0)
; __device__ __forceinline__ float gelu_f(float x) { const float y2 = 1.5957691216057308f * x * (1.0f + 0.044715f * x * x); return x * sigmoid_f(y2); }
; __device__ __forceinline__ void unpack8(const u32x4 w, float* f) { f[0] = bf_lo(w.x); f[1] = bf_hi(w.x); f[2] = bf_lo(w.y); f[3] = bf_hi(w.y); f[4] = bf_lo(w.z); f[5] = bf_hi(w.z); f[6] = bf_lo(w.w); f[7] = bf_hi(w.w); }
; __device__ __forceinline__ void p2_block(LAS unsigned char* lds, const bf16_t* __restrict__ PROJ, bf16_t* __restrict__ ATT, bf16_t* __restrict__ SGU, const float* __restrict__ qn, const float* __restrict__ kn, ...
;     ...
;             for (int c4 = 0; c4 < 4; ++c4) sv[1][c4] = *(const u32x4*)(svsrc + 128 + 8 * c4); }
;         float v[32];
; #pragma unroll
;         for (int c4 = 0; c4 < 4; ++c4) unpack8(sv[gi][c4], v + 8 * c4);
;         float sm = 0.f;
; #pragma unroll
;         for (int j = 0; j < 32; ++j) { v[j] = gelu_f(v[j]); sm += v[j]; }
;     ...
;         const float* gp = lng + gg * 128 + 32 * q4; const float* bp = lnb + gg * 128 + 32 * q4;
	global_load_dwordx4 v[144:147], v182, s[36:37] offset:512
	global_load_dwordx4 v[148:151], v182, s[36:37] offset:528
	global_load_dwordx4 v[152:155], v182, s[36:37] offset:544
	global_load_dwordx4 v[156:159], v182, s[36:37] offset:560
	global_load_dwordx4 v[184:187], v182, s[36:37] offset:576
	global_load_dwordx4 v[188:191], v182, s[36:37] offset:592
	global_load_dwordx4 v[192:195], v182, s[36:37] offset:608
	global_load_dwordx4 v[196:199], v182, s[36:37] offset:624
	global_load_dwordx4 v[218:221], v182, s[18:19] offset:512
	global_load_dwordx4 v[222:225], v182, s[18:19] offset:528
	global_load_dwordx4 v[226:229], v182, s[18:19] offset:544
	global_load_dwordx4 v[230:233], v182, s[18:19] offset:560
	global_load_dwordx4 v[234:237], v182, s[18:19] offset:576
	global_load_dwordx4 v[238:241], v182, s[18:19] offset:592
	global_load_dwordx4 v[242:245], v182, s[18:19] offset:608
	global_load_dwordx4 v[200:203], v182, s[18:19] offset:624
	v_fma_f32 v39, v39, v40, v42
	v_fmac_f32_e32 v43, v38, v41
	v_cvt_pk_bf16_f32 v38, v39, v43
	v_add_u32_e32 v39, 0x137e0, v0
	ds_write_b16 v39, v38
	v_add_u32_e32 v39, 0x138f0, v0
	ds_write_b16_d16_hi v39, v38
	v_lshlrev_b32_e32 v41, 16, v12
	v_and_b32_e32 v40, 0xffff0000, v12
	v_lshlrev_b32_e32 v39, 16, v13
	v_and_b32_e32 v38, 0xffff0000, v13
	v_lshlrev_b32_e32 v13, 16, v7
	v_and_b32_e32 v12, 0xffff0000, v7
	v_lshlrev_b32_e32 v7, 16, v9
	v_mul_f32_e32 v9, 0x3d372713, v61
	v_lshlrev_b32_e32 v43, 16, v11
	v_and_b32_e32 v42, 0xffff0000, v11
	v_lshlrev_b32_e32 v11, 16, v8
	v_mul_f32_e32 v8, 0x3fcc422a, v61
	v_fma_f32 v9, v9, v61, 1.0
	v_mul_f32_e32 v8, v8, v9
	v_mul_f32_e32 v8, 0xbfb8aa3b, v8
	v_exp_f32_e32 v8, v8
	v_mul_f32_e32 v9, 0x3d372713, v62
	v_fma_f32 v9, v9, v62, 1.0
	v_add_f32_e32 v8, 1.0, v8
	v_rcp_f32_e32 v63, v8
	v_mul_f32_e32 v8, 0x3fcc422a, v62
	v_mul_f32_e32 v8, v8, v9
	v_mul_f32_e32 v8, 0xbfb8aa3b, v8
	v_exp_f32_e32 v8, v8
	v_mul_f32_e32 v9, 0x3d372713, v60
	v_fma_f32 v9, v9, v60, 1.0
	v_fma_f32 v16, v63, v61, 0
	v_add_f32_e32 v8, 1.0, v8
	v_rcp_f32_e32 v64, v8
	v_mul_f32_e32 v8, 0x3fcc422a, v60
	v_mul_f32_e32 v8, v8, v9
	v_mul_f32_e32 v8, 0xbfb8aa3b, v8
	v_exp_f32_e32 v8, v8
	v_mul_f32_e32 v9, 0x3d372713, v59
	v_fma_f32 v9, v9, v59, 1.0
	v_fmac_f32_e32 v16, v64, v62
	v_add_f32_e32 v8, 1.0, v8
	v_rcp_f32_e32 v65, v8
	v_mul_f32_e32 v8, 0x3fcc422a, v59
	v_mul_f32_e32 v8, v8, v9
	v_mul_f32_e32 v8, 0xbfb8aa3b, v8
	v_exp_f32_e32 v8, v8
	v_mul_f32_e32 v9, 0x3d372713, v58
	v_fma_f32 v9, v9, v58, 1.0
	v_fmac_f32_e32 v16, v65, v60
	v_add_f32_e32 v8, 1.0, v8
	v_rcp_f32_e32 v66, v8
	v_mul_f32_e32 v8, 0x3fcc422a, v58
	v_mul_f32_e32 v8, v8, v9
	v_mul_f32_e32 v8, 0xbfb8aa3b, v8
	v_exp_f32_e32 v8, v8
	v_mul_f32_e32 v9, 0x3d372713, v57
	v_fma_f32 v9, v9, v57, 1.0
	v_fmac_f32_e32 v16, v66, v59
	v_add_f32_e32 v8, 1.0, v8
	v_rcp_f32_e32 v67, v8
	v_mul_f32_e32 v8, 0x3fcc422a, v57
	v_mul_f32_e32 v8, v8, v9
	v_mul_f32_e32 v8, 0xbfb8aa3b, v8
	v_exp_f32_e32 v8, v8
	v_mul_f32_e32 v9, 0x3d372713, v56
	v_fma_f32 v9, v9, v56, 1.0
	v_fmac_f32_e32 v16, v67, v58
	v_add_f32_e32 v8, 1.0, v8
	v_rcp_f32_e32 v68, v8
	v_mul_f32_e32 v8, 0x3fcc422a, v56
	v_mul_f32_e32 v8, v8, v9
	v_mul_f32_e32 v8, 0xbfb8aa3b, v8
	v_exp_f32_e32 v8, v8
	v_mul_f32_e32 v9, 0x3d372713, v55
	v_fma_f32 v9, v9, v55, 1.0
	v_fmac_f32_e32 v16, v68, v57
	v_add_f32_e32 v8, 1.0, v8
	v_rcp_f32_e32 v69, v8
	v_mul_f32_e32 v8, 0x3fcc422a, v55
	v_mul_f32_e32 v8, v8, v9
	v_mul_f32_e32 v8, 0xbfb8aa3b, v8
	v_exp_f32_e32 v8, v8
	v_mul_f32_e32 v9, 0x3d372713, v53
	v_fma_f32 v9, v9, v53, 1.0
	v_fmac_f32_e32 v16, v69, v56
	v_add_f32_e32 v8, 1.0, v8
	v_rcp_f32_e32 v70, v8
	v_mul_f32_e32 v8, 0x3fcc422a, v53
	v_mul_f32_e32 v8, v8, v9
	v_mul_f32_e32 v8, 0xbfb8aa3b, v8
	v_exp_f32_e32 v8, v8
	v_mul_f32_e32 v9, 0x3d372713, v52
	v_fma_f32 v9, v9, v52, 1.0
	v_fmac_f32_e32 v16, v70, v55
	v_add_f32_e32 v8, 1.0, v8
	v_rcp_f32_e32 v71, v8
	v_mul_f32_e32 v8, 0x3fcc422a, v52
	v_mul_f32_e32 v8, v8, v9
	v_mul_f32_e32 v8, 0xbfb8aa3b, v8
	v_exp_f32_e32 v8, v8
	v_mul_f32_e32 v9, 0x3d372713, v51
	v_fma_f32 v9, v9, v51, 1.0
	v_fmac_f32_e32 v16, v71, v53
	v_add_f32_e32 v8, 1.0, v8
	v_rcp_f32_e32 v72, v8
	v_mul_f32_e32 v8, 0x3fcc422a, v51
	v_mul_f32_e32 v8, v8, v9
	v_mul_f32_e32 v8, 0xbfb8aa3b, v8
	v_exp_f32_e32 v8, v8
	v_mul_f32_e32 v9, 0x3d372713, v50
	v_fma_f32 v9, v9, v50, 1.0
	v_fmac_f32_e32 v16, v72, v52
	v_add_f32_e32 v8, 1.0, v8
	v_rcp_f32_e32 v73, v8
	v_mul_f32_e32 v8, 0x3fcc422a, v50
	v_mul_f32_e32 v8, v8, v9
	v_mul_f32_e32 v8, 0xbfb8aa3b, v8
	v_exp_f32_e32 v8, v8
	v_mul_f32_e32 v9, 0x3d372713, v49
	v_fma_f32 v9, v9, v49, 1.0
	v_fmac_f32_e32 v16, v73, v51
	v_add_f32_e32 v8, 1.0, v8
	v_rcp_f32_e32 v74, v8
	v_mul_f32_e32 v8, 0x3fcc422a, v49
	v_mul_f32_e32 v8, v8, v9
	v_mul_f32_e32 v8, 0xbfb8aa3b, v8
	v_exp_f32_e32 v8, v8
	v_mul_f32_e32 v9, 0x3d372713, v48
	v_fma_f32 v9, v9, v48, 1.0
	v_fmac_f32_e32 v16, v74, v50
	v_add_f32_e32 v8, 1.0, v8
	v_rcp_f32_e32 v75, v8
	v_mul_f32_e32 v8, 0x3fcc422a, v48
	v_mul_f32_e32 v8, v8, v9
	v_mul_f32_e32 v8, 0xbfb8aa3b, v8
	v_exp_f32_e32 v8, v8
	v_mul_f32_e32 v9, 0x3d372713, v47
	v_fma_f32 v9, v9, v47, 1.0
	v_fmac_f32_e32 v16, v75, v49
	v_add_f32_e32 v8, 1.0, v8
	v_rcp_f32_e32 v76, v8
	v_mul_f32_e32 v8, 0x3fcc422a, v47
	v_mul_f32_e32 v8, v8, v9
	v_mul_f32_e32 v8, 0xbfb8aa3b, v8
	v_exp_f32_e32 v8, v8
	v_mul_f32_e32 v9, 0x3d372713, v46
	v_fma_f32 v9, v9, v46, 1.0
	v_fmac_f32_e32 v16, v76, v48
	v_add_f32_e32 v8, 1.0, v8
	v_rcp_f32_e32 v77, v8
	v_mul_f32_e32 v8, 0x3fcc422a, v46
	v_mul_f32_e32 v8, v8, v9
	v_mul_f32_e32 v8, 0xbfb8aa3b, v8
	v_exp_f32_e32 v8, v8
	v_mul_f32_e32 v9, 0x3d372713, v45
	v_fma_f32 v9, v9, v45, 1.0
	v_fmac_f32_e32 v16, v77, v47
	v_add_f32_e32 v8, 1.0, v8
; __device__ __forceinline__ float gelu_f(float x) { const float y2 = 1.5957691216057308f * x * (1.0f + 0.044715f * x * x); return x * sigmoid_f(y2); }
; __device__ __forceinline__ void p2_block(LAS unsigned char* lds, const bf16_t* __restrict__ PROJ, bf16_t* __restrict__ ATT, bf16_t* __restrict__ SGU, const float* __restrict__ qn, const float* __restrict__ kn, ...
;     ...
;         for (int j = 0; j < 32; ++j) { v[j] = gelu_f(v[j]); sm += v[j]; }
;         sm += __shfl_xor(sm, 1); sm += __shfl_xor(sm, 2);
	v_rcp_f32_e32 v78, v8
	v_mul_f32_e32 v8, 0x3fcc422a, v45
	v_mul_f32_e32 v8, v8, v9
	v_mul_f32_e32 v8, 0xbfb8aa3b, v8
	v_exp_f32_e32 v8, v8
	v_mul_f32_e32 v9, 0x3d372713, v44
	v_fma_f32 v9, v9, v44, 1.0
	v_fmac_f32_e32 v16, v78, v46
	v_add_f32_e32 v8, 1.0, v8
	v_rcp_f32_e32 v79, v8
	v_mul_f32_e32 v8, 0x3fcc422a, v44
	v_mul_f32_e32 v8, v8, v9
	v_mul_f32_e32 v8, 0xbfb8aa3b, v8
	v_exp_f32_e32 v8, v8
	v_mul_f32_e32 v9, 0x3d372713, v43
	v_fma_f32 v9, v9, v43, 1.0
	v_fmac_f32_e32 v16, v79, v45
	v_add_f32_e32 v8, 1.0, v8
	v_rcp_f32_e32 v80, v8
	v_mul_f32_e32 v8, 0x3fcc422a, v43
	v_mul_f32_e32 v8, v8, v9
	v_mul_f32_e32 v8, 0xbfb8aa3b, v8
	v_exp_f32_e32 v8, v8
	v_mul_f32_e32 v9, 0x3d372713, v42
	v_fma_f32 v9, v9, v42, 1.0
	v_fmac_f32_e32 v16, v80, v44
	v_add_f32_e32 v8, 1.0, v8
	v_rcp_f32_e32 v81, v8
	v_mul_f32_e32 v8, 0x3fcc422a, v42
	v_mul_f32_e32 v8, v8, v9
	v_mul_f32_e32 v8, 0xbfb8aa3b, v8
	v_exp_f32_e32 v8, v8
	v_mul_f32_e32 v9, 0x3d372713, v41
	v_fma_f32 v9, v9, v41, 1.0
	v_fmac_f32_e32 v16, v81, v43
	v_add_f32_e32 v8, 1.0, v8
	v_rcp_f32_e32 v82, v8
	v_mul_f32_e32 v8, 0x3fcc422a, v41
	v_mul_f32_e32 v8, v8, v9
	v_mul_f32_e32 v8, 0xbfb8aa3b, v8
	v_exp_f32_e32 v8, v8
	v_mul_f32_e32 v9, 0x3d372713, v40
	v_fma_f32 v9, v9, v40, 1.0
	v_fmac_f32_e32 v16, v82, v42
	v_add_f32_e32 v8, 1.0, v8
	v_rcp_f32_e32 v83, v8
	v_mul_f32_e32 v8, 0x3fcc422a, v40
	v_mul_f32_e32 v8, v8, v9
	v_mul_f32_e32 v8, 0xbfb8aa3b, v8
	v_exp_f32_e32 v8, v8
	v_mul_f32_e32 v9, 0x3d372713, v39
	v_fma_f32 v9, v9, v39, 1.0
	v_fmac_f32_e32 v16, v83, v41
	v_add_f32_e32 v8, 1.0, v8
	v_rcp_f32_e32 v84, v8
	v_mul_f32_e32 v8, 0x3fcc422a, v39
	v_mul_f32_e32 v8, v8, v9
	v_mul_f32_e32 v8, 0xbfb8aa3b, v8
	v_exp_f32_e32 v8, v8
	v_mul_f32_e32 v9, 0x3d372713, v38
	v_fma_f32 v9, v9, v38, 1.0
	v_fmac_f32_e32 v16, v84, v40
	v_add_f32_e32 v8, 1.0, v8
	v_rcp_f32_e32 v85, v8
	v_mul_f32_e32 v8, 0x3fcc422a, v38
	v_mul_f32_e32 v8, v8, v9
	v_mul_f32_e32 v8, 0xbfb8aa3b, v8
	v_exp_f32_e32 v8, v8
	v_mul_f32_e32 v9, 0x3d372713, v15
	v_fma_f32 v9, v9, v15, 1.0
	v_fmac_f32_e32 v16, v85, v39
	v_add_f32_e32 v8, 1.0, v8
	v_rcp_f32_e32 v86, v8
	v_mul_f32_e32 v8, 0x3fcc422a, v15
	v_mul_f32_e32 v8, v8, v9
	v_mul_f32_e32 v8, 0xbfb8aa3b, v8
	v_exp_f32_e32 v8, v8
	v_fmac_f32_e32 v16, v86, v38
	v_add_f32_e32 v8, 1.0, v8
	v_rcp_f32_e32 v9, v8
	v_mul_f32_e32 v8, 0x3fcc422a, v14
	v_mul_f32_e32 v8, v8, v17
	v_mul_f32_e32 v8, 0xbfb8aa3b, v8
	v_exp_f32_e32 v8, v8
	v_mul_f32_e32 v17, 0x3d372713, v13
	v_fma_f32 v17, v17, v13, 1.0
	v_add_f32_e32 v8, 1.0, v8
	v_rcp_f32_e32 v8, v8
	s_nop 0
	v_pk_mul_f32 v[18:19], v[8:9], v[14:15]
	s_nop 0
	v_add_f32_e32 v16, v19, v16
	v_add_f32_e32 v20, v18, v16
	v_mul_f32_e32 v16, 0x3fcc422a, v13
	v_mul_f32_e32 v16, v16, v17
	v_mul_f32_e32 v16, 0xbfb8aa3b, v16
	v_exp_f32_e32 v16, v16
	v_mul_f32_e32 v18, 0x3d372713, v12
	v_fma_f32 v18, v18, v12, 1.0
	v_add_f32_e32 v16, 1.0, v16
	v_rcp_f32_e32 v17, v16
	v_mul_f32_e32 v16, 0x3fcc422a, v12
	v_mul_f32_e32 v16, v16, v18
	v_mul_f32_e32 v16, 0xbfb8aa3b, v16
	v_exp_f32_e32 v16, v16
	s_nop 0
	v_add_f32_e32 v16, 1.0, v16
	v_rcp_f32_e32 v16, v16
	s_nop 0
	v_pk_mul_f32 v[18:19], v[16:17], v[12:13]
	s_nop 0
	v_add_f32_e32 v19, v19, v20
	v_add_f32_e32 v87, v18, v19
	v_mul_f32_e32 v19, 0x3d372713, v11
	v_mul_f32_e32 v18, 0x3fcc422a, v11
	v_fma_f32 v19, v19, v11, 1.0
	v_mul_f32_e32 v18, v18, v19
	v_mul_f32_e32 v18, 0xbfb8aa3b, v18
	v_exp_f32_e32 v18, v18
	v_mul_f32_e32 v20, 0x3d372713, v10
	v_fma_f32 v20, v20, v10, 1.0
	v_add_f32_e32 v18, 1.0, v18
	v_rcp_f32_e32 v19, v18
	v_mul_f32_e32 v18, 0x3fcc422a, v10
	v_mul_f32_e32 v18, v18, v20
	v_mul_f32_e32 v18, 0xbfb8aa3b, v18
	v_exp_f32_e32 v18, v18
	s_nop 0
	v_add_f32_e32 v18, 1.0, v18
	v_rcp_f32_e32 v18, v18
	s_nop 0
	v_pk_mul_f32 v[20:21], v[18:19], v[10:11]
	s_nop 0
	v_add_f32_e32 v21, v21, v87
	v_add_f32_e32 v87, v20, v21
	v_mul_f32_e32 v21, 0x3d372713, v7
	v_mul_f32_e32 v20, 0x3fcc422a, v7
	v_fma_f32 v21, v21, v7, 1.0
	v_mul_f32_e32 v20, v20, v21
	v_mul_f32_e32 v20, 0xbfb8aa3b, v20
	v_exp_f32_e32 v20, v20
	s_nop 0
	v_add_f32_e32 v20, 1.0, v20
	v_rcp_f32_e32 v21, v20
	v_mul_f32_e32 v20, 0x3fcc422a, v6
	v_mul_f32_e32 v20, v20, v88
	v_mul_f32_e32 v20, 0xbfb8aa3b, v20
	v_exp_f32_e32 v20, v20
	s_nop 0
	v_add_f32_e32 v20, 1.0, v20
	v_rcp_f32_e32 v20, v20
	s_nop 0
	v_pk_mul_f32 v[88:89], v[20:21], v[6:7]
	s_nop 0
	v_add_f32_e32 v87, v89, v87
	v_add_f32_e32 v87, v88, v87
	ds_bpermute_b32 v88, v164, v87
	s_waitcnt lgkmcnt(0)
	v_add_f32_e32 v87, v87, v88
	ds_bpermute_b32 v88, v54, v87
	s_waitcnt lgkmcnt(0)
; __device__ __forceinline__ unsigned cvt_pk_bf16(float lo, float hi) { unsigned r; asm volatile("v_cvt_pk_bf16_f32 %0, %1, %2" : "=v"(r) : "v"(lo), "v"(hi)); return r; }
; #define LAS __attribute__((address_space(3)))
; __device__ __forceinline__ void p2_block(LAS unsigned char* lds, const bf16_t* __restrict__ PROJ, bf16_t* __restrict__ ATT, bf16_t* __restrict__ SGU, const float* __restrict__ qn, const float* __restrict__ kn, ...
;     ...
;         const float mu = sm * (1.0f / 128.0f); float q = 0.f;
; #pragma unroll
;         for (int j = 0; j < 32; ++j) { v[j] -= mu; q += v[j] * v[j]; }
;         q += __shfl_xor(q, 1); q += __shfl_xor(q, 2);
;         const float rstd = rsqrtf(q * (1.0f / 128.0f) + pg8::EPS);
;         const float* gp = lng + gg * 128 + 32 * q4; const float* bp = lnb + gg * 128 + 32 * q4;
;         LAS unsigned char* dst = lds + (gi ? VN_OFF1 : VN_OFF0) + (32 * q4) * VN_STRIDE + sp_ * 2;
; #pragma unroll
;         for (int j = 0; j < 32; j += 2) { const unsigned pk = cvt_pk_bf16(v[j] * rstd * gp[j] + bp[j], v[j + 1] * rstd * gp[j + 1] + bp[j + 1]);
;             *(LAS unsigned short*)(dst + j * VN_STRIDE) = (unsigned short)(pk & 0xffffu); *(LAS unsigned short*)(dst + (j + 1) * VN_STRIDE) = (unsigned short)(pk >> 16); }
	v_add_f32_e32 v87, v87, v88
	v_mul_f32_e32 v88, 0x3c000000, v87
	v_fma_f32 v63, v63, v61, -v88
	v_fma_f32 v61, v64, v62, -v88
	v_mul_f32_e32 v62, v61, v61
	v_fmac_f32_e32 v62, v63, v63
	v_fma_f32 v60, v65, v60, -v88
	v_fmac_f32_e32 v62, v60, v60
	v_fma_f32 v59, v66, v59, -v88
	v_fmac_f32_e32 v62, v59, v59
	v_fma_f32 v58, v67, v58, -v88
	v_fmac_f32_e32 v62, v58, v58
	v_fma_f32 v57, v68, v57, -v88
	v_fmac_f32_e32 v62, v57, v57
	v_fma_f32 v56, v69, v56, -v88
	v_fmac_f32_e32 v62, v56, v56
	v_fma_f32 v55, v70, v55, -v88
	v_fmac_f32_e32 v62, v55, v55
	v_fma_f32 v53, v71, v53, -v88
	v_fmac_f32_e32 v62, v53, v53
	v_fma_f32 v52, v72, v52, -v88
	v_fmac_f32_e32 v62, v52, v52
	v_fma_f32 v51, v73, v51, -v88
	v_fmac_f32_e32 v62, v51, v51
	v_fma_f32 v50, v74, v50, -v88
	v_fmac_f32_e32 v62, v50, v50
	v_fma_f32 v49, v75, v49, -v88
	v_fmac_f32_e32 v62, v49, v49
	v_fma_f32 v48, v76, v48, -v88
	v_fmac_f32_e32 v62, v48, v48
	v_fma_f32 v47, v77, v47, -v88
	v_fmac_f32_e32 v62, v47, v47
	v_fma_f32 v46, v78, v46, -v88
	v_fmac_f32_e32 v62, v46, v46
	v_fma_f32 v45, v79, v45, -v88
	v_fmac_f32_e32 v62, v45, v45
	v_fma_f32 v44, v80, v44, -v88
	v_fmac_f32_e32 v62, v44, v44
	v_fma_f32 v43, v81, v43, -v88
	v_fmac_f32_e32 v62, v43, v43
	v_fma_f32 v42, v82, v42, -v88
	v_fmac_f32_e32 v62, v42, v42
	v_fma_f32 v41, v83, v41, -v88
	v_fmac_f32_e32 v62, v41, v41
	v_fma_f32 v40, v84, v40, -v88
	v_fmac_f32_e32 v62, v40, v40
	v_fma_f32 v39, v85, v39, -v88
	v_fmac_f32_e32 v62, v39, v39
	v_fma_f32 v38, v86, v38, -v88
	v_pk_fma_f32 v[14:15], v[8:9], v[14:15], v[88:89] op_sel_hi:[1,1,0] neg_lo:[0,0,1] neg_hi:[0,0,1]
	v_fmac_f32_e32 v62, v38, v38
	v_pk_mul_f32 v[8:9], v[14:15], v[14:15]
	v_pk_fma_f32 v[12:13], v[16:17], v[12:13], v[88:89] op_sel_hi:[1,1,0] neg_lo:[0,0,1] neg_hi:[0,0,1]
	v_add_f32_e32 v9, v9, v62
	v_add_f32_e32 v62, v8, v9
	v_pk_mul_f32 v[8:9], v[12:13], v[12:13]
	v_pk_fma_f32 v[6:7], v[20:21], v[6:7], v[88:89] op_sel_hi:[1,1,0] neg_lo:[0,0,1] neg_hi:[0,0,1]
	v_add_f32_e32 v9, v9, v62
	v_add_f32_e32 v16, v8, v9
	v_pk_fma_f32 v[8:9], v[18:19], v[10:11], v[88:89] op_sel_hi:[1,1,0] neg_lo:[0,0,1] neg_hi:[0,0,1]
	v_add_u32_e32 v19, 0x1a000, v0
	v_pk_mul_f32 v[10:11], v[8:9], v[8:9]
	v_lshlrev_b32_e32 v78, 16, v33
	v_add_f32_e32 v11, v11, v16
	v_add_f32_e32 v16, v10, v11
	v_pk_mul_f32 v[10:11], v[6:7], v[6:7]
	v_lshlrev_b32_e32 v79, 16, v5
	v_add_f32_e32 v11, v11, v16
	v_add_f32_e32 v10, v10, v11
	ds_bpermute_b32 v11, v164, v10
	v_and_b32_e32 v5, 0xffff0000, v4
	v_and_b32_e32 v4, 0xffff0000, v32
	v_mov_b32_e32 v32, v5
	v_mov_b32_e32 v33, v101
	s_waitcnt lgkmcnt(0)
	v_add_f32_e32 v10, v10, v11
	ds_bpermute_b32 v11, v54, v10
	v_mov_b32_e32 v54, v96
	v_add_u32_e32 v81, 0, v132
	v_lshlrev_b32_e32 v73, 2, v162
	v_sub_u32_e32 v74, v81, v130
	s_waitcnt lgkmcnt(0)
	v_add_f32_e32 v10, v10, v11
	v_fmamk_f32 v10, v10, 0x3c000000, v209
	v_cmp_gt_f32_e32 vcc, s82, v10
	v_mul_f32_e32 v11, 0x4b800000, v10
	v_or_b32_e32 v71, 2, v130
	v_cndmask_b32_e32 v10, v10, v11, vcc
	v_rsq_f32_e32 v10, v10
	v_or_b32_e32 v70, 3, v130
	v_or_b32_e32 v72, 4, v130
	v_mul_f32_e32 v11, 0x45800000, v10
	v_cndmask_b32_e32 v18, v10, v11, vcc
	s_waitcnt vmcnt(0)
	v_mov_b64_e32 v[10:11], v[144:145]
	v_mov_b64_e32 v[16:17], v[218:219]
	v_mul_f32_e32 v20, v63, v18
	v_mul_f32_e32 v15, v15, v18
	v_mul_f32_e32 v14, v14, v18
	v_mul_f32_e32 v13, v13, v18
	v_mul_f32_e32 v12, v12, v18
	v_mul_f32_e32 v9, v9, v18
	v_mul_f32_e32 v8, v8, v18
	v_mul_f32_e32 v7, v7, v18
	v_mul_f32_e32 v6, v6, v18
	s_waitcnt vmcnt(0)
	v_fma_f32 v10, v10, v20, v16
	v_mul_f32_e32 v16, v61, v18
	v_fmac_f32_e32 v17, v11, v16
	v_add_u32_e32 v11, 0x1a110, v0
	v_cvt_pk_bf16_f32 v10, v10, v17
	ds_write_b16 v19, v10
	ds_write_b16_d16_hi v11, v10
	v_mov_b64_e32 v[10:11], v[146:147]
	v_mov_b64_e32 v[16:17], v[220:221]
	v_mul_f32_e32 v19, v60, v18
	s_waitcnt vmcnt(0)
	v_fma_f32 v10, v10, v19, v16
	v_mul_f32_e32 v16, v59, v18
	v_fmac_f32_e32 v17, v11, v16
	v_add_u32_e32 v11, 0x1a220, v0
	v_cvt_pk_bf16_f32 v10, v10, v17
	ds_write_b16 v11, v10
	v_add_u32_e32 v11, 0x1a330, v0
	ds_write_b16_d16_hi v11, v10
	v_mov_b64_e32 v[10:11], v[148:149]
	v_mov_b64_e32 v[16:17], v[222:223]
	v_mul_f32_e32 v19, v58, v18
	s_waitcnt vmcnt(0)
	v_fma_f32 v10, v10, v19, v16
	v_mul_f32_e32 v16, v57, v18
	v_fmac_f32_e32 v17, v11, v16
	v_add_u32_e32 v11, 0x1a440, v0
	v_cvt_pk_bf16_f32 v10, v10, v17
	ds_write_b16 v11, v10
	v_add_u32_e32 v11, 0x1a550, v0
	ds_write_b16_d16_hi v11, v10
	v_mov_b64_e32 v[10:11], v[150:151]
	v_mov_b64_e32 v[16:17], v[224:225]
	v_mul_f32_e32 v19, v56, v18
	v_mov_b32_e32 v56, v109
	v_mov_b32_e32 v57, v105
	v_pk_fma_f32 v[110:111], v[56:57], v[56:57], v[110:111]
	s_waitcnt vmcnt(0)
	v_fma_f32 v10, v10, v19, v16
	v_mul_f32_e32 v16, v55, v18
	v_fmac_f32_e32 v17, v11, v16
	v_add_u32_e32 v11, 0x1a660, v0
	v_cvt_pk_bf16_f32 v10, v10, v17
	ds_write_b16 v11, v10
	v_add_u32_e32 v11, 0x1a770, v0
	ds_write_b16_d16_hi v11, v10
	v_mov_b64_e32 v[10:11], v[152:153]
	v_mov_b64_e32 v[16:17], v[226:227]
	v_mul_f32_e32 v19, v53, v18
	v_mov_b32_e32 v55, v78
	v_pk_mul_f32 v[54:55], v[54:55], v[54:55]
	s_waitcnt vmcnt(0)
	v_fma_f32 v10, v10, v19, v16
	v_mul_f32_e32 v16, v52, v18
	v_fmac_f32_e32 v17, v11, v16
	v_add_u32_e32 v11, 0x1a880, v0
	v_cvt_pk_bf16_f32 v10, v10, v17
	ds_write_b16 v11, v10
	v_add_u32_e32 v11, 0x1a990, v0
	ds_write_b16_d16_hi v11, v10
	v_mov_b64_e32 v[10:11], v[154:155]
	v_mov_b64_e32 v[16:17], v[228:229]
	v_mul_f32_e32 v19, v51, v18
	s_waitcnt vmcnt(0)
	v_fma_f32 v10, v10, v19, v16
	v_mul_f32_e32 v16, v50, v18
	v_fmac_f32_e32 v17, v11, v16
	v_add_u32_e32 v11, 0x1aaa0, v0
	v_cvt_pk_bf16_f32 v10, v10, v17
	ds_write_b16 v11, v10
	v_add_u32_e32 v11, 0x1abb0, v0
	ds_write_b16_d16_hi v11, v10
	v_mov_b64_e32 v[10:11], v[156:157]
	v_mov_b64_e32 v[16:17], v[230:231]
	v_mul_f32_e32 v19, v49, v18
	s_waitcnt vmcnt(0)
; __device__ __forceinline__ unsigned cvt_pk_bf16(float lo, float hi) { unsigned r; asm volatile("v_cvt_pk_bf16_f32 %0, %1, %2" : "=v"(r) : "v"(lo), "v"(hi)); return r; }
; #define LAS __attribute__((address_space(3)))
; __device__ __forceinline__ void unpack8(const u32x4 w, float* f) { f[0] = bf_lo(w.x); f[1] = bf_hi(w.x); f[2] = bf_lo(w.y); f[3] = bf_hi(w.y); f[4] = bf_lo(w.z); f[5] = bf_hi(w.z); f[6] = bf_lo(w.w); f[7] = bf_hi(w.w); }
; __device__ __forceinline__ void p2_block(LAS unsigned char* lds, const bf16_t* __restrict__ PROJ, bf16_t* __restrict__ ATT, bf16_t* __restrict__ SGU, const float* __restrict__ qn, const float* __restrict__ kn, ...
;     ...
;         for (int j = 0; j < 32; j += 2) { const unsigned pk = cvt_pk_bf16(v[j] * rstd * gp[j] + bp[j], v[j + 1] * rstd * gp[j + 1] + bp[j + 1]);
;             *(LAS unsigned short*)(dst + j * VN_STRIDE) = (unsigned short)(pk & 0xffffu); *(LAS unsigned short*)(dst + (j + 1) * VN_STRIDE) = (unsigned short)(pk >> 16); }
;     }
;     __syncthreads();
; #pragma unroll
;     for (int c = 2; c < 4; ++c) { const bf16_t* qp = PROJ + ((size_t)b * pg8::SEQ + n * 128 + rbase + 16 * c + fr) * pg8::IN_W + hq * 64 + 8 * fq; qa[c] = *(const u32x4*)qp; qb[c] = *(const u32x4*)(qp + 32); }
;     const float sink = sinks[hq];
;     constexpr float LOG2E = 1.4426950408889634f;
; #pragma unroll
;     for (int c = 0; c < 4; ++c) {
;         const int i0 = rbase + 16 * c, irow = i0 + fr, pos = n * 128 + irow; const size_t grow = (size_t)b * pg8::SEQ + pos;
;         bf16x8 qf0, qf1;
;         {
;             float x1[8], x2[8]; unpack8(qa[c], x1); unpack8(qb[c], x2);
;             float ss = 0.f;
; #pragma unroll
;             for (int j = 0; j < 8; ++j) ss += x1[j] * x1[j] + x2[j] * x2[j];
;             ss += __shfl_xor(ss, 16); ss += __shfl_xor(ss, 32);
;             const float rinv = rsqrtf(ss * (1.0f / 64.0f) + pg8::EPS) * 0.125f;
;             const float* cp = COS + pos * 32 + 8 * fq; const float* sp = SIN + pos * 32 + 8 * fq;
;             float o1[8], o2[8];
; #pragma unroll
;             for (int j = 0; j < 8; ++j) { const float a1 = x1[j] * rinv * qn[8 * fq + j], a2 = x2[j] * rinv * qn[32 + 8 * fq + j], cc = cp[j], sn = sp[j]; o1[j] = a1 * cc - a2 * sn; o2[j] = a2 * cc + a1 * sn; }
	v_fma_f32 v10, v10, v19, v16
	v_mul_f32_e32 v16, v48, v18
	v_fmac_f32_e32 v17, v16, v11
	v_add_u32_e32 v11, 0x1acc0, v0
	v_cvt_pk_bf16_f32 v10, v10, v17
	ds_write_b16 v11, v10
	v_add_u32_e32 v11, 0x1add0, v0
	ds_write_b16_d16_hi v11, v10
	v_mov_b64_e32 v[10:11], v[158:159]
	v_mov_b64_e32 v[16:17], v[232:233]
	v_mul_f32_e32 v19, v47, v18
	s_waitcnt vmcnt(0)
	v_fma_f32 v10, v19, v10, v16
	v_mul_f32_e32 v16, v46, v18
	v_fmac_f32_e32 v17, v16, v11
	v_add_u32_e32 v11, 0x1aee0, v0
	v_cvt_pk_bf16_f32 v10, v10, v17
	ds_write_b16 v11, v10
	v_add_u32_e32 v11, 0x1aff0, v0
	ds_write_b16_d16_hi v11, v10
	v_mov_b64_e32 v[10:11], v[184:185]
	v_mov_b64_e32 v[16:17], v[234:235]
	v_mul_f32_e32 v19, v45, v18
	s_waitcnt vmcnt(0)
	v_fma_f32 v10, v19, v10, v16
	v_mul_f32_e32 v16, v44, v18
	v_fmac_f32_e32 v17, v16, v11
	v_add_u32_e32 v11, 0x1b100, v0
	v_cvt_pk_bf16_f32 v10, v10, v17
	ds_write_b16 v11, v10
	v_add_u32_e32 v11, 0x1b210, v0
	ds_write_b16_d16_hi v11, v10
	v_mov_b64_e32 v[10:11], v[186:187]
	v_mov_b64_e32 v[16:17], v[236:237]
	v_mul_f32_e32 v19, v43, v18
	v_or_b32_e32 v44, s17, v161
	s_waitcnt vmcnt(0)
	v_fma_f32 v10, v19, v10, v16
	v_mul_f32_e32 v16, v42, v18
	v_fmac_f32_e32 v17, v16, v11
	v_add_u32_e32 v11, 0x1b320, v0
	v_cvt_pk_bf16_f32 v10, v10, v17
	ds_write_b16 v11, v10
	v_add_u32_e32 v11, 0x1b430, v0
	ds_write_b16_d16_hi v11, v10
	v_mov_b64_e32 v[10:11], v[188:189]
	v_mov_b64_e32 v[16:17], v[238:239]
	v_mul_f32_e32 v19, v41, v18
	s_waitcnt vmcnt(0)
	v_fma_f32 v10, v19, v10, v16
	v_mul_f32_e32 v16, v40, v18
	v_fmac_f32_e32 v17, v16, v11
	v_add_u32_e32 v11, 0x1b540, v0
	v_cvt_pk_bf16_f32 v10, v10, v17
	ds_write_b16 v11, v10
	v_add_u32_e32 v11, 0x1b650, v0
	ds_write_b16_d16_hi v11, v10
	v_mov_b64_e32 v[10:11], v[190:191]
	v_mov_b64_e32 v[16:17], v[240:241]
	v_mul_f32_e32 v19, v39, v18
	s_waitcnt vmcnt(0)
	v_fma_f32 v10, v19, v10, v16
	v_mul_f32_e32 v16, v38, v18
	v_fmac_f32_e32 v17, v16, v11
	v_add_u32_e32 v11, 0x1b760, v0
	v_cvt_pk_bf16_f32 v10, v10, v17
	ds_write_b16 v11, v10
	v_add_u32_e32 v11, 0x1b870, v0
	ds_write_b16_d16_hi v11, v10
	v_mov_b64_e32 v[10:11], v[192:193]
	v_mov_b64_e32 v[16:17], v[242:243]
	s_waitcnt vmcnt(0)
	v_fma_f32 v10, v15, v10, v16
	v_fmac_f32_e32 v17, v14, v11
	v_add_u32_e32 v11, 0x1b980, v0
	v_cvt_pk_bf16_f32 v10, v10, v17
	ds_write_b16 v11, v10
	v_add_u32_e32 v11, 0x1ba90, v0
	ds_write_b16_d16_hi v11, v10
	v_mov_b64_e32 v[10:11], v[194:195]
	v_mov_b64_e32 v[14:15], v[244:245]
	s_waitcnt vmcnt(0)
	v_fma_f32 v10, v13, v10, v14
	v_fmac_f32_e32 v15, v12, v11
	v_add_u32_e32 v11, 0x1bba0, v0
	v_cvt_pk_bf16_f32 v10, v10, v15
	ds_write_b16 v11, v10
	v_add_u32_e32 v11, 0x1bcb0, v0
	ds_write_b16_d16_hi v11, v10
	v_mov_b64_e32 v[10:11], v[196:197]
	v_mov_b64_e32 v[12:13], v[200:201]
	v_lshlrev_b32_e32 v14, 7, v44
	v_mov_b32_e32 v15, v1
	v_or_b32_e32 v44, s48, v44
	s_waitcnt vmcnt(0)
	v_fma_f32 v9, v9, v10, v12
	v_fmac_f32_e32 v13, v8, v11
	v_cvt_pk_bf16_f32 v8, v9, v13
	v_add_u32_e32 v9, 0x1bdc0, v0
	ds_write_b16 v9, v8
	v_add_u32_e32 v9, 0x1bed0, v0
	ds_write_b16_d16_hi v9, v8
	v_mov_b64_e32 v[8:9], v[198:199]
	v_mov_b64_e32 v[10:11], v[202:203]
	s_waitcnt vmcnt(0)
	v_fma_f32 v7, v7, v8, v10
	v_fmac_f32_e32 v11, v6, v9
	v_cvt_pk_bf16_f32 v6, v7, v11
	v_add_u32_e32 v7, 0x1bfe0, v0
	v_add_u32_e32 v0, 0x1c0f0, v0
	ds_write_b16_d16_hi v0, v6
	v_or_b32_e32 v0, 32, v163
	ds_write_b16 v7, v6
	v_mad_u64_u32 v[6:7], s[28:29], v0, s83, v[134:135]
	v_mad_i32_i24 v7, s49, v212, v7
	v_or_b32_e32 v0, 48, v163
	s_waitcnt lgkmcnt(0)
	s_barrier
	global_load_dwordx4 v[38:41], v[6:7], off
	global_load_dwordx4 v[34:37], v[6:7], off offset:64
	v_mad_u64_u32 v[6:7], s[28:29], v0, s83, v[134:135]
	v_xor_b32_e32 v0, 16, v211
	v_cmp_lt_i32_e32 vcc, v0, v133
	s_lshl_b64 s[28:29], s[42:43], 2
	s_add_u32 s28, s63, s28
	v_cndmask_b32_e32 v0, v211, v0, vcc
	v_lshlrev_b32_e32 v76, 2, v0
	v_xor_b32_e32 v0, 32, v211
	v_cmp_lt_i32_e32 vcc, v0, v133
	v_mad_i32_i24 v7, s49, v212, v7
	s_addc_u32 s29, s78, s29
	v_cndmask_b32_e32 v0, v211, v0, vcc
	v_lshlrev_b32_e32 v77, 2, v0
	v_lshlrev_b32_e32 v0, 5, v162
	v_lshl_add_u64 v[46:47], s[44:45], 0, v[0:1]
	v_lshl_add_u64 v[48:49], s[46:47], 0, v[0:1]
	global_load_dwordx4 v[10:13], v[6:7], off
	s_nop 0
	global_load_dwordx4 v[6:9], v[6:7], off offset:64
	v_lshl_add_u64 v[50:51], v[46:47], 0, v[14:15]
	global_load_dword v75, v1, s[28:29]
	v_lshl_add_u64 v[52:53], v[48:49], 0, v[14:15]
	global_load_dwordx4 v[14:17], v0, s[38:39] offset:16
	global_load_dwordx4 v[18:21], v0, s[38:39]
	global_load_dwordx4 v[58:61], v0, s[38:39] offset:144
	global_load_dwordx4 v[62:65], v0, s[38:39] offset:128
	global_load_dwordx4 v[66:69], v[50:51], off offset:16
	global_load_dwordx4 v[82:85], v[50:51], off
	global_load_dwordx4 v[86:89], v[52:53], off offset:16
	global_load_dwordx4 v[90:93], v[52:53], off
	v_mov_b32_e32 v52, v97
	v_mov_b32_e32 v53, v79
	v_pk_fma_f32 v[98:99], v[52:53], v[52:53], v[54:55]
	v_mov_b32_e32 v54, v4
	v_mov_b32_e32 v55, v100
	v_pk_mul_f32 v[54:55], v[54:55], v[54:55]
	s_cmp_lg_u32 s27, 0
	v_pk_fma_f32 v[32:33], v[32:33], v[32:33], v[54:55]
	s_cselect_b64 s[50:51], -1, 0
	s_add_u32 s6, s60, s6
	s_addc_u32 s7, s61, s7
	v_lshl_add_u64 v[42:43], s[6:7], 0, v[130:131]
	s_lshr_b32 s29, s26, 4
	s_mov_b32 s6, s5
	s_mov_b32 s7, s5
	s_add_i32 s28, s29, 4
	s_waitcnt vmcnt(7)
	v_mov_b32_e32 v53, v14
	v_add_f32_e32 v14, v30, v31
	v_add_f32_e32 v14, v111, v14
	v_add_f32_e32 v14, v110, v14
	v_add_f32_e32 v14, v33, v14
	v_add_f32_e32 v14, v32, v14
	v_add_f32_e32 v14, v99, v14
	v_add_f32_e32 v14, v98, v14
	v_mov_b32_e32 v51, v16
	ds_bpermute_b32 v16, v76, v14
	s_waitcnt vmcnt(4)
	v_mov_b32_e32 v56, v62
	v_mov_b32_e32 v57, v18
	s_waitcnt vmcnt(2)
; __device__ __forceinline__ unsigned cvt_pk_bf16(float lo, float hi) { unsigned r; asm volatile("v_cvt_pk_bf16_f32 %0, %1, %2" : "=v"(r) : "v"(lo), "v"(hi)); return r; }
; __device__ __forceinline__ void p2_block(LAS unsigned char* lds, const bf16_t* __restrict__ PROJ, bf16_t* __restrict__ ATT, bf16_t* __restrict__ SGU, const float* __restrict__ qn, const float* __restrict__ kn, ...
;     ...
;             float x1[8], x2[8]; unpack8(qa[c], x1); unpack8(qb[c], x2);
;             float ss = 0.f;
; #pragma unroll
;             for (int j = 0; j < 8; ++j) ss += x1[j] * x1[j] + x2[j] * x2[j];
;             ss += __shfl_xor(ss, 16); ss += __shfl_xor(ss, 32);
;             const float rinv = rsqrtf(ss * (1.0f / 64.0f) + pg8::EPS) * 0.125f;
;             const float* cp = COS + pos * 32 + 8 * fq; const float* sp = SIN + pos * 32 + 8 * fq;
;             float o1[8], o2[8];
; #pragma unroll
;             for (int j = 0; j < 8; ++j) { const float a1 = x1[j] * rinv * qn[8 * fq + j], a2 = x2[j] * rinv * qn[32 + 8 * fq + j], cc = cp[j], sn = sp[j]; o1[j] = a1 * cc - a2 * sn; o2[j] = a2 * cc + a1 * sn; }
;             u32x4 w0, w1;
;             w0.x = cvt_pk_bf16(o1[0], o1[1]); w0.y = cvt_pk_bf16(o1[2], o1[3]); w0.z = cvt_pk_bf16(o1[4], o1[5]); w0.w = cvt_pk_bf16(o1[6], o1[7]);
;             w1.x = cvt_pk_bf16(o2[0], o2[1]); w1.y = cvt_pk_bf16(o2[2], o2[3]); w1.z = cvt_pk_bf16(o2[4], o2[5]); w1.w = cvt_pk_bf16(o2[6], o2[7]);
;             qf0 = __builtin_bit_cast(bf16x8, w0); qf1 = __builtin_bit_cast(bf16x8, w1);
;         }
;         const int t0 = (i0 >> 4) < 6 ? (i0 >> 4) : 6;
;         f32x4 sc_[10];
;         const LAS unsigned char* kbase = KS + (16 * t0 + fr) * KS_STRIDE + 16 * fq;
; #pragma unroll
;         for (int t = 0; t < 10; ++t) { const bf16x8 k0 = *(const LAS bf16x8*)(kbase + t * 16 * KS_STRIDE), k1 = *(const LAS bf16x8*)(kbase + t * 16 * KS_STRIDE + 64);
;             f32x4 z = (f32x4){0.f, 0.f, 0.f, 0.f}; z = MFMA16(k0, qf0, z); sc_[t] = MFMA16(k1, qf1, z); }
;     ...
;         const float bias = bsp[gg * 128 + irow];
;         const size_t grow = (size_t)b * pg8::SEQ + n * 128 + irow;
;         const bf16_t* up = PROJ + grow * pg8::IN_W + pg8::C_U + gg * 128 + 4 * fq; bf16_t* op = SGU + grow * 1024 + gg * 128 + 4 * fq;
; #pragma unroll
;         for (int dt = 0; dt < 8; ++dt) { const u32x2 uw = *(const u32x2*)(up + 16 * dt);
	v_mov_b32_e32 v114, v82
	s_waitcnt vmcnt(0)
	v_mov_b32_e32 v115, v90
	v_lshrrev_b32_e32 v183, 2, v204
	v_and_b32_e32 v183, 0x70, v183
	v_and_b32_e32 v184, 15, v204
	v_or_b32_e32 v183, v183, v184
	v_lshrrev_b32_e32 v184, 1, v204
	v_and_b32_e32 v184, 24, v184
	v_and_b32_e64 v185, s2, 3
	v_lshlrev_b32_e32 v185, 9, v185
	v_and_b32_e64 v186, s2, -4
	v_lshl_add_u32 v186, v186, 5, v183
	v_mul_u32_u24_e32 v187, 0x3c00, v186
	v_add3_u32 v187, v187, v185, v184
	v_lshlrev_b32_e32 v188, 1, v185
	v_lshl_add_u32 v188, v183, 2, v188
	global_load_dwordx2 v[218:219], v187, s[10:11] offset:3072
	global_load_dwordx2 v[220:221], v187, s[10:11] offset:3104
	global_load_dwordx2 v[222:223], v187, s[10:11] offset:3136
	global_load_dwordx2 v[224:225], v187, s[10:11] offset:3168
	global_load_dwordx2 v[226:227], v187, s[10:11] offset:3200
	global_load_dwordx2 v[228:229], v187, s[10:11] offset:3232
	global_load_dwordx2 v[230:231], v187, s[10:11] offset:3264
	global_load_dwordx2 v[232:233], v187, s[10:11] offset:3296
	global_load_dword v198, v188, s[22:23]
	global_load_dword v199, v188, s[22:23] offset:512
	global_load_dwordx2 v[234:235], v187, s[10:11] offset:3328
	global_load_dwordx2 v[236:237], v187, s[10:11] offset:3360
	global_load_dwordx2 v[238:239], v187, s[10:11] offset:3392
	global_load_dwordx2 v[240:241], v187, s[10:11] offset:3424
	global_load_dwordx2 v[242:243], v187, s[10:11] offset:3456
	global_load_dwordx2 v[244:245], v187, s[10:11] offset:3488
	global_load_dwordx2 v[200:201], v187, s[10:11] offset:3520
	global_load_dwordx2 v[202:203], v187, s[10:11] offset:3552
	s_waitcnt lgkmcnt(0)
	v_add_f32_e32 v14, v14, v16
	ds_bpermute_b32 v16, v77, v14
	v_mov_b32_e32 v32, v90
	v_mov_b32_e32 v33, v82
	v_mov_b32_e32 v18, v63
	v_mov_b32_e32 v82, v91
	s_waitcnt lgkmcnt(0)
	v_add_f32_e32 v14, v14, v16
	v_fmamk_f32 v14, v14, 0x3c800000, v209
	v_cmp_gt_f32_e32 vcc, s82, v14
	v_mul_f32_e32 v16, 0x4b800000, v14
	v_mov_b32_e32 v90, v83
	v_cndmask_b32_e32 v14, v14, v16, vcc
	v_rsq_f32_e32 v14, v14
	v_mov_b32_e32 v52, v58
	v_mov_b32_e32 v54, v64
	v_mov_b32_e32 v55, v20
	v_mul_f32_e32 v16, 0x45800000, v14
	v_cndmask_b32_e32 v14, v14, v16, vcc
	v_mul_f32_e32 v16, 0x3e000000, v14
	v_pk_mul_f32 v[30:31], v[16:17], v[112:113] op_sel_hi:[0,1]
	v_pk_mul_f32 v[30:31], v[56:57], v[30:31]
	v_pk_mul_f32 v[2:3], v[16:17], v[2:3] op_sel_hi:[0,1]
	v_pk_mul_f32 v[32:33], v[32:33], v[30:31]
	v_pk_mul_f32 v[30:31], v[114:115], v[30:31]
	v_pk_mul_f32 v[2:3], v[18:19], v[2:3]
	v_add_f32_e32 v45, v30, v31
	v_pk_mul_f32 v[30:31], v[82:83], v[2:3]
	v_pk_mul_f32 v[2:3], v[90:91], v[2:3]
	v_mov_b32_e32 v106, v84
	v_add_f32_e32 v58, v2, v3
	v_pk_mul_f32 v[2:3], v[16:17], v[104:105] op_sel_hi:[0,1]
	v_mov_b32_e32 v107, v92
	v_sub_f32_e32 v32, v33, v32
	v_sub_f32_e32 v33, v31, v30
	v_pk_mul_f32 v[2:3], v[54:55], v[2:3]
	v_mov_b32_e32 v30, v92
	v_mov_b32_e32 v31, v84
	v_pk_mul_f32 v[30:31], v[30:31], v[2:3]
	v_pk_mul_f32 v[2:3], v[106:107], v[2:3]
	v_mov_b32_e32 v20, v65
	v_add_f32_e32 v62, v2, v3
	v_pk_mul_f32 v[2:3], v[16:17], v[108:109] op_sel_hi:[0,1]
	v_pk_mul_f32 v[2:3], v[2:3], v[20:21]
	v_mov_b32_e32 v84, v93
	v_mov_b32_e32 v92, v85
	v_mov_b32_e32 v50, v60
	v_sub_f32_e32 v60, v31, v30
	v_pk_mul_f32 v[30:31], v[2:3], v[84:85]
	v_pk_mul_f32 v[2:3], v[2:3], v[92:93]
	v_mov_b32_e32 v102, v66
	v_add_f32_e32 v64, v2, v3
	v_pk_mul_f32 v[2:3], v[16:17], v[100:101] op_sel_hi:[0,1]
	v_mov_b32_e32 v103, v86
	v_sub_f32_e32 v63, v31, v30
	v_pk_mul_f32 v[2:3], v[2:3], v[52:53]
	v_mov_b32_e32 v30, v86
	v_mov_b32_e32 v31, v66
	v_pk_mul_f32 v[30:31], v[2:3], v[30:31]
	v_pk_mul_f32 v[2:3], v[2:3], v[102:103]
	v_mov_b32_e32 v14, v59
	v_add_f32_e32 v80, v2, v3
	v_pk_mul_f32 v[2:3], v[16:17], v[4:5] op_sel_hi:[0,1]
	v_pk_mul_f32 v[2:3], v[2:3], v[14:15]
	v_mov_b32_e32 v66, v87
	v_mov_b32_e32 v86, v67
	v_pk_mul_f32 v[4:5], v[2:3], v[66:67]
	v_pk_mul_f32 v[2:3], v[2:3], v[86:87]
	v_mov_b32_e32 v94, v68
	v_add_f32_e32 v66, v2, v3
	v_pk_mul_f32 v[2:3], v[16:17], v[78:79] op_sel_hi:[0,1]
	v_mov_b32_e32 v95, v88
	v_sub_f32_e32 v59, v5, v4
	v_pk_mul_f32 v[2:3], v[2:3], v[50:51]
	v_mov_b32_e32 v4, v88
	v_mov_b32_e32 v5, v68
	v_pk_mul_f32 v[4:5], v[2:3], v[4:5]
	v_pk_mul_f32 v[2:3], v[2:3], v[94:95]
	v_mov_b32_e32 v68, v89
	v_add_f32_e32 v78, v2, v3
	v_pk_mul_f32 v[2:3], v[16:17], v[96:97] op_sel_hi:[0,1]
	v_mov_b32_e32 v16, v61
	v_pk_mul_f32 v[2:3], v[2:3], v[16:17]
	v_sub_f32_e32 v67, v5, v4
	v_pk_mul_f32 v[4:5], v[2:3], v[68:69]
	v_mov_b32_e32 v88, v69
	v_sub_f32_e32 v65, v31, v30
	v_sub_f32_e32 v4, v5, v4
	v_pk_mul_f32 v[2:3], v[2:3], v[88:89]
	v_cvt_pk_bf16_f32 v30, v32, v33
	v_cvt_pk_bf16_f32 v31, v60, v63
	v_cvt_pk_bf16_f32 v32, v65, v59
	v_cvt_pk_bf16_f32 v33, v67, v4
	v_cvt_pk_bf16_f32 v58, v45, v58
	v_mad_u32_u24 v45, v161, s59, v81
	v_add_f32_e32 v2, v2, v3
	v_cvt_pk_bf16_f32 v59, v62, v64
	v_cvt_pk_bf16_f32 v60, v80, v66
	v_cvt_pk_bf16_f32 v61, v78, v2
	ds_read_b128 v[62:65], v45
	ds_read_b128 v[66:69], v45 offset:64
	s_waitcnt lgkmcnt(1)
	v_mfma_f32_16x16x32_bf16 v[62:65], v[62:65], v[30:33], 0
	v_mov_b64_e32 v[2:3], s[4:5]
	v_mov_b64_e32 v[4:5], s[6:7]
	s_or_b32 s4, s29, 2
	s_waitcnt lgkmcnt(0)
	v_mfma_f32_16x16x32_bf16 v[62:65], v[66:69], v[58:61], v[62:65]
	ds_read_b128 v[66:69], v45 offset:2304
	ds_read_b128 v[82:85], v45 offset:2368
	s_or_b32 s6, s26, s27
	s_waitcnt lgkmcnt(1)
	v_mfma_f32_16x16x32_bf16 v[66:69], v[66:69], v[30:33], 0
	s_waitcnt lgkmcnt(0)
	v_mfma_f32_16x16x32_bf16 v[66:69], v[82:85], v[58:61], v[66:69]
	ds_read_b128 v[82:85], v45 offset:4608
	ds_read_b128 v[86:89], v45 offset:4672
	s_waitcnt lgkmcnt(1)
	v_mfma_f32_16x16x32_bf16 v[82:85], v[82:85], v[30:33], 0
	s_waitcnt lgkmcnt(0)
; #define LAS __attribute__((address_space(3)))
; #define MFMA16(a, b, c) __builtin_amdgcn_mfma_f32_16x16x32_bf16((a), (b), (c), 0, 0, 0)
; __device__ __forceinline__ void p2_block(LAS unsigned char* lds, const bf16_t* __restrict__ PROJ, bf16_t* __restrict__ ATT, bf16_t* __restrict__ SGU, const float* __restrict__ qn, const float* __restrict__ kn, ...
;     ...
;         const int t0 = (i0 >> 4) < 6 ? (i0 >> 4) : 6;
;         f32x4 sc_[10];
;         const LAS unsigned char* kbase = KS + (16 * t0 + fr) * KS_STRIDE + 16 * fq;
; #pragma unroll
;         for (int t = 0; t < 10; ++t) { const bf16x8 k0 = *(const LAS bf16x8*)(kbase + t * 16 * KS_STRIDE), k1 = *(const LAS bf16x8*)(kbase + t * 16 * KS_STRIDE + 64);
;             f32x4 z = (f32x4){0.f, 0.f, 0.f, 0.f}; z = MFMA16(k0, qf0, z); sc_[t] = MFMA16(k1, qf1, z); }
;         float mx = -1e30f;
; #pragma unroll
;         for (int t = 0; t < 10; ++t)
; #pragma unroll
;             for (int e = 0; e < 4; ++e) { const int kx = 16 * (t0 + t) + 4 * fq + e, d = kx - irow; const bool ok = (d >= 1) && (d <= 128) && (n > 0 || kx >= 128);
;                 const float v = ok ? sc_[t][e] : -1e30f; sc_[t][e] = v; mx = fmaxf(mx, v); }
	v_mfma_f32_16x16x32_bf16 v[84:87], v[86:89], v[58:61], v[82:85]
	ds_read_b128 v[88:91], v45 offset:6912
	ds_read_b128 v[92:95], v45 offset:6976
	s_nop 3
	v_or_b32_e32 v82, s26, v73
	s_waitcnt lgkmcnt(1)
	v_mfma_f32_16x16x32_bf16 v[88:91], v[88:91], v[30:33], 0
	v_or_b32_e32 v83, 48, v82
	s_waitcnt lgkmcnt(0)
	v_mfma_f32_16x16x32_bf16 v[88:91], v[92:95], v[58:61], v[88:91]
	ds_read_b128 v[92:95], v45 offset:9216
	ds_read_b128 v[96:99], v45 offset:9280
	s_waitcnt lgkmcnt(1)
	v_mfma_f32_16x16x32_bf16 v[92:95], v[92:95], v[30:33], 0
	s_waitcnt lgkmcnt(0)
	v_mfma_f32_16x16x32_bf16 v[92:95], v[96:99], v[58:61], v[92:95]
	ds_read_b128 v[96:99], v45 offset:11520
	ds_read_b128 v[100:103], v45 offset:11584
	s_waitcnt lgkmcnt(1)
	v_mfma_f32_16x16x32_bf16 v[96:99], v[96:99], v[30:33], 0
	s_waitcnt lgkmcnt(0)
	v_mfma_f32_16x16x32_bf16 v[96:99], v[100:103], v[58:61], v[96:99]
	ds_read_b128 v[100:103], v45 offset:13824
	ds_read_b128 v[104:107], v45 offset:13888
	s_waitcnt lgkmcnt(1)
	v_mfma_f32_16x16x32_bf16 v[100:103], v[100:103], v[30:33], 0
	s_waitcnt lgkmcnt(0)
	v_mfma_f32_16x16x32_bf16 v[100:103], v[104:107], v[58:61], v[100:103]
	ds_read_b128 v[104:107], v45 offset:16128
	ds_read_b128 v[108:111], v45 offset:16192
	s_waitcnt lgkmcnt(1)
	v_mfma_f32_16x16x32_bf16 v[104:107], v[104:107], v[30:33], 0
	s_waitcnt lgkmcnt(0)
	v_mfma_f32_16x16x32_bf16 v[104:107], v[108:111], v[58:61], v[104:107]
	ds_read_b128 v[108:111], v45 offset:18432
	ds_read_b128 v[112:115], v45 offset:18496
	s_waitcnt lgkmcnt(1)
	v_mfma_f32_16x16x32_bf16 v[108:111], v[108:111], v[30:33], 0
	s_waitcnt lgkmcnt(0)
	v_mfma_f32_16x16x32_bf16 v[108:111], v[112:115], v[58:61], v[108:111]
	ds_read_b128 v[112:115], v45 offset:20736
	ds_read_b128 v[116:119], v45 offset:20800
	v_add_u32_e32 v45, -2, v161
	s_waitcnt lgkmcnt(1)
	v_mfma_f32_16x16x32_bf16 v[30:33], v[112:115], v[30:33], 0
	s_waitcnt lgkmcnt(0)
	v_mfma_f32_16x16x32_bf16 v[58:61], v[116:119], v[58:61], v[30:33]
	s_nop 5
	v_sub_u32_e32 v32, v137, v73
	v_cmp_lt_u32_e32 vcc, s79, v32
	s_and_b64 s[40:41], s[50:51], vcc
	v_sub_u32_e32 v31, v73, v137
	v_cndmask_b32_e64 v30, v213, v62, s[40:41]
	v_cmp_gt_u32_e32 vcc, s84, v31
	v_sub_u32_e32 v62, v45, v82
	s_and_b64 s[42:43], s[50:51], vcc
	v_cmp_lt_u32_e32 vcc, s79, v62
	v_cndmask_b32_e64 v31, v213, v63, s[42:43]
	s_and_b64 vcc, s[50:51], vcc
	v_add_u32_e32 v63, -3, v161
	v_cndmask_b32_e32 v62, v213, v64, vcc
	v_sub_u32_e32 v64, v63, v82
	v_cmp_lt_u32_e32 vcc, s79, v64
	s_and_b64 vcc, s[50:51], vcc
	v_max3_f32 v33, v30, s52, v31
	v_cndmask_b32_e32 v64, v213, v65, vcc
	v_sub_u32_e32 v65, v161, v82
	v_add_u32_e32 v78, -16, v65
	v_cmp_lt_u32_e32 vcc, s79, v78
	s_and_b64 vcc, s[50:51], vcc
	v_subrev_u32_e32 v78, 17, v65
	v_cndmask_b32_e32 v66, v213, v66, vcc
	v_cmp_lt_u32_e32 vcc, s79, v78
	s_and_b64 vcc, s[50:51], vcc
	v_subrev_u32_e32 v78, 18, v65
	v_cndmask_b32_e32 v67, v213, v67, vcc
	v_cmp_lt_u32_e32 vcc, s79, v78
	s_and_b64 vcc, s[50:51], vcc
	v_subrev_u32_e32 v65, 19, v65
	v_cndmask_b32_e32 v68, v213, v68, vcc
	v_cmp_lt_u32_e32 vcc, s79, v65
	s_and_b64 vcc, s[50:51], vcc
	v_max3_f32 v33, v33, v62, v64
	v_cndmask_b32_e32 v65, v213, v69, vcc
	v_lshl_or_b32 v69, s4, 4, v73
	v_sub_u32_e32 v78, v161, v69
	v_cmp_lt_u32_e32 vcc, s79, v78
	s_and_b64 vcc, s[50:51], vcc
	v_sub_u32_e32 v79, v69, v161
	v_cndmask_b32_e32 v78, v213, v84, vcc
	v_cmp_gt_u32_e32 vcc, s84, v79
	s_and_b64 vcc, s[50:51], vcc
	v_sub_u32_e32 v80, v45, v69
	v_cndmask_b32_e32 v79, v213, v85, vcc
	v_cmp_lt_u32_e32 vcc, s79, v80
	s_and_b64 vcc, s[50:51], vcc
	v_sub_u32_e32 v69, v63, v69
	v_cndmask_b32_e32 v80, v213, v86, vcc
	v_cmp_lt_u32_e32 vcc, s79, v69
	s_and_b64 vcc, s[50:51], vcc
	v_sub_u32_e32 v84, v161, v83
	v_cndmask_b32_e32 v69, v213, v87, vcc
	v_cmp_lt_u32_e32 vcc, s79, v84
	v_or_b32_e32 v84, 49, v82
	s_and_b64 vcc, s[50:51], vcc
	v_sub_u32_e32 v85, v161, v84
	v_cndmask_b32_e32 v112, v213, v88, vcc
	v_cmp_lt_u32_e32 vcc, s79, v85
	v_or_b32_e32 v85, 50, v82
	s_and_b64 vcc, s[50:51], vcc
	v_sub_u32_e32 v86, v161, v85
	v_cndmask_b32_e32 v113, v213, v89, vcc
	v_cmp_lt_u32_e32 vcc, s79, v86
	v_or_b32_e32 v87, 51, v82
	s_and_b64 vcc, s[50:51], vcc
	v_sub_u32_e32 v86, v161, v87
	v_cndmask_b32_e32 v114, v213, v90, vcc
	v_cmp_lt_u32_e32 vcc, s79, v86
	s_and_b64 vcc, s[50:51], vcc
	v_lshl_or_b32 v86, s28, 4, v73
	v_sub_u32_e32 v88, v161, v86
	s_cmp_lg_u32 s6, 0
	v_cndmask_b32_e32 v115, v213, v91, vcc
	v_cmp_lt_u32_e32 vcc, s79, v88
	s_cselect_b64 s[6:7], -1, 0
	s_and_b64 vcc, vcc, s[6:7]
	v_sub_u32_e32 v88, v86, v161
	v_cndmask_b32_e32 v116, v213, v92, vcc
	v_cmp_gt_u32_e32 vcc, s84, v88
	s_and_b64 vcc, vcc, s[6:7]
	v_sub_u32_e32 v88, v45, v86
	v_cndmask_b32_e32 v117, v213, v93, vcc
	v_cmp_lt_u32_e32 vcc, s79, v88
	s_and_b64 vcc, vcc, s[6:7]
	v_sub_u32_e32 v86, v63, v86
	s_add_i32 s27, s26, 0x50
	v_cndmask_b32_e32 v118, v213, v94, vcc
	v_cmp_lt_u32_e32 vcc, s79, v86
	v_or_b32_e32 v86, s27, v73
	s_and_b64 vcc, vcc, s[6:7]
	v_sub_u32_e32 v88, v161, v86
	v_cndmask_b32_e32 v119, v213, v95, vcc
	v_cmp_lt_u32_e32 vcc, s79, v88
	s_and_b64 vcc, vcc, s[6:7]
	v_sub_u32_e32 v88, v86, v161
	v_cndmask_b32_e32 v120, v213, v96, vcc
	v_cmp_gt_u32_e32 vcc, s84, v88
	v_or_b32_e32 v89, 2, v86
	s_and_b64 vcc, vcc, s[6:7]
	v_sub_u32_e32 v88, v161, v89
	v_cndmask_b32_e32 v97, v213, v97, vcc
	v_cmp_lt_u32_e32 vcc, s79, v88
	v_or_b32_e32 v90, 3, v86
	s_and_b64 vcc, vcc, s[6:7]
	v_sub_u32_e32 v88, v161, v90
	s_add_i32 s27, s29, 6
	v_cndmask_b32_e32 v98, v213, v98, vcc
	v_cmp_lt_u32_e32 vcc, s79, v88
	v_lshl_or_b32 v88, s27, 4, v73
	s_and_b64 vcc, vcc, s[6:7]
	v_sub_u32_e32 v91, v161, v88
	v_cndmask_b32_e32 v99, v213, v99, vcc
	v_cmp_lt_u32_e32 vcc, s79, v91
; __device__ __forceinline__ void p2_block(LAS unsigned char* lds, const bf16_t* __restrict__ PROJ, bf16_t* __restrict__ ATT, bf16_t* __restrict__ SGU, const float* __restrict__ qn, const float* __restrict__ kn, ...
;     ...
;             for (int e = 0; e < 4; ++e) { const int kx = 16 * (t0 + t) + 4 * fq + e, d = kx - irow; const bool ok = (d >= 1) && (d <= 128) && (n > 0 || kx >= 128);
;                 const float v = ok ? sc_[t][e] : -1e30f; sc_[t][e] = v; mx = fmaxf(mx, v); }
;         mx = fmaxf(mx, __shfl_xor(mx, 16)); mx = fmaxf(mx, __shfl_xor(mx, 32)); mx = fmaxf(mx, sink);
;         float sum = 0.f;
; #pragma unroll
;         for (int t = 0; t < 10; ++t)
; #pragma unroll
;             for (int e = 0; e < 4; ++e) { const float p = __builtin_amdgcn_exp2f((sc_[t][e] - mx) * LOG2E); sc_[t][e] = p; sum += p; }
	s_and_b64 vcc, vcc, s[6:7]
	v_sub_u32_e32 v91, v88, v161
	v_cndmask_b32_e32 v100, v213, v100, vcc
	v_cmp_gt_u32_e32 vcc, s84, v91
	s_and_b64 vcc, vcc, s[6:7]
	v_sub_u32_e32 v91, v45, v88
	v_cndmask_b32_e32 v101, v213, v101, vcc
	v_cmp_lt_u32_e32 vcc, s79, v91
	s_and_b64 vcc, vcc, s[6:7]
	v_sub_u32_e32 v88, v63, v88
	s_add_i32 s44, s26, 0x70
	v_cndmask_b32_e32 v102, v213, v102, vcc
	v_cmp_lt_u32_e32 vcc, s79, v88
	v_or_b32_e32 v88, s44, v73
	s_and_b64 vcc, vcc, s[6:7]
	v_sub_u32_e32 v91, v161, v88
	v_cndmask_b32_e32 v103, v213, v103, vcc
	v_cmp_lt_u32_e32 vcc, s79, v91
	s_and_b64 vcc, vcc, s[6:7]
	v_sub_u32_e32 v91, v88, v161
	v_cndmask_b32_e32 v104, v213, v104, vcc
	v_cmp_gt_u32_e32 vcc, s84, v91
	v_or_b32_e32 v91, 2, v88
	v_max3_f32 v33, v33, v66, v67
	s_and_b64 vcc, vcc, s[6:7]
	v_sub_u32_e32 v92, v161, v91
	v_max3_f32 v33, v33, v68, v65
	v_cndmask_b32_e32 v105, v213, v105, vcc
	v_cmp_lt_u32_e32 vcc, s79, v92
	v_or_b32_e32 v92, 3, v88
	v_max3_f32 v33, v33, v78, v79
	s_and_b64 vcc, vcc, s[6:7]
	v_sub_u32_e32 v93, v161, v92
	s_or_b32 s29, s29, 8
	v_max3_f32 v33, v33, v80, v69
	v_cndmask_b32_e32 v106, v213, v106, vcc
	v_cmp_lt_u32_e32 vcc, s79, v93
	v_lshl_or_b32 v93, s29, 4, v73
	v_max3_f32 v33, v33, v112, v113
	s_and_b64 vcc, vcc, s[6:7]
	v_sub_u32_e32 v94, v161, v93
	v_max3_f32 v33, v33, v114, v115
	v_cndmask_b32_e32 v107, v213, v107, vcc
	v_cmp_lt_u32_e32 vcc, s79, v94
	v_sub_u32_e32 v94, v93, v161
	v_max3_f32 v33, v33, v116, v117
	v_cndmask_b32_e32 v108, v213, v108, vcc
	v_cmp_gt_u32_e32 vcc, s84, v94
	v_sub_u32_e32 v45, v45, v93
	v_max3_f32 v33, v33, v118, v119
	v_cndmask_b32_e32 v109, v213, v109, vcc
	v_cmp_lt_u32_e32 vcc, s79, v45
	v_sub_u32_e32 v63, v63, v93
	v_or_b32_e32 v93, 0x90, v82
	v_max3_f32 v33, v33, v120, v97
	v_cndmask_b32_e32 v45, v213, v110, vcc
	v_cmp_lt_u32_e32 vcc, s79, v63
	v_sub_u32_e32 v94, v161, v93
	v_max3_f32 v33, v33, v98, v99
	v_cndmask_b32_e32 v63, v213, v111, vcc
	v_cmp_lt_u32_e32 vcc, s79, v94
	v_or_b32_e32 v94, 0x91, v82
	v_max3_f32 v33, v33, v100, v101
	v_sub_u32_e32 v95, v161, v94
	v_max3_f32 v33, v33, v102, v103
	v_cndmask_b32_e32 v58, v213, v58, vcc
	v_cmp_lt_u32_e32 vcc, s79, v95
	v_or_b32_e32 v95, 0x92, v82
	v_max3_f32 v33, v33, v104, v105
	v_sub_u32_e32 v96, v161, v95
	v_max3_f32 v33, v33, v106, v107
	v_cndmask_b32_e32 v59, v213, v59, vcc
	v_cmp_lt_u32_e32 vcc, s79, v96
	v_or_b32_e32 v96, 0x93, v82
	v_max3_f32 v33, v33, v108, v109
	v_sub_u32_e32 v110, v161, v96
	v_max3_f32 v33, v33, v45, v63
	v_cndmask_b32_e32 v60, v213, v60, vcc
	v_cmp_lt_u32_e32 vcc, s79, v110
	v_max3_f32 v33, v33, v58, v59
	s_nop 0
	v_cndmask_b32_e32 v61, v213, v61, vcc
	v_max3_f32 v33, v33, v60, v61
	ds_bpermute_b32 v110, v76, v33
	s_waitcnt lgkmcnt(0)
	v_max_f32_e32 v110, v110, v110
	v_max_f32_e32 v33, v33, v110
	ds_bpermute_b32 v110, v77, v33
	s_waitcnt lgkmcnt(0)
	v_max3_f32 v33, v33, v110, v75
	v_sub_f32_e32 v30, v30, v33
	v_mul_f32_e32 v30, 0x3fb8aa3b, v30
	v_sub_f32_e32 v31, v31, v33
	v_exp_f32_e32 v30, v30
	v_mul_f32_e32 v31, 0x3fb8aa3b, v31
	v_sub_f32_e32 v62, v62, v33
	v_exp_f32_e32 v31, v31
	v_mul_f32_e32 v62, 0x3fb8aa3b, v62
	v_sub_f32_e32 v64, v64, v33
	v_exp_f32_e32 v62, v62
	v_mul_f32_e32 v64, 0x3fb8aa3b, v64
	v_sub_f32_e32 v66, v66, v33
	v_exp_f32_e32 v64, v64
	v_mul_f32_e32 v66, 0x3fb8aa3b, v66
	v_sub_f32_e32 v67, v67, v33
	v_add_f32_e32 v110, 0, v30
	v_exp_f32_e32 v66, v66
	v_mul_f32_e32 v67, 0x3fb8aa3b, v67
	v_sub_f32_e32 v68, v68, v33
	v_add_f32_e32 v110, v31, v110
	v_exp_f32_e32 v67, v67
	v_mul_f32_e32 v68, 0x3fb8aa3b, v68
	v_sub_f32_e32 v65, v65, v33
	v_add_f32_e32 v110, v62, v110
	v_exp_f32_e32 v68, v68
	v_mul_f32_e32 v65, 0x3fb8aa3b, v65
	v_sub_f32_e32 v78, v78, v33
	v_add_f32_e32 v110, v64, v110
	v_exp_f32_e32 v65, v65
	v_mul_f32_e32 v78, 0x3fb8aa3b, v78
	v_add_f32_e32 v110, v66, v110
	v_exp_f32_e32 v111, v78
	v_add_f32_e32 v110, v67, v110
	v_add_f32_e32 v110, v68, v110
	v_sub_f32_e32 v79, v79, v33
	v_add_f32_e32 v110, v65, v110
	v_mul_f32_e32 v79, 0x3fb8aa3b, v79
	v_add_f32_e32 v78, v111, v110
	v_exp_f32_e32 v110, v79
	v_sub_f32_e32 v79, v80, v33
	v_mul_f32_e32 v79, 0x3fb8aa3b, v79
	v_sub_f32_e32 v69, v69, v33
	v_exp_f32_e32 v121, v79
	v_mul_f32_e32 v69, 0x3fb8aa3b, v69
	v_exp_f32_e32 v122, v69
	v_add_f32_e32 v78, v110, v78
	v_add_f32_e32 v78, v121, v78
	v_sub_f32_e32 v58, v58, v33
	v_add_f32_e32 v69, v122, v78
	v_sub_f32_e32 v78, v112, v33
	v_mul_f32_e32 v78, 0x3fb8aa3b, v78
	v_exp_f32_e32 v112, v78
	v_sub_f32_e32 v78, v113, v33
	v_mul_f32_e32 v78, 0x3fb8aa3b, v78
	v_exp_f32_e32 v113, v78
	v_sub_f32_e32 v78, v114, v33
	v_mul_f32_e32 v78, 0x3fb8aa3b, v78
	v_exp_f32_e32 v114, v78
	v_sub_f32_e32 v78, v115, v33
	v_mul_f32_e32 v78, 0x3fb8aa3b, v78
	v_exp_f32_e32 v115, v78
	v_sub_f32_e32 v78, v116, v33
	v_mul_f32_e32 v78, 0x3fb8aa3b, v78
	v_exp_f32_e32 v116, v78
	v_sub_f32_e32 v78, v117, v33
	v_mul_f32_e32 v78, 0x3fb8aa3b, v78
	v_exp_f32_e32 v117, v78
	v_sub_f32_e32 v78, v118, v33
	v_mul_f32_e32 v78, 0x3fb8aa3b, v78
	v_exp_f32_e32 v118, v78
	v_sub_f32_e32 v78, v119, v33
	v_mul_f32_e32 v78, 0x3fb8aa3b, v78
	v_exp_f32_e32 v119, v78
	v_sub_f32_e32 v78, v120, v33
	v_mul_f32_e32 v78, 0x3fb8aa3b, v78
	v_exp_f32_e32 v120, v78
	v_sub_f32_e32 v78, v97, v33
	v_mul_f32_e32 v78, 0x3fb8aa3b, v78
	v_exp_f32_e32 v97, v78
	v_sub_f32_e32 v78, v98, v33
	v_mul_f32_e32 v78, 0x3fb8aa3b, v78
	v_exp_f32_e32 v123, v78
	v_sub_f32_e32 v78, v99, v33
	v_mul_f32_e32 v78, 0x3fb8aa3b, v78
	v_exp_f32_e32 v124, v78
	v_sub_f32_e32 v78, v100, v33
	v_mul_f32_e32 v78, 0x3fb8aa3b, v78
	v_exp_f32_e32 v125, v78
	v_sub_f32_e32 v78, v101, v33
	v_add_f32_e32 v69, v112, v69
	v_mul_f32_e32 v78, 0x3fb8aa3b, v78
	v_add_f32_e32 v69, v113, v69
; __device__ __forceinline__ unsigned cvt_pk_bf16(float lo, float hi) { unsigned r; asm volatile("v_cvt_pk_bf16_f32 %0, %1, %2" : "=v"(r) : "v"(lo), "v"(hi)); return r; }
; #define LAS __attribute__((address_space(3)))
; #define MFMA16(a, b, c) __builtin_amdgcn_mfma_f32_16x16x32_bf16((a), (b), (c), 0, 0, 0)
; __device__ __forceinline__ void p2_block(LAS unsigned char* lds, const bf16_t* __restrict__ PROJ, bf16_t* __restrict__ ATT, bf16_t* __restrict__ SGU, const float* __restrict__ qn, const float* __restrict__ kn, ...
;     ...
;             for (int e = 0; e < 4; ++e) { const float p = __builtin_amdgcn_exp2f((sc_[t][e] - mx) * LOG2E); sc_[t][e] = p; sum += p; }
;         sum += __shfl_xor(sum, 16); sum += __shfl_xor(sum, 32);
;         const float inv = 1.0f / (sum + __builtin_amdgcn_exp2f((sink - mx) * LOG2E));
;         f32x4 o[4];
; #pragma unroll
;         for (int dt = 0; dt < 4; ++dt) o[dt] = (f32x4){0.f, 0.f, 0.f, 0.f};
; #pragma unroll
;         for (int j = 0; j < 5; ++j) {
;             u32x4 pw; pw.x = cvt_pk_bf16(sc_[2 * j][0], sc_[2 * j][1]); pw.y = cvt_pk_bf16(sc_[2 * j][2], sc_[2 * j][3]); pw.z = cvt_pk_bf16(sc_[2 * j + 1][0], sc_[2 * j + 1][1]); pw.w = cvt_pk_bf16(sc_[2 * j + 1][2], sc_[2 * j + 1][3]);
;             const bf16x8 pf = __builtin_bit_cast(bf16x8, pw);
; #pragma unroll
;             for (int dt = 0; dt < 4; ++dt) { const LAS unsigned char* vb = VT + (16 * dt + fr) * VT_STRIDE + (16 * (t0 + 2 * j) + 4 * fq) * 2;
;                 const u32x2 va = *(const LAS u32x2*)vb, vc = *(const LAS u32x2*)(vb + 32); u32x4 vw; vw.x = va.x; vw.y = va.y; vw.z = vc.x; vw.w = vc.y;
;                 o[dt] = MFMA16(__builtin_bit_cast(bf16x8, vw), pf, o[dt]); }
;         }
	v_exp_f32_e32 v126, v78
	v_sub_f32_e32 v78, v102, v33
	v_add_f32_e32 v69, v114, v69
	v_mul_f32_e32 v78, 0x3fb8aa3b, v78
	v_add_f32_e32 v69, v115, v69
	v_exp_f32_e32 v127, v78
	v_sub_f32_e32 v78, v103, v33
	v_add_f32_e32 v69, v116, v69
	v_mul_f32_e32 v78, 0x3fb8aa3b, v78
	v_add_f32_e32 v69, v117, v69
	v_exp_f32_e32 v128, v78
	v_sub_f32_e32 v78, v104, v33
	v_add_f32_e32 v69, v118, v69
	v_mul_f32_e32 v78, 0x3fb8aa3b, v78
	v_add_f32_e32 v69, v119, v69
	v_exp_f32_e32 v129, v78
	v_sub_f32_e32 v78, v105, v33
	v_add_f32_e32 v69, v120, v69
	v_mul_f32_e32 v78, 0x3fb8aa3b, v78
	v_add_f32_e32 v69, v97, v69
	v_exp_f32_e32 v131, v78
	v_sub_f32_e32 v78, v106, v33
	v_add_f32_e32 v69, v123, v69
	v_mul_f32_e32 v78, 0x3fb8aa3b, v78
	v_add_f32_e32 v69, v124, v69
	v_exp_f32_e32 v133, v78
	v_sub_f32_e32 v78, v107, v33
	v_add_f32_e32 v69, v125, v69
	v_mul_f32_e32 v78, 0x3fb8aa3b, v78
	v_add_f32_e32 v69, v126, v69
	v_exp_f32_e32 v134, v78
	v_sub_f32_e32 v78, v108, v33
	v_add_f32_e32 v69, v127, v69
	v_mul_f32_e32 v78, 0x3fb8aa3b, v78
	v_add_f32_e32 v69, v128, v69
	v_exp_f32_e32 v135, v78
	v_sub_f32_e32 v78, v109, v33
	v_add_f32_e32 v69, v129, v69
	v_mul_f32_e32 v78, 0x3fb8aa3b, v78
	v_sub_f32_e32 v45, v45, v33
	v_mul_f32_e32 v58, 0x3fb8aa3b, v58
	v_add_f32_e32 v69, v131, v69
	v_exp_f32_e32 v136, v78
	v_mul_f32_e32 v45, 0x3fb8aa3b, v45
	v_sub_f32_e32 v63, v63, v33
	v_exp_f32_e32 v140, v58
	v_sub_f32_e32 v58, v59, v33
	v_add_f32_e32 v69, v133, v69
	v_exp_f32_e32 v138, v45
	v_mul_f32_e32 v63, 0x3fb8aa3b, v63
	v_mul_f32_e32 v58, 0x3fb8aa3b, v58
	v_add_f32_e32 v69, v134, v69
	v_exp_f32_e32 v139, v63
	v_exp_f32_e32 v141, v58
	v_sub_f32_e32 v58, v60, v33
	v_add_f32_e32 v69, v135, v69
	v_mul_f32_e32 v58, 0x3fb8aa3b, v58
	v_add_f32_e32 v69, v136, v69
	v_exp_f32_e32 v142, v58
	v_sub_f32_e32 v58, v61, v33
	v_add_f32_e32 v45, v138, v69
	v_mul_f32_e32 v58, 0x3fb8aa3b, v58
	v_add_f32_e32 v45, v139, v45
	v_exp_f32_e32 v143, v58
	v_add_f32_e32 v45, v140, v45
	v_add_f32_e32 v45, v141, v45
	v_add_f32_e32 v45, v142, v45
	v_add_f32_e32 v45, v143, v45
	ds_bpermute_b32 v58, v76, v45
	v_mad_u32_u24 v80, v137, s81, v214
	v_mad_u32_u24 v79, v137, s81, v215
	v_mad_u32_u24 v78, v137, s81, v216
	v_sub_f32_e32 v33, v75, v33
	s_waitcnt lgkmcnt(0)
	v_add_f32_e32 v45, v45, v58
	ds_bpermute_b32 v58, v77, v45
	v_mul_f32_e32 v33, 0x3fb8aa3b, v33
	v_exp_f32_e32 v33, v33
	s_waitcnt lgkmcnt(0)
	v_add_f32_e32 v45, v45, v58
	v_cvt_pk_bf16_f32 v58, v30, v31
	v_lshl_add_u32 v30, s26, 1, v74
	v_mad_u32_u24 v31, v137, s81, v30
	v_add_u32_e32 v31, 0x9000, v31
	v_cvt_pk_bf16_f32 v59, v62, v64
	v_cvt_pk_bf16_f32 v60, v66, v67
	v_cvt_pk_bf16_f32 v61, v68, v65
	ds_read2_b64 v[62:65], v31 offset1:4
	v_add_u32_e32 v31, v30, v80
	v_add_u32_e32 v31, 0x9000, v31
	ds_read2_b64 v[66:69], v31 offset1:4
	v_add_u32_e32 v31, v30, v79
	v_add_u32_e32 v30, v30, v78
	v_add_u32_e32 v31, 0x9000, v31
	v_add_u32_e32 v30, 0x9000, v30
	ds_read2_b64 v[98:101], v31 offset1:4
	ds_read2_b64 v[102:105], v30 offset1:4
	v_lshl_add_u32 v30, s4, 5, v74
	v_mad_u32_u24 v31, v137, s81, v30
	v_add_u32_e32 v31, 0x9000, v31
	s_waitcnt lgkmcnt(3)
	v_mfma_f32_16x16x32_bf16 v[62:65], v[62:65], v[58:61], 0
	v_add_f32_e32 v33, v33, v45
	v_mov_b32_e32 v45, s49
	s_or_b32 s4, s26, 16
	s_waitcnt lgkmcnt(2)
	v_mfma_f32_16x16x32_bf16 v[66:69], v[66:69], v[58:61], 0
	s_lshr_b32 s49, s4, 4
	s_waitcnt lgkmcnt(1)
	v_mfma_f32_16x16x32_bf16 v[98:101], v[98:101], v[58:61], 0
	s_waitcnt lgkmcnt(0)
	v_mfma_f32_16x16x32_bf16 v[58:61], v[102:105], v[58:61], 0
	v_cvt_pk_bf16_f32 v102, v111, v110
	v_cvt_pk_bf16_f32 v103, v121, v122
	v_cvt_pk_bf16_f32 v104, v112, v113
	v_cvt_pk_bf16_f32 v105, v114, v115
	ds_read2_b64 v[106:109], v31 offset1:4
	v_add_u32_e32 v31, v30, v80
	v_add_u32_e32 v31, 0x9000, v31
	s_waitcnt lgkmcnt(0)
	v_mfma_f32_16x16x32_bf16 v[62:65], v[106:109], v[102:105], v[62:65]
	ds_read2_b64 v[106:109], v31 offset1:4
	v_add_u32_e32 v31, v30, v79
	v_add_u32_e32 v31, 0x9000, v31
	s_waitcnt lgkmcnt(0)
	v_mfma_f32_16x16x32_bf16 v[66:69], v[106:109], v[102:105], v[66:69]
	ds_read2_b64 v[106:109], v31 offset1:4
	v_add_u32_e32 v30, v30, v78
	v_add_u32_e32 v30, 0x9000, v30
	s_waitcnt lgkmcnt(0)
	v_mfma_f32_16x16x32_bf16 v[98:101], v[106:109], v[102:105], v[98:101]
	ds_read2_b64 v[106:109], v30 offset1:4
	v_lshl_add_u32 v30, s28, 5, v74
	v_mad_u32_u24 v31, v137, s81, v30
	v_add_u32_e32 v31, 0x9000, v31
	s_waitcnt lgkmcnt(0)
	v_mfma_f32_16x16x32_bf16 v[58:61], v[106:109], v[102:105], v[58:61]
	v_cvt_pk_bf16_f32 v102, v116, v117
	v_cvt_pk_bf16_f32 v103, v118, v119
	v_cvt_pk_bf16_f32 v104, v120, v97
	v_cvt_pk_bf16_f32 v105, v123, v124
	ds_read2_b64 v[106:109], v31 offset1:4
	v_add_u32_e32 v31, v30, v80
	v_add_u32_e32 v31, 0x9000, v31
	s_waitcnt lgkmcnt(0)
	v_mfma_f32_16x16x32_bf16 v[62:65], v[106:109], v[102:105], v[62:65]
	ds_read2_b64 v[106:109], v31 offset1:4
	v_add_u32_e32 v31, v30, v79
	v_add_u32_e32 v31, 0x9000, v31
	s_waitcnt lgkmcnt(0)
	v_mfma_f32_16x16x32_bf16 v[66:69], v[106:109], v[102:105], v[66:69]
	ds_read2_b64 v[106:109], v31 offset1:4
	v_add_u32_e32 v30, v30, v78
	v_add_u32_e32 v30, 0x9000, v30
	s_waitcnt lgkmcnt(0)
	v_mfma_f32_16x16x32_bf16 v[98:101], v[106:109], v[102:105], v[98:101]
	ds_read2_b64 v[106:109], v30 offset1:4
	v_lshl_add_u32 v30, s27, 5, v74
	v_mad_u32_u24 v31, v137, s81, v30
	v_add_u32_e32 v31, 0x9000, v31
	s_waitcnt lgkmcnt(0)
	v_mfma_f32_16x16x32_bf16 v[58:61], v[106:109], v[102:105], v[58:61]
	v_cvt_pk_bf16_f32 v102, v125, v126
	v_cvt_pk_bf16_f32 v103, v127, v128
	v_cvt_pk_bf16_f32 v104, v129, v131
	v_cvt_pk_bf16_f32 v105, v133, v134
	ds_read2_b64 v[106:109], v31 offset1:4
	v_add_u32_e32 v31, v30, v80
	v_add_u32_e32 v31, 0x9000, v31
	s_waitcnt lgkmcnt(0)
; __device__ __forceinline__ unsigned cvt_pk_bf16(float lo, float hi) { unsigned r; asm volatile("v_cvt_pk_bf16_f32 %0, %1, %2" : "=v"(r) : "v"(lo), "v"(hi)); return r; }
; #define LAS __attribute__((address_space(3)))
; #define MFMA16(a, b, c) __builtin_amdgcn_mfma_f32_16x16x32_bf16((a), (b), (c), 0, 0, 0)
; __device__ __forceinline__ void unpack8(const u32x4 w, float* f) { f[0] = bf_lo(w.x); f[1] = bf_hi(w.x); f[2] = bf_lo(w.y); f[3] = bf_hi(w.y); f[4] = bf_lo(w.z); f[5] = bf_hi(w.z); f[6] = bf_lo(w.w); f[7] = bf_hi(w.w); }
; __device__ __forceinline__ void p2_block(LAS unsigned char* lds, const bf16_t* __restrict__ PROJ, bf16_t* __restrict__ ATT, bf16_t* __restrict__ SGU, const float* __restrict__ qn, const float* __restrict__ kn, ...
;     ...
;             float x1[8], x2[8]; unpack8(qa[c], x1); unpack8(qb[c], x2);
;             float ss = 0.f;
; #pragma unroll
;             for (int j = 0; j < 8; ++j) ss += x1[j] * x1[j] + x2[j] * x2[j];
;             ss += __shfl_xor(ss, 16); ss += __shfl_xor(ss, 32);
;             const float rinv = rsqrtf(ss * (1.0f / 64.0f) + pg8::EPS) * 0.125f;
;     ...
;         const float inv = 1.0f / (sum + __builtin_amdgcn_exp2f((sink - mx) * LOG2E));
;         f32x4 o[4];
; #pragma unroll
;         for (int dt = 0; dt < 4; ++dt) o[dt] = (f32x4){0.f, 0.f, 0.f, 0.f};
; #pragma unroll
;         for (int j = 0; j < 5; ++j) {
;             u32x4 pw; pw.x = cvt_pk_bf16(sc_[2 * j][0], sc_[2 * j][1]); pw.y = cvt_pk_bf16(sc_[2 * j][2], sc_[2 * j][3]); pw.z = cvt_pk_bf16(sc_[2 * j + 1][0], sc_[2 * j + 1][1]); pw.w = cvt_pk_bf16(sc_[2 * j + 1][2], sc_[2 * j + 1][3]);
;             const bf16x8 pf = __builtin_bit_cast(bf16x8, pw);
; #pragma unroll
;             for (int dt = 0; dt < 4; ++dt) { const LAS unsigned char* vb = VT + (16 * dt + fr) * VT_STRIDE + (16 * (t0 + 2 * j) + 4 * fq) * 2;
;                 const u32x2 va = *(const LAS u32x2*)vb, vc = *(const LAS u32x2*)(vb + 32); u32x4 vw; vw.x = va.x; vw.y = va.y; vw.z = vc.x; vw.w = vc.y;
;                 o[dt] = MFMA16(__builtin_bit_cast(bf16x8, vw), pf, o[dt]); }
;         }
;         bf16_t* op = ATT + grow * 1024 + hq * 64 + 4 * fq;
; #pragma unroll
;         for (int dt = 0; dt < 4; ++dt) { u32x2 ow; ow.x = cvt_pk_bf16(o[dt][0] * inv, o[dt][1] * inv); ow.y = cvt_pk_bf16(o[dt][2] * inv, o[dt][3] * inv); *(u32x2*)(op + 16 * dt) = ow; }
	v_mfma_f32_16x16x32_bf16 v[62:65], v[106:109], v[102:105], v[62:65]
	ds_read2_b64 v[106:109], v31 offset1:4
	v_add_u32_e32 v31, v30, v79
	v_add_u32_e32 v31, 0x9000, v31
	s_waitcnt lgkmcnt(0)
	v_mfma_f32_16x16x32_bf16 v[66:69], v[106:109], v[102:105], v[66:69]
	ds_read2_b64 v[106:109], v31 offset1:4
	v_add_u32_e32 v30, v30, v78
	v_add_u32_e32 v30, 0x9000, v30
	s_waitcnt lgkmcnt(0)
	v_mfma_f32_16x16x32_bf16 v[98:101], v[106:109], v[102:105], v[98:101]
	ds_read2_b64 v[106:109], v30 offset1:4
	v_lshl_add_u32 v30, s29, 5, v74
	v_mad_u32_u24 v31, v137, s81, v30
	v_add_u32_e32 v31, 0x9000, v31
	s_waitcnt lgkmcnt(0)
	v_mfma_f32_16x16x32_bf16 v[58:61], v[106:109], v[102:105], v[58:61]
	v_cvt_pk_bf16_f32 v102, v135, v136
	v_cvt_pk_bf16_f32 v103, v138, v139
	v_cvt_pk_bf16_f32 v104, v140, v141
	v_cvt_pk_bf16_f32 v105, v142, v143
	ds_read2_b64 v[106:109], v31 offset1:4
	v_add_u32_e32 v31, v30, v80
	v_add_u32_e32 v31, 0x9000, v31
	s_waitcnt lgkmcnt(0)
	v_mfma_f32_16x16x32_bf16 v[62:65], v[106:109], v[102:105], v[62:65]
	ds_read2_b64 v[106:109], v31 offset1:4
	v_add_u32_e32 v31, v30, v79
	v_add_u32_e32 v31, 0x9000, v31
	s_waitcnt lgkmcnt(0)
	v_mfma_f32_16x16x32_bf16 v[66:69], v[106:109], v[102:105], v[66:69]
	ds_read2_b64 v[106:109], v31 offset1:4
	v_add_u32_e32 v30, v30, v78
	v_add_u32_e32 v30, 0x9000, v30
	s_waitcnt lgkmcnt(0)
	v_mfma_f32_16x16x32_bf16 v[98:101], v[106:109], v[102:105], v[98:101]
	ds_read2_b64 v[106:109], v30 offset1:4
	v_div_scale_f32 v30, s[28:29], v33, v33, 1.0
	v_rcp_f32_e32 v31, v30
	s_waitcnt lgkmcnt(0)
	v_mfma_f32_16x16x32_bf16 v[58:61], v[106:109], v[102:105], v[58:61]
	v_fma_f32 v97, -v30, v31, 1.0
	v_fmac_f32_e32 v31, v97, v31
	v_div_scale_f32 v97, vcc, 1.0, v33, 1.0
	v_mul_f32_e32 v102, v97, v31
	v_fma_f32 v103, -v30, v102, v97
	v_fmac_f32_e32 v102, v103, v31
	v_fma_f32 v30, -v30, v102, v97
	v_div_fmas_f32 v30, v30, v31, v102
	v_div_fixup_f32 v33, v30, v33, 1.0
	v_lshlrev_b64 v[30:31], 11, v[44:45]
	v_mul_f32_e32 v44, v33, v62
	v_mul_f32_e32 v62, v33, v63
	v_lshl_add_u64 v[30:31], v[42:43], 0, v[30:31]
	v_cvt_pk_bf16_f32 v62, v44, v62
	v_mul_f32_e32 v44, v33, v64
	v_mul_f32_e32 v63, v33, v65
	v_cvt_pk_bf16_f32 v63, v44, v63
	global_store_dwordx2 v[30:31], v[62:63], off
	v_mul_f32_e32 v44, v33, v66
	v_mul_f32_e32 v62, v33, v67
	v_cvt_pk_bf16_f32 v62, v44, v62
	v_mul_f32_e32 v44, v33, v68
	v_mul_f32_e32 v63, v33, v69
	v_cvt_pk_bf16_f32 v63, v44, v63
	global_store_dwordx2 v[30:31], v[62:63], off offset:32
	v_mul_f32_e32 v44, v33, v98
	v_mul_f32_e32 v62, v33, v99
	v_cvt_pk_bf16_f32 v62, v44, v62
	v_mul_f32_e32 v44, v33, v100
	v_mul_f32_e32 v63, v33, v101
	v_cvt_pk_bf16_f32 v63, v44, v63
	v_mul_f32_e32 v44, v33, v58
	v_mul_f32_e32 v58, v33, v59
	global_store_dwordx2 v[30:31], v[62:63], off offset:64
	v_cvt_pk_bf16_f32 v58, v44, v58
	v_mul_f32_e32 v44, v33, v60
	v_mul_f32_e32 v33, v33, v61
	v_cvt_pk_bf16_f32 v59, v44, v33
	v_or_b32_e32 v44, s4, v137
	v_or_b32_e32 v33, s17, v44
	global_store_dwordx2 v[30:31], v[58:59], off offset:96
	v_lshlrev_b32_e32 v30, 7, v33
	v_mov_b32_e32 v31, v1
	v_lshl_add_u64 v[62:63], v[46:47], 0, v[30:31]
	v_lshl_add_u64 v[30:31], v[48:49], 0, v[30:31]
	global_load_dwordx4 v[58:61], v[62:63], off offset:16
	s_nop 0
	global_load_dwordx4 v[62:65], v[62:63], off
	s_nop 0
	global_load_dwordx4 v[66:69], v[30:31], off offset:16
	global_load_dwordx4 v[98:101], v[30:31], off
	v_lshlrev_b32_e32 v30, 16, v29
	v_and_b32_e32 v104, 0xffff0000, v29
	v_lshlrev_b32_e32 v31, 16, v25
	v_and_b32_e32 v105, 0xffff0000, v25
	v_mov_b32_e32 v108, v104
	v_mov_b32_e32 v109, v30
	v_mov_b32_e32 v106, v105
	v_mov_b32_e32 v107, v31
	v_pk_mul_f32 v[108:109], v[108:109], v[108:109]
	v_and_b32_e32 v25, 0xffff0000, v24
	v_pk_fma_f32 v[106:107], v[106:107], v[106:107], v[108:109]
	v_lshlrev_b32_e32 v109, 16, v24
	v_lshlrev_b32_e32 v108, 16, v28
	v_and_b32_e32 v24, 0xffff0000, v28
	v_mov_b32_e32 v112, v24
	v_mov_b32_e32 v113, v108
	v_mov_b32_e32 v28, v25
	v_mov_b32_e32 v29, v109
	v_pk_mul_f32 v[112:113], v[112:113], v[112:113]
	v_and_b32_e32 v116, 0xffff0000, v27
	v_pk_fma_f32 v[28:29], v[28:29], v[28:29], v[112:113]
	v_lshlrev_b32_e32 v112, 16, v27
	v_lshlrev_b32_e32 v113, 16, v23
	v_and_b32_e32 v117, 0xffff0000, v23
	v_mov_b32_e32 v120, v116
	v_mov_b32_e32 v121, v112
	v_mov_b32_e32 v118, v117
	v_mov_b32_e32 v119, v113
	v_pk_mul_f32 v[120:121], v[120:121], v[120:121]
	v_and_b32_e32 v23, 0xffff0000, v22
	v_pk_fma_f32 v[118:119], v[118:119], v[118:119], v[120:121]
	v_lshlrev_b32_e32 v121, 16, v22
	v_lshlrev_b32_e32 v120, 16, v26
	v_and_b32_e32 v22, 0xffff0000, v26
	v_mov_b32_e32 v124, v120
	v_mov_b32_e32 v125, v22
	v_mov_b32_e32 v26, v121
	v_mov_b32_e32 v27, v23
	v_pk_mul_f32 v[124:125], v[124:125], v[124:125]
	s_or_b32 s27, s49, 2
	v_pk_fma_f32 v[26:27], v[26:27], v[26:27], v[124:125]
	s_add_i32 s28, s26, 64
	v_add_f32_e32 v26, v26, v27
	v_add_f32_e32 v26, v119, v26
	v_add_f32_e32 v26, v118, v26
	v_add_f32_e32 v26, v29, v26
	v_add_f32_e32 v26, v28, v26
	v_add_f32_e32 v26, v107, v26
	v_add_f32_e32 v26, v106, v26
	ds_bpermute_b32 v27, v76, v26
	s_add_i32 s29, s26, 0x60
	s_waitcnt lgkmcnt(0)
	v_add_f32_e32 v26, v26, v27
	ds_bpermute_b32 v27, v77, v26
	s_waitcnt lgkmcnt(0)
	v_add_f32_e32 v26, v26, v27
	v_fmamk_f32 v26, v26, 0x3c800000, v209
	v_cmp_gt_f32_e32 vcc, s82, v26
	v_mul_f32_e32 v27, 0x4b800000, v26
	s_waitcnt vmcnt(3)
	v_mov_b32_e32 v110, v58
	v_cndmask_b32_e32 v26, v26, v27, vcc
	v_rsq_f32_e32 v26, v26
	s_waitcnt vmcnt(0)
; __device__ __forceinline__ unsigned cvt_pk_bf16(float lo, float hi) { unsigned r; asm volatile("v_cvt_pk_bf16_f32 %0, %1, %2" : "=v"(r) : "v"(lo), "v"(hi)); return r; }
; #define LAS __attribute__((address_space(3)))
; #define MFMA16(a, b, c) __builtin_amdgcn_mfma_f32_16x16x32_bf16((a), (b), (c), 0, 0, 0)
; __device__ __forceinline__ void p2_block(LAS unsigned char* lds, const bf16_t* __restrict__ PROJ, bf16_t* __restrict__ ATT, bf16_t* __restrict__ SGU, const float* __restrict__ qn, const float* __restrict__ kn, ...
;     ...
;             const float* cp = COS + pos * 32 + 8 * fq; const float* sp = SIN + pos * 32 + 8 * fq;
;             float o1[8], o2[8];
; #pragma unroll
;             for (int j = 0; j < 8; ++j) { const float a1 = x1[j] * rinv * qn[8 * fq + j], a2 = x2[j] * rinv * qn[32 + 8 * fq + j], cc = cp[j], sn = sp[j]; o1[j] = a1 * cc - a2 * sn; o2[j] = a2 * cc + a1 * sn; }
;             u32x4 w0, w1;
;             w0.x = cvt_pk_bf16(o1[0], o1[1]); w0.y = cvt_pk_bf16(o1[2], o1[3]); w0.z = cvt_pk_bf16(o1[4], o1[5]); w0.w = cvt_pk_bf16(o1[6], o1[7]);
;             w1.x = cvt_pk_bf16(o2[0], o2[1]); w1.y = cvt_pk_bf16(o2[2], o2[3]); w1.z = cvt_pk_bf16(o2[4], o2[5]); w1.w = cvt_pk_bf16(o2[6], o2[7]);
;             qf0 = __builtin_bit_cast(bf16x8, w0); qf1 = __builtin_bit_cast(bf16x8, w1);
;         }
;         const int t0 = (i0 >> 4) < 6 ? (i0 >> 4) : 6;
;         f32x4 sc_[10];
;         const LAS unsigned char* kbase = KS + (16 * t0 + fr) * KS_STRIDE + 16 * fq;
; #pragma unroll
;         for (int t = 0; t < 10; ++t) { const bf16x8 k0 = *(const LAS bf16x8*)(kbase + t * 16 * KS_STRIDE), k1 = *(const LAS bf16x8*)(kbase + t * 16 * KS_STRIDE + 64);
;             f32x4 z = (f32x4){0.f, 0.f, 0.f, 0.f}; z = MFMA16(k0, qf0, z); sc_[t] = MFMA16(k1, qf1, z); }
	v_mov_b32_e32 v106, v98
	v_mov_b32_e32 v107, v62
	v_mov_b32_e32 v122, v62
	v_mul_f32_e32 v27, 0x45800000, v26
	v_cndmask_b32_e32 v26, v26, v27, vcc
	v_mul_f32_e32 v26, 0x3e000000, v26
	v_pk_mul_f32 v[28:29], v[26:27], v[120:121] op_sel_hi:[0,1]
	v_pk_mul_f32 v[28:29], v[56:57], v[28:29]
	v_mov_b32_e32 v123, v98
	v_pk_mul_f32 v[106:107], v[106:107], v[28:29]
	v_pk_mul_f32 v[28:29], v[122:123], v[28:29]
	v_sub_f32_e32 v27, v107, v106
	v_pk_mul_f32 v[22:23], v[26:27], v[22:23] op_sel_hi:[0,1]
	v_pk_mul_f32 v[22:23], v[18:19], v[22:23]
	v_mov_b32_e32 v62, v99
	v_mov_b32_e32 v98, v63
	v_add_f32_e32 v97, v28, v29
	v_pk_mul_f32 v[28:29], v[62:63], v[22:23]
	v_pk_mul_f32 v[22:23], v[98:99], v[22:23]
	v_mov_b32_e32 v114, v64
	v_add_f32_e32 v63, v22, v23
	v_pk_mul_f32 v[22:23], v[26:27], v[112:113] op_sel_hi:[0,1]
	v_mov_b32_e32 v115, v100
	v_sub_f32_e32 v62, v29, v28
	v_pk_mul_f32 v[22:23], v[54:55], v[22:23]
	v_mov_b32_e32 v28, v100
	v_mov_b32_e32 v29, v64
	v_pk_mul_f32 v[28:29], v[28:29], v[22:23]
	v_pk_mul_f32 v[22:23], v[114:115], v[22:23]
	v_mov_b32_e32 v64, v101
	v_add_f32_e32 v99, v22, v23
	v_pk_mul_f32 v[22:23], v[26:27], v[116:117] op_sel_hi:[0,1]
	v_pk_mul_f32 v[22:23], v[20:21], v[22:23]
	v_mov_b32_e32 v100, v65
	v_sub_f32_e32 v98, v29, v28
	v_pk_mul_f32 v[28:29], v[64:65], v[22:23]
	v_pk_mul_f32 v[22:23], v[100:101], v[22:23]
	v_mov_b32_e32 v111, v66
	v_add_f32_e32 v65, v22, v23
	v_pk_mul_f32 v[22:23], v[26:27], v[108:109] op_sel_hi:[0,1]
	v_sub_f32_e32 v64, v29, v28
	v_pk_mul_f32 v[22:23], v[52:53], v[22:23]
	v_mov_b32_e32 v28, v66
	v_mov_b32_e32 v29, v58
	v_pk_mul_f32 v[28:29], v[28:29], v[22:23]
	v_pk_mul_f32 v[22:23], v[110:111], v[22:23]
	v_sub_f32_e32 v28, v29, v28
	v_add_f32_e32 v29, v22, v23
	v_pk_mul_f32 v[22:23], v[26:27], v[24:25] op_sel_hi:[0,1]
	v_pk_mul_f32 v[22:23], v[14:15], v[22:23]
	v_mov_b32_e32 v58, v67
	v_mov_b32_e32 v66, v59
	v_pk_mul_f32 v[24:25], v[58:59], v[22:23]
	v_pk_mul_f32 v[22:23], v[66:67], v[22:23]
	v_mov_b32_e32 v102, v60
	v_add_f32_e32 v59, v22, v23
	v_pk_mul_f32 v[22:23], v[26:27], v[30:31] op_sel_hi:[0,1]
	v_mov_b32_e32 v103, v68
	v_sub_f32_e32 v58, v25, v24
	v_pk_mul_f32 v[22:23], v[50:51], v[22:23]
	v_mov_b32_e32 v24, v68
	v_mov_b32_e32 v25, v60
	v_pk_mul_f32 v[24:25], v[22:23], v[24:25]
	v_pk_mul_f32 v[22:23], v[22:23], v[102:103]
	v_mov_b32_e32 v60, v69
	v_add_f32_e32 v31, v22, v23
	v_pk_mul_f32 v[22:23], v[26:27], v[104:105] op_sel_hi:[0,1]
	v_pk_mul_f32 v[22:23], v[16:17], v[22:23]
	v_sub_f32_e32 v30, v25, v24
	v_pk_mul_f32 v[24:25], v[22:23], v[60:61]
	v_mov_b32_e32 v68, v61
	v_sub_f32_e32 v25, v25, v24
	v_pk_mul_f32 v[22:23], v[22:23], v[68:69]
	s_nop 0
	v_add_f32_e32 v60, v22, v23
	v_cvt_pk_bf16_f32 v22, v27, v62
	v_cvt_pk_bf16_f32 v23, v98, v64
	v_cvt_pk_bf16_f32 v24, v28, v58
	v_cvt_pk_bf16_f32 v25, v30, v25
	v_mad_u32_u24 v30, v44, s59, v81
	v_cvt_pk_bf16_f32 v26, v97, v63
	v_cvt_pk_bf16_f32 v27, v99, v65
	v_cvt_pk_bf16_f32 v28, v29, v59
	v_cvt_pk_bf16_f32 v29, v31, v60
	ds_read_b128 v[58:61], v30
	ds_read_b128 v[62:65], v30 offset:64
	s_waitcnt lgkmcnt(1)
	v_mfma_f32_16x16x32_bf16 v[58:61], v[58:61], v[22:25], 0
	v_sub_u32_e32 v31, v44, v82
	s_waitcnt lgkmcnt(0)
	v_mfma_f32_16x16x32_bf16 v[58:61], v[62:65], v[26:29], v[58:61]
	ds_read_b128 v[62:65], v30 offset:2304
	ds_read_b128 v[66:69], v30 offset:2368
	s_waitcnt lgkmcnt(1)
	v_mfma_f32_16x16x32_bf16 v[62:65], v[62:65], v[22:25], 0
	s_waitcnt lgkmcnt(0)
	v_mfma_f32_16x16x32_bf16 v[62:65], v[66:69], v[26:29], v[62:65]
	ds_read_b128 v[66:69], v30 offset:4608
	ds_read_b128 v[98:101], v30 offset:4672
	s_waitcnt lgkmcnt(1)
	v_mfma_f32_16x16x32_bf16 v[66:69], v[66:69], v[22:25], 0
	s_waitcnt lgkmcnt(0)
	v_mfma_f32_16x16x32_bf16 v[66:69], v[98:101], v[26:29], v[66:69]
	ds_read_b128 v[98:101], v30 offset:6912
	ds_read_b128 v[102:105], v30 offset:6976
	s_waitcnt lgkmcnt(1)
	v_mfma_f32_16x16x32_bf16 v[98:101], v[98:101], v[22:25], 0
	s_waitcnt lgkmcnt(0)
	v_mfma_f32_16x16x32_bf16 v[98:101], v[102:105], v[26:29], v[98:101]
	ds_read_b128 v[102:105], v30 offset:9216
	ds_read_b128 v[106:109], v30 offset:9280
	s_waitcnt lgkmcnt(1)
	v_mfma_f32_16x16x32_bf16 v[102:105], v[102:105], v[22:25], 0
	s_waitcnt lgkmcnt(0)
	v_mfma_f32_16x16x32_bf16 v[102:105], v[106:109], v[26:29], v[102:105]
	ds_read_b128 v[106:109], v30 offset:11520
	ds_read_b128 v[110:113], v30 offset:11584
	s_waitcnt lgkmcnt(1)
	v_mfma_f32_16x16x32_bf16 v[106:109], v[106:109], v[22:25], 0
	s_waitcnt lgkmcnt(0)
	v_mfma_f32_16x16x32_bf16 v[106:109], v[110:113], v[26:29], v[106:109]
	ds_read_b128 v[110:113], v30 offset:13824
	ds_read_b128 v[114:117], v30 offset:13888
	s_waitcnt lgkmcnt(1)
	v_mfma_f32_16x16x32_bf16 v[110:113], v[110:113], v[22:25], 0
	s_waitcnt lgkmcnt(0)
	v_mfma_f32_16x16x32_bf16 v[110:113], v[114:117], v[26:29], v[110:113]
	ds_read_b128 v[114:117], v30 offset:16128
	ds_read_b128 v[118:121], v30 offset:16192
	s_waitcnt lgkmcnt(1)
	v_mfma_f32_16x16x32_bf16 v[114:117], v[114:117], v[22:25], 0
	s_waitcnt lgkmcnt(0)
	v_mfma_f32_16x16x32_bf16 v[114:117], v[118:121], v[26:29], v[114:117]
	ds_read_b128 v[118:121], v30 offset:18432
	ds_read_b128 v[122:125], v30 offset:18496
	s_waitcnt lgkmcnt(1)
	v_mfma_f32_16x16x32_bf16 v[118:121], v[118:121], v[22:25], 0
	s_waitcnt lgkmcnt(0)
	v_mfma_f32_16x16x32_bf16 v[118:121], v[122:125], v[26:29], v[118:121]
	ds_read_b128 v[122:125], v30 offset:20736
	ds_read_b128 v[126:129], v30 offset:20800
	v_add_u32_e32 v30, 0x7d, v32
	s_waitcnt lgkmcnt(1)
	v_mfma_f32_16x16x32_bf16 v[22:25], v[122:125], v[22:25], 0
	s_waitcnt lgkmcnt(0)
; __device__ __forceinline__ void p2_block(LAS unsigned char* lds, const bf16_t* __restrict__ PROJ, bf16_t* __restrict__ ATT, bf16_t* __restrict__ SGU, const float* __restrict__ qn, const float* __restrict__ kn, ...
;     ...
;         float mx = -1e30f;
; #pragma unroll
;         for (int t = 0; t < 10; ++t)
; #pragma unroll
;             for (int e = 0; e < 4; ++e) { const int kx = 16 * (t0 + t) + 4 * fq + e, d = kx - irow; const bool ok = (d >= 1) && (d <= 128) && (n > 0 || kx >= 128);
;                 const float v = ok ? sc_[t][e] : -1e30f; sc_[t][e] = v; mx = fmaxf(mx, v); }
;         mx = fmaxf(mx, __shfl_xor(mx, 16)); mx = fmaxf(mx, __shfl_xor(mx, 32)); mx = fmaxf(mx, sink);
	v_mfma_f32_16x16x32_bf16 v[22:25], v[126:129], v[26:29], v[22:25]
	v_add_u32_e32 v29, 0x7e, v32
	v_cmp_gt_u32_e32 vcc, s84, v29
	s_and_b64 s[44:45], s[50:51], vcc
	v_cmp_gt_u32_e32 vcc, s84, v30
	v_add_u32_e32 v32, 0x60, v31
	s_and_b64 s[46:47], s[50:51], vcc
	v_cmp_gt_u32_e32 vcc, s84, v32
	v_cndmask_b32_e64 v26, v213, v58, s[40:41]
	s_and_b64 vcc, s[50:51], vcc
	v_add_u32_e32 v58, 0x5f, v31
	v_cndmask_b32_e32 v32, v213, v62, vcc
	v_cmp_gt_u32_e32 vcc, s84, v58
	v_cndmask_b32_e64 v27, v213, v59, s[42:43]
	s_and_b64 vcc, s[50:51], vcc
	v_add_u32_e32 v59, 0x5e, v31
	v_cndmask_b32_e32 v58, v213, v63, vcc
	v_cmp_gt_u32_e32 vcc, s84, v59
	v_cndmask_b32_e64 v29, v213, v60, s[44:45]
	s_and_b64 vcc, s[50:51], vcc
	v_add_u32_e32 v60, 0x5d, v31
	v_cndmask_b32_e64 v30, v213, v61, s[46:47]
	v_cndmask_b32_e32 v59, v213, v64, vcc
	v_cmp_gt_u32_e32 vcc, s84, v60
	v_lshl_or_b32 v61, s27, 4, v73
	s_and_b64 vcc, s[50:51], vcc
	v_sub_u32_e32 v62, v44, v61
	v_cndmask_b32_e32 v60, v213, v65, vcc
	v_cmp_lt_u32_e32 vcc, s79, v62
	s_and_b64 vcc, s[50:51], vcc
	v_sub_u32_e32 v63, v61, v44
	v_cndmask_b32_e32 v62, v213, v66, vcc
	v_cmp_gt_u32_e32 vcc, s84, v63
	v_add_u32_e32 v64, -2, v44
	s_and_b64 vcc, s[50:51], vcc
	v_sub_u32_e32 v65, v64, v61
	v_cndmask_b32_e32 v63, v213, v67, vcc
	v_cmp_lt_u32_e32 vcc, s79, v65
	v_add_u32_e32 v66, -3, v44
	s_and_b64 vcc, s[50:51], vcc
	v_sub_u32_e32 v61, v66, v61
	v_cndmask_b32_e32 v65, v213, v68, vcc
	v_cmp_lt_u32_e32 vcc, s79, v61
	v_or_b32_e32 v67, s28, v73
	s_and_b64 vcc, s[50:51], vcc
	v_sub_u32_e32 v68, v44, v67
	v_cndmask_b32_e32 v61, v213, v69, vcc
	v_cmp_lt_u32_e32 vcc, s79, v68
	s_and_b64 vcc, vcc, s[6:7]
	v_sub_u32_e32 v67, v67, v44
	v_cndmask_b32_e32 v69, v213, v98, vcc
	v_cmp_gt_u32_e32 vcc, s84, v67
	s_and_b64 vcc, vcc, s[6:7]
	v_add_u32_e32 v97, 0x7e, v68
	v_cndmask_b32_e32 v67, v213, v99, vcc
	v_cmp_gt_u32_e32 vcc, s84, v97
	s_and_b64 vcc, vcc, s[6:7]
	v_add_u32_e32 v68, 0x7d, v68
	s_add_i32 s28, s49, 4
	v_cndmask_b32_e32 v97, v213, v100, vcc
	v_cmp_gt_u32_e32 vcc, s84, v68
	v_lshl_or_b32 v98, s28, 4, v73
	s_and_b64 vcc, vcc, s[6:7]
	v_sub_u32_e32 v99, v44, v98
	v_cndmask_b32_e32 v68, v213, v101, vcc
	v_cmp_lt_u32_e32 vcc, s79, v99
	s_and_b64 vcc, vcc, s[6:7]
	v_sub_u32_e32 v100, v98, v44
	v_cndmask_b32_e32 v99, v213, v102, vcc
	v_cmp_gt_u32_e32 vcc, s84, v100
	s_and_b64 vcc, vcc, s[6:7]
	v_sub_u32_e32 v101, v64, v98
	v_cndmask_b32_e32 v100, v213, v103, vcc
	v_cmp_lt_u32_e32 vcc, s79, v101
	s_and_b64 vcc, vcc, s[6:7]
	v_sub_u32_e32 v98, v66, v98
	v_cndmask_b32_e32 v101, v213, v104, vcc
	v_cmp_lt_u32_e32 vcc, s79, v98
	v_or_b32_e32 v102, s29, v73
	s_and_b64 vcc, vcc, s[6:7]
	v_sub_u32_e32 v103, v44, v102
	v_cndmask_b32_e32 v98, v213, v105, vcc
	v_cmp_lt_u32_e32 vcc, s79, v103
	s_and_b64 vcc, vcc, s[6:7]
	v_sub_u32_e32 v102, v102, v44
	v_cndmask_b32_e32 v104, v213, v106, vcc
	v_cmp_gt_u32_e32 vcc, s84, v102
	s_and_b64 vcc, vcc, s[6:7]
	v_add_u32_e32 v105, 0x7e, v103
	v_cndmask_b32_e32 v102, v213, v107, vcc
	v_cmp_gt_u32_e32 vcc, s84, v105
	s_and_b64 vcc, vcc, s[6:7]
	v_add_u32_e32 v103, 0x7d, v103
	s_add_i32 s29, s49, 6
	v_cndmask_b32_e32 v105, v213, v108, vcc
	v_cmp_gt_u32_e32 vcc, s84, v103
	v_lshl_or_b32 v106, s29, 4, v73
	s_and_b64 vcc, vcc, s[6:7]
	v_sub_u32_e32 v107, v44, v106
	v_cndmask_b32_e32 v103, v213, v109, vcc
	v_cmp_lt_u32_e32 vcc, s79, v107
	s_and_b64 vcc, vcc, s[6:7]
	v_sub_u32_e32 v108, v106, v44
	v_max3_f32 v28, v26, s52, v27
	v_cndmask_b32_e32 v107, v213, v110, vcc
	v_cmp_gt_u32_e32 vcc, s84, v108
	v_max3_f32 v28, v28, v29, v30
	s_and_b64 vcc, vcc, s[6:7]
	v_sub_u32_e32 v109, v64, v106
	v_max3_f32 v28, v28, v32, v58
	v_cndmask_b32_e32 v108, v213, v111, vcc
	v_cmp_lt_u32_e32 vcc, s79, v109
	v_max3_f32 v28, v28, v59, v60
	s_and_b64 vcc, vcc, s[6:7]
	v_sub_u32_e32 v106, v66, v106
	v_max3_f32 v28, v28, v62, v63
	v_cndmask_b32_e32 v109, v213, v112, vcc
	v_cmp_lt_u32_e32 vcc, s79, v106
	v_max3_f32 v28, v28, v65, v61
	s_and_b64 vcc, vcc, s[6:7]
	v_max3_f32 v28, v28, v69, v67
	v_cndmask_b32_e32 v106, v213, v113, vcc
	v_cmp_gt_u32_e32 vcc, s84, v31
	v_sub_u32_e32 v111, v82, v44
	v_max3_f32 v28, v28, v97, v68
	v_cndmask_b32_e32 v110, v213, v114, vcc
	v_cmp_lt_u32_e32 vcc, s79, v111
	v_add_u32_e32 v112, -2, v31
	s_or_b32 s49, s49, 8
	v_max3_f32 v28, v28, v99, v100
	v_cndmask_b32_e32 v111, v213, v115, vcc
	v_cmp_gt_u32_e32 vcc, s84, v112
	v_add_u32_e32 v113, -3, v31
	v_lshl_or_b32 v114, s49, 4, v73
	v_max3_f32 v28, v28, v101, v98
	v_cndmask_b32_e32 v112, v213, v116, vcc
	v_cmp_gt_u32_e32 vcc, s84, v113
	v_sub_u32_e32 v115, v44, v114
	v_max3_f32 v28, v28, v104, v102
	v_cndmask_b32_e32 v113, v213, v117, vcc
	v_cmp_lt_u32_e32 vcc, s79, v115
	v_sub_u32_e32 v44, v114, v44
	v_max3_f32 v28, v28, v105, v103
	v_cndmask_b32_e32 v115, v213, v118, vcc
	v_cmp_gt_u32_e32 vcc, s84, v44
	v_sub_u32_e32 v64, v64, v114
	v_max3_f32 v28, v28, v107, v108
	v_cndmask_b32_e32 v44, v213, v119, vcc
	v_cmp_lt_u32_e32 vcc, s79, v64
	v_sub_u32_e32 v66, v66, v114
	v_max3_f32 v28, v28, v109, v106
	v_cndmask_b32_e32 v64, v213, v120, vcc
	v_cmp_lt_u32_e32 vcc, s79, v66
	v_subrev_u32_e32 v114, 32, v31
	v_max3_f32 v28, v28, v110, v111
	v_cndmask_b32_e32 v66, v213, v121, vcc
	v_cmp_gt_u32_e32 vcc, s84, v114
	v_subrev_u32_e32 v114, 33, v31
	v_max3_f32 v28, v28, v112, v113
	v_cndmask_b32_e32 v22, v213, v22, vcc
	v_cmp_gt_u32_e32 vcc, s84, v114
	v_subrev_u32_e32 v114, 34, v31
	v_max3_f32 v28, v28, v115, v44
	v_cndmask_b32_e32 v23, v213, v23, vcc
	v_cmp_gt_u32_e32 vcc, s84, v114
	v_subrev_u32_e32 v31, 35, v31
	v_max3_f32 v28, v28, v64, v66
	v_cndmask_b32_e32 v24, v213, v24, vcc
	v_cmp_gt_u32_e32 vcc, s84, v31
	v_max3_f32 v28, v28, v22, v23
	s_nop 0
	v_cndmask_b32_e32 v25, v213, v25, vcc
	v_max3_f32 v28, v28, v24, v25
	ds_bpermute_b32 v31, v76, v28
	s_waitcnt lgkmcnt(0)
; __device__ __forceinline__ unsigned cvt_pk_bf16(float lo, float hi) { unsigned r; asm volatile("v_cvt_pk_bf16_f32 %0, %1, %2" : "=v"(r) : "v"(lo), "v"(hi)); return r; }
; #define LAS __attribute__((address_space(3)))
; __device__ __forceinline__ void p2_block(LAS unsigned char* lds, const bf16_t* __restrict__ PROJ, bf16_t* __restrict__ ATT, bf16_t* __restrict__ SGU, const float* __restrict__ qn, const float* __restrict__ kn, ...
;     ...
;         mx = fmaxf(mx, __shfl_xor(mx, 16)); mx = fmaxf(mx, __shfl_xor(mx, 32)); mx = fmaxf(mx, sink);
;         float sum = 0.f;
; #pragma unroll
;         for (int t = 0; t < 10; ++t)
; #pragma unroll
;             for (int e = 0; e < 4; ++e) { const float p = __builtin_amdgcn_exp2f((sc_[t][e] - mx) * LOG2E); sc_[t][e] = p; sum += p; }
;         sum += __shfl_xor(sum, 16); sum += __shfl_xor(sum, 32);
;         const float inv = 1.0f / (sum + __builtin_amdgcn_exp2f((sink - mx) * LOG2E));
;         f32x4 o[4];
; #pragma unroll
;         for (int dt = 0; dt < 4; ++dt) o[dt] = (f32x4){0.f, 0.f, 0.f, 0.f};
; #pragma unroll
;         for (int j = 0; j < 5; ++j) {
;             u32x4 pw; pw.x = cvt_pk_bf16(sc_[2 * j][0], sc_[2 * j][1]); pw.y = cvt_pk_bf16(sc_[2 * j][2], sc_[2 * j][3]); pw.z = cvt_pk_bf16(sc_[2 * j + 1][0], sc_[2 * j + 1][1]); pw.w = cvt_pk_bf16(sc_[2 * j + 1][2], sc_[2 * j + 1][3]);
;             const bf16x8 pf = __builtin_bit_cast(bf16x8, pw);
; #pragma unroll
;             for (int dt = 0; dt < 4; ++dt) { const LAS unsigned char* vb = VT + (16 * dt + fr) * VT_STRIDE + (16 * (t0 + 2 * j) + 4 * fq) * 2;
;                 const u32x2 va = *(const LAS u32x2*)vb, vc = *(const LAS u32x2*)(vb + 32); u32x4 vw; vw.x = va.x; vw.y = va.y; vw.z = vc.x; vw.w = vc.y;
	v_max_f32_e32 v31, v31, v31
	v_max_f32_e32 v28, v28, v31
	ds_bpermute_b32 v31, v77, v28
	s_waitcnt lgkmcnt(0)
	v_max3_f32 v28, v28, v31, v75
	v_sub_f32_e32 v61, v61, v28
	v_mul_f32_e32 v61, 0x3fb8aa3b, v61
	v_exp_f32_e32 v118, v61
	v_sub_f32_e32 v61, v69, v28
	v_mul_f32_e32 v61, 0x3fb8aa3b, v61
	v_exp_f32_e32 v69, v61
	v_sub_f32_e32 v61, v67, v28
	v_mul_f32_e32 v61, 0x3fb8aa3b, v61
	v_exp_f32_e32 v67, v61
	v_sub_f32_e32 v61, v97, v28
	v_mul_f32_e32 v61, 0x3fb8aa3b, v61
	v_exp_f32_e32 v97, v61
	v_sub_f32_e32 v61, v68, v28
	v_mul_f32_e32 v61, 0x3fb8aa3b, v61
	v_sub_f32_e32 v26, v26, v28
	v_exp_f32_e32 v68, v61
	v_sub_f32_e32 v61, v99, v28
	v_mul_f32_e32 v26, 0x3fb8aa3b, v26
	v_sub_f32_e32 v27, v27, v28
	v_mul_f32_e32 v61, 0x3fb8aa3b, v61
	v_exp_f32_e32 v26, v26
	v_mul_f32_e32 v27, 0x3fb8aa3b, v27
	v_sub_f32_e32 v29, v29, v28
	v_exp_f32_e32 v99, v61
	v_sub_f32_e32 v61, v100, v28
	v_exp_f32_e32 v27, v27
	v_mul_f32_e32 v29, 0x3fb8aa3b, v29
	v_sub_f32_e32 v30, v30, v28
	v_mul_f32_e32 v61, 0x3fb8aa3b, v61
	v_exp_f32_e32 v29, v29
	v_mul_f32_e32 v30, 0x3fb8aa3b, v30
	v_sub_f32_e32 v32, v32, v28
	v_exp_f32_e32 v100, v61
	v_sub_f32_e32 v61, v101, v28
	v_exp_f32_e32 v30, v30
	v_mul_f32_e32 v32, 0x3fb8aa3b, v32
	v_sub_f32_e32 v58, v58, v28
	v_mul_f32_e32 v61, 0x3fb8aa3b, v61
	v_add_f32_e32 v31, 0, v26
	v_exp_f32_e32 v32, v32
	v_mul_f32_e32 v58, 0x3fb8aa3b, v58
	v_sub_f32_e32 v59, v59, v28
	v_sub_f32_e32 v62, v62, v28
	v_exp_f32_e32 v101, v61
	v_sub_f32_e32 v61, v98, v28
	v_add_f32_e32 v31, v27, v31
	v_exp_f32_e32 v58, v58
	v_mul_f32_e32 v59, 0x3fb8aa3b, v59
	v_sub_f32_e32 v60, v60, v28
	v_mul_f32_e32 v62, 0x3fb8aa3b, v62
	v_mul_f32_e32 v61, 0x3fb8aa3b, v61
	v_add_f32_e32 v31, v29, v31
	v_exp_f32_e32 v59, v59
	v_mul_f32_e32 v60, 0x3fb8aa3b, v60
	v_exp_f32_e32 v114, v62
	v_sub_f32_e32 v62, v63, v28
	v_exp_f32_e32 v98, v61
	v_sub_f32_e32 v61, v104, v28
	v_add_f32_e32 v31, v30, v31
	v_exp_f32_e32 v60, v60
	v_mul_f32_e32 v62, 0x3fb8aa3b, v62
	v_mul_f32_e32 v61, 0x3fb8aa3b, v61
	v_add_f32_e32 v31, v32, v31
	v_exp_f32_e32 v116, v62
	v_sub_f32_e32 v62, v65, v28
	v_exp_f32_e32 v104, v61
	v_sub_f32_e32 v61, v102, v28
	v_add_f32_e32 v31, v58, v31
	v_mul_f32_e32 v62, 0x3fb8aa3b, v62
	v_mul_f32_e32 v61, 0x3fb8aa3b, v61
	v_add_f32_e32 v31, v59, v31
	v_exp_f32_e32 v117, v62
	v_exp_f32_e32 v102, v61
	v_sub_f32_e32 v61, v105, v28
	v_add_f32_e32 v31, v60, v31
	v_mul_f32_e32 v61, 0x3fb8aa3b, v61
	v_add_f32_e32 v31, v114, v31
	v_exp_f32_e32 v105, v61
	v_sub_f32_e32 v61, v103, v28
	v_add_f32_e32 v31, v116, v31
	v_mul_f32_e32 v61, 0x3fb8aa3b, v61
	v_add_f32_e32 v31, v117, v31
	v_exp_f32_e32 v103, v61
	v_sub_f32_e32 v61, v107, v28
	v_add_f32_e32 v31, v118, v31
	v_mul_f32_e32 v61, 0x3fb8aa3b, v61
	v_add_f32_e32 v31, v69, v31
	v_exp_f32_e32 v107, v61
	v_sub_f32_e32 v61, v108, v28
	v_add_f32_e32 v31, v67, v31
	v_mul_f32_e32 v61, 0x3fb8aa3b, v61
	v_add_f32_e32 v31, v97, v31
	v_exp_f32_e32 v108, v61
	v_sub_f32_e32 v61, v109, v28
	v_add_f32_e32 v31, v68, v31
	v_mul_f32_e32 v61, 0x3fb8aa3b, v61
	v_add_f32_e32 v31, v99, v31
	v_exp_f32_e32 v109, v61
	v_sub_f32_e32 v61, v106, v28
	v_add_f32_e32 v31, v100, v31
	v_mul_f32_e32 v61, 0x3fb8aa3b, v61
	v_add_f32_e32 v31, v101, v31
	v_exp_f32_e32 v106, v61
	v_sub_f32_e32 v61, v110, v28
	v_add_f32_e32 v31, v98, v31
	v_mul_f32_e32 v61, 0x3fb8aa3b, v61
	v_add_f32_e32 v31, v104, v31
	v_exp_f32_e32 v110, v61
	v_sub_f32_e32 v61, v111, v28
	v_add_f32_e32 v31, v102, v31
	v_mul_f32_e32 v61, 0x3fb8aa3b, v61
	v_add_f32_e32 v31, v105, v31
	v_exp_f32_e32 v111, v61
	v_sub_f32_e32 v61, v112, v28
	v_add_f32_e32 v31, v103, v31
	v_mul_f32_e32 v61, 0x3fb8aa3b, v61
	v_add_f32_e32 v31, v107, v31
	v_exp_f32_e32 v112, v61
	v_sub_f32_e32 v61, v113, v28
	v_add_f32_e32 v31, v108, v31
	v_mul_f32_e32 v61, 0x3fb8aa3b, v61
	v_sub_f32_e32 v44, v44, v28
	v_add_f32_e32 v31, v109, v31
	v_exp_f32_e32 v113, v61
	v_sub_f32_e32 v61, v115, v28
	v_mul_f32_e32 v44, 0x3fb8aa3b, v44
	v_add_f32_e32 v31, v106, v31
	v_mul_f32_e32 v61, 0x3fb8aa3b, v61
	v_exp_f32_e32 v119, v44
	v_sub_f32_e32 v44, v64, v28
	v_add_f32_e32 v31, v110, v31
	v_exp_f32_e32 v115, v61
	v_mul_f32_e32 v44, 0x3fb8aa3b, v44
	v_add_f32_e32 v31, v111, v31
	v_exp_f32_e32 v120, v44
	v_sub_f32_e32 v44, v66, v28
	v_sub_f32_e32 v23, v23, v28
	v_add_f32_e32 v31, v112, v31
	v_mul_f32_e32 v44, 0x3fb8aa3b, v44
	v_sub_f32_e32 v22, v22, v28
	v_mul_f32_e32 v23, 0x3fb8aa3b, v23
	v_add_f32_e32 v31, v113, v31
	v_exp_f32_e32 v121, v44
	v_mul_f32_e32 v22, 0x3fb8aa3b, v22
	v_exp_f32_e32 v123, v23
	v_sub_f32_e32 v23, v24, v28
	v_add_f32_e32 v31, v115, v31
	v_exp_f32_e32 v122, v22
	v_mul_f32_e32 v23, 0x3fb8aa3b, v23
	v_add_f32_e32 v31, v119, v31
	v_exp_f32_e32 v124, v23
	v_sub_f32_e32 v23, v25, v28
	v_add_f32_e32 v31, v120, v31
	v_mul_f32_e32 v23, 0x3fb8aa3b, v23
	v_add_f32_e32 v31, v121, v31
	v_exp_f32_e32 v125, v23
	v_add_f32_e32 v22, v122, v31
	v_add_f32_e32 v22, v123, v22
	v_add_f32_e32 v22, v124, v22
	v_add_f32_e32 v22, v125, v22
	ds_bpermute_b32 v23, v76, v22
	v_lshl_add_u32 v62, s4, 1, v74
	v_or_b32_e32 v44, s48, v33
	s_or_b32 s4, s26, 32
	s_waitcnt lgkmcnt(0)
	v_add_f32_e32 v22, v22, v23
	ds_bpermute_b32 v23, v77, v22
	s_waitcnt lgkmcnt(0)
	v_add_f32_e32 v22, v22, v23
	v_sub_f32_e32 v23, v75, v28
	v_mul_f32_e32 v23, 0x3fb8aa3b, v23
	v_exp_f32_e32 v23, v23
	s_nop 0
	v_add_f32_e32 v126, v23, v22
	v_cvt_pk_bf16_f32 v22, v26, v27
	v_cvt_pk_bf16_f32 v23, v29, v30
	v_cvt_pk_bf16_f32 v24, v32, v58
	v_mad_u32_u24 v26, v137, s81, v62
	v_add_u32_e32 v30, v62, v80
	v_add_u32_e32 v58, v62, v79
	v_add_u32_e32 v62, v62, v78
	v_add_u32_e32 v26, 0x9000, v26
	v_add_u32_e32 v30, 0x9000, v30
	v_add_u32_e32 v58, 0x9000, v58
	v_add_u32_e32 v62, 0x9000, v62
	v_cvt_pk_bf16_f32 v25, v59, v60
	ds_read2_b64 v[26:29], v26 offset1:4
	ds_read2_b64 v[30:33], v30 offset1:4
	ds_read2_b64 v[58:61], v58 offset1:4
	ds_read2_b64 v[62:65], v62 offset1:4
	s_waitcnt lgkmcnt(3)
; __device__ __forceinline__ unsigned cvt_pk_bf16(float lo, float hi) { unsigned r; asm volatile("v_cvt_pk_bf16_f32 %0, %1, %2" : "=v"(r) : "v"(lo), "v"(hi)); return r; }
; #define LAS __attribute__((address_space(3)))
; #define MFMA16(a, b, c) __builtin_amdgcn_mfma_f32_16x16x32_bf16((a), (b), (c), 0, 0, 0)
; __device__ __forceinline__ void unpack8(const u32x4 w, float* f) { f[0] = bf_lo(w.x); f[1] = bf_hi(w.x); f[2] = bf_lo(w.y); f[3] = bf_hi(w.y); f[4] = bf_lo(w.z); f[5] = bf_hi(w.z); f[6] = bf_lo(w.w); f[7] = bf_hi(w.w); }
; __device__ __forceinline__ void p2_block(LAS unsigned char* lds, const bf16_t* __restrict__ PROJ, bf16_t* __restrict__ ATT, bf16_t* __restrict__ SGU, const float* __restrict__ qn, const float* __restrict__ kn, ...
;     ...
;             float x1[8], x2[8]; unpack8(qa[c], x1); unpack8(qb[c], x2);
;             float ss = 0.f;
; #pragma unroll
;             for (int j = 0; j < 8; ++j) ss += x1[j] * x1[j] + x2[j] * x2[j];
;             ss += __shfl_xor(ss, 16); ss += __shfl_xor(ss, 32);
;     ...
;         for (int j = 0; j < 5; ++j) {
;             u32x4 pw; pw.x = cvt_pk_bf16(sc_[2 * j][0], sc_[2 * j][1]); pw.y = cvt_pk_bf16(sc_[2 * j][2], sc_[2 * j][3]); pw.z = cvt_pk_bf16(sc_[2 * j + 1][0], sc_[2 * j + 1][1]); pw.w = cvt_pk_bf16(sc_[2 * j + 1][2], sc_[2 * j + 1][3]);
;             const bf16x8 pf = __builtin_bit_cast(bf16x8, pw);
; #pragma unroll
;             for (int dt = 0; dt < 4; ++dt) { const LAS unsigned char* vb = VT + (16 * dt + fr) * VT_STRIDE + (16 * (t0 + 2 * j) + 4 * fq) * 2;
;                 const u32x2 va = *(const LAS u32x2*)vb, vc = *(const LAS u32x2*)(vb + 32); u32x4 vw; vw.x = va.x; vw.y = va.y; vw.z = vc.x; vw.w = vc.y;
;                 o[dt] = MFMA16(__builtin_bit_cast(bf16x8, vw), pf, o[dt]); }
;         }
;         bf16_t* op = ATT + grow * 1024 + hq * 64 + 4 * fq;
; #pragma unroll
;         for (int dt = 0; dt < 4; ++dt) { u32x2 ow; ow.x = cvt_pk_bf16(o[dt][0] * inv, o[dt][1] * inv); ow.y = cvt_pk_bf16(o[dt][2] * inv, o[dt][3] * inv); *(u32x2*)(op + 16 * dt) = ow; }
	v_mfma_f32_16x16x32_bf16 v[26:29], v[26:29], v[22:25], 0
	s_waitcnt lgkmcnt(2)
	v_mfma_f32_16x16x32_bf16 v[30:33], v[30:33], v[22:25], 0
	s_waitcnt lgkmcnt(1)
	v_mfma_f32_16x16x32_bf16 v[58:61], v[58:61], v[22:25], 0
	s_waitcnt lgkmcnt(0)
	v_mfma_f32_16x16x32_bf16 v[22:25], v[62:65], v[22:25], 0
	v_cvt_pk_bf16_f32 v62, v114, v116
	v_cvt_pk_bf16_f32 v63, v117, v118
	v_cvt_pk_bf16_f32 v64, v69, v67
	v_cvt_pk_bf16_f32 v65, v97, v68
	v_lshl_add_u32 v97, s27, 5, v74
	v_mad_u32_u24 v66, v137, s81, v97
	v_add_u32_e32 v66, 0x9000, v66
	ds_read2_b64 v[66:69], v66 offset1:4
	s_lshr_b32 s27, s4, 4
	s_waitcnt lgkmcnt(0)
	v_mfma_f32_16x16x32_bf16 v[26:29], v[66:69], v[62:65], v[26:29]
	v_add_u32_e32 v66, v97, v80
	v_add_u32_e32 v66, 0x9000, v66
	ds_read2_b64 v[66:69], v66 offset1:4
	s_waitcnt lgkmcnt(0)
	v_mfma_f32_16x16x32_bf16 v[30:33], v[66:69], v[62:65], v[30:33]
	v_add_u32_e32 v66, v97, v79
	v_add_u32_e32 v66, 0x9000, v66
	ds_read2_b64 v[66:69], v66 offset1:4
	s_waitcnt lgkmcnt(0)
	v_mfma_f32_16x16x32_bf16 v[58:61], v[66:69], v[62:65], v[58:61]
	v_add_u32_e32 v66, v97, v78
	v_add_u32_e32 v66, 0x9000, v66
	ds_read2_b64 v[66:69], v66 offset1:4
	v_lshl_add_u32 v97, s28, 5, v74
	s_waitcnt lgkmcnt(0)
	v_mfma_f32_16x16x32_bf16 v[22:25], v[66:69], v[62:65], v[22:25]
	v_mad_u32_u24 v66, v137, s81, v97
	v_add_u32_e32 v66, 0x9000, v66
	v_cvt_pk_bf16_f32 v62, v99, v100
	v_cvt_pk_bf16_f32 v63, v101, v98
	v_cvt_pk_bf16_f32 v64, v104, v102
	v_cvt_pk_bf16_f32 v65, v105, v103
	ds_read2_b64 v[66:69], v66 offset1:4
	s_waitcnt lgkmcnt(0)
	v_mfma_f32_16x16x32_bf16 v[26:29], v[66:69], v[62:65], v[26:29]
	v_add_u32_e32 v66, v97, v80
	v_add_u32_e32 v66, 0x9000, v66
	ds_read2_b64 v[66:69], v66 offset1:4
	v_or_b32_e32 v98, s4, v137
	s_waitcnt lgkmcnt(0)
	v_mfma_f32_16x16x32_bf16 v[30:33], v[66:69], v[62:65], v[30:33]
	v_add_u32_e32 v66, v97, v79
	v_add_u32_e32 v66, 0x9000, v66
	ds_read2_b64 v[66:69], v66 offset1:4
	s_waitcnt lgkmcnt(0)
	v_mfma_f32_16x16x32_bf16 v[58:61], v[66:69], v[62:65], v[58:61]
	v_add_u32_e32 v66, v97, v78
	v_add_u32_e32 v66, 0x9000, v66
	ds_read2_b64 v[66:69], v66 offset1:4
	v_lshl_add_u32 v97, s29, 5, v74
	s_waitcnt lgkmcnt(0)
	v_mfma_f32_16x16x32_bf16 v[22:25], v[66:69], v[62:65], v[22:25]
	v_mad_u32_u24 v66, v137, s81, v97
	v_add_u32_e32 v66, 0x9000, v66
	v_cvt_pk_bf16_f32 v62, v107, v108
	v_cvt_pk_bf16_f32 v63, v109, v106
	v_cvt_pk_bf16_f32 v64, v110, v111
	v_cvt_pk_bf16_f32 v65, v112, v113
	ds_read2_b64 v[66:69], v66 offset1:4
	s_waitcnt lgkmcnt(0)
	v_mfma_f32_16x16x32_bf16 v[26:29], v[66:69], v[62:65], v[26:29]
	v_add_u32_e32 v66, v97, v80
	v_add_u32_e32 v66, 0x9000, v66
	ds_read2_b64 v[66:69], v66 offset1:4
	s_waitcnt lgkmcnt(0)
	v_mfma_f32_16x16x32_bf16 v[30:33], v[66:69], v[62:65], v[30:33]
	v_add_u32_e32 v66, v97, v79
	v_add_u32_e32 v66, 0x9000, v66
	ds_read2_b64 v[66:69], v66 offset1:4
	s_waitcnt lgkmcnt(0)
	v_mfma_f32_16x16x32_bf16 v[58:61], v[66:69], v[62:65], v[58:61]
	v_add_u32_e32 v66, v97, v78
	v_add_u32_e32 v66, 0x9000, v66
	ds_read2_b64 v[66:69], v66 offset1:4
	v_lshl_add_u32 v97, s49, 5, v74
	s_waitcnt lgkmcnt(0)
	v_mfma_f32_16x16x32_bf16 v[22:25], v[66:69], v[62:65], v[22:25]
	v_mad_u32_u24 v66, v137, s81, v97
	v_add_u32_e32 v66, 0x9000, v66
	v_cvt_pk_bf16_f32 v62, v115, v119
	v_cvt_pk_bf16_f32 v63, v120, v121
	v_cvt_pk_bf16_f32 v64, v122, v123
	v_cvt_pk_bf16_f32 v65, v124, v125
	ds_read2_b64 v[66:69], v66 offset1:4
	s_waitcnt lgkmcnt(0)
	v_mfma_f32_16x16x32_bf16 v[26:29], v[66:69], v[62:65], v[26:29]
	v_add_u32_e32 v66, v97, v80
	v_add_u32_e32 v66, 0x9000, v66
	ds_read2_b64 v[66:69], v66 offset1:4
	s_waitcnt lgkmcnt(0)
	v_mfma_f32_16x16x32_bf16 v[30:33], v[66:69], v[62:65], v[30:33]
	v_add_u32_e32 v66, v97, v79
	v_add_u32_e32 v66, 0x9000, v66
	ds_read2_b64 v[66:69], v66 offset1:4
	s_waitcnt lgkmcnt(0)
	v_mfma_f32_16x16x32_bf16 v[58:61], v[66:69], v[62:65], v[58:61]
	v_add_u32_e32 v66, v97, v78
	v_add_u32_e32 v66, 0x9000, v66
	ds_read2_b64 v[66:69], v66 offset1:4
	v_or_b32_e32 v97, s17, v98
	s_waitcnt lgkmcnt(0)
	v_mfma_f32_16x16x32_bf16 v[22:25], v[66:69], v[62:65], v[22:25]
	v_div_scale_f32 v62, s[28:29], v126, v126, 1.0
	v_rcp_f32_e32 v63, v62
	v_lshlrev_b32_e32 v68, 16, v34
	v_and_b32_e32 v69, 0xffff0000, v34
	v_and_b32_e32 v67, 0xffff0000, v38
	v_fma_f32 v64, -v62, v63, 1.0
	v_fmac_f32_e32 v63, v64, v63
	v_div_scale_f32 v64, vcc, 1.0, v126, 1.0
	v_mul_f32_e32 v65, v64, v63
	v_fma_f32 v66, -v62, v65, v64
	v_fmac_f32_e32 v65, v66, v63
	v_fma_f32 v62, -v62, v65, v64
	v_div_fmas_f32 v62, v62, v63, v65
	v_div_fixup_f32 v64, v62, v126, 1.0
	v_mul_f32_e32 v26, v64, v26
	v_mul_f32_e32 v27, v64, v27
	v_lshlrev_b64 v[62:63], 11, v[44:45]
	v_cvt_pk_bf16_f32 v26, v26, v27
	v_mul_f32_e32 v27, v64, v28
	v_lshl_add_u64 v[62:63], v[42:43], 0, v[62:63]
	v_mul_f32_e32 v28, v64, v29
	v_cvt_pk_bf16_f32 v27, v27, v28
	global_store_dwordx2 v[62:63], v[26:27], off
	v_mul_f32_e32 v26, v64, v30
	v_mul_f32_e32 v27, v64, v31
	v_cvt_pk_bf16_f32 v26, v26, v27
	v_mul_f32_e32 v27, v64, v32
	v_mul_f32_e32 v28, v64, v33
	v_cvt_pk_bf16_f32 v27, v27, v28
	global_store_dwordx2 v[62:63], v[26:27], off offset:32
	v_mul_f32_e32 v26, v64, v58
	v_mul_f32_e32 v27, v64, v59
	v_cvt_pk_bf16_f32 v26, v26, v27
	v_mul_f32_e32 v27, v64, v60
	v_mul_f32_e32 v22, v64, v22
	v_mul_f32_e32 v23, v64, v23
	v_mul_f32_e32 v28, v64, v61
	v_cvt_pk_bf16_f32 v27, v27, v28
	global_store_dwordx2 v[62:63], v[26:27], off offset:64
	v_cvt_pk_bf16_f32 v22, v22, v23
	v_mul_f32_e32 v23, v64, v24
	v_mul_f32_e32 v24, v64, v25
	v_cvt_pk_bf16_f32 v23, v23, v24
	global_store_dwordx2 v[62:63], v[22:23], off offset:96
	v_lshlrev_b32_e32 v66, 16, v38
	v_lshlrev_b32_e32 v65, 16, v35
	v_and_b32_e32 v64, 0xffff0000, v35
	v_pk_mul_f32 v[22:23], v[68:69], v[68:69]
	v_lshlrev_b32_e32 v63, 16, v39
	v_and_b32_e32 v62, 0xffff0000, v39
	v_pk_fma_f32 v[22:23], v[66:67], v[66:67], v[22:23]
	v_pk_mul_f32 v[24:25], v[64:65], v[64:65]
	v_lshlrev_b32_e32 v61, 16, v36
	v_and_b32_e32 v60, 0xffff0000, v36
	v_pk_fma_f32 v[24:25], v[62:63], v[62:63], v[24:25]
	v_add_f32_e32 v22, v22, v23
	v_lshlrev_b32_e32 v59, 16, v40
	v_and_b32_e32 v58, 0xffff0000, v40
	v_pk_mul_f32 v[26:27], v[60:61], v[60:61]
	v_add_f32_e32 v22, v25, v22
	v_lshlrev_b32_e32 v39, 16, v41
	v_and_b32_e32 v38, 0xffff0000, v41
	v_lshlrev_b32_e32 v41, 16, v37
	v_and_b32_e32 v40, 0xffff0000, v37
	v_pk_fma_f32 v[26:27], v[58:59], v[58:59], v[26:27]
	v_add_f32_e32 v22, v24, v22
	v_pk_mul_f32 v[28:29], v[40:41], v[40:41]
	v_add_f32_e32 v22, v27, v22
	v_pk_fma_f32 v[28:29], v[38:39], v[38:39], v[28:29]
	v_add_f32_e32 v22, v26, v22
	v_add_f32_e32 v22, v29, v22
	v_add_f32_e32 v22, v28, v22
	ds_bpermute_b32 v23, v76, v22
	v_mov_b32_e32 v100, v68
	v_mov_b32_e32 v101, v66
	v_mov_b32_e32 v66, v69
	s_add_i32 s29, s27, 4
	s_waitcnt lgkmcnt(0)
; __device__ __forceinline__ unsigned cvt_pk_bf16(float lo, float hi) { unsigned r; asm volatile("v_cvt_pk_bf16_f32 %0, %1, %2" : "=v"(r) : "v"(lo), "v"(hi)); return r; }
; #define LAS __attribute__((address_space(3)))
; #define MFMA16(a, b, c) __builtin_amdgcn_mfma_f32_16x16x32_bf16((a), (b), (c), 0, 0, 0)
; __device__ __forceinline__ void unpack8(const u32x4 w, float* f) { f[0] = bf_lo(w.x); f[1] = bf_hi(w.x); f[2] = bf_lo(w.y); f[3] = bf_hi(w.y); f[4] = bf_lo(w.z); f[5] = bf_hi(w.z); f[6] = bf_lo(w.w); f[7] = bf_hi(w.w); }
; __device__ __forceinline__ void p2_block(LAS unsigned char* lds, const bf16_t* __restrict__ PROJ, bf16_t* __restrict__ ATT, bf16_t* __restrict__ SGU, const float* __restrict__ qn, const float* __restrict__ kn, ...
;     ...
;             float x1[8], x2[8]; unpack8(qa[c], x1); unpack8(qb[c], x2);
;             float ss = 0.f;
; #pragma unroll
;             for (int j = 0; j < 8; ++j) ss += x1[j] * x1[j] + x2[j] * x2[j];
;             ss += __shfl_xor(ss, 16); ss += __shfl_xor(ss, 32);
;             const float rinv = rsqrtf(ss * (1.0f / 64.0f) + pg8::EPS) * 0.125f;
;             const float* cp = COS + pos * 32 + 8 * fq; const float* sp = SIN + pos * 32 + 8 * fq;
;             float o1[8], o2[8];
; #pragma unroll
;             for (int j = 0; j < 8; ++j) { const float a1 = x1[j] * rinv * qn[8 * fq + j], a2 = x2[j] * rinv * qn[32 + 8 * fq + j], cc = cp[j], sn = sp[j]; o1[j] = a1 * cc - a2 * sn; o2[j] = a2 * cc + a1 * sn; }
;             u32x4 w0, w1;
;             w0.x = cvt_pk_bf16(o1[0], o1[1]); w0.y = cvt_pk_bf16(o1[2], o1[3]); w0.z = cvt_pk_bf16(o1[4], o1[5]); w0.w = cvt_pk_bf16(o1[6], o1[7]);
;             w1.x = cvt_pk_bf16(o2[0], o2[1]); w1.y = cvt_pk_bf16(o2[2], o2[3]); w1.z = cvt_pk_bf16(o2[4], o2[5]); w1.w = cvt_pk_bf16(o2[6], o2[7]);
;             qf0 = __builtin_bit_cast(bf16x8, w0); qf1 = __builtin_bit_cast(bf16x8, w1);
;         }
;         const int t0 = (i0 >> 4) < 6 ? (i0 >> 4) : 6;
;         f32x4 sc_[10];
;         const LAS unsigned char* kbase = KS + (16 * t0 + fr) * KS_STRIDE + 16 * fq;
; #pragma unroll
;         for (int t = 0; t < 10; ++t) { const bf16x8 k0 = *(const LAS bf16x8*)(kbase + t * 16 * KS_STRIDE), k1 = *(const LAS bf16x8*)(kbase + t * 16 * KS_STRIDE + 64);
;             f32x4 z = (f32x4){0.f, 0.f, 0.f, 0.f}; z = MFMA16(k0, qf0, z); sc_[t] = MFMA16(k1, qf1, z); }
	v_add_f32_e32 v22, v22, v23
	ds_bpermute_b32 v23, v77, v22
	s_waitcnt lgkmcnt(0)
	v_add_f32_e32 v22, v22, v23
	v_fmamk_f32 v22, v22, 0x3c800000, v209
	v_cmp_gt_f32_e32 vcc, s82, v22
	v_mul_f32_e32 v23, 0x4b800000, v22
	s_nop 0
	v_cndmask_b32_e32 v22, v22, v23, vcc
	v_rsq_f32_e32 v22, v22
	s_nop 0
	v_mul_f32_e32 v23, 0x45800000, v22
	v_cndmask_b32_e32 v22, v22, v23, vcc
	v_mul_f32_e32 v44, 0x3e000000, v22
	v_lshlrev_b32_e32 v22, 7, v97
	v_mov_b32_e32 v23, v1
	v_lshl_add_u64 v[26:27], v[46:47], 0, v[22:23]
	v_lshl_add_u64 v[34:35], v[48:49], 0, v[22:23]
	global_load_dwordx4 v[22:25], v[26:27], off offset:16
	global_load_dwordx4 v[30:33], v[26:27], off
	s_nop 0
	global_load_dwordx4 v[26:29], v[34:35], off offset:16
	s_nop 0
	global_load_dwordx4 v[34:37], v[34:35], off
	v_pk_mul_f32 v[100:101], v[44:45], v[100:101] op_sel_hi:[0,1]
	v_pk_mul_f32 v[66:67], v[44:45], v[66:67] op_sel_hi:[0,1]
	v_pk_mul_f32 v[100:101], v[56:57], v[100:101]
	v_pk_mul_f32 v[66:67], v[18:19], v[66:67]
	s_waitcnt vmcnt(2)
	v_mov_b32_e32 v57, v30
	v_mov_b32_e32 v102, v30
	s_waitcnt vmcnt(0)
	v_mov_b32_e32 v56, v34
	v_mov_b32_e32 v103, v34
	v_mov_b32_e32 v30, v35
	v_mov_b32_e32 v34, v31
	v_pk_mul_f32 v[18:19], v[30:31], v[66:67]
	v_pk_mul_f32 v[30:31], v[34:35], v[66:67]
	v_sub_f32_e32 v19, v19, v18
	v_add_f32_e32 v18, v30, v31
	v_mov_b32_e32 v30, v65
	v_mov_b32_e32 v31, v63
	v_pk_mul_f32 v[30:31], v[44:45], v[30:31] op_sel_hi:[0,1]
	v_pk_mul_f32 v[30:31], v[54:55], v[30:31]
	v_mov_b32_e32 v34, v36
	v_mov_b32_e32 v35, v32
	v_pk_mul_f32 v[34:35], v[34:35], v[30:31]
	v_mov_b32_e32 v65, v62
	v_sub_f32_e32 v54, v35, v34
	v_mov_b32_e32 v34, v32
	v_mov_b32_e32 v35, v36
	v_pk_mul_f32 v[30:31], v[34:35], v[30:31]
	v_mov_b32_e32 v32, v37
	v_add_f32_e32 v34, v30, v31
	v_pk_mul_f32 v[30:31], v[44:45], v[64:65] op_sel_hi:[0,1]
	v_pk_mul_f32 v[20:21], v[20:21], v[30:31]
	v_mov_b32_e32 v36, v33
	v_pk_mul_f32 v[30:31], v[32:33], v[20:21]
	v_pk_mul_f32 v[20:21], v[36:37], v[20:21]
	v_sub_f32_e32 v32, v31, v30
	v_add_f32_e32 v33, v20, v21
	v_mov_b32_e32 v20, v61
	v_mov_b32_e32 v21, v59
	v_pk_mul_f32 v[20:21], v[44:45], v[20:21] op_sel_hi:[0,1]
	v_pk_mul_f32 v[20:21], v[52:53], v[20:21]
	v_mov_b32_e32 v30, v26
	v_mov_b32_e32 v31, v22
	v_pk_mul_f32 v[30:31], v[30:31], v[20:21]
	v_mov_b32_e32 v61, v58
	v_sub_f32_e32 v35, v31, v30
	v_mov_b32_e32 v30, v22
	v_mov_b32_e32 v31, v26
	v_pk_mul_f32 v[20:21], v[30:31], v[20:21]
	v_mov_b32_e32 v22, v27
	v_add_f32_e32 v30, v20, v21
	v_pk_mul_f32 v[20:21], v[44:45], v[60:61] op_sel_hi:[0,1]
	v_pk_mul_f32 v[14:15], v[14:15], v[20:21]
	v_mov_b32_e32 v26, v23
	v_pk_mul_f32 v[20:21], v[22:23], v[14:15]
	v_pk_mul_f32 v[14:15], v[26:27], v[14:15]
	v_sub_f32_e32 v22, v21, v20
	v_add_f32_e32 v23, v14, v15
	v_mov_b32_e32 v14, v41
	v_mov_b32_e32 v15, v39
	v_pk_mul_f32 v[14:15], v[44:45], v[14:15] op_sel_hi:[0,1]
	v_pk_mul_f32 v[14:15], v[50:51], v[14:15]
	v_mov_b32_e32 v20, v28
	v_mov_b32_e32 v21, v24
	v_pk_mul_f32 v[20:21], v[14:15], v[20:21]
	v_mov_b32_e32 v41, v38
	v_sub_f32_e32 v26, v21, v20
	v_mov_b32_e32 v20, v24
	v_mov_b32_e32 v21, v28
	v_pk_mul_f32 v[14:15], v[14:15], v[20:21]
	v_mov_b32_e32 v24, v29
	v_add_f32_e32 v21, v14, v15
	v_pk_mul_f32 v[14:15], v[44:45], v[40:41] op_sel_hi:[0,1]
	v_pk_mul_f32 v[14:15], v[16:17], v[14:15]
	v_mov_b32_e32 v28, v25
	v_pk_mul_f32 v[16:17], v[14:15], v[24:25]
	v_pk_mul_f32 v[14:15], v[14:15], v[28:29]
	v_pk_mul_f32 v[56:57], v[56:57], v[100:101]
	v_pk_mul_f32 v[100:101], v[102:103], v[100:101]
	v_sub_f32_e32 v17, v17, v16
	v_add_f32_e32 v24, v14, v15
	v_mad_u32_u24 v44, v98, s59, v81
	v_sub_f32_e32 v57, v57, v56
	v_add_f32_e32 v56, v100, v101
	v_cvt_pk_bf16_f32 v14, v57, v19
	v_cvt_pk_bf16_f32 v15, v54, v32
	v_cvt_pk_bf16_f32 v16, v35, v22
	v_cvt_pk_bf16_f32 v17, v26, v17
	v_cvt_pk_bf16_f32 v18, v56, v18
	v_cvt_pk_bf16_f32 v19, v34, v33
	v_cvt_pk_bf16_f32 v20, v30, v23
	v_cvt_pk_bf16_f32 v21, v21, v24
	ds_read_b128 v[22:25], v44
	ds_read_b128 v[26:29], v44 offset:64
	s_waitcnt lgkmcnt(1)
	v_mfma_f32_16x16x32_bf16 v[22:25], v[22:25], v[14:17], 0
	s_waitcnt lgkmcnt(0)
	v_mfma_f32_16x16x32_bf16 v[22:25], v[26:29], v[18:21], v[22:25]
	ds_read_b128 v[26:29], v44 offset:2304
	ds_read_b128 v[30:33], v44 offset:2368
	s_waitcnt lgkmcnt(1)
	v_mfma_f32_16x16x32_bf16 v[26:29], v[26:29], v[14:17], 0
	s_waitcnt lgkmcnt(0)
	v_mfma_f32_16x16x32_bf16 v[26:29], v[30:33], v[18:21], v[26:29]
	ds_read_b128 v[30:33], v44 offset:4608
	ds_read_b128 v[34:37], v44 offset:4672
	s_waitcnt lgkmcnt(1)
	v_mfma_f32_16x16x32_bf16 v[30:33], v[30:33], v[14:17], 0
	s_waitcnt lgkmcnt(0)
	v_mfma_f32_16x16x32_bf16 v[30:33], v[34:37], v[18:21], v[30:33]
	ds_read_b128 v[34:37], v44 offset:6912
	ds_read_b128 v[38:41], v44 offset:6976
	s_waitcnt lgkmcnt(1)
	v_mfma_f32_16x16x32_bf16 v[34:37], v[34:37], v[14:17], 0
	s_waitcnt lgkmcnt(0)
	v_mfma_f32_16x16x32_bf16 v[34:37], v[38:41], v[18:21], v[34:37]
	ds_read_b128 v[38:41], v44 offset:9216
	ds_read_b128 v[50:53], v44 offset:9280
	s_waitcnt lgkmcnt(1)
	v_mfma_f32_16x16x32_bf16 v[38:41], v[38:41], v[14:17], 0
	s_waitcnt lgkmcnt(0)
	v_mfma_f32_16x16x32_bf16 v[38:41], v[50:53], v[18:21], v[38:41]
	ds_read_b128 v[50:53], v44 offset:11520
	ds_read_b128 v[54:57], v44 offset:11584
	s_waitcnt lgkmcnt(1)
	v_mfma_f32_16x16x32_bf16 v[50:53], v[50:53], v[14:17], 0
	s_waitcnt lgkmcnt(0)
	v_mfma_f32_16x16x32_bf16 v[50:53], v[54:57], v[18:21], v[50:53]
	ds_read_b128 v[54:57], v44 offset:13824
	ds_read_b128 v[58:61], v44 offset:13888
	s_waitcnt lgkmcnt(1)
	v_mfma_f32_16x16x32_bf16 v[54:57], v[54:57], v[14:17], 0
	s_waitcnt lgkmcnt(0)
	v_mfma_f32_16x16x32_bf16 v[54:57], v[58:61], v[18:21], v[54:57]
	ds_read_b128 v[58:61], v44 offset:16128
	ds_read_b128 v[62:65], v44 offset:16192
	s_waitcnt lgkmcnt(1)
; #define LAS __attribute__((address_space(3)))
; #define MFMA16(a, b, c) __builtin_amdgcn_mfma_f32_16x16x32_bf16((a), (b), (c), 0, 0, 0)
; __device__ __forceinline__ void p2_block(LAS unsigned char* lds, const bf16_t* __restrict__ PROJ, bf16_t* __restrict__ ATT, bf16_t* __restrict__ SGU, const float* __restrict__ qn, const float* __restrict__ kn, ...
;     ...
;         for (int t = 0; t < 10; ++t) { const bf16x8 k0 = *(const LAS bf16x8*)(kbase + t * 16 * KS_STRIDE), k1 = *(const LAS bf16x8*)(kbase + t * 16 * KS_STRIDE + 64);
;             f32x4 z = (f32x4){0.f, 0.f, 0.f, 0.f}; z = MFMA16(k0, qf0, z); sc_[t] = MFMA16(k1, qf1, z); }
;         float mx = -1e30f;
; #pragma unroll
;         for (int t = 0; t < 10; ++t)
; #pragma unroll
;             for (int e = 0; e < 4; ++e) { const int kx = 16 * (t0 + t) + 4 * fq + e, d = kx - irow; const bool ok = (d >= 1) && (d <= 128) && (n > 0 || kx >= 128);
;                 const float v = ok ? sc_[t][e] : -1e30f; sc_[t][e] = v; mx = fmaxf(mx, v); }
;         mx = fmaxf(mx, __shfl_xor(mx, 16)); mx = fmaxf(mx, __shfl_xor(mx, 32)); mx = fmaxf(mx, sink);
	v_mfma_f32_16x16x32_bf16 v[58:61], v[58:61], v[14:17], 0
	s_waitcnt lgkmcnt(0)
	v_mfma_f32_16x16x32_bf16 v[58:61], v[62:65], v[18:21], v[58:61]
	ds_read_b128 v[62:65], v44 offset:18432
	ds_read_b128 v[66:69], v44 offset:18496
	s_waitcnt lgkmcnt(1)
	v_mfma_f32_16x16x32_bf16 v[62:65], v[62:65], v[14:17], 0
	s_waitcnt lgkmcnt(0)
	v_mfma_f32_16x16x32_bf16 v[62:65], v[66:69], v[18:21], v[62:65]
	ds_read_b128 v[66:69], v44 offset:20736
	ds_read_b128 v[100:103], v44 offset:20800
	s_waitcnt lgkmcnt(1)
	v_mfma_f32_16x16x32_bf16 v[14:17], v[66:69], v[14:17], 0
	s_waitcnt lgkmcnt(0)
	v_mfma_f32_16x16x32_bf16 v[14:17], v[100:103], v[18:21], v[14:17]
	v_cndmask_b32_e64 v19, v213, v23, s[42:43]
	v_sub_u32_e32 v23, v98, v83
	v_cmp_lt_u32_e32 vcc, s79, v23
	v_cndmask_b32_e64 v21, v213, v24, s[44:45]
	s_and_b64 vcc, s[50:51], vcc
	v_sub_u32_e32 v24, v98, v84
	v_cndmask_b32_e32 v23, v213, v26, vcc
	v_cmp_lt_u32_e32 vcc, s79, v24
	v_cndmask_b32_e64 v18, v213, v22, s[40:41]
	v_cndmask_b32_e64 v22, v213, v25, s[46:47]
	s_and_b64 vcc, s[50:51], vcc
	v_sub_u32_e32 v25, v98, v85
	v_cndmask_b32_e32 v24, v213, v27, vcc
	v_cmp_lt_u32_e32 vcc, s79, v25
	s_and_b64 vcc, s[50:51], vcc
	v_sub_u32_e32 v26, v98, v87
	s_add_i32 s40, s27, 2
	v_cndmask_b32_e32 v25, v213, v28, vcc
	v_cmp_lt_u32_e32 vcc, s79, v26
	v_lshl_or_b32 v27, s40, 4, v73
	s_and_b64 vcc, s[50:51], vcc
	v_sub_u32_e32 v28, v98, v27
	v_cndmask_b32_e32 v26, v213, v29, vcc
	v_cmp_lt_u32_e32 vcc, s79, v28
	s_and_b64 vcc, vcc, s[6:7]
	v_sub_u32_e32 v29, v27, v98
	v_cndmask_b32_e32 v28, v213, v30, vcc
	v_cmp_gt_u32_e32 vcc, s84, v29
	s_and_b64 vcc, vcc, s[6:7]
	v_add_u32_e32 v30, -2, v98
	v_cndmask_b32_e32 v29, v213, v31, vcc
	v_sub_u32_e32 v31, v30, v27
	v_cmp_lt_u32_e32 vcc, s79, v31
	v_add_u32_e32 v31, -3, v98
	s_and_b64 vcc, vcc, s[6:7]
	v_sub_u32_e32 v27, v31, v27
	v_cndmask_b32_e32 v44, v213, v32, vcc
	v_cmp_lt_u32_e32 vcc, s79, v27
	s_and_b64 vcc, vcc, s[6:7]
	v_sub_u32_e32 v32, v98, v86
	v_cndmask_b32_e32 v27, v213, v33, vcc
	v_cmp_lt_u32_e32 vcc, s79, v32
	s_and_b64 vcc, vcc, s[6:7]
	v_sub_u32_e32 v32, v86, v98
	v_cndmask_b32_e32 v33, v213, v34, vcc
	v_cmp_gt_u32_e32 vcc, s84, v32
	s_and_b64 vcc, vcc, s[6:7]
	v_sub_u32_e32 v32, v98, v89
	v_cndmask_b32_e32 v35, v213, v35, vcc
	v_cmp_lt_u32_e32 vcc, s79, v32
	s_and_b64 vcc, vcc, s[6:7]
	v_sub_u32_e32 v32, v98, v90
	v_cndmask_b32_e32 v66, v213, v36, vcc
	v_cmp_lt_u32_e32 vcc, s79, v32
	s_and_b64 vcc, vcc, s[6:7]
	v_lshl_or_b32 v32, s29, 4, v73
	s_cmp_gt_u32 s4, 48
	v_sub_u32_e32 v34, v98, v32
	s_cselect_b64 s[42:43], -1, 0
	v_cndmask_b32_e32 v37, v213, v37, vcc
	v_cmp_lt_u32_e32 vcc, s79, v34
	s_or_b64 s[42:43], s[50:51], s[42:43]
	s_and_b64 vcc, vcc, s[42:43]
	v_sub_u32_e32 v34, v32, v98
	v_cndmask_b32_e32 v67, v213, v38, vcc
	v_cmp_gt_u32_e32 vcc, s84, v34
	s_and_b64 vcc, vcc, s[42:43]
	v_sub_u32_e32 v34, v30, v32
	v_cndmask_b32_e32 v68, v213, v39, vcc
	v_cmp_lt_u32_e32 vcc, s79, v34
	s_and_b64 vcc, vcc, s[42:43]
	v_sub_u32_e32 v32, v31, v32
	v_cndmask_b32_e32 v40, v213, v40, vcc
	v_cmp_lt_u32_e32 vcc, s79, v32
	s_and_b64 vcc, vcc, s[42:43]
	v_sub_u32_e32 v32, v98, v88
	v_cndmask_b32_e32 v69, v213, v41, vcc
	v_cmp_lt_u32_e32 vcc, s79, v32
	s_and_b64 vcc, vcc, s[6:7]
	v_sub_u32_e32 v32, v88, v98
	v_cndmask_b32_e32 v83, v213, v50, vcc
	v_cmp_gt_u32_e32 vcc, s84, v32
	s_and_b64 vcc, vcc, s[6:7]
	v_sub_u32_e32 v32, v98, v91
	v_cndmask_b32_e32 v51, v213, v51, vcc
	v_cmp_lt_u32_e32 vcc, s79, v32
	s_and_b64 vcc, vcc, s[6:7]
	v_sub_u32_e32 v32, v98, v92
	s_add_i32 s28, s27, 6
	v_cndmask_b32_e32 v84, v213, v52, vcc
	v_cmp_lt_u32_e32 vcc, s79, v32
	v_lshl_or_b32 v32, s28, 4, v73
	v_max3_f32 v20, v18, s52, v19
	s_and_b64 vcc, vcc, s[6:7]
	v_sub_u32_e32 v34, v98, v32
	v_max3_f32 v20, v20, v21, v22
	v_cndmask_b32_e32 v85, v213, v53, vcc
	v_cmp_lt_u32_e32 vcc, s79, v34
	v_sub_u32_e32 v34, v32, v98
	v_max3_f32 v20, v20, v23, v24
	v_cndmask_b32_e32 v54, v213, v54, vcc
	v_cmp_gt_u32_e32 vcc, s84, v34
	v_sub_u32_e32 v34, v30, v32
	v_max3_f32 v20, v20, v25, v26
	v_cndmask_b32_e32 v55, v213, v55, vcc
	v_cmp_lt_u32_e32 vcc, s79, v34
	v_sub_u32_e32 v32, v31, v32
	v_max3_f32 v20, v20, v28, v29
	v_cndmask_b32_e32 v56, v213, v56, vcc
	v_cmp_lt_u32_e32 vcc, s79, v32
	v_sub_u32_e32 v32, v98, v93
	v_max3_f32 v20, v20, v44, v27
	v_cndmask_b32_e32 v57, v213, v57, vcc
	v_cmp_lt_u32_e32 vcc, s79, v32
	v_sub_u32_e32 v32, v98, v94
	v_max3_f32 v20, v20, v33, v35
	v_cndmask_b32_e32 v58, v213, v58, vcc
	v_cmp_lt_u32_e32 vcc, s79, v32
	v_sub_u32_e32 v32, v98, v95
	v_max3_f32 v20, v20, v66, v37
	v_cndmask_b32_e32 v59, v213, v59, vcc
	v_cmp_lt_u32_e32 vcc, s79, v32
	v_sub_u32_e32 v32, v98, v96
	s_or_b32 s27, s27, 8
	v_max3_f32 v20, v20, v67, v68
	v_cndmask_b32_e32 v60, v213, v60, vcc
	v_cmp_lt_u32_e32 vcc, s79, v32
	v_lshl_or_b32 v32, s27, 4, v73
	v_max3_f32 v20, v20, v40, v69
	v_sub_u32_e32 v34, v98, v32
	v_max3_f32 v20, v20, v83, v51
	v_cndmask_b32_e32 v61, v213, v61, vcc
	v_cmp_lt_u32_e32 vcc, s79, v34
	v_sub_u32_e32 v34, v32, v98
	v_max3_f32 v20, v20, v84, v85
	v_cndmask_b32_e32 v62, v213, v62, vcc
	v_cmp_gt_u32_e32 vcc, s84, v34
	v_sub_u32_e32 v30, v30, v32
	v_max3_f32 v20, v20, v54, v55
	v_cndmask_b32_e32 v63, v213, v63, vcc
	v_cmp_lt_u32_e32 vcc, s79, v30
	v_sub_u32_e32 v30, v31, v32
	v_max3_f32 v20, v20, v56, v57
	v_cndmask_b32_e32 v64, v213, v64, vcc
	v_cmp_lt_u32_e32 vcc, s79, v30
	v_sub_u32_e32 v30, v98, v82
	v_max3_f32 v20, v20, v58, v59
	v_subrev_u32_e32 v31, 48, v30
	v_max3_f32 v20, v20, v60, v61
	v_cndmask_b32_e32 v65, v213, v65, vcc
	v_cmp_gt_u32_e32 vcc, s84, v31
	v_subrev_u32_e32 v31, 49, v30
	v_max3_f32 v20, v20, v62, v63
	v_cndmask_b32_e32 v14, v213, v14, vcc
	v_cmp_gt_u32_e32 vcc, s84, v31
	v_max3_f32 v20, v20, v64, v65
	s_nop 0
	v_cndmask_b32_e32 v82, v213, v15, vcc
	v_max3_f32 v15, v20, v14, v82
	v_subrev_u32_e32 v20, 50, v30
	v_cmp_gt_u32_e32 vcc, s84, v20
	s_nop 1
	v_cndmask_b32_e32 v86, v213, v16, vcc
	v_subrev_u32_e32 v16, 51, v30
	v_cmp_gt_u32_e32 vcc, s84, v16
	s_nop 1
	v_cndmask_b32_e32 v87, v213, v17, vcc
	v_max3_f32 v15, v15, v86, v87
	ds_bpermute_b32 v16, v76, v15
	s_waitcnt lgkmcnt(0)
; __device__ __forceinline__ unsigned cvt_pk_bf16(float lo, float hi) { unsigned r; asm volatile("v_cvt_pk_bf16_f32 %0, %1, %2" : "=v"(r) : "v"(lo), "v"(hi)); return r; }
; #define LAS __attribute__((address_space(3)))
; #define MFMA16(a, b, c) __builtin_amdgcn_mfma_f32_16x16x32_bf16((a), (b), (c), 0, 0, 0)
; __device__ __forceinline__ void p2_block(LAS unsigned char* lds, const bf16_t* __restrict__ PROJ, bf16_t* __restrict__ ATT, bf16_t* __restrict__ SGU, const float* __restrict__ qn, const float* __restrict__ kn, ...
;     ...
;         mx = fmaxf(mx, __shfl_xor(mx, 16)); mx = fmaxf(mx, __shfl_xor(mx, 32)); mx = fmaxf(mx, sink);
;         float sum = 0.f;
; #pragma unroll
;         for (int t = 0; t < 10; ++t)
; #pragma unroll
;             for (int e = 0; e < 4; ++e) { const float p = __builtin_amdgcn_exp2f((sc_[t][e] - mx) * LOG2E); sc_[t][e] = p; sum += p; }
;         sum += __shfl_xor(sum, 16); sum += __shfl_xor(sum, 32);
;         const float inv = 1.0f / (sum + __builtin_amdgcn_exp2f((sink - mx) * LOG2E));
;         f32x4 o[4];
; #pragma unroll
;         for (int dt = 0; dt < 4; ++dt) o[dt] = (f32x4){0.f, 0.f, 0.f, 0.f};
; #pragma unroll
;         for (int j = 0; j < 5; ++j) {
;             u32x4 pw; pw.x = cvt_pk_bf16(sc_[2 * j][0], sc_[2 * j][1]); pw.y = cvt_pk_bf16(sc_[2 * j][2], sc_[2 * j][3]); pw.z = cvt_pk_bf16(sc_[2 * j + 1][0], sc_[2 * j + 1][1]); pw.w = cvt_pk_bf16(sc_[2 * j + 1][2], sc_[2 * j + 1][3]);
;             const bf16x8 pf = __builtin_bit_cast(bf16x8, pw);
; #pragma unroll
;             for (int dt = 0; dt < 4; ++dt) { const LAS unsigned char* vb = VT + (16 * dt + fr) * VT_STRIDE + (16 * (t0 + 2 * j) + 4 * fq) * 2;
;                 const u32x2 va = *(const LAS u32x2*)vb, vc = *(const LAS u32x2*)(vb + 32); u32x4 vw; vw.x = va.x; vw.y = va.y; vw.z = vc.x; vw.w = vc.y;
;                 o[dt] = MFMA16(__builtin_bit_cast(bf16x8, vw), pf, o[dt]); }
	v_max_f32_e32 v16, v16, v16
	v_max_f32_e32 v15, v15, v16
	ds_bpermute_b32 v16, v77, v15
	s_waitcnt lgkmcnt(0)
	v_max3_f32 v88, v15, v16, v75
	v_sub_f32_e32 v16, v19, v88
	v_mul_f32_e32 v16, 0x3fb8aa3b, v16
	v_exp_f32_e32 v36, v16
	v_sub_f32_e32 v16, v21, v88
	v_mul_f32_e32 v16, 0x3fb8aa3b, v16
	v_exp_f32_e32 v38, v16
	v_sub_f32_e32 v16, v22, v88
	v_mul_f32_e32 v16, 0x3fb8aa3b, v16
	v_exp_f32_e32 v50, v16
	v_sub_f32_e32 v16, v23, v88
	v_mul_f32_e32 v16, 0x3fb8aa3b, v16
	v_exp_f32_e32 v53, v16
	v_sub_f32_e32 v16, v24, v88
	v_mul_f32_e32 v16, 0x3fb8aa3b, v16
	v_exp_f32_e32 v89, v16
	v_sub_f32_e32 v16, v25, v88
	v_mul_f32_e32 v16, 0x3fb8aa3b, v16
	v_exp_f32_e32 v90, v16
	v_sub_f32_e32 v16, v26, v88
	v_mul_f32_e32 v16, 0x3fb8aa3b, v16
	v_exp_f32_e32 v91, v16
	v_sub_f32_e32 v16, v28, v88
	v_mul_f32_e32 v16, 0x3fb8aa3b, v16
	v_exp_f32_e32 v23, v16
	v_sub_f32_e32 v16, v29, v88
	v_mul_f32_e32 v16, 0x3fb8aa3b, v16
	v_exp_f32_e32 v31, v16
	v_sub_f32_e32 v16, v44, v88
	v_mul_f32_e32 v16, 0x3fb8aa3b, v16
	v_exp_f32_e32 v34, v16
	v_sub_f32_e32 v16, v27, v88
	v_mul_f32_e32 v16, 0x3fb8aa3b, v16
	v_sub_f32_e32 v15, v18, v88
	v_exp_f32_e32 v39, v16
	v_sub_f32_e32 v16, v33, v88
	v_mul_f32_e32 v15, 0x3fb8aa3b, v15
	v_mul_f32_e32 v16, 0x3fb8aa3b, v16
	v_exp_f32_e32 v32, v15
	v_exp_f32_e32 v41, v16
	v_sub_f32_e32 v16, v35, v88
	v_mul_f32_e32 v16, 0x3fb8aa3b, v16
	v_exp_f32_e32 v92, v16
	v_sub_f32_e32 v16, v66, v88
	v_mul_f32_e32 v16, 0x3fb8aa3b, v16
	v_add_f32_e32 v15, 0, v32
	v_exp_f32_e32 v93, v16
	v_sub_f32_e32 v16, v37, v88
	v_add_f32_e32 v15, v36, v15
	v_mul_f32_e32 v16, 0x3fb8aa3b, v16
	v_add_f32_e32 v15, v38, v15
	v_exp_f32_e32 v94, v16
	v_sub_f32_e32 v16, v67, v88
	v_add_f32_e32 v15, v50, v15
	v_mul_f32_e32 v16, 0x3fb8aa3b, v16
	v_add_f32_e32 v15, v53, v15
	v_exp_f32_e32 v19, v16
	v_sub_f32_e32 v16, v68, v88
	v_add_f32_e32 v15, v89, v15
	v_mul_f32_e32 v16, 0x3fb8aa3b, v16
	v_add_f32_e32 v15, v90, v15
	v_exp_f32_e32 v28, v16
	v_sub_f32_e32 v16, v40, v88
	v_add_f32_e32 v15, v91, v15
	v_mul_f32_e32 v16, 0x3fb8aa3b, v16
	v_add_f32_e32 v15, v23, v15
	v_exp_f32_e32 v29, v16
	v_sub_f32_e32 v16, v69, v88
	v_add_f32_e32 v15, v31, v15
	v_mul_f32_e32 v16, 0x3fb8aa3b, v16
	v_add_f32_e32 v15, v34, v15
	v_exp_f32_e32 v35, v16
	v_sub_f32_e32 v16, v83, v88
	v_add_f32_e32 v15, v39, v15
	v_mul_f32_e32 v16, 0x3fb8aa3b, v16
	v_add_f32_e32 v15, v41, v15
	v_exp_f32_e32 v37, v16
	v_sub_f32_e32 v16, v51, v88
	v_add_f32_e32 v15, v92, v15
	v_mul_f32_e32 v16, 0x3fb8aa3b, v16
	v_sub_f32_e32 v17, v55, v88
	v_add_f32_e32 v15, v93, v15
	v_exp_f32_e32 v52, v16
	v_sub_f32_e32 v16, v84, v88
	v_mul_f32_e32 v17, 0x3fb8aa3b, v17
	v_add_f32_e32 v15, v94, v15
	v_mul_f32_e32 v16, 0x3fb8aa3b, v16
	v_exp_f32_e32 v22, v17
	v_sub_f32_e32 v17, v56, v88
	v_add_f32_e32 v15, v19, v15
	v_exp_f32_e32 v95, v16
	v_sub_f32_e32 v16, v85, v88
	v_mul_f32_e32 v17, 0x3fb8aa3b, v17
	v_add_f32_e32 v15, v28, v15
	v_mul_f32_e32 v16, 0x3fb8aa3b, v16
	v_exp_f32_e32 v26, v17
	v_sub_f32_e32 v17, v57, v88
	v_add_f32_e32 v15, v29, v15
	v_exp_f32_e32 v96, v16
	v_sub_f32_e32 v16, v54, v88
	v_mul_f32_e32 v17, 0x3fb8aa3b, v17
	v_add_f32_e32 v15, v35, v15
	v_mul_f32_e32 v16, 0x3fb8aa3b, v16
	v_exp_f32_e32 v30, v17
	v_sub_f32_e32 v17, v58, v88
	v_add_f32_e32 v15, v37, v15
	v_exp_f32_e32 v16, v16
	v_mul_f32_e32 v17, 0x3fb8aa3b, v17
	v_add_f32_e32 v15, v52, v15
	v_exp_f32_e32 v33, v17
	v_sub_f32_e32 v17, v59, v88
	v_add_f32_e32 v15, v95, v15
	v_mul_f32_e32 v17, 0x3fb8aa3b, v17
	v_add_f32_e32 v15, v96, v15
	v_exp_f32_e32 v40, v17
	v_sub_f32_e32 v17, v60, v88
	v_add_f32_e32 v15, v16, v15
	v_mul_f32_e32 v17, 0x3fb8aa3b, v17
	v_add_f32_e32 v15, v22, v15
	v_exp_f32_e32 v51, v17
	v_sub_f32_e32 v17, v61, v88
	v_add_f32_e32 v15, v26, v15
	v_mul_f32_e32 v17, 0x3fb8aa3b, v17
	v_add_f32_e32 v15, v30, v15
	v_exp_f32_e32 v98, v17
	v_add_f32_e32 v15, v33, v15
	v_add_f32_e32 v15, v40, v15
	v_add_f32_e32 v15, v51, v15
	v_add_f32_e32 v17, v98, v15
	v_sub_f32_e32 v15, v62, v88
	v_mul_f32_e32 v15, 0x3fb8aa3b, v15
	v_exp_f32_e32 v15, v15
	v_sub_f32_e32 v14, v14, v88
	v_mul_f32_e32 v14, 0x3fb8aa3b, v14
	v_sub_f32_e32 v25, v86, v88
	v_add_f32_e32 v18, v15, v17
	v_sub_f32_e32 v17, v63, v88
	v_mul_f32_e32 v17, 0x3fb8aa3b, v17
	v_exp_f32_e32 v17, v17
	v_cvt_pk_bf16_f32 v54, v32, v36
	v_lshl_add_u32 v32, s4, 1, v74
	v_mul_f32_e32 v25, 0x3fb8aa3b, v25
	v_add_f32_e32 v20, v17, v18
	v_sub_f32_e32 v18, v64, v88
	v_mul_f32_e32 v18, 0x3fb8aa3b, v18
	v_exp_f32_e32 v18, v18
	v_sub_f32_e32 v27, v87, v88
	v_mad_u32_u24 v36, v137, s81, v32
	v_exp_f32_e32 v25, v25
	v_add_f32_e32 v21, v18, v20
	v_sub_f32_e32 v20, v65, v88
	v_mul_f32_e32 v20, 0x3fb8aa3b, v20
	v_exp_f32_e32 v20, v20
	v_mul_f32_e32 v27, 0x3fb8aa3b, v27
	v_add_u32_e32 v36, 0x9000, v36
	v_exp_f32_e32 v27, v27
	v_add_f32_e32 v24, v20, v21
	v_exp_f32_e32 v21, v14
	v_cvt_pk_bf16_f32 v55, v38, v50
	v_cvt_pk_bf16_f32 v56, v53, v89
	v_cvt_pk_bf16_f32 v57, v90, v91
	ds_read2_b64 v[58:61], v36 offset1:4
	v_add_f32_e32 v14, v21, v24
	v_sub_f32_e32 v24, v82, v88
	v_mul_f32_e32 v24, 0x3fb8aa3b, v24
	v_exp_f32_e32 v24, v24
	v_add_u32_e32 v36, v32, v80
	v_add_u32_e32 v36, 0x9000, v36
	ds_read2_b64 v[62:65], v36 offset1:4
	v_add_f32_e32 v14, v24, v14
	v_add_u32_e32 v36, v32, v79
	v_add_u32_e32 v32, v32, v78
	v_add_f32_e32 v14, v25, v14
	v_add_u32_e32 v36, 0x9000, v36
	v_add_u32_e32 v32, 0x9000, v32
	v_add_f32_e32 v14, v27, v14
	ds_read2_b64 v[66:69], v36 offset1:4
	ds_read2_b64 v[82:85], v32 offset1:4
	ds_bpermute_b32 v44, v76, v14
	s_waitcnt lgkmcnt(4)
	v_mfma_f32_16x16x32_bf16 v[58:61], v[58:61], v[54:57], 0
	s_or_b32 s4, s26, 48
	s_waitcnt lgkmcnt(0)
; __device__ __forceinline__ unsigned cvt_pk_bf16(float lo, float hi) { unsigned r; asm volatile("v_cvt_pk_bf16_f32 %0, %1, %2" : "=v"(r) : "v"(lo), "v"(hi)); return r; }
; #define LAS __attribute__((address_space(3)))
; #define MFMA16(a, b, c) __builtin_amdgcn_mfma_f32_16x16x32_bf16((a), (b), (c), 0, 0, 0)
; __device__ __forceinline__ void unpack8(const u32x4 w, float* f) { f[0] = bf_lo(w.x); f[1] = bf_hi(w.x); f[2] = bf_lo(w.y); f[3] = bf_hi(w.y); f[4] = bf_lo(w.z); f[5] = bf_hi(w.z); f[6] = bf_lo(w.w); f[7] = bf_hi(w.w); }
; __device__ __forceinline__ void p2_block(LAS unsigned char* lds, const bf16_t* __restrict__ PROJ, bf16_t* __restrict__ ATT, bf16_t* __restrict__ SGU, const float* __restrict__ qn, const float* __restrict__ kn, ...
;     ...
;             float x1[8], x2[8]; unpack8(qa[c], x1); unpack8(qb[c], x2);
;             float ss = 0.f;
; #pragma unroll
;             for (int j = 0; j < 8; ++j) ss += x1[j] * x1[j] + x2[j] * x2[j];
;             ss += __shfl_xor(ss, 16); ss += __shfl_xor(ss, 32);
;     ...
;         sum += __shfl_xor(sum, 16); sum += __shfl_xor(sum, 32);
;         const float inv = 1.0f / (sum + __builtin_amdgcn_exp2f((sink - mx) * LOG2E));
;         f32x4 o[4];
; #pragma unroll
;         for (int dt = 0; dt < 4; ++dt) o[dt] = (f32x4){0.f, 0.f, 0.f, 0.f};
; #pragma unroll
;         for (int j = 0; j < 5; ++j) {
;             u32x4 pw; pw.x = cvt_pk_bf16(sc_[2 * j][0], sc_[2 * j][1]); pw.y = cvt_pk_bf16(sc_[2 * j][2], sc_[2 * j][3]); pw.z = cvt_pk_bf16(sc_[2 * j + 1][0], sc_[2 * j + 1][1]); pw.w = cvt_pk_bf16(sc_[2 * j + 1][2], sc_[2 * j + 1][3]);
;             const bf16x8 pf = __builtin_bit_cast(bf16x8, pw);
; #pragma unroll
;             for (int dt = 0; dt < 4; ++dt) { const LAS unsigned char* vb = VT + (16 * dt + fr) * VT_STRIDE + (16 * (t0 + 2 * j) + 4 * fq) * 2;
;                 const u32x2 va = *(const LAS u32x2*)vb, vc = *(const LAS u32x2*)(vb + 32); u32x4 vw; vw.x = va.x; vw.y = va.y; vw.z = vc.x; vw.w = vc.y;
;                 o[dt] = MFMA16(__builtin_bit_cast(bf16x8, vw), pf, o[dt]); }
	v_add_f32_e32 v14, v14, v44
	ds_bpermute_b32 v44, v77, v14
	v_mfma_f32_16x16x32_bf16 v[62:65], v[62:65], v[54:57], 0
	s_waitcnt lgkmcnt(0)
	v_add_f32_e32 v14, v14, v44
	v_mfma_f32_16x16x32_bf16 v[66:69], v[66:69], v[54:57], 0
	v_sub_f32_e32 v44, v75, v88
	v_mul_f32_e32 v44, 0x3fb8aa3b, v44
	v_exp_f32_e32 v44, v44
	v_mfma_f32_16x16x32_bf16 v[54:57], v[82:85], v[54:57], 0
	v_cvt_pk_bf16_f32 v82, v23, v31
	v_lshl_add_u32 v23, s40, 5, v74
	v_mad_u32_u24 v31, v137, s81, v23
	v_add_u32_e32 v31, 0x9000, v31
	v_cvt_pk_bf16_f32 v83, v34, v39
	v_cvt_pk_bf16_f32 v84, v41, v92
	v_cvt_pk_bf16_f32 v85, v93, v94
	ds_read2_b64 v[86:89], v31 offset1:4
	v_add_u32_e32 v31, v23, v80
	v_add_u32_e32 v31, 0x9000, v31
	s_waitcnt lgkmcnt(0)
	v_mfma_f32_16x16x32_bf16 v[58:61], v[86:89], v[82:85], v[58:61]
	ds_read2_b64 v[86:89], v31 offset1:4
	v_add_u32_e32 v31, v23, v79
	v_add_u32_e32 v31, 0x9000, v31
	s_waitcnt lgkmcnt(0)
	v_mfma_f32_16x16x32_bf16 v[62:65], v[86:89], v[82:85], v[62:65]
	ds_read2_b64 v[86:89], v31 offset1:4
	v_add_u32_e32 v23, v23, v78
	v_add_u32_e32 v23, 0x9000, v23
	s_waitcnt lgkmcnt(0)
	v_mfma_f32_16x16x32_bf16 v[66:69], v[86:89], v[82:85], v[66:69]
	ds_read2_b64 v[86:89], v23 offset1:4
	v_cvt_pk_bf16_f32 v34, v19, v28
	v_lshl_add_u32 v19, s29, 5, v74
	v_mad_u32_u24 v23, v137, s81, v19
	v_add_u32_e32 v23, 0x9000, v23
	s_waitcnt lgkmcnt(0)
	v_mfma_f32_16x16x32_bf16 v[54:57], v[86:89], v[82:85], v[54:57]
	v_cvt_pk_bf16_f32 v35, v29, v35
	v_cvt_pk_bf16_f32 v36, v37, v52
	v_cvt_pk_bf16_f32 v37, v95, v96
	ds_read2_b64 v[82:85], v23 offset1:4
	v_add_u32_e32 v23, v19, v80
	v_add_u32_e32 v23, 0x9000, v23
	s_waitcnt lgkmcnt(0)
	v_mfma_f32_16x16x32_bf16 v[58:61], v[82:85], v[34:37], v[58:61]
	ds_read2_b64 v[82:85], v23 offset1:4
	v_add_u32_e32 v23, v19, v79
	v_add_u32_e32 v23, 0x9000, v23
	s_waitcnt lgkmcnt(0)
	v_mfma_f32_16x16x32_bf16 v[62:65], v[82:85], v[34:37], v[62:65]
	ds_read2_b64 v[82:85], v23 offset1:4
	v_add_u32_e32 v19, v19, v78
	v_add_u32_e32 v19, 0x9000, v19
	s_waitcnt lgkmcnt(0)
	v_mfma_f32_16x16x32_bf16 v[66:69], v[82:85], v[34:37], v[66:69]
	ds_read2_b64 v[82:85], v19 offset1:4
	v_cvt_pk_bf16_f32 v28, v16, v22
	v_lshl_add_u32 v16, s28, 5, v74
	v_mad_u32_u24 v19, v137, s81, v16
	v_add_u32_e32 v19, 0x9000, v19
	v_cvt_pk_bf16_f32 v29, v26, v30
	v_cvt_pk_bf16_f32 v30, v33, v40
	v_cvt_pk_bf16_f32 v31, v51, v98
	ds_read2_b64 v[38:41], v19 offset1:4
	v_add_u32_e32 v19, v16, v80
	v_add_u32_e32 v19, 0x9000, v19
	ds_read2_b64 v[50:53], v19 offset1:4
	v_add_u32_e32 v19, v16, v79
	v_add_u32_e32 v16, v16, v78
	v_add_u32_e32 v19, 0x9000, v19
	v_add_u32_e32 v16, 0x9000, v16
	s_waitcnt lgkmcnt(2)
	v_mfma_f32_16x16x32_bf16 v[34:37], v[82:85], v[34:37], v[54:57]
	v_add_f32_e32 v14, v44, v14
	v_or_b32_e32 v44, s48, v97
	s_waitcnt lgkmcnt(1)
	v_mfma_f32_16x16x32_bf16 v[38:41], v[38:41], v[28:31], v[58:61]
	ds_read2_b64 v[54:57], v19 offset1:4
	s_nop 1
	ds_read2_b64 v[58:61], v16 offset1:4
	v_cvt_pk_bf16_f32 v16, v15, v17
	v_lshl_add_u32 v15, s27, 5, v74
	v_cvt_pk_bf16_f32 v17, v18, v20
	v_mad_u32_u24 v20, v137, s81, v15
	v_add_u32_e32 v20, 0x9000, v20
	v_cvt_pk_bf16_f32 v18, v21, v24
	v_cvt_pk_bf16_f32 v19, v25, v27
	ds_read2_b64 v[20:23], v20 offset1:4
	v_add_u32_e32 v32, v15, v79
	v_add_u32_e32 v24, v15, v80
	v_add_u32_e32 v32, 0x9000, v32
	s_waitcnt lgkmcnt(3)
	v_mfma_f32_16x16x32_bf16 v[50:53], v[50:53], v[28:31], v[62:65]
	v_add_u32_e32 v24, 0x9000, v24
	ds_read2_b64 v[24:27], v24 offset1:4
	v_add_u32_e32 v15, v15, v78
	s_waitcnt lgkmcnt(3)
	v_mfma_f32_16x16x32_bf16 v[54:57], v[54:57], v[28:31], v[66:69]
	v_add_u32_e32 v15, 0x9000, v15
	v_or_b32_e32 v63, s4, v137
	v_or_b32_e32 v62, s17, v63
	s_waitcnt lgkmcnt(2)
	v_mfma_f32_16x16x32_bf16 v[28:31], v[58:61], v[28:31], v[34:37]
	v_lshlrev_b32_e32 v60, 16, v6
	v_and_b32_e32 v61, 0xffff0000, v6
	v_lshlrev_b32_e32 v58, 16, v10
	ds_read2_b64 v[32:35], v32 offset1:4
	s_waitcnt lgkmcnt(2)
	v_mfma_f32_16x16x32_bf16 v[20:23], v[20:23], v[16:19], v[38:41]
	v_and_b32_e32 v59, 0xffff0000, v10
	s_lshr_b32 s17, s4, 4
	s_min_u32 s17, s17, 6
	ds_read2_b64 v[36:39], v15 offset1:4
	s_waitcnt lgkmcnt(1)
	v_mfma_f32_16x16x32_bf16 v[32:35], v[32:35], v[16:19], v[54:57]
	s_nop 2
	v_lshlrev_b32_e32 v57, 16, v7
	v_and_b32_e32 v56, 0xffff0000, v7
	v_pk_mul_f32 v[6:7], v[60:61], v[60:61]
	v_mfma_f32_16x16x32_bf16 v[24:27], v[24:27], v[16:19], v[50:53]
	v_lshlrev_b32_e32 v55, 16, v11
	v_and_b32_e32 v54, 0xffff0000, v11
	v_lshlrev_b32_e32 v41, 16, v9
	v_lshlrev_b32_e32 v53, 16, v8
	v_and_b32_e32 v52, 0xffff0000, v8
	v_and_b32_e32 v40, 0xffff0000, v9
	v_pk_fma_f32 v[6:7], v[58:59], v[58:59], v[6:7]
	v_pk_mul_f32 v[8:9], v[56:57], v[56:57]
	v_add_f32_e32 v6, v6, v7
	v_pk_fma_f32 v[8:9], v[54:55], v[54:55], v[8:9]
	v_lshlrev_b32_e32 v51, 16, v12
	v_and_b32_e32 v50, 0xffff0000, v12
	v_pk_mul_f32 v[10:11], v[52:53], v[52:53]
	v_add_f32_e32 v6, v9, v6
	v_pk_fma_f32 v[10:11], v[50:51], v[50:51], v[10:11]
	v_add_f32_e32 v6, v8, v6
	s_waitcnt lgkmcnt(0)
	v_mfma_f32_16x16x32_bf16 v[16:19], v[36:39], v[16:19], v[28:31]
	v_lshlrev_b32_e32 v39, 16, v13
	v_and_b32_e32 v38, 0xffff0000, v13
	v_pk_mul_f32 v[12:13], v[40:41], v[40:41]
	v_add_f32_e32 v6, v11, v6
	v_pk_fma_f32 v[12:13], v[38:39], v[38:39], v[12:13]
	v_add_f32_e32 v6, v10, v6
	v_add_f32_e32 v6, v13, v6
	v_add_f32_e32 v6, v12, v6
	v_div_scale_f32 v15, s[28:29], v14, v14, 1.0
	ds_bpermute_b32 v7, v76, v6
	v_rcp_f32_e32 v28, v15
	s_lshl_b32 s28, s17, 4
	s_add_i32 s26, s28, 16
	s_add_i32 s27, s17, 2
	v_fma_f32 v29, -v15, v28, 1.0
	s_waitcnt lgkmcnt(0)
; __device__ __forceinline__ unsigned cvt_pk_bf16(float lo, float hi) { unsigned r; asm volatile("v_cvt_pk_bf16_f32 %0, %1, %2" : "=v"(r) : "v"(lo), "v"(hi)); return r; }
; #define LAS __attribute__((address_space(3)))
; #define MFMA16(a, b, c) __builtin_amdgcn_mfma_f32_16x16x32_bf16((a), (b), (c), 0, 0, 0)
; __device__ __forceinline__ void p2_block(LAS unsigned char* lds, const bf16_t* __restrict__ PROJ, bf16_t* __restrict__ ATT, bf16_t* __restrict__ SGU, const float* __restrict__ qn, const float* __restrict__ kn, ...
;     ...
;             float x1[8], x2[8]; unpack8(qa[c], x1); unpack8(qb[c], x2);
;             float ss = 0.f;
; #pragma unroll
;             for (int j = 0; j < 8; ++j) ss += x1[j] * x1[j] + x2[j] * x2[j];
;             ss += __shfl_xor(ss, 16); ss += __shfl_xor(ss, 32);
;             const float rinv = rsqrtf(ss * (1.0f / 64.0f) + pg8::EPS) * 0.125f;
;             const float* cp = COS + pos * 32 + 8 * fq; const float* sp = SIN + pos * 32 + 8 * fq;
;             float o1[8], o2[8];
; #pragma unroll
;             for (int j = 0; j < 8; ++j) { const float a1 = x1[j] * rinv * qn[8 * fq + j], a2 = x2[j] * rinv * qn[32 + 8 * fq + j], cc = cp[j], sn = sp[j]; o1[j] = a1 * cc - a2 * sn; o2[j] = a2 * cc + a1 * sn; }
;             u32x4 w0, w1;
;             w0.x = cvt_pk_bf16(o1[0], o1[1]); w0.y = cvt_pk_bf16(o1[2], o1[3]); w0.z = cvt_pk_bf16(o1[4], o1[5]); w0.w = cvt_pk_bf16(o1[6], o1[7]);
;             w1.x = cvt_pk_bf16(o2[0], o2[1]); w1.y = cvt_pk_bf16(o2[2], o2[3]); w1.z = cvt_pk_bf16(o2[4], o2[5]); w1.w = cvt_pk_bf16(o2[6], o2[7]);
;             qf0 = __builtin_bit_cast(bf16x8, w0); qf1 = __builtin_bit_cast(bf16x8, w1);
;         }
;         const int t0 = (i0 >> 4) < 6 ? (i0 >> 4) : 6;
;         f32x4 sc_[10];
;         const LAS unsigned char* kbase = KS + (16 * t0 + fr) * KS_STRIDE + 16 * fq;
; #pragma unroll
;         for (int t = 0; t < 10; ++t) { const bf16x8 k0 = *(const LAS bf16x8*)(kbase + t * 16 * KS_STRIDE), k1 = *(const LAS bf16x8*)(kbase + t * 16 * KS_STRIDE + 64);
;             f32x4 z = (f32x4){0.f, 0.f, 0.f, 0.f}; z = MFMA16(k0, qf0, z); sc_[t] = MFMA16(k1, qf1, z); }
;     ...
;         bf16_t* op = ATT + grow * 1024 + hq * 64 + 4 * fq;
; #pragma unroll
;         for (int dt = 0; dt < 4; ++dt) { u32x2 ow; ow.x = cvt_pk_bf16(o[dt][0] * inv, o[dt][1] * inv); ow.y = cvt_pk_bf16(o[dt][2] * inv, o[dt][3] * inv); *(u32x2*)(op + 16 * dt) = ow; }
	v_add_f32_e32 v6, v6, v7
	v_fmac_f32_e32 v28, v29, v28
	v_div_scale_f32 v29, vcc, 1.0, v14, 1.0
	ds_bpermute_b32 v7, v77, v6
	v_mul_f32_e32 v30, v29, v28
	v_fma_f32 v31, -v15, v30, v29
	v_fmac_f32_e32 v30, v31, v28
	v_fma_f32 v15, -v15, v30, v29
	v_div_fmas_f32 v15, v15, v28, v30
	s_waitcnt lgkmcnt(0)
	v_add_f32_e32 v6, v6, v7
	v_div_fixup_f32 v28, v15, v14, 1.0
	v_fmamk_f32 v6, v6, 0x3c800000, v209
	v_mul_f32_e32 v20, v28, v20
	v_mul_f32_e32 v21, v28, v21
	v_cmp_gt_f32_e32 vcc, s82, v6
	v_mul_f32_e32 v7, 0x4b800000, v6
	v_lshlrev_b64 v[14:15], 11, v[44:45]
	v_cvt_pk_bf16_f32 v20, v20, v21
	v_mul_f32_e32 v21, v28, v22
	v_cndmask_b32_e32 v6, v6, v7, vcc
	v_lshl_add_u64 v[14:15], v[42:43], 0, v[14:15]
	v_mul_f32_e32 v22, v28, v23
	v_cvt_pk_bf16_f32 v21, v21, v22
	v_rsq_f32_e32 v6, v6
	global_store_dwordx2 v[14:15], v[20:21], off
	v_mul_f32_e32 v20, v28, v24
	v_mul_f32_e32 v21, v28, v25
	v_cvt_pk_bf16_f32 v20, v20, v21
	v_mul_f32_e32 v21, v28, v26
	v_mul_f32_e32 v22, v28, v27
	v_cvt_pk_bf16_f32 v21, v21, v22
	global_store_dwordx2 v[14:15], v[20:21], off offset:32
	v_mul_f32_e32 v20, v28, v32
	v_mul_f32_e32 v21, v28, v33
	v_mul_f32_e32 v7, 0x45800000, v6
	v_cvt_pk_bf16_f32 v20, v20, v21
	v_mul_f32_e32 v21, v28, v34
	v_mul_f32_e32 v16, v28, v16
	v_mul_f32_e32 v17, v28, v17
	v_cndmask_b32_e32 v6, v6, v7, vcc
	v_mul_f32_e32 v22, v28, v35
	v_cvt_pk_bf16_f32 v21, v21, v22
	global_store_dwordx2 v[14:15], v[20:21], off offset:64
	v_cvt_pk_bf16_f32 v16, v16, v17
	v_mul_f32_e32 v17, v28, v18
	v_mul_f32_e32 v18, v28, v19
	v_mul_f32_e32 v44, 0x3e000000, v6
	v_lshlrev_b32_e32 v6, 7, v62
	v_mov_b32_e32 v7, v1
	v_cvt_pk_bf16_f32 v17, v17, v18
	global_store_dwordx2 v[14:15], v[16:17], off offset:96
	v_lshl_add_u64 v[18:19], v[46:47], 0, v[6:7]
	v_lshl_add_u64 v[34:35], v[48:49], 0, v[6:7]
	global_load_dwordx4 v[6:9], v0, s[38:39] offset:16
	global_load_dwordx4 v[22:25], v0, s[38:39]
	global_load_dwordx4 v[10:13], v0, s[38:39] offset:144
	global_load_dwordx4 v[30:33], v0, s[38:39] offset:128
	global_load_dwordx4 v[14:17], v[18:19], off offset:16
	global_load_dwordx4 v[26:29], v[18:19], off
	s_nop 0
	global_load_dwordx4 v[18:21], v[34:35], off offset:16
	s_nop 0
	global_load_dwordx4 v[34:37], v[34:35], off
	v_mov_b32_e32 v46, v60
	v_mov_b32_e32 v47, v58
	v_pk_mul_f32 v[46:47], v[44:45], v[46:47] op_sel_hi:[0,1]
	v_mov_b32_e32 v58, v61
	s_waitcnt vmcnt(6)
	v_mov_b32_e32 v49, v22
	s_waitcnt vmcnt(4)
	v_mov_b32_e32 v48, v30
	v_pk_mul_f32 v[46:47], v[48:49], v[46:47]
	s_waitcnt vmcnt(2)
	v_mov_b32_e32 v49, v26
	v_mov_b32_e32 v22, v31
	s_waitcnt vmcnt(0)
	v_mov_b32_e32 v48, v34
	v_pk_mul_f32 v[48:49], v[48:49], v[46:47]
	s_nop 0
	v_sub_f32_e32 v60, v49, v48
	v_mov_b32_e32 v48, v26
	v_mov_b32_e32 v49, v34
	v_pk_mul_f32 v[46:47], v[48:49], v[46:47]
	v_mov_b32_e32 v26, v35
	v_add_f32_e32 v48, v46, v47
	v_pk_mul_f32 v[46:47], v[44:45], v[58:59] op_sel_hi:[0,1]
	v_pk_mul_f32 v[22:23], v[22:23], v[46:47]
	v_mov_b32_e32 v34, v27
	v_pk_mul_f32 v[30:31], v[26:27], v[22:23]
	v_pk_mul_f32 v[22:23], v[34:35], v[22:23]
	v_sub_f32_e32 v30, v31, v30
	v_add_f32_e32 v31, v22, v23
	v_mov_b32_e32 v22, v57
	v_mov_b32_e32 v23, v55
	v_pk_mul_f32 v[22:23], v[44:45], v[22:23] op_sel_hi:[0,1]
	v_mov_b32_e32 v26, v32
	v_mov_b32_e32 v27, v24
	v_pk_mul_f32 v[22:23], v[26:27], v[22:23]
	v_mov_b32_e32 v26, v36
	v_mov_b32_e32 v27, v28
	v_pk_mul_f32 v[26:27], v[26:27], v[22:23]
	v_mov_b32_e32 v57, v54
	v_sub_f32_e32 v32, v27, v26
	v_mov_b32_e32 v26, v28
	v_mov_b32_e32 v27, v36
	v_pk_mul_f32 v[22:23], v[26:27], v[22:23]
	v_mov_b32_e32 v24, v33
	v_add_f32_e32 v26, v22, v23
	v_pk_mul_f32 v[22:23], v[44:45], v[56:57] op_sel_hi:[0,1]
	v_pk_mul_f32 v[22:23], v[22:23], v[24:25]
	v_mov_b32_e32 v28, v37
	v_mov_b32_e32 v36, v29
	v_pk_mul_f32 v[24:25], v[22:23], v[28:29]
	v_pk_mul_f32 v[22:23], v[22:23], v[36:37]
	v_sub_f32_e32 v27, v25, v24
	v_add_f32_e32 v28, v22, v23
	v_mov_b32_e32 v22, v53
	v_mov_b32_e32 v23, v51
	v_pk_mul_f32 v[22:23], v[44:45], v[22:23] op_sel_hi:[0,1]
	v_mov_b32_e32 v24, v10
	v_mov_b32_e32 v25, v6
	v_pk_mul_f32 v[22:23], v[22:23], v[24:25]
	v_mov_b32_e32 v24, v18
	v_mov_b32_e32 v25, v14
	v_pk_mul_f32 v[24:25], v[22:23], v[24:25]
	v_mov_b32_e32 v53, v50
	v_sub_f32_e32 v29, v25, v24
	v_mov_b32_e32 v24, v14
	v_mov_b32_e32 v25, v18
	v_pk_mul_f32 v[22:23], v[22:23], v[24:25]
	v_mov_b32_e32 v6, v11
	v_add_f32_e32 v24, v22, v23
	v_pk_mul_f32 v[22:23], v[44:45], v[52:53] op_sel_hi:[0,1]
	v_pk_mul_f32 v[6:7], v[22:23], v[6:7]
	v_mov_b32_e32 v14, v19
	v_mov_b32_e32 v18, v15
	v_pk_mul_f32 v[10:11], v[6:7], v[14:15]
	v_pk_mul_f32 v[6:7], v[6:7], v[18:19]
	v_sub_f32_e32 v14, v11, v10
	v_add_f32_e32 v15, v6, v7
	v_mov_b32_e32 v6, v41
	v_mov_b32_e32 v7, v39
	v_pk_mul_f32 v[6:7], v[44:45], v[6:7] op_sel_hi:[0,1]
	v_mov_b32_e32 v10, v12
	v_mov_b32_e32 v11, v8
	v_pk_mul_f32 v[6:7], v[6:7], v[10:11]
	v_mov_b32_e32 v10, v20
	v_mov_b32_e32 v11, v16
	v_pk_mul_f32 v[10:11], v[6:7], v[10:11]
	v_mov_b32_e32 v41, v38
	v_sub_f32_e32 v12, v11, v10
	v_mov_b32_e32 v10, v16
	v_mov_b32_e32 v11, v20
	v_pk_mul_f32 v[6:7], v[6:7], v[10:11]
	v_mov_b32_e32 v8, v13
	v_add_f32_e32 v18, v6, v7
	v_pk_mul_f32 v[6:7], v[44:45], v[40:41] op_sel_hi:[0,1]
	v_pk_mul_f32 v[6:7], v[6:7], v[8:9]
	v_mov_b32_e32 v16, v21
	v_mov_b32_e32 v20, v17
	v_pk_mul_f32 v[8:9], v[6:7], v[16:17]
	v_pk_mul_f32 v[6:7], v[6:7], v[20:21]
	v_sub_f32_e32 v9, v9, v8
	v_add_f32_e32 v13, v6, v7
	v_cvt_pk_bf16_f32 v6, v60, v30
	v_cvt_pk_bf16_f32 v7, v32, v27
	v_cvt_pk_bf16_f32 v8, v29, v14
	v_or_b32_e32 v14, s28, v137
	v_mad_u32_u24 v44, v14, s59, v81
	v_cvt_pk_bf16_f32 v9, v12, v9
	v_cvt_pk_bf16_f32 v10, v48, v31
	v_cvt_pk_bf16_f32 v11, v26, v28
	v_cvt_pk_bf16_f32 v12, v24, v15
	v_cvt_pk_bf16_f32 v13, v18, v13
	ds_read_b128 v[14:17], v44
	ds_read_b128 v[18:21], v44 offset:64
	s_waitcnt lgkmcnt(1)
; #define LAS __attribute__((address_space(3)))
; #define MFMA16(a, b, c) __builtin_amdgcn_mfma_f32_16x16x32_bf16((a), (b), (c), 0, 0, 0)
; __device__ __forceinline__ void p2_block(LAS unsigned char* lds, const bf16_t* __restrict__ PROJ, bf16_t* __restrict__ ATT, bf16_t* __restrict__ SGU, const float* __restrict__ qn, const float* __restrict__ kn, ...
;     ...
;         const LAS unsigned char* kbase = KS + (16 * t0 + fr) * KS_STRIDE + 16 * fq;
; #pragma unroll
;         for (int t = 0; t < 10; ++t) { const bf16x8 k0 = *(const LAS bf16x8*)(kbase + t * 16 * KS_STRIDE), k1 = *(const LAS bf16x8*)(kbase + t * 16 * KS_STRIDE + 64);
;             f32x4 z = (f32x4){0.f, 0.f, 0.f, 0.f}; z = MFMA16(k0, qf0, z); sc_[t] = MFMA16(k1, qf1, z); }
;         float mx = -1e30f;
; #pragma unroll
;         for (int t = 0; t < 10; ++t)
; #pragma unroll
;             for (int e = 0; e < 4; ++e) { const int kx = 16 * (t0 + t) + 4 * fq + e, d = kx - irow; const bool ok = (d >= 1) && (d <= 128) && (n > 0 || kx >= 128);
;                 const float v = ok ? sc_[t][e] : -1e30f; sc_[t][e] = v; mx = fmaxf(mx, v); }
	v_mfma_f32_16x16x32_bf16 v[14:17], v[14:17], v[6:9], 0
	s_waitcnt lgkmcnt(0)
	v_mfma_f32_16x16x32_bf16 v[14:17], v[18:21], v[10:13], v[14:17]
	ds_read_b128 v[18:21], v44 offset:2304
	ds_read_b128 v[22:25], v44 offset:2368
	s_waitcnt lgkmcnt(1)
	v_mfma_f32_16x16x32_bf16 v[18:21], v[18:21], v[6:9], 0
	s_waitcnt lgkmcnt(0)
	v_mfma_f32_16x16x32_bf16 v[18:21], v[22:25], v[10:13], v[18:21]
	ds_read_b128 v[22:25], v44 offset:4608
	ds_read_b128 v[26:29], v44 offset:4672
	s_waitcnt lgkmcnt(1)
	v_mfma_f32_16x16x32_bf16 v[22:25], v[22:25], v[6:9], 0
	s_waitcnt lgkmcnt(0)
	v_mfma_f32_16x16x32_bf16 v[22:25], v[26:29], v[10:13], v[22:25]
	ds_read_b128 v[26:29], v44 offset:6912
	ds_read_b128 v[30:33], v44 offset:6976
	s_waitcnt lgkmcnt(1)
	v_mfma_f32_16x16x32_bf16 v[26:29], v[26:29], v[6:9], 0
	s_waitcnt lgkmcnt(0)
	v_mfma_f32_16x16x32_bf16 v[26:29], v[30:33], v[10:13], v[26:29]
	ds_read_b128 v[30:33], v44 offset:9216
	ds_read_b128 v[34:37], v44 offset:9280
	s_waitcnt lgkmcnt(1)
	v_mfma_f32_16x16x32_bf16 v[30:33], v[30:33], v[6:9], 0
	s_waitcnt lgkmcnt(0)
	v_mfma_f32_16x16x32_bf16 v[30:33], v[34:37], v[10:13], v[30:33]
	ds_read_b128 v[34:37], v44 offset:11520
	ds_read_b128 v[38:41], v44 offset:11584
	s_waitcnt lgkmcnt(1)
	v_mfma_f32_16x16x32_bf16 v[34:37], v[34:37], v[6:9], 0
	s_waitcnt lgkmcnt(0)
	v_mfma_f32_16x16x32_bf16 v[34:37], v[38:41], v[10:13], v[34:37]
	ds_read_b128 v[38:41], v44 offset:13824
	ds_read_b128 v[46:49], v44 offset:13888
	s_waitcnt lgkmcnt(1)
	v_mfma_f32_16x16x32_bf16 v[38:41], v[38:41], v[6:9], 0
	s_waitcnt lgkmcnt(0)
	v_mfma_f32_16x16x32_bf16 v[38:41], v[46:49], v[10:13], v[38:41]
	ds_read_b128 v[46:49], v44 offset:16128
	ds_read_b128 v[50:53], v44 offset:16192
	s_waitcnt lgkmcnt(1)
	v_mfma_f32_16x16x32_bf16 v[46:49], v[46:49], v[6:9], 0
	s_waitcnt lgkmcnt(0)
	v_mfma_f32_16x16x32_bf16 v[46:49], v[50:53], v[10:13], v[46:49]
	ds_read_b128 v[50:53], v44 offset:18432
	ds_read_b128 v[54:57], v44 offset:18496
	s_waitcnt lgkmcnt(1)
	v_mfma_f32_16x16x32_bf16 v[50:53], v[50:53], v[6:9], 0
	s_waitcnt lgkmcnt(0)
	v_mfma_f32_16x16x32_bf16 v[50:53], v[54:57], v[10:13], v[50:53]
	ds_read_b128 v[54:57], v44 offset:20736
	ds_read_b128 v[58:61], v44 offset:20800
	s_waitcnt lgkmcnt(1)
	v_mfma_f32_16x16x32_bf16 v[6:9], v[54:57], v[6:9], 0
	s_waitcnt lgkmcnt(0)
	v_mfma_f32_16x16x32_bf16 v[6:9], v[58:61], v[10:13], v[6:9]
	v_or_b32_e32 v10, s28, v73
	v_sub_u32_e32 v11, v63, v10
	v_cmp_lt_u32_e32 vcc, s79, v11
	s_and_b64 vcc, s[50:51], vcc
	v_sub_u32_e32 v12, v10, v63
	v_cndmask_b32_e32 v11, v213, v14, vcc
	v_cmp_gt_u32_e32 vcc, s84, v12
	s_and_b64 vcc, s[50:51], vcc
	v_add_u32_e32 v14, -2, v63
	v_cndmask_b32_e32 v12, v213, v15, vcc
	v_sub_u32_e32 v15, v14, v10
	v_cmp_lt_u32_e32 vcc, s79, v15
	s_and_b64 vcc, s[50:51], vcc
	v_max3_f32 v13, v11, s52, v12
	v_cndmask_b32_e32 v15, v213, v16, vcc
	v_add_u32_e32 v16, -3, v63
	v_sub_u32_e32 v10, v16, v10
	v_cmp_lt_u32_e32 vcc, s79, v10
	s_and_b64 vcc, s[50:51], vcc
	s_nop 0
	v_cndmask_b32_e32 v10, v213, v17, vcc
	v_or_b32_e32 v17, s26, v73
	v_sub_u32_e32 v44, v63, v17
	v_cmp_lt_u32_e32 vcc, s79, v44
	s_and_b64 vcc, s[50:51], vcc
	v_sub_u32_e32 v44, v17, v63
	v_cndmask_b32_e32 v18, v213, v18, vcc
	v_cmp_gt_u32_e32 vcc, s84, v44
	s_and_b64 vcc, s[50:51], vcc
	v_sub_u32_e32 v44, v14, v17
	v_cndmask_b32_e32 v19, v213, v19, vcc
	v_cmp_lt_u32_e32 vcc, s79, v44
	s_and_b64 vcc, s[50:51], vcc
	v_sub_u32_e32 v17, v16, v17
	v_cndmask_b32_e32 v20, v213, v20, vcc
	v_cmp_lt_u32_e32 vcc, s79, v17
	s_and_b64 vcc, s[50:51], vcc
	s_cmpk_gt_u32 s4, 0x50
	v_cndmask_b32_e32 v17, v213, v21, vcc
	v_lshl_or_b32 v21, s27, 4, v73
	v_sub_u32_e32 v44, v63, v21
	s_cselect_b64 s[40:41], -1, 0
	v_cmp_lt_u32_e32 vcc, s79, v44
	s_or_b64 s[40:41], s[50:51], s[40:41]
	s_and_b64 vcc, vcc, s[40:41]
	v_sub_u32_e32 v44, v21, v63
	v_cndmask_b32_e32 v22, v213, v22, vcc
	v_cmp_gt_u32_e32 vcc, s84, v44
	s_and_b64 vcc, vcc, s[40:41]
	v_sub_u32_e32 v44, v14, v21
	v_cndmask_b32_e32 v23, v213, v23, vcc
	v_cmp_lt_u32_e32 vcc, s79, v44
	s_and_b64 vcc, vcc, s[40:41]
	v_sub_u32_e32 v21, v16, v21
	v_cndmask_b32_e32 v44, v213, v24, vcc
	v_cmp_lt_u32_e32 vcc, s79, v21
	s_and_b64 vcc, vcc, s[40:41]
	s_add_i32 s26, s28, 48
	v_or_b32_e32 v21, s26, v73
	s_cmp_gt_u32 s4, 64
	v_sub_u32_e32 v24, v63, v21
	s_cselect_b64 s[40:41], -1, 0
	v_cndmask_b32_e32 v25, v213, v25, vcc
	v_cmp_lt_u32_e32 vcc, s79, v24
	s_or_b64 s[40:41], s[50:51], s[40:41]
	s_and_b64 vcc, vcc, s[40:41]
	v_sub_u32_e32 v24, v21, v63
	v_cndmask_b32_e32 v54, v213, v26, vcc
	v_cmp_gt_u32_e32 vcc, s84, v24
	s_and_b64 vcc, vcc, s[40:41]
	v_sub_u32_e32 v24, v14, v21
	v_cndmask_b32_e32 v27, v213, v27, vcc
	v_cmp_lt_u32_e32 vcc, s79, v24
	s_and_b64 vcc, vcc, s[40:41]
	v_sub_u32_e32 v21, v16, v21
	s_add_i32 s26, s17, 4
	v_cndmask_b32_e32 v55, v213, v28, vcc
	v_cmp_lt_u32_e32 vcc, s79, v21
	v_lshl_or_b32 v21, s26, 4, v73
	s_and_b64 vcc, vcc, s[40:41]
	v_sub_u32_e32 v24, v63, v21
	v_cndmask_b32_e32 v29, v213, v29, vcc
	v_cmp_lt_u32_e32 vcc, s79, v24
	s_and_b64 vcc, vcc, s[6:7]
	v_sub_u32_e32 v24, v21, v63
	v_cndmask_b32_e32 v56, v213, v30, vcc
	v_cmp_gt_u32_e32 vcc, s84, v24
	s_and_b64 vcc, vcc, s[6:7]
	v_sub_u32_e32 v24, v14, v21
	v_cndmask_b32_e32 v57, v213, v31, vcc
	v_cmp_lt_u32_e32 vcc, s79, v24
	s_and_b64 vcc, vcc, s[6:7]
	v_sub_u32_e32 v21, v16, v21
	s_add_i32 s4, s28, 0x50
	v_cndmask_b32_e32 v32, v213, v32, vcc
	v_cmp_lt_u32_e32 vcc, s79, v21
	v_or_b32_e32 v21, s4, v73
	s_and_b64 vcc, vcc, s[6:7]
	v_sub_u32_e32 v24, v63, v21
	v_cndmask_b32_e32 v58, v213, v33, vcc
	v_cmp_lt_u32_e32 vcc, s79, v24
	v_sub_u32_e32 v24, v21, v63
	s_add_i32 s6, s17, 6
	v_cndmask_b32_e32 v59, v213, v34, vcc
	v_cmp_gt_u32_e32 vcc, s84, v24
; __device__ __forceinline__ void p2_block(LAS unsigned char* lds, const bf16_t* __restrict__ PROJ, bf16_t* __restrict__ ATT, bf16_t* __restrict__ SGU, const float* __restrict__ qn, const float* __restrict__ kn, ...
;     ...
;         for (int t = 0; t < 10; ++t)
; #pragma unroll
;             for (int e = 0; e < 4; ++e) { const int kx = 16 * (t0 + t) + 4 * fq + e, d = kx - irow; const bool ok = (d >= 1) && (d <= 128) && (n > 0 || kx >= 128);
;                 const float v = ok ? sc_[t][e] : -1e30f; sc_[t][e] = v; mx = fmaxf(mx, v); }
;         mx = fmaxf(mx, __shfl_xor(mx, 16)); mx = fmaxf(mx, __shfl_xor(mx, 32)); mx = fmaxf(mx, sink);
;         float sum = 0.f;
; #pragma unroll
;         for (int t = 0; t < 10; ++t)
; #pragma unroll
;             for (int e = 0; e < 4; ++e) { const float p = __builtin_amdgcn_exp2f((sc_[t][e] - mx) * LOG2E); sc_[t][e] = p; sum += p; }
;         sum += __shfl_xor(sum, 16); sum += __shfl_xor(sum, 32);
;         const float inv = 1.0f / (sum + __builtin_amdgcn_exp2f((sink - mx) * LOG2E));
	v_sub_u32_e32 v24, v14, v21
	v_sub_u32_e32 v21, v16, v21
	v_cndmask_b32_e32 v35, v213, v35, vcc
	v_cmp_lt_u32_e32 vcc, s79, v24
	v_max3_f32 v13, v13, v15, v10
	v_max3_f32 v13, v13, v18, v19
	v_cndmask_b32_e32 v60, v213, v36, vcc
	v_cmp_lt_u32_e32 vcc, s79, v21
	v_lshl_or_b32 v21, s6, 4, v73
	v_sub_u32_e32 v24, v63, v21
	v_cndmask_b32_e32 v61, v213, v37, vcc
	v_cmp_lt_u32_e32 vcc, s79, v24
	v_sub_u32_e32 v24, v21, v63
	s_add_i32 s4, s28, 0x70
	v_cndmask_b32_e32 v38, v213, v38, vcc
	v_cmp_gt_u32_e32 vcc, s84, v24
	v_sub_u32_e32 v24, v14, v21
	v_sub_u32_e32 v21, v16, v21
	v_cndmask_b32_e32 v39, v213, v39, vcc
	v_cmp_lt_u32_e32 vcc, s79, v24
	v_max3_f32 v13, v13, v20, v17
	v_max3_f32 v13, v13, v22, v23
	v_cndmask_b32_e32 v40, v213, v40, vcc
	v_cmp_lt_u32_e32 vcc, s79, v21
	v_or_b32_e32 v21, s4, v73
	v_sub_u32_e32 v24, v63, v21
	v_max3_f32 v13, v13, v44, v25
	v_cndmask_b32_e32 v41, v213, v41, vcc
	v_cmp_lt_u32_e32 vcc, s79, v24
	v_sub_u32_e32 v24, v21, v63
	v_max3_f32 v13, v13, v54, v27
	v_cndmask_b32_e32 v46, v213, v46, vcc
	v_cmp_gt_u32_e32 vcc, s84, v24
	v_sub_u32_e32 v24, v14, v21
	v_max3_f32 v13, v13, v55, v29
	v_cndmask_b32_e32 v47, v213, v47, vcc
	v_cmp_lt_u32_e32 vcc, s79, v24
	v_sub_u32_e32 v21, v16, v21
	s_or_b32 s4, s17, 8
	v_max3_f32 v13, v13, v56, v57
	v_cndmask_b32_e32 v48, v213, v48, vcc
	v_cmp_lt_u32_e32 vcc, s79, v21
	v_lshl_or_b32 v21, s4, 4, v73
	v_max3_f32 v13, v13, v32, v58
	v_sub_u32_e32 v24, v63, v21
	v_max3_f32 v13, v13, v59, v35
	v_cndmask_b32_e32 v49, v213, v49, vcc
	v_cmp_lt_u32_e32 vcc, s79, v24
	v_sub_u32_e32 v24, v21, v63
	v_max3_f32 v13, v13, v60, v61
	v_cndmask_b32_e32 v50, v213, v50, vcc
	v_cmp_gt_u32_e32 vcc, s84, v24
	v_sub_u32_e32 v24, v14, v21
	v_max3_f32 v13, v13, v38, v39
	v_cndmask_b32_e32 v51, v213, v51, vcc
	v_cmp_lt_u32_e32 vcc, s79, v24
	v_sub_u32_e32 v21, v16, v21
	s_addk_i32 s28, 0x90
	v_max3_f32 v13, v13, v40, v41
	v_cndmask_b32_e32 v52, v213, v52, vcc
	v_cmp_lt_u32_e32 vcc, s79, v21
	v_or_b32_e32 v21, s28, v73
	v_max3_f32 v13, v13, v46, v47
	v_sub_u32_e32 v24, v63, v21
	v_max3_f32 v13, v13, v48, v49
	v_cndmask_b32_e32 v53, v213, v53, vcc
	v_cmp_lt_u32_e32 vcc, s79, v24
	v_sub_u32_e32 v24, v21, v63
	v_max3_f32 v13, v13, v50, v51
	v_cndmask_b32_e32 v6, v213, v6, vcc
	v_cmp_gt_u32_e32 vcc, s84, v24
	v_max3_f32 v13, v13, v52, v53
	s_nop 0
	v_cndmask_b32_e32 v63, v213, v7, vcc
	v_max3_f32 v7, v13, v6, v63
	v_sub_u32_e32 v13, v14, v21
	v_cmp_lt_u32_e32 vcc, s79, v13
	s_nop 1
	v_cndmask_b32_e32 v64, v213, v8, vcc
	v_sub_u32_e32 v8, v16, v21
	v_cmp_lt_u32_e32 vcc, s79, v8
	s_nop 1
	v_cndmask_b32_e32 v65, v213, v9, vcc
	v_max3_f32 v7, v7, v64, v65
	ds_bpermute_b32 v8, v76, v7
	s_waitcnt lgkmcnt(0)
	v_max_f32_e32 v8, v8, v8
	v_max_f32_e32 v7, v7, v8
	ds_bpermute_b32 v8, v77, v7
	s_waitcnt lgkmcnt(0)
	v_max3_f32 v66, v7, v8, v75
	v_sub_f32_e32 v8, v12, v66
	v_mul_f32_e32 v8, 0x3fb8aa3b, v8
	v_exp_f32_e32 v28, v8
	v_sub_f32_e32 v8, v15, v66
	v_mul_f32_e32 v8, 0x3fb8aa3b, v8
	v_exp_f32_e32 v30, v8
	v_sub_f32_e32 v8, v10, v66
	v_mul_f32_e32 v8, 0x3fb8aa3b, v8
	v_exp_f32_e32 v34, v8
	v_sub_f32_e32 v8, v18, v66
	v_mul_f32_e32 v8, 0x3fb8aa3b, v8
	v_exp_f32_e32 v37, v8
	v_sub_f32_e32 v8, v19, v66
	v_mul_f32_e32 v8, 0x3fb8aa3b, v8
	v_exp_f32_e32 v67, v8
	v_sub_f32_e32 v8, v20, v66
	v_mul_f32_e32 v8, 0x3fb8aa3b, v8
	v_exp_f32_e32 v68, v8
	v_sub_f32_e32 v8, v17, v66
	v_mul_f32_e32 v8, 0x3fb8aa3b, v8
	v_exp_f32_e32 v69, v8
	v_sub_f32_e32 v8, v22, v66
	v_mul_f32_e32 v8, 0x3fb8aa3b, v8
	v_exp_f32_e32 v15, v8
	v_sub_f32_e32 v8, v23, v66
	v_mul_f32_e32 v8, 0x3fb8aa3b, v8
	v_exp_f32_e32 v24, v8
	v_sub_f32_e32 v8, v44, v66
	v_mul_f32_e32 v8, 0x3fb8aa3b, v8
	v_exp_f32_e32 v26, v8
	v_sub_f32_e32 v8, v25, v66
	v_mul_f32_e32 v8, 0x3fb8aa3b, v8
	v_sub_f32_e32 v7, v11, v66
	v_exp_f32_e32 v31, v8
	v_sub_f32_e32 v8, v54, v66
	v_mul_f32_e32 v7, 0x3fb8aa3b, v7
	v_mul_f32_e32 v8, 0x3fb8aa3b, v8
	v_exp_f32_e32 v21, v7
	v_exp_f32_e32 v33, v8
	v_sub_f32_e32 v8, v27, v66
	v_mul_f32_e32 v8, 0x3fb8aa3b, v8
	v_exp_f32_e32 v81, v8
	v_sub_f32_e32 v8, v55, v66
	v_mul_f32_e32 v8, 0x3fb8aa3b, v8
	v_add_f32_e32 v7, 0, v21
	v_exp_f32_e32 v82, v8
	v_sub_f32_e32 v8, v29, v66
	v_add_f32_e32 v7, v28, v7
	v_mul_f32_e32 v8, 0x3fb8aa3b, v8
	v_add_f32_e32 v7, v30, v7
	v_exp_f32_e32 v83, v8
	v_sub_f32_e32 v8, v56, v66
	v_add_f32_e32 v7, v34, v7
	v_mul_f32_e32 v8, 0x3fb8aa3b, v8
	v_add_f32_e32 v7, v37, v7
	v_exp_f32_e32 v11, v8
	v_sub_f32_e32 v8, v57, v66
	v_add_f32_e32 v7, v67, v7
	v_mul_f32_e32 v8, 0x3fb8aa3b, v8
	v_add_f32_e32 v7, v68, v7
	v_exp_f32_e32 v20, v8
	v_sub_f32_e32 v8, v32, v66
	v_add_f32_e32 v7, v69, v7
	v_mul_f32_e32 v8, 0x3fb8aa3b, v8
	v_add_f32_e32 v7, v15, v7
	v_exp_f32_e32 v22, v8
	v_sub_f32_e32 v8, v58, v66
	v_add_f32_e32 v7, v24, v7
	v_mul_f32_e32 v8, 0x3fb8aa3b, v8
	v_add_f32_e32 v7, v26, v7
	v_exp_f32_e32 v27, v8
	v_sub_f32_e32 v8, v59, v66
	v_add_f32_e32 v7, v31, v7
	v_mul_f32_e32 v8, 0x3fb8aa3b, v8
	v_add_f32_e32 v7, v33, v7
	v_exp_f32_e32 v29, v8
	v_sub_f32_e32 v8, v35, v66
	v_add_f32_e32 v7, v81, v7
	v_mul_f32_e32 v8, 0x3fb8aa3b, v8
	v_sub_f32_e32 v9, v39, v66
	v_add_f32_e32 v7, v82, v7
	v_exp_f32_e32 v36, v8
	v_sub_f32_e32 v8, v60, v66
	v_mul_f32_e32 v9, 0x3fb8aa3b, v9
	v_add_f32_e32 v7, v83, v7
	v_mul_f32_e32 v8, 0x3fb8aa3b, v8
	v_exp_f32_e32 v14, v9
	v_sub_f32_e32 v9, v40, v66
	v_add_f32_e32 v7, v11, v7
	v_exp_f32_e32 v84, v8
	v_sub_f32_e32 v8, v61, v66
	v_mul_f32_e32 v9, 0x3fb8aa3b, v9
	v_add_f32_e32 v7, v20, v7
	v_mul_f32_e32 v8, 0x3fb8aa3b, v8
	v_exp_f32_e32 v18, v9
	v_sub_f32_e32 v9, v41, v66
	v_add_f32_e32 v7, v22, v7
	v_exp_f32_e32 v85, v8
	v_sub_f32_e32 v8, v38, v66
	v_mul_f32_e32 v9, 0x3fb8aa3b, v9
	v_add_f32_e32 v7, v27, v7
; __device__ __forceinline__ unsigned cvt_pk_bf16(float lo, float hi) { unsigned r; asm volatile("v_cvt_pk_bf16_f32 %0, %1, %2" : "=v"(r) : "v"(lo), "v"(hi)); return r; }
; #define LAS __attribute__((address_space(3)))
; #define MFMA16(a, b, c) __builtin_amdgcn_mfma_f32_16x16x32_bf16((a), (b), (c), 0, 0, 0)
; __device__ __forceinline__ void p2_block(LAS unsigned char* lds, const bf16_t* __restrict__ PROJ, bf16_t* __restrict__ ATT, bf16_t* __restrict__ SGU, const float* __restrict__ qn, const float* __restrict__ kn, ...
;     ...
;             for (int e = 0; e < 4; ++e) { const float p = __builtin_amdgcn_exp2f((sc_[t][e] - mx) * LOG2E); sc_[t][e] = p; sum += p; }
;         sum += __shfl_xor(sum, 16); sum += __shfl_xor(sum, 32);
;         const float inv = 1.0f / (sum + __builtin_amdgcn_exp2f((sink - mx) * LOG2E));
;         f32x4 o[4];
; #pragma unroll
;         for (int dt = 0; dt < 4; ++dt) o[dt] = (f32x4){0.f, 0.f, 0.f, 0.f};
; #pragma unroll
;         for (int j = 0; j < 5; ++j) {
;             u32x4 pw; pw.x = cvt_pk_bf16(sc_[2 * j][0], sc_[2 * j][1]); pw.y = cvt_pk_bf16(sc_[2 * j][2], sc_[2 * j][3]); pw.z = cvt_pk_bf16(sc_[2 * j + 1][0], sc_[2 * j + 1][1]); pw.w = cvt_pk_bf16(sc_[2 * j + 1][2], sc_[2 * j + 1][3]);
;             const bf16x8 pf = __builtin_bit_cast(bf16x8, pw);
; #pragma unroll
;             for (int dt = 0; dt < 4; ++dt) { const LAS unsigned char* vb = VT + (16 * dt + fr) * VT_STRIDE + (16 * (t0 + 2 * j) + 4 * fq) * 2;
;                 const u32x2 va = *(const LAS u32x2*)vb, vc = *(const LAS u32x2*)(vb + 32); u32x4 vw; vw.x = va.x; vw.y = va.y; vw.z = vc.x; vw.w = vc.y;
;                 o[dt] = MFMA16(__builtin_bit_cast(bf16x8, vw), pf, o[dt]); }
	v_mul_f32_e32 v8, 0x3fb8aa3b, v8
	v_exp_f32_e32 v23, v9
	v_sub_f32_e32 v9, v46, v66
	v_add_f32_e32 v7, v29, v7
	v_exp_f32_e32 v8, v8
	v_mul_f32_e32 v9, 0x3fb8aa3b, v9
	v_add_f32_e32 v7, v36, v7
	v_exp_f32_e32 v25, v9
	v_sub_f32_e32 v9, v47, v66
	v_add_f32_e32 v7, v84, v7
	v_mul_f32_e32 v9, 0x3fb8aa3b, v9
	v_add_f32_e32 v7, v85, v7
	v_exp_f32_e32 v32, v9
	v_sub_f32_e32 v9, v48, v66
	v_add_f32_e32 v7, v8, v7
	v_mul_f32_e32 v9, 0x3fb8aa3b, v9
	v_add_f32_e32 v7, v14, v7
	v_exp_f32_e32 v35, v9
	v_sub_f32_e32 v9, v49, v66
	v_add_f32_e32 v7, v18, v7
	v_mul_f32_e32 v9, 0x3fb8aa3b, v9
	v_add_f32_e32 v7, v23, v7
	v_exp_f32_e32 v86, v9
	v_add_f32_e32 v7, v25, v7
	v_add_f32_e32 v7, v32, v7
	v_add_f32_e32 v7, v35, v7
	v_add_f32_e32 v9, v86, v7
	v_sub_f32_e32 v7, v50, v66
	v_mul_f32_e32 v7, 0x3fb8aa3b, v7
	v_exp_f32_e32 v7, v7
	v_sub_f32_e32 v6, v6, v66
	v_mul_f32_e32 v6, 0x3fb8aa3b, v6
	v_sub_f32_e32 v17, v64, v66
	v_add_f32_e32 v10, v7, v9
	v_sub_f32_e32 v9, v51, v66
	v_mul_f32_e32 v9, 0x3fb8aa3b, v9
	v_exp_f32_e32 v9, v9
	v_mul_f32_e32 v17, 0x3fb8aa3b, v17
	v_sub_f32_e32 v19, v65, v66
	v_exp_f32_e32 v17, v17
	v_add_f32_e32 v12, v9, v10
	v_sub_f32_e32 v10, v52, v66
	v_mul_f32_e32 v10, 0x3fb8aa3b, v10
	v_exp_f32_e32 v10, v10
	v_mul_f32_e32 v19, 0x3fb8aa3b, v19
	v_exp_f32_e32 v19, v19
	v_or_b32_e32 v44, s48, v62
	v_add_f32_e32 v13, v10, v12
	v_sub_f32_e32 v12, v53, v66
	v_mul_f32_e32 v12, 0x3fb8aa3b, v12
	v_exp_f32_e32 v12, v12
	s_nop 0
	v_add_f32_e32 v16, v12, v13
	v_exp_f32_e32 v13, v6
	s_nop 0
	v_add_f32_e32 v6, v13, v16
	v_sub_f32_e32 v16, v63, v66
	v_mul_f32_e32 v16, 0x3fb8aa3b, v16
	v_exp_f32_e32 v16, v16
	s_nop 0
	v_add_f32_e32 v6, v16, v6
	v_add_f32_e32 v6, v17, v6
	v_add_f32_e32 v6, v19, v6
	ds_bpermute_b32 v38, v76, v6
	s_waitcnt lgkmcnt(0)
	v_add_f32_e32 v6, v6, v38
	ds_bpermute_b32 v38, v77, v6
	s_waitcnt lgkmcnt(0)
	v_add_f32_e32 v6, v6, v38
	v_sub_f32_e32 v38, v75, v66
	v_mul_f32_e32 v38, 0x3fb8aa3b, v38
	v_exp_f32_e32 v38, v38
	s_nop 0
	v_add_f32_e32 v6, v38, v6
	v_cvt_pk_bf16_f32 v38, v21, v28
	v_lshl_add_u32 v21, s17, 5, v74
	v_mad_u32_u24 v28, v137, s81, v21
	v_add_u32_e32 v28, 0x9000, v28
	v_cvt_pk_bf16_f32 v39, v30, v34
	v_cvt_pk_bf16_f32 v40, v37, v67
	v_cvt_pk_bf16_f32 v41, v68, v69
	ds_read2_b64 v[46:49], v28 offset1:4
	v_add_u32_e32 v28, v21, v80
	v_add_u32_e32 v28, 0x9000, v28
	ds_read2_b64 v[50:53], v28 offset1:4
	v_add_u32_e32 v28, v21, v79
	v_add_u32_e32 v21, v21, v78
	v_add_u32_e32 v28, 0x9000, v28
	v_add_u32_e32 v21, 0x9000, v21
	ds_read2_b64 v[54:57], v28 offset1:4
	ds_read2_b64 v[58:61], v21 offset1:4
	s_waitcnt lgkmcnt(3)
	v_mfma_f32_16x16x32_bf16 v[46:49], v[46:49], v[38:41], 0
	s_waitcnt lgkmcnt(2)
	v_mfma_f32_16x16x32_bf16 v[50:53], v[50:53], v[38:41], 0
	s_waitcnt lgkmcnt(1)
	v_mfma_f32_16x16x32_bf16 v[54:57], v[54:57], v[38:41], 0
	s_waitcnt lgkmcnt(0)
	v_mfma_f32_16x16x32_bf16 v[38:41], v[58:61], v[38:41], 0
	v_cvt_pk_bf16_f32 v58, v15, v24
	v_lshl_add_u32 v15, s27, 5, v74
	v_mad_u32_u24 v21, v137, s81, v15
	v_add_u32_e32 v21, 0x9000, v21
	v_cvt_pk_bf16_f32 v59, v26, v31
	v_cvt_pk_bf16_f32 v60, v33, v81
	v_cvt_pk_bf16_f32 v61, v82, v83
	ds_read2_b64 v[62:65], v21 offset1:4
	v_add_u32_e32 v21, v15, v80
	v_add_u32_e32 v21, 0x9000, v21
	s_waitcnt lgkmcnt(0)
	v_mfma_f32_16x16x32_bf16 v[46:49], v[62:65], v[58:61], v[46:49]
	ds_read2_b64 v[62:65], v21 offset1:4
	v_add_u32_e32 v21, v15, v79
	v_add_u32_e32 v21, 0x9000, v21
	s_waitcnt lgkmcnt(0)
	v_mfma_f32_16x16x32_bf16 v[50:53], v[62:65], v[58:61], v[50:53]
	ds_read2_b64 v[62:65], v21 offset1:4
	v_add_u32_e32 v15, v15, v78
	v_add_u32_e32 v15, 0x9000, v15
	s_waitcnt lgkmcnt(0)
	v_mfma_f32_16x16x32_bf16 v[54:57], v[62:65], v[58:61], v[54:57]
	ds_read2_b64 v[62:65], v15 offset1:4
	v_cvt_pk_bf16_f32 v26, v11, v20
	v_lshl_add_u32 v11, s26, 5, v74
	v_mad_u32_u24 v15, v137, s81, v11
	v_add_u32_e32 v15, 0x9000, v15
	s_waitcnt lgkmcnt(0)
	v_mfma_f32_16x16x32_bf16 v[38:41], v[62:65], v[58:61], v[38:41]
	v_cvt_pk_bf16_f32 v27, v22, v27
	v_cvt_pk_bf16_f32 v28, v29, v36
	v_cvt_pk_bf16_f32 v29, v84, v85
	ds_read2_b64 v[58:61], v15 offset1:4
	v_add_u32_e32 v15, v11, v80
	v_add_u32_e32 v15, 0x9000, v15
	s_waitcnt lgkmcnt(0)
	v_mfma_f32_16x16x32_bf16 v[46:49], v[58:61], v[26:29], v[46:49]
	ds_read2_b64 v[58:61], v15 offset1:4
	v_add_u32_e32 v15, v11, v79
	v_add_u32_e32 v15, 0x9000, v15
	s_waitcnt lgkmcnt(0)
	v_mfma_f32_16x16x32_bf16 v[50:53], v[58:61], v[26:29], v[50:53]
	ds_read2_b64 v[58:61], v15 offset1:4
	v_add_u32_e32 v11, v11, v78
	v_add_u32_e32 v11, 0x9000, v11
	s_waitcnt lgkmcnt(0)
	v_mfma_f32_16x16x32_bf16 v[54:57], v[58:61], v[26:29], v[54:57]
	ds_read2_b64 v[58:61], v11 offset1:4
	v_cvt_pk_bf16_f32 v20, v8, v14
	v_lshl_add_u32 v8, s6, 5, v74
	v_mad_u32_u24 v11, v137, s81, v8
	v_add_u32_e32 v11, 0x9000, v11
	v_cvt_pk_bf16_f32 v21, v18, v23
	v_cvt_pk_bf16_f32 v22, v25, v32
	v_cvt_pk_bf16_f32 v23, v35, v86
	ds_read2_b64 v[30:33], v11 offset1:4
	v_add_u32_e32 v11, v8, v80
	v_add_u32_e32 v11, 0x9000, v11
	ds_read2_b64 v[34:37], v11 offset1:4
	v_add_u32_e32 v11, v8, v79
	v_add_u32_e32 v8, v8, v78
	v_add_u32_e32 v11, 0x9000, v11
	v_add_u32_e32 v8, 0x9000, v8
	s_waitcnt lgkmcnt(2)
	v_mfma_f32_16x16x32_bf16 v[26:29], v[58:61], v[26:29], v[38:41]
	s_waitcnt lgkmcnt(1)
	v_mfma_f32_16x16x32_bf16 v[30:33], v[30:33], v[20:23], v[46:49]
	s_nop 0
	ds_read2_b64 v[38:41], v11 offset1:4
	s_nop 0
	ds_read2_b64 v[46:49], v8 offset1:4
	v_cvt_pk_bf16_f32 v8, v7, v9
	v_lshl_add_u32 v7, s4, 5, v74
	v_cvt_pk_bf16_f32 v9, v10, v12
	v_mad_u32_u24 v12, v137, s81, v7
	v_add_u32_e32 v12, 0x9000, v12
	v_cvt_pk_bf16_f32 v10, v13, v16
	v_cvt_pk_bf16_f32 v11, v17, v19
	ds_read2_b64 v[12:15], v12 offset1:4
	v_add_u32_e32 v16, v7, v80
	v_add_u32_e32 v24, v7, v79
	v_add_u32_e32 v7, v7, v78
	v_add_u32_e32 v16, 0x9000, v16
	v_add_u32_e32 v24, 0x9000, v24
	v_add_u32_e32 v7, 0x9000, v7
	s_waitcnt lgkmcnt(3)
; __device__ __forceinline__ unsigned cvt_pk_bf16(float lo, float hi) { unsigned r; asm volatile("v_cvt_pk_bf16_f32 %0, %1, %2" : "=v"(r) : "v"(lo), "v"(hi)); return r; }
; #define LAS __attribute__((address_space(3)))
; #define MFMA16(a, b, c) __builtin_amdgcn_mfma_f32_16x16x32_bf16((a), (b), (c), 0, 0, 0)
; __device__ __forceinline__ void p2_block(LAS unsigned char* lds, const bf16_t* __restrict__ PROJ, bf16_t* __restrict__ ATT, bf16_t* __restrict__ SGU, const float* __restrict__ qn, const float* __restrict__ kn, ...
;     ...
;         bf16_t* op = ATT + grow * 1024 + hq * 64 + 4 * fq;
; #pragma unroll
;         for (int dt = 0; dt < 4; ++dt) { u32x2 ow; ow.x = cvt_pk_bf16(o[dt][0] * inv, o[dt][1] * inv); ow.y = cvt_pk_bf16(o[dt][2] * inv, o[dt][3] * inv); *(u32x2*)(op + 16 * dt) = ow; }
;     ...
;     for (int gi = 0; gi < 2; ++gi) {
;         const int gg = 2 * kvh + gi, irow = 16 * w + fr, nks = (w >> 1) + 1;
;         const LAS unsigned char* VNT = lds + (gi ? VN_OFF1 : VN_OFF0);
;         f32x4 acc[8];
; #pragma unroll
;         for (int dt = 0; dt < 8; ++dt) acc[dt] = (f32x4){0.f, 0.f, 0.f, 0.f};
;         const float* wrow = wsp + (size_t)gg * 16384 + irow * 128 + 8 * fq;
; #pragma unroll
;         for (int ks = 0; ks < 4; ++ks) if (ks < nks) {
;             const f32x4 wa = *(const f32x4*)(wrow + 32 * ks), wb = *(const f32x4*)(wrow + 32 * ks + 4);
;             const int j0 = 32 * ks + 8 * fq; float wv[8];
; #pragma unroll
;             for (int e = 0; e < 4; ++e) { wv[e] = (j0 + e <= irow) ? wa[e] : 0.f; wv[4 + e] = (j0 + 4 + e <= irow) ? wb[e] : 0.f; }
;             u32x4 ww; ww.x = cvt_pk_bf16(wv[0], wv[1]); ww.y = cvt_pk_bf16(wv[2], wv[3]); ww.z = cvt_pk_bf16(wv[4], wv[5]); ww.w = cvt_pk_bf16(wv[6], wv[7]);
;             const bf16x8 wf = __builtin_bit_cast(bf16x8, ww);
; #pragma unroll
;             for (int dt = 0; dt < 8; ++dt) { const bf16x8 af = *(const LAS bf16x8*)(VNT + (16 * dt + fr) * VN_STRIDE + (32 * ks + 8 * fq) * 2); acc[dt] = MFMA16(af, wf, acc[dt]); }
	v_mfma_f32_16x16x32_bf16 v[34:37], v[34:37], v[20:23], v[50:53]
	ds_read2_b64 v[16:19], v16 offset1:4
	s_ashr_i32 s4, s16, 2
	s_waitcnt lgkmcnt(3)
	v_mfma_f32_16x16x32_bf16 v[38:41], v[38:41], v[20:23], v[54:57]
	s_waitcnt lgkmcnt(2)
	v_mfma_f32_16x16x32_bf16 v[20:23], v[46:49], v[20:23], v[26:29]
	v_or_b32_e32 v49, 5, v130
	v_or_b32_e32 v48, 6, v130
	v_or_b32_e32 v46, 7, v130
	s_waitcnt lgkmcnt(1)
	v_mfma_f32_16x16x32_bf16 v[12:15], v[12:15], v[8:11], v[30:33]
	ds_read2_b64 v[24:27], v24 offset1:4
	s_nop 1
	ds_read2_b64 v[28:31], v7 offset1:4
	v_div_scale_f32 v7, s[6:7], v6, v6, 1.0
	s_waitcnt lgkmcnt(2)
	v_mfma_f32_16x16x32_bf16 v[16:19], v[16:19], v[8:11], v[34:37]
	s_waitcnt lgkmcnt(1)
	v_mfma_f32_16x16x32_bf16 v[24:27], v[24:27], v[8:11], v[38:41]
	s_nop 0
	v_bfi_b32 v36, -16, s4, v160
	s_lshl_b32 s4, s73, 17
	s_cmp_gt_i32 s77, -1
	s_waitcnt lgkmcnt(0)
	v_mfma_f32_16x16x32_bf16 v[8:11], v[28:31], v[8:11], v[20:23]
	v_mov_b64_e32 v[32:33], v[4:5]
	s_cselect_b64 s[28:29], -1, 0
	s_cmp_lt_i32 s77, 0
	v_rcp_f32_e32 v20, v7
	v_cmp_le_i32_e64 s[40:41], v72, v36
	v_cmp_lt_i32_e64 s[42:43], v130, v36
	v_cmp_le_i32_e64 s[44:45], v71, v36
	v_fma_f32 v21, -v7, v20, 1.0
	v_fmac_f32_e32 v20, v21, v20
	v_div_scale_f32 v21, vcc, 1.0, v6, 1.0
	v_mul_f32_e32 v22, v21, v20
	v_fma_f32 v23, -v7, v22, v21
	v_fmac_f32_e32 v22, v23, v20
	v_fma_f32 v7, -v7, v22, v21
	v_div_fmas_f32 v7, v7, v20, v22
	v_div_fixup_f32 v20, v7, v6, 1.0
	v_mul_f32_e32 v12, v20, v12
	v_mul_f32_e32 v13, v20, v13
	v_lshlrev_b64 v[6:7], 11, v[44:45]
	v_cvt_pk_bf16_f32 v12, v12, v13
	v_mul_f32_e32 v13, v20, v14
	v_lshl_add_u64 v[6:7], v[42:43], 0, v[6:7]
	v_mul_f32_e32 v14, v20, v15
	v_cvt_pk_bf16_f32 v13, v13, v14
	global_store_dwordx2 v[6:7], v[12:13], off
	v_mul_f32_e32 v12, v20, v16
	v_mul_f32_e32 v13, v20, v17
	v_cvt_pk_bf16_f32 v12, v12, v13
	v_mul_f32_e32 v13, v20, v18
	v_mul_f32_e32 v14, v20, v19
	v_cvt_pk_bf16_f32 v13, v13, v14
	global_store_dwordx2 v[6:7], v[12:13], off offset:32
	v_mul_f32_e32 v12, v20, v24
	v_mul_f32_e32 v13, v20, v25
	v_cvt_pk_bf16_f32 v12, v12, v13
	v_mul_f32_e32 v13, v20, v26
	v_mul_f32_e32 v8, v20, v8
	v_mul_f32_e32 v9, v20, v9
	v_mul_f32_e32 v14, v20, v27
	v_cvt_pk_bf16_f32 v13, v13, v14
	global_store_dwordx2 v[6:7], v[12:13], off offset:64
	v_cvt_pk_bf16_f32 v8, v8, v9
	v_mul_f32_e32 v9, v20, v10
	v_mul_f32_e32 v10, v20, v11
	v_cvt_pk_bf16_f32 v9, v9, v10
	global_store_dwordx2 v[6:7], v[8:9], off offset:96
	v_readfirstlane_b32 s16, v204
	v_and_b32_e32 v184, 15, v204
	v_bfe_u32 v185, v204, 4, 2
	s_and_b32 s24, s2, 3
	s_lshr_b32 s16, s16, 6
	s_lshl_b32 s4, s24, 17
	s_lshr_b32 s17, s16, 1
	v_lshl_add_u32 v191, s16, 4, v184
	v_lshlrev_b32_e32 v186, 9, v191
	v_lshl_add_u32 v186, v185, 5, v186
	v_add_u32_e32 v186, s4, v186
	v_add_u32_e32 v187, 0x10000, v186
	global_load_dwordx4 v[98:101], v186, s[20:21] offset:0
	global_load_dwordx4 v[102:105], v186, s[20:21] offset:16
	global_load_dwordx4 v[106:109], v186, s[20:21] offset:128
	global_load_dwordx4 v[110:113], v186, s[20:21] offset:144
	global_load_dwordx4 v[114:117], v186, s[20:21] offset:256
	global_load_dwordx4 v[118:121], v186, s[20:21] offset:272
	global_load_dwordx4 v[122:125], v186, s[20:21] offset:384
	global_load_dwordx4 v[126:129], v186, s[20:21] offset:400
	global_load_dwordx4 v[66:69], v187, s[20:21] offset:0
	global_load_dwordx4 v[70:73], v187, s[20:21] offset:16
	global_load_dwordx4 v[74:77], v187, s[20:21] offset:128
	global_load_dwordx4 v[78:81], v187, s[20:21] offset:144
	global_load_dwordx4 v[82:85], v187, s[20:21] offset:256
	global_load_dwordx4 v[86:89], v187, s[20:21] offset:272
	global_load_dwordx4 v[90:93], v187, s[20:21] offset:384
	global_load_dwordx4 v[94:97], v187, s[20:21] offset:400
	v_mul_u32_u24_e32 v194, 0x110, v184
	v_lshl_add_u32 v194, v185, 4, v194
	v_add_u32_e32 v194, 0x11800, v194
	v_lshlrev_b32_e32 v195, 3, v185
	v_sub_u32_e32 v195, v191, v195
	s_and_b32 s25, s2, -4
	s_lshl_b32 s25, s25, 5
	v_add_u32_e32 v192, s25, v191
	s_lshl_b32 s4, s24, 9
	v_lshl_add_u32 v193, v185, 3, s4
	v_lshl_add_u32 v189, v192, 11, v193
	s_cmp_eq_u32 s17, 0
	s_cbranch_scc1 .Lsgu_n1
	s_cmp_eq_u32 s17, 1
	s_cbranch_scc1 .Lsgu_n2
	s_cmp_eq_u32 s17, 2
	s_cbranch_scc1 .Lsgu_n3
	s_branch .Lsgu_n4
.Lsgu_n1:
	s_waitcnt vmcnt(8)
	v_mov_b32_e32 v196, v195
	v_cmp_le_i32_e64 s[40:41], 0, v196
	v_cmp_le_i32_e64 s[42:43], 1, v196
	v_cmp_le_i32_e64 s[44:45], 2, v196
	v_cmp_le_i32_e64 s[46:47], 3, v196
	v_cmp_le_i32_e64 s[48:49], 4, v196
	v_cmp_le_i32_e64 s[50:51], 5, v196
	v_cmp_le_i32_e64 s[52:53], 6, v196
	v_cmp_le_i32_e32 vcc, 7, v196
	v_cndmask_b32_e64 v98, 0, v98, s[40:41]
	v_cndmask_b32_e64 v99, 0, v99, s[42:43]
	v_cndmask_b32_e64 v100, 0, v100, s[44:45]
	v_cndmask_b32_e64 v101, 0, v101, s[46:47]
	v_cndmask_b32_e64 v102, 0, v102, s[48:49]
	v_cndmask_b32_e64 v103, 0, v103, s[50:51]
	v_cndmask_b32_e64 v104, 0, v104, s[52:53]
	v_cndmask_b32_e32 v105, 0, v105, vcc
	v_cvt_pk_bf16_f32 v144, v98, v99
	v_cvt_pk_bf16_f32 v145, v100, v101
	v_cvt_pk_bf16_f32 v146, v102, v103
	v_cvt_pk_bf16_f32 v147, v104, v105
	ds_read_b128 v[34:37], v194 offset:0
	ds_read_b128 v[38:41], v194 offset:4352
	ds_read_b128 v[42:45], v194 offset:8704
	ds_read_b128 v[46:49], v194 offset:13056
	ds_read_b128 v[50:53], v194 offset:17408
	ds_read_b128 v[54:57], v194 offset:21760
	ds_read_b128 v[58:61], v194 offset:26112
	ds_read_b128 v[62:65], v194 offset:30464
	s_waitcnt vmcnt(0)
; __device__ __forceinline__ unsigned cvt_pk_bf16(float lo, float hi) { unsigned r; asm volatile("v_cvt_pk_bf16_f32 %0, %1, %2" : "=v"(r) : "v"(lo), "v"(hi)); return r; }
; #define LAS __attribute__((address_space(3)))
; #define MFMA16(a, b, c) __builtin_amdgcn_mfma_f32_16x16x32_bf16((a), (b), (c), 0, 0, 0)
; __device__ __forceinline__ void p2_block(LAS unsigned char* lds, const bf16_t* __restrict__ PROJ, bf16_t* __restrict__ ATT, bf16_t* __restrict__ SGU, const float* __restrict__ qn, const float* __restrict__ kn, ...
;     ...
;         for (int ks = 0; ks < 4; ++ks) if (ks < nks) {
;             const f32x4 wa = *(const f32x4*)(wrow + 32 * ks), wb = *(const f32x4*)(wrow + 32 * ks + 4);
;             const int j0 = 32 * ks + 8 * fq; float wv[8];
; #pragma unroll
;             for (int e = 0; e < 4; ++e) { wv[e] = (j0 + e <= irow) ? wa[e] : 0.f; wv[4 + e] = (j0 + 4 + e <= irow) ? wb[e] : 0.f; }
;             u32x4 ww; ww.x = cvt_pk_bf16(wv[0], wv[1]); ww.y = cvt_pk_bf16(wv[2], wv[3]); ww.z = cvt_pk_bf16(wv[4], wv[5]); ww.w = cvt_pk_bf16(wv[6], wv[7]);
;             const bf16x8 wf = __builtin_bit_cast(bf16x8, ww);
; #pragma unroll
;             for (int dt = 0; dt < 8; ++dt) { const bf16x8 af = *(const LAS bf16x8*)(VNT + (16 * dt + fr) * VN_STRIDE + (32 * ks + 8 * fq) * 2); acc[dt] = MFMA16(af, wf, acc[dt]); }
	v_mov_b32_e32 v196, v195
	v_cmp_le_i32_e64 s[40:41], 0, v196
	v_cmp_le_i32_e64 s[42:43], 1, v196
	v_cmp_le_i32_e64 s[44:45], 2, v196
	v_cmp_le_i32_e64 s[46:47], 3, v196
	v_cmp_le_i32_e64 s[48:49], 4, v196
	v_cmp_le_i32_e64 s[50:51], 5, v196
	v_cmp_le_i32_e64 s[52:53], 6, v196
	v_cmp_le_i32_e32 vcc, 7, v196
	v_cndmask_b32_e64 v66, 0, v66, s[40:41]
	v_cndmask_b32_e64 v67, 0, v67, s[42:43]
	v_cndmask_b32_e64 v68, 0, v68, s[44:45]
	v_cndmask_b32_e64 v69, 0, v69, s[46:47]
	v_cndmask_b32_e64 v70, 0, v70, s[48:49]
	v_cndmask_b32_e64 v71, 0, v71, s[50:51]
	v_cndmask_b32_e64 v72, 0, v72, s[52:53]
	v_cndmask_b32_e32 v73, 0, v73, vcc
	v_cvt_pk_bf16_f32 v98, v66, v67
	v_cvt_pk_bf16_f32 v99, v68, v69
	v_cvt_pk_bf16_f32 v100, v70, v71
	v_cvt_pk_bf16_f32 v101, v72, v73
	ds_read_b128 v[66:69], v194 offset:34816
	ds_read_b128 v[70:73], v194 offset:39168
	ds_read_b128 v[74:77], v194 offset:43520
	ds_read_b128 v[78:81], v194 offset:47872
	ds_read_b128 v[82:85], v194 offset:52224
	ds_read_b128 v[86:89], v194 offset:56576
	ds_read_b128 v[90:93], v194 offset:60928
	ds_read_b128 v[94:97], v194 offset:65280
	s_waitcnt lgkmcnt(15)
	v_mfma_f32_16x16x32_bf16 v[2:5], v[34:37], v[144:147], 0
	s_waitcnt lgkmcnt(14)
	v_mfma_f32_16x16x32_bf16 v[6:9], v[38:41], v[144:147], 0
	s_waitcnt lgkmcnt(13)
	v_mfma_f32_16x16x32_bf16 v[10:13], v[42:45], v[144:147], 0
	s_waitcnt lgkmcnt(12)
	v_mfma_f32_16x16x32_bf16 v[14:17], v[46:49], v[144:147], 0
	s_waitcnt lgkmcnt(11)
	v_mfma_f32_16x16x32_bf16 v[18:21], v[50:53], v[144:147], 0
	s_waitcnt lgkmcnt(10)
	v_mfma_f32_16x16x32_bf16 v[22:25], v[54:57], v[144:147], 0
	s_waitcnt lgkmcnt(9)
	v_mfma_f32_16x16x32_bf16 v[26:29], v[58:61], v[144:147], 0
	s_waitcnt lgkmcnt(8)
	v_mfma_f32_16x16x32_bf16 v[30:33], v[62:65], v[144:147], 0
	s_waitcnt lgkmcnt(7)
	v_mfma_f32_16x16x32_bf16 v[114:117], v[66:69], v[98:101], 0
	s_waitcnt lgkmcnt(6)
	v_mfma_f32_16x16x32_bf16 v[118:121], v[70:73], v[98:101], 0
	s_waitcnt lgkmcnt(5)
	v_mfma_f32_16x16x32_bf16 v[122:125], v[74:77], v[98:101], 0
	s_waitcnt lgkmcnt(4)
	v_mfma_f32_16x16x32_bf16 v[126:129], v[78:81], v[98:101], 0
	s_waitcnt lgkmcnt(3)
	v_mfma_f32_16x16x32_bf16 v[130:133], v[82:85], v[98:101], 0
	s_waitcnt lgkmcnt(2)
	v_mfma_f32_16x16x32_bf16 v[134:137], v[86:89], v[98:101], 0
	s_waitcnt lgkmcnt(1)
	v_mfma_f32_16x16x32_bf16 v[138:141], v[90:93], v[98:101], 0
	s_waitcnt lgkmcnt(0)
	v_mfma_f32_16x16x32_bf16 v[160:163], v[94:97], v[98:101], 0
	s_branch .Lsgu_epi
.Lsgu_n2:
	s_waitcnt vmcnt(8)
	v_mov_b32_e32 v196, v195
	v_cmp_le_i32_e64 s[40:41], 0, v196
	v_cmp_le_i32_e64 s[42:43], 1, v196
	v_cmp_le_i32_e64 s[44:45], 2, v196
	v_cmp_le_i32_e64 s[46:47], 3, v196
	v_cmp_le_i32_e64 s[48:49], 4, v196
	v_cmp_le_i32_e64 s[50:51], 5, v196
	v_cmp_le_i32_e64 s[52:53], 6, v196
	v_cmp_le_i32_e32 vcc, 7, v196
	v_cndmask_b32_e64 v98, 0, v98, s[40:41]
	v_cndmask_b32_e64 v99, 0, v99, s[42:43]
	v_cndmask_b32_e64 v100, 0, v100, s[44:45]
	v_cndmask_b32_e64 v101, 0, v101, s[46:47]
	v_cndmask_b32_e64 v102, 0, v102, s[48:49]
	v_cndmask_b32_e64 v103, 0, v103, s[50:51]
	v_cndmask_b32_e64 v104, 0, v104, s[52:53]
	v_cndmask_b32_e32 v105, 0, v105, vcc
	v_cvt_pk_bf16_f32 v144, v98, v99
	v_cvt_pk_bf16_f32 v145, v100, v101
	v_cvt_pk_bf16_f32 v146, v102, v103
	v_cvt_pk_bf16_f32 v147, v104, v105
	v_add_u32_e32 v196, 4294967264, v195
	v_cmp_le_i32_e64 s[40:41], 0, v196
	v_cmp_le_i32_e64 s[42:43], 1, v196
	v_cmp_le_i32_e64 s[44:45], 2, v196
	v_cmp_le_i32_e64 s[46:47], 3, v196
	v_cmp_le_i32_e64 s[48:49], 4, v196
	v_cmp_le_i32_e64 s[50:51], 5, v196
	v_cmp_le_i32_e64 s[52:53], 6, v196
	v_cmp_le_i32_e32 vcc, 7, v196
	v_cndmask_b32_e64 v106, 0, v106, s[40:41]
	v_cndmask_b32_e64 v107, 0, v107, s[42:43]
	v_cndmask_b32_e64 v108, 0, v108, s[44:45]
	v_cndmask_b32_e64 v109, 0, v109, s[46:47]
	v_cndmask_b32_e64 v110, 0, v110, s[48:49]
	v_cndmask_b32_e64 v111, 0, v111, s[50:51]
	v_cndmask_b32_e64 v112, 0, v112, s[52:53]
	v_cndmask_b32_e32 v113, 0, v113, vcc
	v_cvt_pk_bf16_f32 v148, v106, v107
	v_cvt_pk_bf16_f32 v149, v108, v109
	v_cvt_pk_bf16_f32 v150, v110, v111
	v_cvt_pk_bf16_f32 v151, v112, v113
	ds_read_b128 v[34:37], v194 offset:0
	ds_read_b128 v[38:41], v194 offset:4352
	ds_read_b128 v[42:45], v194 offset:8704
	ds_read_b128 v[46:49], v194 offset:13056
	ds_read_b128 v[50:53], v194 offset:17408
	ds_read_b128 v[54:57], v194 offset:21760
	ds_read_b128 v[58:61], v194 offset:26112
	ds_read_b128 v[62:65], v194 offset:30464
	s_waitcnt vmcnt(0)
	v_mov_b32_e32 v196, v195
	v_cmp_le_i32_e64 s[40:41], 0, v196
	v_cmp_le_i32_e64 s[42:43], 1, v196
	v_cmp_le_i32_e64 s[44:45], 2, v196
	v_cmp_le_i32_e64 s[46:47], 3, v196
	v_cmp_le_i32_e64 s[48:49], 4, v196
	v_cmp_le_i32_e64 s[50:51], 5, v196
	v_cmp_le_i32_e64 s[52:53], 6, v196
	v_cmp_le_i32_e32 vcc, 7, v196
	v_cndmask_b32_e64 v66, 0, v66, s[40:41]
	v_cndmask_b32_e64 v67, 0, v67, s[42:43]
	v_cndmask_b32_e64 v68, 0, v68, s[44:45]
	v_cndmask_b32_e64 v69, 0, v69, s[46:47]
	v_cndmask_b32_e64 v70, 0, v70, s[48:49]
	v_cndmask_b32_e64 v71, 0, v71, s[50:51]
	v_cndmask_b32_e64 v72, 0, v72, s[52:53]
	v_cndmask_b32_e32 v73, 0, v73, vcc
	v_cvt_pk_bf16_f32 v98, v66, v67
	v_cvt_pk_bf16_f32 v99, v68, v69
	v_cvt_pk_bf16_f32 v100, v70, v71
	v_cvt_pk_bf16_f32 v101, v72, v73
	v_add_u32_e32 v196, 4294967264, v195
	v_cmp_le_i32_e64 s[40:41], 0, v196
	v_cmp_le_i32_e64 s[42:43], 1, v196
	v_cmp_le_i32_e64 s[44:45], 2, v196
	v_cmp_le_i32_e64 s[46:47], 3, v196
	v_cmp_le_i32_e64 s[48:49], 4, v196
	v_cmp_le_i32_e64 s[50:51], 5, v196
	v_cmp_le_i32_e64 s[52:53], 6, v196
	v_cmp_le_i32_e32 vcc, 7, v196
	v_cndmask_b32_e64 v74, 0, v74, s[40:41]
	v_cndmask_b32_e64 v75, 0, v75, s[42:43]
	v_cndmask_b32_e64 v76, 0, v76, s[44:45]
	v_cndmask_b32_e64 v77, 0, v77, s[46:47]
	v_cndmask_b32_e64 v78, 0, v78, s[48:49]
	v_cndmask_b32_e64 v79, 0, v79, s[50:51]
	v_cndmask_b32_e64 v80, 0, v80, s[52:53]
	v_cndmask_b32_e32 v81, 0, v81, vcc
	v_cvt_pk_bf16_f32 v102, v74, v75
	v_cvt_pk_bf16_f32 v103, v76, v77
	v_cvt_pk_bf16_f32 v104, v78, v79
	v_cvt_pk_bf16_f32 v105, v80, v81
	ds_read_b128 v[66:69], v194 offset:64
	ds_read_b128 v[70:73], v194 offset:4416
	ds_read_b128 v[74:77], v194 offset:8768
	ds_read_b128 v[78:81], v194 offset:13120
	ds_read_b128 v[82:85], v194 offset:17472
	ds_read_b128 v[86:89], v194 offset:21824
	ds_read_b128 v[90:93], v194 offset:26176
	ds_read_b128 v[94:97], v194 offset:30528
	s_waitcnt lgkmcnt(15)
; __device__ __forceinline__ unsigned cvt_pk_bf16(float lo, float hi) { unsigned r; asm volatile("v_cvt_pk_bf16_f32 %0, %1, %2" : "=v"(r) : "v"(lo), "v"(hi)); return r; }
; #define LAS __attribute__((address_space(3)))
; #define MFMA16(a, b, c) __builtin_amdgcn_mfma_f32_16x16x32_bf16((a), (b), (c), 0, 0, 0)
; __device__ __forceinline__ void p2_block(LAS unsigned char* lds, const bf16_t* __restrict__ PROJ, bf16_t* __restrict__ ATT, bf16_t* __restrict__ SGU, const float* __restrict__ qn, const float* __restrict__ kn, ...
;     ...
;         for (int ks = 0; ks < 4; ++ks) if (ks < nks) {
;             const f32x4 wa = *(const f32x4*)(wrow + 32 * ks), wb = *(const f32x4*)(wrow + 32 * ks + 4);
;             const int j0 = 32 * ks + 8 * fq; float wv[8];
; #pragma unroll
;             for (int e = 0; e < 4; ++e) { wv[e] = (j0 + e <= irow) ? wa[e] : 0.f; wv[4 + e] = (j0 + 4 + e <= irow) ? wb[e] : 0.f; }
;             u32x4 ww; ww.x = cvt_pk_bf16(wv[0], wv[1]); ww.y = cvt_pk_bf16(wv[2], wv[3]); ww.z = cvt_pk_bf16(wv[4], wv[5]); ww.w = cvt_pk_bf16(wv[6], wv[7]);
;             const bf16x8 wf = __builtin_bit_cast(bf16x8, ww);
; #pragma unroll
;             for (int dt = 0; dt < 8; ++dt) { const bf16x8 af = *(const LAS bf16x8*)(VNT + (16 * dt + fr) * VN_STRIDE + (32 * ks + 8 * fq) * 2); acc[dt] = MFMA16(af, wf, acc[dt]); }
	v_mfma_f32_16x16x32_bf16 v[2:5], v[34:37], v[144:147], 0
	s_waitcnt lgkmcnt(14)
	v_mfma_f32_16x16x32_bf16 v[6:9], v[38:41], v[144:147], 0
	s_waitcnt lgkmcnt(13)
	v_mfma_f32_16x16x32_bf16 v[10:13], v[42:45], v[144:147], 0
	s_waitcnt lgkmcnt(12)
	v_mfma_f32_16x16x32_bf16 v[14:17], v[46:49], v[144:147], 0
	s_waitcnt lgkmcnt(11)
	v_mfma_f32_16x16x32_bf16 v[18:21], v[50:53], v[144:147], 0
	s_waitcnt lgkmcnt(10)
	v_mfma_f32_16x16x32_bf16 v[22:25], v[54:57], v[144:147], 0
	s_waitcnt lgkmcnt(9)
	v_mfma_f32_16x16x32_bf16 v[26:29], v[58:61], v[144:147], 0
	s_waitcnt lgkmcnt(8)
	v_mfma_f32_16x16x32_bf16 v[30:33], v[62:65], v[144:147], 0
	ds_read_b128 v[34:37], v194 offset:34816
	ds_read_b128 v[38:41], v194 offset:39168
	ds_read_b128 v[42:45], v194 offset:43520
	ds_read_b128 v[46:49], v194 offset:47872
	ds_read_b128 v[50:53], v194 offset:52224
	ds_read_b128 v[54:57], v194 offset:56576
	ds_read_b128 v[58:61], v194 offset:60928
	ds_read_b128 v[62:65], v194 offset:65280
	s_waitcnt lgkmcnt(15)
	v_mfma_f32_16x16x32_bf16 v[2:5], v[66:69], v[148:151], v[2:5]
	s_waitcnt lgkmcnt(14)
	v_mfma_f32_16x16x32_bf16 v[6:9], v[70:73], v[148:151], v[6:9]
	s_waitcnt lgkmcnt(13)
	v_mfma_f32_16x16x32_bf16 v[10:13], v[74:77], v[148:151], v[10:13]
	s_waitcnt lgkmcnt(12)
	v_mfma_f32_16x16x32_bf16 v[14:17], v[78:81], v[148:151], v[14:17]
	s_waitcnt lgkmcnt(11)
	v_mfma_f32_16x16x32_bf16 v[18:21], v[82:85], v[148:151], v[18:21]
	s_waitcnt lgkmcnt(10)
	v_mfma_f32_16x16x32_bf16 v[22:25], v[86:89], v[148:151], v[22:25]
	s_waitcnt lgkmcnt(9)
	v_mfma_f32_16x16x32_bf16 v[26:29], v[90:93], v[148:151], v[26:29]
	s_waitcnt lgkmcnt(8)
	v_mfma_f32_16x16x32_bf16 v[30:33], v[94:97], v[148:151], v[30:33]
	ds_read_b128 v[66:69], v194 offset:34880
	ds_read_b128 v[70:73], v194 offset:39232
	ds_read_b128 v[74:77], v194 offset:43584
	ds_read_b128 v[78:81], v194 offset:47936
	ds_read_b128 v[82:85], v194 offset:52288
	ds_read_b128 v[86:89], v194 offset:56640
	ds_read_b128 v[90:93], v194 offset:60992
	ds_read_b128 v[94:97], v194 offset:65344
	s_waitcnt lgkmcnt(15)
	v_mfma_f32_16x16x32_bf16 v[114:117], v[34:37], v[98:101], 0
	s_waitcnt lgkmcnt(14)
	v_mfma_f32_16x16x32_bf16 v[118:121], v[38:41], v[98:101], 0
	s_waitcnt lgkmcnt(13)
	v_mfma_f32_16x16x32_bf16 v[122:125], v[42:45], v[98:101], 0
	s_waitcnt lgkmcnt(12)
	v_mfma_f32_16x16x32_bf16 v[126:129], v[46:49], v[98:101], 0
	s_waitcnt lgkmcnt(11)
	v_mfma_f32_16x16x32_bf16 v[130:133], v[50:53], v[98:101], 0
	s_waitcnt lgkmcnt(10)
	v_mfma_f32_16x16x32_bf16 v[134:137], v[54:57], v[98:101], 0
	s_waitcnt lgkmcnt(9)
	v_mfma_f32_16x16x32_bf16 v[138:141], v[58:61], v[98:101], 0
	s_waitcnt lgkmcnt(8)
	v_mfma_f32_16x16x32_bf16 v[160:163], v[62:65], v[98:101], 0
	s_waitcnt lgkmcnt(7)
	v_mfma_f32_16x16x32_bf16 v[114:117], v[66:69], v[102:105], v[114:117]
	s_waitcnt lgkmcnt(6)
	v_mfma_f32_16x16x32_bf16 v[118:121], v[70:73], v[102:105], v[118:121]
	s_waitcnt lgkmcnt(5)
	v_mfma_f32_16x16x32_bf16 v[122:125], v[74:77], v[102:105], v[122:125]
	s_waitcnt lgkmcnt(4)
	v_mfma_f32_16x16x32_bf16 v[126:129], v[78:81], v[102:105], v[126:129]
	s_waitcnt lgkmcnt(3)
	v_mfma_f32_16x16x32_bf16 v[130:133], v[82:85], v[102:105], v[130:133]
	s_waitcnt lgkmcnt(2)
	v_mfma_f32_16x16x32_bf16 v[134:137], v[86:89], v[102:105], v[134:137]
	s_waitcnt lgkmcnt(1)
	v_mfma_f32_16x16x32_bf16 v[138:141], v[90:93], v[102:105], v[138:141]
	s_waitcnt lgkmcnt(0)
	v_mfma_f32_16x16x32_bf16 v[160:163], v[94:97], v[102:105], v[160:163]
	s_branch .Lsgu_epi
.Lsgu_n3:
	s_waitcnt vmcnt(8)
	v_mov_b32_e32 v196, v195
	v_cmp_le_i32_e64 s[40:41], 0, v196
	v_cmp_le_i32_e64 s[42:43], 1, v196
	v_cmp_le_i32_e64 s[44:45], 2, v196
	v_cmp_le_i32_e64 s[46:47], 3, v196
	v_cmp_le_i32_e64 s[48:49], 4, v196
	v_cmp_le_i32_e64 s[50:51], 5, v196
	v_cmp_le_i32_e64 s[52:53], 6, v196
	v_cmp_le_i32_e32 vcc, 7, v196
	v_cndmask_b32_e64 v98, 0, v98, s[40:41]
	v_cndmask_b32_e64 v99, 0, v99, s[42:43]
	v_cndmask_b32_e64 v100, 0, v100, s[44:45]
	v_cndmask_b32_e64 v101, 0, v101, s[46:47]
	v_cndmask_b32_e64 v102, 0, v102, s[48:49]
	v_cndmask_b32_e64 v103, 0, v103, s[50:51]
	v_cndmask_b32_e64 v104, 0, v104, s[52:53]
	v_cndmask_b32_e32 v105, 0, v105, vcc
	v_cvt_pk_bf16_f32 v144, v98, v99
	v_cvt_pk_bf16_f32 v145, v100, v101
	v_cvt_pk_bf16_f32 v146, v102, v103
	v_cvt_pk_bf16_f32 v147, v104, v105
	v_add_u32_e32 v196, 4294967264, v195
	v_cmp_le_i32_e64 s[40:41], 0, v196
	v_cmp_le_i32_e64 s[42:43], 1, v196
	v_cmp_le_i32_e64 s[44:45], 2, v196
	v_cmp_le_i32_e64 s[46:47], 3, v196
	v_cmp_le_i32_e64 s[48:49], 4, v196
	v_cmp_le_i32_e64 s[50:51], 5, v196
	v_cmp_le_i32_e64 s[52:53], 6, v196
	v_cmp_le_i32_e32 vcc, 7, v196
	v_cndmask_b32_e64 v106, 0, v106, s[40:41]
	v_cndmask_b32_e64 v107, 0, v107, s[42:43]
	v_cndmask_b32_e64 v108, 0, v108, s[44:45]
	v_cndmask_b32_e64 v109, 0, v109, s[46:47]
	v_cndmask_b32_e64 v110, 0, v110, s[48:49]
	v_cndmask_b32_e64 v111, 0, v111, s[50:51]
	v_cndmask_b32_e64 v112, 0, v112, s[52:53]
	v_cndmask_b32_e32 v113, 0, v113, vcc
	v_cvt_pk_bf16_f32 v148, v106, v107
	v_cvt_pk_bf16_f32 v149, v108, v109
	v_cvt_pk_bf16_f32 v150, v110, v111
	v_cvt_pk_bf16_f32 v151, v112, v113
	v_add_u32_e32 v196, 4294967232, v195
	v_cmp_le_i32_e64 s[40:41], 0, v196
	v_cmp_le_i32_e64 s[42:43], 1, v196
	v_cmp_le_i32_e64 s[44:45], 2, v196
	v_cmp_le_i32_e64 s[46:47], 3, v196
	v_cmp_le_i32_e64 s[48:49], 4, v196
	v_cmp_le_i32_e64 s[50:51], 5, v196
	v_cmp_le_i32_e64 s[52:53], 6, v196
	v_cmp_le_i32_e32 vcc, 7, v196
	v_cndmask_b32_e64 v114, 0, v114, s[40:41]
	v_cndmask_b32_e64 v115, 0, v115, s[42:43]
	v_cndmask_b32_e64 v116, 0, v116, s[44:45]
	v_cndmask_b32_e64 v117, 0, v117, s[46:47]
	v_cndmask_b32_e64 v118, 0, v118, s[48:49]
	v_cndmask_b32_e64 v119, 0, v119, s[50:51]
	v_cndmask_b32_e64 v120, 0, v120, s[52:53]
	v_cndmask_b32_e32 v121, 0, v121, vcc
	v_cvt_pk_bf16_f32 v152, v114, v115
	v_cvt_pk_bf16_f32 v153, v116, v117
	v_cvt_pk_bf16_f32 v154, v118, v119
	v_cvt_pk_bf16_f32 v155, v120, v121
	ds_read_b128 v[34:37], v194 offset:0
	ds_read_b128 v[38:41], v194 offset:4352
	ds_read_b128 v[42:45], v194 offset:8704
	ds_read_b128 v[46:49], v194 offset:13056
	ds_read_b128 v[50:53], v194 offset:17408
	ds_read_b128 v[54:57], v194 offset:21760
	ds_read_b128 v[58:61], v194 offset:26112
	ds_read_b128 v[62:65], v194 offset:30464
	s_waitcnt vmcnt(0)
; __device__ __forceinline__ unsigned cvt_pk_bf16(float lo, float hi) { unsigned r; asm volatile("v_cvt_pk_bf16_f32 %0, %1, %2" : "=v"(r) : "v"(lo), "v"(hi)); return r; }
; #define LAS __attribute__((address_space(3)))
; #define MFMA16(a, b, c) __builtin_amdgcn_mfma_f32_16x16x32_bf16((a), (b), (c), 0, 0, 0)
; __device__ __forceinline__ void p2_block(LAS unsigned char* lds, const bf16_t* __restrict__ PROJ, bf16_t* __restrict__ ATT, bf16_t* __restrict__ SGU, const float* __restrict__ qn, const float* __restrict__ kn, ...
;     ...
;         for (int ks = 0; ks < 4; ++ks) if (ks < nks) {
;             const f32x4 wa = *(const f32x4*)(wrow + 32 * ks), wb = *(const f32x4*)(wrow + 32 * ks + 4);
;             const int j0 = 32 * ks + 8 * fq; float wv[8];
; #pragma unroll
;             for (int e = 0; e < 4; ++e) { wv[e] = (j0 + e <= irow) ? wa[e] : 0.f; wv[4 + e] = (j0 + 4 + e <= irow) ? wb[e] : 0.f; }
;             u32x4 ww; ww.x = cvt_pk_bf16(wv[0], wv[1]); ww.y = cvt_pk_bf16(wv[2], wv[3]); ww.z = cvt_pk_bf16(wv[4], wv[5]); ww.w = cvt_pk_bf16(wv[6], wv[7]);
;             const bf16x8 wf = __builtin_bit_cast(bf16x8, ww);
; #pragma unroll
;             for (int dt = 0; dt < 8; ++dt) { const bf16x8 af = *(const LAS bf16x8*)(VNT + (16 * dt + fr) * VN_STRIDE + (32 * ks + 8 * fq) * 2); acc[dt] = MFMA16(af, wf, acc[dt]); }
	v_mov_b32_e32 v196, v195
	v_cmp_le_i32_e64 s[40:41], 0, v196
	v_cmp_le_i32_e64 s[42:43], 1, v196
	v_cmp_le_i32_e64 s[44:45], 2, v196
	v_cmp_le_i32_e64 s[46:47], 3, v196
	v_cmp_le_i32_e64 s[48:49], 4, v196
	v_cmp_le_i32_e64 s[50:51], 5, v196
	v_cmp_le_i32_e64 s[52:53], 6, v196
	v_cmp_le_i32_e32 vcc, 7, v196
	v_cndmask_b32_e64 v66, 0, v66, s[40:41]
	v_cndmask_b32_e64 v67, 0, v67, s[42:43]
	v_cndmask_b32_e64 v68, 0, v68, s[44:45]
	v_cndmask_b32_e64 v69, 0, v69, s[46:47]
	v_cndmask_b32_e64 v70, 0, v70, s[48:49]
	v_cndmask_b32_e64 v71, 0, v71, s[50:51]
	v_cndmask_b32_e64 v72, 0, v72, s[52:53]
	v_cndmask_b32_e32 v73, 0, v73, vcc
	v_cvt_pk_bf16_f32 v98, v66, v67
	v_cvt_pk_bf16_f32 v99, v68, v69
	v_cvt_pk_bf16_f32 v100, v70, v71
	v_cvt_pk_bf16_f32 v101, v72, v73
	v_add_u32_e32 v196, 4294967264, v195
	v_cmp_le_i32_e64 s[40:41], 0, v196
	v_cmp_le_i32_e64 s[42:43], 1, v196
	v_cmp_le_i32_e64 s[44:45], 2, v196
	v_cmp_le_i32_e64 s[46:47], 3, v196
	v_cmp_le_i32_e64 s[48:49], 4, v196
	v_cmp_le_i32_e64 s[50:51], 5, v196
	v_cmp_le_i32_e64 s[52:53], 6, v196
	v_cmp_le_i32_e32 vcc, 7, v196
	v_cndmask_b32_e64 v74, 0, v74, s[40:41]
	v_cndmask_b32_e64 v75, 0, v75, s[42:43]
	v_cndmask_b32_e64 v76, 0, v76, s[44:45]
	v_cndmask_b32_e64 v77, 0, v77, s[46:47]
	v_cndmask_b32_e64 v78, 0, v78, s[48:49]
	v_cndmask_b32_e64 v79, 0, v79, s[50:51]
	v_cndmask_b32_e64 v80, 0, v80, s[52:53]
	v_cndmask_b32_e32 v81, 0, v81, vcc
	v_cvt_pk_bf16_f32 v102, v74, v75
	v_cvt_pk_bf16_f32 v103, v76, v77
	v_cvt_pk_bf16_f32 v104, v78, v79
	v_cvt_pk_bf16_f32 v105, v80, v81
	v_add_u32_e32 v196, 4294967232, v195
	v_cmp_le_i32_e64 s[40:41], 0, v196
	v_cmp_le_i32_e64 s[42:43], 1, v196
	v_cmp_le_i32_e64 s[44:45], 2, v196
	v_cmp_le_i32_e64 s[46:47], 3, v196
	v_cmp_le_i32_e64 s[48:49], 4, v196
	v_cmp_le_i32_e64 s[50:51], 5, v196
	v_cmp_le_i32_e64 s[52:53], 6, v196
	v_cmp_le_i32_e32 vcc, 7, v196
	v_cndmask_b32_e64 v82, 0, v82, s[40:41]
	v_cndmask_b32_e64 v83, 0, v83, s[42:43]
	v_cndmask_b32_e64 v84, 0, v84, s[44:45]
	v_cndmask_b32_e64 v85, 0, v85, s[46:47]
	v_cndmask_b32_e64 v86, 0, v86, s[48:49]
	v_cndmask_b32_e64 v87, 0, v87, s[50:51]
	v_cndmask_b32_e64 v88, 0, v88, s[52:53]
	v_cndmask_b32_e32 v89, 0, v89, vcc
	v_cvt_pk_bf16_f32 v106, v82, v83
	v_cvt_pk_bf16_f32 v107, v84, v85
	v_cvt_pk_bf16_f32 v108, v86, v87
	v_cvt_pk_bf16_f32 v109, v88, v89
	ds_read_b128 v[66:69], v194 offset:64
	ds_read_b128 v[70:73], v194 offset:4416
	ds_read_b128 v[74:77], v194 offset:8768
	ds_read_b128 v[78:81], v194 offset:13120
	ds_read_b128 v[82:85], v194 offset:17472
	ds_read_b128 v[86:89], v194 offset:21824
	ds_read_b128 v[90:93], v194 offset:26176
	ds_read_b128 v[94:97], v194 offset:30528
	s_waitcnt lgkmcnt(15)
	v_mfma_f32_16x16x32_bf16 v[2:5], v[34:37], v[144:147], 0
	s_waitcnt lgkmcnt(14)
	v_mfma_f32_16x16x32_bf16 v[6:9], v[38:41], v[144:147], 0
	s_waitcnt lgkmcnt(13)
	v_mfma_f32_16x16x32_bf16 v[10:13], v[42:45], v[144:147], 0
	s_waitcnt lgkmcnt(12)
	v_mfma_f32_16x16x32_bf16 v[14:17], v[46:49], v[144:147], 0
	s_waitcnt lgkmcnt(11)
	v_mfma_f32_16x16x32_bf16 v[18:21], v[50:53], v[144:147], 0
	s_waitcnt lgkmcnt(10)
	v_mfma_f32_16x16x32_bf16 v[22:25], v[54:57], v[144:147], 0
	s_waitcnt lgkmcnt(9)
	v_mfma_f32_16x16x32_bf16 v[26:29], v[58:61], v[144:147], 0
	s_waitcnt lgkmcnt(8)
	v_mfma_f32_16x16x32_bf16 v[30:33], v[62:65], v[144:147], 0
	ds_read_b128 v[34:37], v194 offset:128
	ds_read_b128 v[38:41], v194 offset:4480
	ds_read_b128 v[42:45], v194 offset:8832
	ds_read_b128 v[46:49], v194 offset:13184
	ds_read_b128 v[50:53], v194 offset:17536
	ds_read_b128 v[54:57], v194 offset:21888
	ds_read_b128 v[58:61], v194 offset:26240
	ds_read_b128 v[62:65], v194 offset:30592
	s_waitcnt lgkmcnt(15)
	v_mfma_f32_16x16x32_bf16 v[2:5], v[66:69], v[148:151], v[2:5]
	s_waitcnt lgkmcnt(14)
	v_mfma_f32_16x16x32_bf16 v[6:9], v[70:73], v[148:151], v[6:9]
	s_waitcnt lgkmcnt(13)
	v_mfma_f32_16x16x32_bf16 v[10:13], v[74:77], v[148:151], v[10:13]
	s_waitcnt lgkmcnt(12)
	v_mfma_f32_16x16x32_bf16 v[14:17], v[78:81], v[148:151], v[14:17]
	s_waitcnt lgkmcnt(11)
	v_mfma_f32_16x16x32_bf16 v[18:21], v[82:85], v[148:151], v[18:21]
	s_waitcnt lgkmcnt(10)
	v_mfma_f32_16x16x32_bf16 v[22:25], v[86:89], v[148:151], v[22:25]
	s_waitcnt lgkmcnt(9)
	v_mfma_f32_16x16x32_bf16 v[26:29], v[90:93], v[148:151], v[26:29]
	s_waitcnt lgkmcnt(8)
	v_mfma_f32_16x16x32_bf16 v[30:33], v[94:97], v[148:151], v[30:33]
	ds_read_b128 v[66:69], v194 offset:34816
	ds_read_b128 v[70:73], v194 offset:39168
	ds_read_b128 v[74:77], v194 offset:43520
	ds_read_b128 v[78:81], v194 offset:47872
	ds_read_b128 v[82:85], v194 offset:52224
	ds_read_b128 v[86:89], v194 offset:56576
	ds_read_b128 v[90:93], v194 offset:60928
	ds_read_b128 v[94:97], v194 offset:65280
	s_waitcnt lgkmcnt(15)
	v_mfma_f32_16x16x32_bf16 v[2:5], v[34:37], v[152:155], v[2:5]
	s_waitcnt lgkmcnt(14)
	v_mfma_f32_16x16x32_bf16 v[6:9], v[38:41], v[152:155], v[6:9]
	s_waitcnt lgkmcnt(13)
	v_mfma_f32_16x16x32_bf16 v[10:13], v[42:45], v[152:155], v[10:13]
	s_waitcnt lgkmcnt(12)
	v_mfma_f32_16x16x32_bf16 v[14:17], v[46:49], v[152:155], v[14:17]
	s_waitcnt lgkmcnt(11)
	v_mfma_f32_16x16x32_bf16 v[18:21], v[50:53], v[152:155], v[18:21]
	s_waitcnt lgkmcnt(10)
	v_mfma_f32_16x16x32_bf16 v[22:25], v[54:57], v[152:155], v[22:25]
	s_waitcnt lgkmcnt(9)
	v_mfma_f32_16x16x32_bf16 v[26:29], v[58:61], v[152:155], v[26:29]
	s_waitcnt lgkmcnt(8)
	v_mfma_f32_16x16x32_bf16 v[30:33], v[62:65], v[152:155], v[30:33]
	ds_read_b128 v[34:37], v194 offset:34880
	ds_read_b128 v[38:41], v194 offset:39232
	ds_read_b128 v[42:45], v194 offset:43584
	ds_read_b128 v[46:49], v194 offset:47936
	ds_read_b128 v[50:53], v194 offset:52288
	ds_read_b128 v[54:57], v194 offset:56640
	ds_read_b128 v[58:61], v194 offset:60992
	ds_read_b128 v[62:65], v194 offset:65344
	s_waitcnt lgkmcnt(15)
; __device__ __forceinline__ unsigned cvt_pk_bf16(float lo, float hi) { unsigned r; asm volatile("v_cvt_pk_bf16_f32 %0, %1, %2" : "=v"(r) : "v"(lo), "v"(hi)); return r; }
; #define LAS __attribute__((address_space(3)))
; #define MFMA16(a, b, c) __builtin_amdgcn_mfma_f32_16x16x32_bf16((a), (b), (c), 0, 0, 0)
; __device__ __forceinline__ void p2_block(LAS unsigned char* lds, const bf16_t* __restrict__ PROJ, bf16_t* __restrict__ ATT, bf16_t* __restrict__ SGU, const float* __restrict__ qn, const float* __restrict__ kn, ...
;     ...
;         for (int ks = 0; ks < 4; ++ks) if (ks < nks) {
;             const f32x4 wa = *(const f32x4*)(wrow + 32 * ks), wb = *(const f32x4*)(wrow + 32 * ks + 4);
;             const int j0 = 32 * ks + 8 * fq; float wv[8];
; #pragma unroll
;             for (int e = 0; e < 4; ++e) { wv[e] = (j0 + e <= irow) ? wa[e] : 0.f; wv[4 + e] = (j0 + 4 + e <= irow) ? wb[e] : 0.f; }
;             u32x4 ww; ww.x = cvt_pk_bf16(wv[0], wv[1]); ww.y = cvt_pk_bf16(wv[2], wv[3]); ww.z = cvt_pk_bf16(wv[4], wv[5]); ww.w = cvt_pk_bf16(wv[6], wv[7]);
;             const bf16x8 wf = __builtin_bit_cast(bf16x8, ww);
; #pragma unroll
;             for (int dt = 0; dt < 8; ++dt) { const bf16x8 af = *(const LAS bf16x8*)(VNT + (16 * dt + fr) * VN_STRIDE + (32 * ks + 8 * fq) * 2); acc[dt] = MFMA16(af, wf, acc[dt]); }
	v_mfma_f32_16x16x32_bf16 v[114:117], v[66:69], v[98:101], 0
	s_waitcnt lgkmcnt(14)
	v_mfma_f32_16x16x32_bf16 v[118:121], v[70:73], v[98:101], 0
	s_waitcnt lgkmcnt(13)
	v_mfma_f32_16x16x32_bf16 v[122:125], v[74:77], v[98:101], 0
	s_waitcnt lgkmcnt(12)
	v_mfma_f32_16x16x32_bf16 v[126:129], v[78:81], v[98:101], 0
	s_waitcnt lgkmcnt(11)
	v_mfma_f32_16x16x32_bf16 v[130:133], v[82:85], v[98:101], 0
	s_waitcnt lgkmcnt(10)
	v_mfma_f32_16x16x32_bf16 v[134:137], v[86:89], v[98:101], 0
	s_waitcnt lgkmcnt(9)
	v_mfma_f32_16x16x32_bf16 v[138:141], v[90:93], v[98:101], 0
	s_waitcnt lgkmcnt(8)
	v_mfma_f32_16x16x32_bf16 v[160:163], v[94:97], v[98:101], 0
	ds_read_b128 v[66:69], v194 offset:34944
	ds_read_b128 v[70:73], v194 offset:39296
	ds_read_b128 v[74:77], v194 offset:43648
	ds_read_b128 v[78:81], v194 offset:48000
	ds_read_b128 v[82:85], v194 offset:52352
	ds_read_b128 v[86:89], v194 offset:56704
	ds_read_b128 v[90:93], v194 offset:61056
	ds_read_b128 v[94:97], v194 offset:65408
	s_waitcnt lgkmcnt(15)
	v_mfma_f32_16x16x32_bf16 v[114:117], v[34:37], v[102:105], v[114:117]
	s_waitcnt lgkmcnt(14)
	v_mfma_f32_16x16x32_bf16 v[118:121], v[38:41], v[102:105], v[118:121]
	s_waitcnt lgkmcnt(13)
	v_mfma_f32_16x16x32_bf16 v[122:125], v[42:45], v[102:105], v[122:125]
	s_waitcnt lgkmcnt(12)
	v_mfma_f32_16x16x32_bf16 v[126:129], v[46:49], v[102:105], v[126:129]
	s_waitcnt lgkmcnt(11)
	v_mfma_f32_16x16x32_bf16 v[130:133], v[50:53], v[102:105], v[130:133]
	s_waitcnt lgkmcnt(10)
	v_mfma_f32_16x16x32_bf16 v[134:137], v[54:57], v[102:105], v[134:137]
	s_waitcnt lgkmcnt(9)
	v_mfma_f32_16x16x32_bf16 v[138:141], v[58:61], v[102:105], v[138:141]
	s_waitcnt lgkmcnt(8)
	v_mfma_f32_16x16x32_bf16 v[160:163], v[62:65], v[102:105], v[160:163]
	s_waitcnt lgkmcnt(7)
	v_mfma_f32_16x16x32_bf16 v[114:117], v[66:69], v[106:109], v[114:117]
	s_waitcnt lgkmcnt(6)
	v_mfma_f32_16x16x32_bf16 v[118:121], v[70:73], v[106:109], v[118:121]
	s_waitcnt lgkmcnt(5)
	v_mfma_f32_16x16x32_bf16 v[122:125], v[74:77], v[106:109], v[122:125]
	s_waitcnt lgkmcnt(4)
	v_mfma_f32_16x16x32_bf16 v[126:129], v[78:81], v[106:109], v[126:129]
	s_waitcnt lgkmcnt(3)
	v_mfma_f32_16x16x32_bf16 v[130:133], v[82:85], v[106:109], v[130:133]
	s_waitcnt lgkmcnt(2)
	v_mfma_f32_16x16x32_bf16 v[134:137], v[86:89], v[106:109], v[134:137]
	s_waitcnt lgkmcnt(1)
	v_mfma_f32_16x16x32_bf16 v[138:141], v[90:93], v[106:109], v[138:141]
	s_waitcnt lgkmcnt(0)
	v_mfma_f32_16x16x32_bf16 v[160:163], v[94:97], v[106:109], v[160:163]
	s_branch .Lsgu_epi
.Lsgu_n4:
	s_waitcnt vmcnt(8)
	v_mov_b32_e32 v196, v195
	v_cmp_le_i32_e64 s[40:41], 0, v196
	v_cmp_le_i32_e64 s[42:43], 1, v196
	v_cmp_le_i32_e64 s[44:45], 2, v196
	v_cmp_le_i32_e64 s[46:47], 3, v196
	v_cmp_le_i32_e64 s[48:49], 4, v196
	v_cmp_le_i32_e64 s[50:51], 5, v196
	v_cmp_le_i32_e64 s[52:53], 6, v196
	v_cmp_le_i32_e32 vcc, 7, v196
	v_cndmask_b32_e64 v98, 0, v98, s[40:41]
	v_cndmask_b32_e64 v99, 0, v99, s[42:43]
	v_cndmask_b32_e64 v100, 0, v100, s[44:45]
	v_cndmask_b32_e64 v101, 0, v101, s[46:47]
	v_cndmask_b32_e64 v102, 0, v102, s[48:49]
	v_cndmask_b32_e64 v103, 0, v103, s[50:51]
	v_cndmask_b32_e64 v104, 0, v104, s[52:53]
	v_cndmask_b32_e32 v105, 0, v105, vcc
	v_cvt_pk_bf16_f32 v144, v98, v99
	v_cvt_pk_bf16_f32 v145, v100, v101
	v_cvt_pk_bf16_f32 v146, v102, v103
	v_cvt_pk_bf16_f32 v147, v104, v105
	v_add_u32_e32 v196, 4294967264, v195
	v_cmp_le_i32_e64 s[40:41], 0, v196
	v_cmp_le_i32_e64 s[42:43], 1, v196
	v_cmp_le_i32_e64 s[44:45], 2, v196
	v_cmp_le_i32_e64 s[46:47], 3, v196
	v_cmp_le_i32_e64 s[48:49], 4, v196
	v_cmp_le_i32_e64 s[50:51], 5, v196
	v_cmp_le_i32_e64 s[52:53], 6, v196
	v_cmp_le_i32_e32 vcc, 7, v196
	v_cndmask_b32_e64 v106, 0, v106, s[40:41]
	v_cndmask_b32_e64 v107, 0, v107, s[42:43]
	v_cndmask_b32_e64 v108, 0, v108, s[44:45]
	v_cndmask_b32_e64 v109, 0, v109, s[46:47]
	v_cndmask_b32_e64 v110, 0, v110, s[48:49]
	v_cndmask_b32_e64 v111, 0, v111, s[50:51]
	v_cndmask_b32_e64 v112, 0, v112, s[52:53]
	v_cndmask_b32_e32 v113, 0, v113, vcc
	v_cvt_pk_bf16_f32 v148, v106, v107
	v_cvt_pk_bf16_f32 v149, v108, v109
	v_cvt_pk_bf16_f32 v150, v110, v111
	v_cvt_pk_bf16_f32 v151, v112, v113
	v_add_u32_e32 v196, 4294967232, v195
	v_cmp_le_i32_e64 s[40:41], 0, v196
	v_cmp_le_i32_e64 s[42:43], 1, v196
	v_cmp_le_i32_e64 s[44:45], 2, v196
	v_cmp_le_i32_e64 s[46:47], 3, v196
	v_cmp_le_i32_e64 s[48:49], 4, v196
	v_cmp_le_i32_e64 s[50:51], 5, v196
	v_cmp_le_i32_e64 s[52:53], 6, v196
	v_cmp_le_i32_e32 vcc, 7, v196
	v_cndmask_b32_e64 v114, 0, v114, s[40:41]
	v_cndmask_b32_e64 v115, 0, v115, s[42:43]
	v_cndmask_b32_e64 v116, 0, v116, s[44:45]
	v_cndmask_b32_e64 v117, 0, v117, s[46:47]
	v_cndmask_b32_e64 v118, 0, v118, s[48:49]
	v_cndmask_b32_e64 v119, 0, v119, s[50:51]
	v_cndmask_b32_e64 v120, 0, v120, s[52:53]
	v_cndmask_b32_e32 v121, 0, v121, vcc
	v_cvt_pk_bf16_f32 v152, v114, v115
	v_cvt_pk_bf16_f32 v153, v116, v117
	v_cvt_pk_bf16_f32 v154, v118, v119
	v_cvt_pk_bf16_f32 v155, v120, v121
	v_add_u32_e32 v196, 4294967200, v195
	v_cmp_le_i32_e64 s[40:41], 0, v196
	v_cmp_le_i32_e64 s[42:43], 1, v196
	v_cmp_le_i32_e64 s[44:45], 2, v196
	v_cmp_le_i32_e64 s[46:47], 3, v196
	v_cmp_le_i32_e64 s[48:49], 4, v196
	v_cmp_le_i32_e64 s[50:51], 5, v196
	v_cmp_le_i32_e64 s[52:53], 6, v196
	v_cmp_le_i32_e32 vcc, 7, v196
	v_cndmask_b32_e64 v122, 0, v122, s[40:41]
	v_cndmask_b32_e64 v123, 0, v123, s[42:43]
	v_cndmask_b32_e64 v124, 0, v124, s[44:45]
	v_cndmask_b32_e64 v125, 0, v125, s[46:47]
	v_cndmask_b32_e64 v126, 0, v126, s[48:49]
	v_cndmask_b32_e64 v127, 0, v127, s[50:51]
	v_cndmask_b32_e64 v128, 0, v128, s[52:53]
	v_cndmask_b32_e32 v129, 0, v129, vcc
	v_cvt_pk_bf16_f32 v156, v122, v123
	v_cvt_pk_bf16_f32 v157, v124, v125
	v_cvt_pk_bf16_f32 v158, v126, v127
	v_cvt_pk_bf16_f32 v159, v128, v129
	ds_read_b128 v[34:37], v194 offset:0
	ds_read_b128 v[38:41], v194 offset:4352
	ds_read_b128 v[42:45], v194 offset:8704
	ds_read_b128 v[46:49], v194 offset:13056
	ds_read_b128 v[50:53], v194 offset:17408
	ds_read_b128 v[54:57], v194 offset:21760
	ds_read_b128 v[58:61], v194 offset:26112
	ds_read_b128 v[62:65], v194 offset:30464
	s_waitcnt vmcnt(0)
; __device__ __forceinline__ unsigned cvt_pk_bf16(float lo, float hi) { unsigned r; asm volatile("v_cvt_pk_bf16_f32 %0, %1, %2" : "=v"(r) : "v"(lo), "v"(hi)); return r; }
; #define LAS __attribute__((address_space(3)))
; #define MFMA16(a, b, c) __builtin_amdgcn_mfma_f32_16x16x32_bf16((a), (b), (c), 0, 0, 0)
; __device__ __forceinline__ void p2_block(LAS unsigned char* lds, const bf16_t* __restrict__ PROJ, bf16_t* __restrict__ ATT, bf16_t* __restrict__ SGU, const float* __restrict__ qn, const float* __restrict__ kn, ...
;     ...
;         for (int ks = 0; ks < 4; ++ks) if (ks < nks) {
;             const f32x4 wa = *(const f32x4*)(wrow + 32 * ks), wb = *(const f32x4*)(wrow + 32 * ks + 4);
;             const int j0 = 32 * ks + 8 * fq; float wv[8];
; #pragma unroll
;             for (int e = 0; e < 4; ++e) { wv[e] = (j0 + e <= irow) ? wa[e] : 0.f; wv[4 + e] = (j0 + 4 + e <= irow) ? wb[e] : 0.f; }
;             u32x4 ww; ww.x = cvt_pk_bf16(wv[0], wv[1]); ww.y = cvt_pk_bf16(wv[2], wv[3]); ww.z = cvt_pk_bf16(wv[4], wv[5]); ww.w = cvt_pk_bf16(wv[6], wv[7]);
;             const bf16x8 wf = __builtin_bit_cast(bf16x8, ww);
; #pragma unroll
;             for (int dt = 0; dt < 8; ++dt) { const bf16x8 af = *(const LAS bf16x8*)(VNT + (16 * dt + fr) * VN_STRIDE + (32 * ks + 8 * fq) * 2); acc[dt] = MFMA16(af, wf, acc[dt]); }
	v_mov_b32_e32 v196, v195
	v_cmp_le_i32_e64 s[40:41], 0, v196
	v_cmp_le_i32_e64 s[42:43], 1, v196
	v_cmp_le_i32_e64 s[44:45], 2, v196
	v_cmp_le_i32_e64 s[46:47], 3, v196
	v_cmp_le_i32_e64 s[48:49], 4, v196
	v_cmp_le_i32_e64 s[50:51], 5, v196
	v_cmp_le_i32_e64 s[52:53], 6, v196
	v_cmp_le_i32_e32 vcc, 7, v196
	v_cndmask_b32_e64 v66, 0, v66, s[40:41]
	v_cndmask_b32_e64 v67, 0, v67, s[42:43]
	v_cndmask_b32_e64 v68, 0, v68, s[44:45]
	v_cndmask_b32_e64 v69, 0, v69, s[46:47]
	v_cndmask_b32_e64 v70, 0, v70, s[48:49]
	v_cndmask_b32_e64 v71, 0, v71, s[50:51]
	v_cndmask_b32_e64 v72, 0, v72, s[52:53]
	v_cndmask_b32_e32 v73, 0, v73, vcc
	v_cvt_pk_bf16_f32 v98, v66, v67
	v_cvt_pk_bf16_f32 v99, v68, v69
	v_cvt_pk_bf16_f32 v100, v70, v71
	v_cvt_pk_bf16_f32 v101, v72, v73
	v_add_u32_e32 v196, 4294967264, v195
	v_cmp_le_i32_e64 s[40:41], 0, v196
	v_cmp_le_i32_e64 s[42:43], 1, v196
	v_cmp_le_i32_e64 s[44:45], 2, v196
	v_cmp_le_i32_e64 s[46:47], 3, v196
	v_cmp_le_i32_e64 s[48:49], 4, v196
	v_cmp_le_i32_e64 s[50:51], 5, v196
	v_cmp_le_i32_e64 s[52:53], 6, v196
	v_cmp_le_i32_e32 vcc, 7, v196
	v_cndmask_b32_e64 v74, 0, v74, s[40:41]
	v_cndmask_b32_e64 v75, 0, v75, s[42:43]
	v_cndmask_b32_e64 v76, 0, v76, s[44:45]
	v_cndmask_b32_e64 v77, 0, v77, s[46:47]
	v_cndmask_b32_e64 v78, 0, v78, s[48:49]
	v_cndmask_b32_e64 v79, 0, v79, s[50:51]
	v_cndmask_b32_e64 v80, 0, v80, s[52:53]
	v_cndmask_b32_e32 v81, 0, v81, vcc
	v_cvt_pk_bf16_f32 v102, v74, v75
	v_cvt_pk_bf16_f32 v103, v76, v77
	v_cvt_pk_bf16_f32 v104, v78, v79
	v_cvt_pk_bf16_f32 v105, v80, v81
	v_add_u32_e32 v196, 4294967232, v195
	v_cmp_le_i32_e64 s[40:41], 0, v196
	v_cmp_le_i32_e64 s[42:43], 1, v196
	v_cmp_le_i32_e64 s[44:45], 2, v196
	v_cmp_le_i32_e64 s[46:47], 3, v196
	v_cmp_le_i32_e64 s[48:49], 4, v196
	v_cmp_le_i32_e64 s[50:51], 5, v196
	v_cmp_le_i32_e64 s[52:53], 6, v196
	v_cmp_le_i32_e32 vcc, 7, v196
	v_cndmask_b32_e64 v82, 0, v82, s[40:41]
	v_cndmask_b32_e64 v83, 0, v83, s[42:43]
	v_cndmask_b32_e64 v84, 0, v84, s[44:45]
	v_cndmask_b32_e64 v85, 0, v85, s[46:47]
	v_cndmask_b32_e64 v86, 0, v86, s[48:49]
	v_cndmask_b32_e64 v87, 0, v87, s[50:51]
	v_cndmask_b32_e64 v88, 0, v88, s[52:53]
	v_cndmask_b32_e32 v89, 0, v89, vcc
	v_cvt_pk_bf16_f32 v106, v82, v83
	v_cvt_pk_bf16_f32 v107, v84, v85
	v_cvt_pk_bf16_f32 v108, v86, v87
	v_cvt_pk_bf16_f32 v109, v88, v89
	v_add_u32_e32 v196, 4294967200, v195
	v_cmp_le_i32_e64 s[40:41], 0, v196
	v_cmp_le_i32_e64 s[42:43], 1, v196
	v_cmp_le_i32_e64 s[44:45], 2, v196
	v_cmp_le_i32_e64 s[46:47], 3, v196
	v_cmp_le_i32_e64 s[48:49], 4, v196
	v_cmp_le_i32_e64 s[50:51], 5, v196
	v_cmp_le_i32_e64 s[52:53], 6, v196
	v_cmp_le_i32_e32 vcc, 7, v196
	v_cndmask_b32_e64 v90, 0, v90, s[40:41]
	v_cndmask_b32_e64 v91, 0, v91, s[42:43]
	v_cndmask_b32_e64 v92, 0, v92, s[44:45]
	v_cndmask_b32_e64 v93, 0, v93, s[46:47]
	v_cndmask_b32_e64 v94, 0, v94, s[48:49]
	v_cndmask_b32_e64 v95, 0, v95, s[50:51]
	v_cndmask_b32_e64 v96, 0, v96, s[52:53]
	v_cndmask_b32_e32 v97, 0, v97, vcc
	v_cvt_pk_bf16_f32 v110, v90, v91
	v_cvt_pk_bf16_f32 v111, v92, v93
	v_cvt_pk_bf16_f32 v112, v94, v95
	v_cvt_pk_bf16_f32 v113, v96, v97
	ds_read_b128 v[66:69], v194 offset:64
	ds_read_b128 v[70:73], v194 offset:4416
	ds_read_b128 v[74:77], v194 offset:8768
	ds_read_b128 v[78:81], v194 offset:13120
	ds_read_b128 v[82:85], v194 offset:17472
	ds_read_b128 v[86:89], v194 offset:21824
	ds_read_b128 v[90:93], v194 offset:26176
	ds_read_b128 v[94:97], v194 offset:30528
	s_waitcnt lgkmcnt(15)
	v_mfma_f32_16x16x32_bf16 v[2:5], v[34:37], v[144:147], 0
	s_waitcnt lgkmcnt(14)
	v_mfma_f32_16x16x32_bf16 v[6:9], v[38:41], v[144:147], 0
	s_waitcnt lgkmcnt(13)
	v_mfma_f32_16x16x32_bf16 v[10:13], v[42:45], v[144:147], 0
	s_waitcnt lgkmcnt(12)
	v_mfma_f32_16x16x32_bf16 v[14:17], v[46:49], v[144:147], 0
	s_waitcnt lgkmcnt(11)
	v_mfma_f32_16x16x32_bf16 v[18:21], v[50:53], v[144:147], 0
	s_waitcnt lgkmcnt(10)
	v_mfma_f32_16x16x32_bf16 v[22:25], v[54:57], v[144:147], 0
	s_waitcnt lgkmcnt(9)
	v_mfma_f32_16x16x32_bf16 v[26:29], v[58:61], v[144:147], 0
	s_waitcnt lgkmcnt(8)
	v_mfma_f32_16x16x32_bf16 v[30:33], v[62:65], v[144:147], 0
	ds_read_b128 v[34:37], v194 offset:128
	ds_read_b128 v[38:41], v194 offset:4480
	ds_read_b128 v[42:45], v194 offset:8832
	ds_read_b128 v[46:49], v194 offset:13184
	ds_read_b128 v[50:53], v194 offset:17536
	ds_read_b128 v[54:57], v194 offset:21888
	ds_read_b128 v[58:61], v194 offset:26240
	ds_read_b128 v[62:65], v194 offset:30592
	s_waitcnt lgkmcnt(15)
	v_mfma_f32_16x16x32_bf16 v[2:5], v[66:69], v[148:151], v[2:5]
	s_waitcnt lgkmcnt(14)
	v_mfma_f32_16x16x32_bf16 v[6:9], v[70:73], v[148:151], v[6:9]
	s_waitcnt lgkmcnt(13)
	v_mfma_f32_16x16x32_bf16 v[10:13], v[74:77], v[148:151], v[10:13]
	s_waitcnt lgkmcnt(12)
	v_mfma_f32_16x16x32_bf16 v[14:17], v[78:81], v[148:151], v[14:17]
	s_waitcnt lgkmcnt(11)
	v_mfma_f32_16x16x32_bf16 v[18:21], v[82:85], v[148:151], v[18:21]
	s_waitcnt lgkmcnt(10)
	v_mfma_f32_16x16x32_bf16 v[22:25], v[86:89], v[148:151], v[22:25]
	s_waitcnt lgkmcnt(9)
	v_mfma_f32_16x16x32_bf16 v[26:29], v[90:93], v[148:151], v[26:29]
	s_waitcnt lgkmcnt(8)
	v_mfma_f32_16x16x32_bf16 v[30:33], v[94:97], v[148:151], v[30:33]
	ds_read_b128 v[66:69], v194 offset:192
	ds_read_b128 v[70:73], v194 offset:4544
	ds_read_b128 v[74:77], v194 offset:8896
	ds_read_b128 v[78:81], v194 offset:13248
	ds_read_b128 v[82:85], v194 offset:17600
	ds_read_b128 v[86:89], v194 offset:21952
	ds_read_b128 v[90:93], v194 offset:26304
	ds_read_b128 v[94:97], v194 offset:30656
	s_waitcnt lgkmcnt(15)
	v_mfma_f32_16x16x32_bf16 v[2:5], v[34:37], v[152:155], v[2:5]
	s_waitcnt lgkmcnt(14)
	v_mfma_f32_16x16x32_bf16 v[6:9], v[38:41], v[152:155], v[6:9]
	s_waitcnt lgkmcnt(13)
; __device__ __forceinline__ unsigned cvt_pk_bf16(float lo, float hi) { unsigned r; asm volatile("v_cvt_pk_bf16_f32 %0, %1, %2" : "=v"(r) : "v"(lo), "v"(hi)); return r; }
; #define LAS __attribute__((address_space(3)))
; #define MFMA16(a, b, c) __builtin_amdgcn_mfma_f32_16x16x32_bf16((a), (b), (c), 0, 0, 0)
; __device__ __forceinline__ void p2_block(LAS unsigned char* lds, const bf16_t* __restrict__ PROJ, bf16_t* __restrict__ ATT, bf16_t* __restrict__ SGU, const float* __restrict__ qn, const float* __restrict__ kn, ...
;     ...
;         for (int ks = 0; ks < 4; ++ks) if (ks < nks) {
;             const f32x4 wa = *(const f32x4*)(wrow + 32 * ks), wb = *(const f32x4*)(wrow + 32 * ks + 4);
;             const int j0 = 32 * ks + 8 * fq; float wv[8];
; #pragma unroll
;             for (int e = 0; e < 4; ++e) { wv[e] = (j0 + e <= irow) ? wa[e] : 0.f; wv[4 + e] = (j0 + 4 + e <= irow) ? wb[e] : 0.f; }
;             u32x4 ww; ww.x = cvt_pk_bf16(wv[0], wv[1]); ww.y = cvt_pk_bf16(wv[2], wv[3]); ww.z = cvt_pk_bf16(wv[4], wv[5]); ww.w = cvt_pk_bf16(wv[6], wv[7]);
;             const bf16x8 wf = __builtin_bit_cast(bf16x8, ww);
; #pragma unroll
;             for (int dt = 0; dt < 8; ++dt) { const bf16x8 af = *(const LAS bf16x8*)(VNT + (16 * dt + fr) * VN_STRIDE + (32 * ks + 8 * fq) * 2); acc[dt] = MFMA16(af, wf, acc[dt]); }
	v_mfma_f32_16x16x32_bf16 v[10:13], v[42:45], v[152:155], v[10:13]
	s_waitcnt lgkmcnt(12)
	v_mfma_f32_16x16x32_bf16 v[14:17], v[46:49], v[152:155], v[14:17]
	s_waitcnt lgkmcnt(11)
	v_mfma_f32_16x16x32_bf16 v[18:21], v[50:53], v[152:155], v[18:21]
	s_waitcnt lgkmcnt(10)
	v_mfma_f32_16x16x32_bf16 v[22:25], v[54:57], v[152:155], v[22:25]
	s_waitcnt lgkmcnt(9)
	v_mfma_f32_16x16x32_bf16 v[26:29], v[58:61], v[152:155], v[26:29]
	s_waitcnt lgkmcnt(8)
	v_mfma_f32_16x16x32_bf16 v[30:33], v[62:65], v[152:155], v[30:33]
	ds_read_b128 v[34:37], v194 offset:34816
	ds_read_b128 v[38:41], v194 offset:39168
	ds_read_b128 v[42:45], v194 offset:43520
	ds_read_b128 v[46:49], v194 offset:47872
	ds_read_b128 v[50:53], v194 offset:52224
	ds_read_b128 v[54:57], v194 offset:56576
	ds_read_b128 v[58:61], v194 offset:60928
	ds_read_b128 v[62:65], v194 offset:65280
	s_waitcnt lgkmcnt(15)
	v_mfma_f32_16x16x32_bf16 v[2:5], v[66:69], v[156:159], v[2:5]
	s_waitcnt lgkmcnt(14)
	v_mfma_f32_16x16x32_bf16 v[6:9], v[70:73], v[156:159], v[6:9]
	s_waitcnt lgkmcnt(13)
	v_mfma_f32_16x16x32_bf16 v[10:13], v[74:77], v[156:159], v[10:13]
	s_waitcnt lgkmcnt(12)
	v_mfma_f32_16x16x32_bf16 v[14:17], v[78:81], v[156:159], v[14:17]
	s_waitcnt lgkmcnt(11)
	v_mfma_f32_16x16x32_bf16 v[18:21], v[82:85], v[156:159], v[18:21]
	s_waitcnt lgkmcnt(10)
	v_mfma_f32_16x16x32_bf16 v[22:25], v[86:89], v[156:159], v[22:25]
	s_waitcnt lgkmcnt(9)
	v_mfma_f32_16x16x32_bf16 v[26:29], v[90:93], v[156:159], v[26:29]
	s_waitcnt lgkmcnt(8)
	v_mfma_f32_16x16x32_bf16 v[30:33], v[94:97], v[156:159], v[30:33]
	ds_read_b128 v[66:69], v194 offset:34880
	ds_read_b128 v[70:73], v194 offset:39232
	ds_read_b128 v[74:77], v194 offset:43584
	ds_read_b128 v[78:81], v194 offset:47936
	ds_read_b128 v[82:85], v194 offset:52288
	ds_read_b128 v[86:89], v194 offset:56640
	ds_read_b128 v[90:93], v194 offset:60992
	ds_read_b128 v[94:97], v194 offset:65344
	s_waitcnt lgkmcnt(15)
	v_mfma_f32_16x16x32_bf16 v[114:117], v[34:37], v[98:101], 0
	s_waitcnt lgkmcnt(14)
	v_mfma_f32_16x16x32_bf16 v[118:121], v[38:41], v[98:101], 0
	s_waitcnt lgkmcnt(13)
	v_mfma_f32_16x16x32_bf16 v[122:125], v[42:45], v[98:101], 0
	s_waitcnt lgkmcnt(12)
	v_mfma_f32_16x16x32_bf16 v[126:129], v[46:49], v[98:101], 0
	s_waitcnt lgkmcnt(11)
	v_mfma_f32_16x16x32_bf16 v[130:133], v[50:53], v[98:101], 0
	s_waitcnt lgkmcnt(10)
	v_mfma_f32_16x16x32_bf16 v[134:137], v[54:57], v[98:101], 0
	s_waitcnt lgkmcnt(9)
	v_mfma_f32_16x16x32_bf16 v[138:141], v[58:61], v[98:101], 0
	s_waitcnt lgkmcnt(8)
	v_mfma_f32_16x16x32_bf16 v[160:163], v[62:65], v[98:101], 0
	ds_read_b128 v[34:37], v194 offset:34944
	ds_read_b128 v[38:41], v194 offset:39296
	ds_read_b128 v[42:45], v194 offset:43648
	ds_read_b128 v[46:49], v194 offset:48000
	ds_read_b128 v[50:53], v194 offset:52352
	ds_read_b128 v[54:57], v194 offset:56704
	ds_read_b128 v[58:61], v194 offset:61056
	ds_read_b128 v[62:65], v194 offset:65408
	s_waitcnt lgkmcnt(15)
	v_mfma_f32_16x16x32_bf16 v[114:117], v[66:69], v[102:105], v[114:117]
	s_waitcnt lgkmcnt(14)
	v_mfma_f32_16x16x32_bf16 v[118:121], v[70:73], v[102:105], v[118:121]
	s_waitcnt lgkmcnt(13)
	v_mfma_f32_16x16x32_bf16 v[122:125], v[74:77], v[102:105], v[122:125]
	s_waitcnt lgkmcnt(12)
	v_mfma_f32_16x16x32_bf16 v[126:129], v[78:81], v[102:105], v[126:129]
	s_waitcnt lgkmcnt(11)
	v_mfma_f32_16x16x32_bf16 v[130:133], v[82:85], v[102:105], v[130:133]
	s_waitcnt lgkmcnt(10)
	v_mfma_f32_16x16x32_bf16 v[134:137], v[86:89], v[102:105], v[134:137]
	s_waitcnt lgkmcnt(9)
	v_mfma_f32_16x16x32_bf16 v[138:141], v[90:93], v[102:105], v[138:141]
	s_waitcnt lgkmcnt(8)
	v_mfma_f32_16x16x32_bf16 v[160:163], v[94:97], v[102:105], v[160:163]
	ds_read_b128 v[66:69], v194 offset:35008
	ds_read_b128 v[70:73], v194 offset:39360
	ds_read_b128 v[74:77], v194 offset:43712
	ds_read_b128 v[78:81], v194 offset:48064
	ds_read_b128 v[82:85], v194 offset:52416
	ds_read_b128 v[86:89], v194 offset:56768
	ds_read_b128 v[90:93], v194 offset:61120
	ds_read_b128 v[94:97], v194 offset:65472
	s_waitcnt lgkmcnt(15)
	v_mfma_f32_16x16x32_bf16 v[114:117], v[34:37], v[106:109], v[114:117]
	s_waitcnt lgkmcnt(14)
	v_mfma_f32_16x16x32_bf16 v[118:121], v[38:41], v[106:109], v[118:121]
	s_waitcnt lgkmcnt(13)
	v_mfma_f32_16x16x32_bf16 v[122:125], v[42:45], v[106:109], v[122:125]
	s_waitcnt lgkmcnt(12)
	v_mfma_f32_16x16x32_bf16 v[126:129], v[46:49], v[106:109], v[126:129]
	s_waitcnt lgkmcnt(11)
	v_mfma_f32_16x16x32_bf16 v[130:133], v[50:53], v[106:109], v[130:133]
	s_waitcnt lgkmcnt(10)
	v_mfma_f32_16x16x32_bf16 v[134:137], v[54:57], v[106:109], v[134:137]
	s_waitcnt lgkmcnt(9)
	v_mfma_f32_16x16x32_bf16 v[138:141], v[58:61], v[106:109], v[138:141]
	s_waitcnt lgkmcnt(8)
	v_mfma_f32_16x16x32_bf16 v[160:163], v[62:65], v[106:109], v[160:163]
	s_waitcnt lgkmcnt(7)
	v_mfma_f32_16x16x32_bf16 v[114:117], v[66:69], v[110:113], v[114:117]
	s_waitcnt lgkmcnt(6)
	v_mfma_f32_16x16x32_bf16 v[118:121], v[70:73], v[110:113], v[118:121]
	s_waitcnt lgkmcnt(5)
	v_mfma_f32_16x16x32_bf16 v[122:125], v[74:77], v[110:113], v[122:125]
	s_waitcnt lgkmcnt(4)
	v_mfma_f32_16x16x32_bf16 v[126:129], v[78:81], v[110:113], v[126:129]
	s_waitcnt lgkmcnt(3)
	v_mfma_f32_16x16x32_bf16 v[130:133], v[82:85], v[110:113], v[130:133]
	s_waitcnt lgkmcnt(2)
	v_mfma_f32_16x16x32_bf16 v[134:137], v[86:89], v[110:113], v[134:137]
	s_waitcnt lgkmcnt(1)
	v_mfma_f32_16x16x32_bf16 v[138:141], v[90:93], v[110:113], v[138:141]
	s_waitcnt lgkmcnt(0)
	v_mfma_f32_16x16x32_bf16 v[160:163], v[94:97], v[110:113], v[160:163]
	s_branch .Lsgu_epi
; __device__ __forceinline__ unsigned cvt_pk_bf16(float lo, float hi) { unsigned r; asm volatile("v_cvt_pk_bf16_f32 %0, %1, %2" : "=v"(r) : "v"(lo), "v"(hi)); return r; }
; __device__ __forceinline__ float bf_lo(unsigned w) { return __uint_as_float(w << 16); }
; __device__ __forceinline__ float bf_hi(unsigned w) { return __uint_as_float(w & 0xffff0000u); }
; __device__ __forceinline__ float gelu_f(float x) { const float y2 = 1.5957691216057308f * x * (1.0f + 0.044715f * x * x); return x * sigmoid_f(y2); }
; __device__ __forceinline__ void p2_block(LAS unsigned char* lds, const bf16_t* __restrict__ PROJ, bf16_t* __restrict__ ATT, bf16_t* __restrict__ SGU, const float* __restrict__ qn, const float* __restrict__ kn, ...
;     ...
;         const float bias = bsp[gg * 128 + irow];
;         const size_t grow = (size_t)b * pg8::SEQ + n * 128 + irow;
;         const bf16_t* up = PROJ + grow * pg8::IN_W + pg8::C_U + gg * 128 + 4 * fq; bf16_t* op = SGU + grow * 1024 + gg * 128 + 4 * fq;
; #pragma unroll
;         for (int dt = 0; dt < 8; ++dt) { const u32x2 uw = *(const u32x2*)(up + 16 * dt);
;             const float u0 = gelu_f(bf_lo(uw.x)), u1 = gelu_f(bf_hi(uw.x)), u2 = gelu_f(bf_lo(uw.y)), u3 = gelu_f(bf_hi(uw.y));
;             u32x2 ow; ow.x = cvt_pk_bf16(u0 * (acc[dt][0] + bias), u1 * (acc[dt][1] + bias)); ow.y = cvt_pk_bf16(u2 * (acc[dt][2] + bias), u3 * (acc[dt][3] + bias)); *(u32x2*)(op + 16 * dt) = ow; }
.Lsgu_epi:
	s_waitcnt vmcnt(0)
	v_lshlrev_b32_e32 v34, 16, v218
	v_and_b32_e32 v35, 0xffff0000, v218
	v_lshlrev_b32_e32 v36, 16, v219
	v_and_b32_e32 v37, 0xffff0000, v219
	v_mul_f32_e32 v38, 0x3d372713, v34
	v_mul_f32_e32 v39, 0x3d372713, v35
	v_mul_f32_e32 v40, 0x3d372713, v36
	v_mul_f32_e32 v41, 0x3d372713, v37
	v_mul_f32_e32 v42, 0x3fcc422a, v34
	v_mul_f32_e32 v43, 0x3fcc422a, v35
	v_mul_f32_e32 v44, 0x3fcc422a, v36
	v_mul_f32_e32 v45, 0x3fcc422a, v37
	v_fma_f32 v38, v38, v34, 1.0
	v_fma_f32 v39, v39, v35, 1.0
	v_fma_f32 v40, v40, v36, 1.0
	v_fma_f32 v41, v41, v37, 1.0
	v_mul_f32_e32 v42, v42, v38
	v_mul_f32_e32 v43, v43, v39
	v_mul_f32_e32 v44, v44, v40
	v_mul_f32_e32 v45, v45, v41
	v_mul_f32_e32 v42, 0xbfb8aa3b, v42
	v_mul_f32_e32 v43, 0xbfb8aa3b, v43
	v_mul_f32_e32 v44, 0xbfb8aa3b, v44
	v_mul_f32_e32 v45, 0xbfb8aa3b, v45
	v_exp_f32_e32 v42, v42
	v_exp_f32_e32 v43, v43
	v_exp_f32_e32 v44, v44
	v_exp_f32_e32 v45, v45
	v_add_f32_e32 v42, 1.0, v42
	v_add_f32_e32 v43, 1.0, v43
	v_add_f32_e32 v44, 1.0, v44
	v_add_f32_e32 v45, 1.0, v45
	v_rcp_f32_e32 v42, v42
	v_rcp_f32_e32 v43, v43
	v_rcp_f32_e32 v44, v44
	v_rcp_f32_e32 v45, v45
	v_mul_f32_e32 v34, v42, v34
	v_mul_f32_e32 v35, v43, v35
	v_mul_f32_e32 v36, v44, v36
	v_mul_f32_e32 v37, v45, v37
	v_add_f32_e32 v46, v198, v2
	v_add_f32_e32 v47, v198, v3
	v_add_f32_e32 v48, v198, v4
	v_add_f32_e32 v49, v198, v5
	v_mul_f32_e32 v46, v46, v34
	v_mul_f32_e32 v47, v47, v35
	v_mul_f32_e32 v48, v48, v36
	v_mul_f32_e32 v49, v49, v37
	v_cvt_pk_bf16_f32 v50, v46, v47
	v_cvt_pk_bf16_f32 v51, v48, v49
	global_store_dwordx2 v189, v[50:51], s[12:13] offset:0
	v_lshlrev_b32_e32 v34, 16, v220
	v_and_b32_e32 v35, 0xffff0000, v220
	v_lshlrev_b32_e32 v36, 16, v221
	v_and_b32_e32 v37, 0xffff0000, v221
	v_mul_f32_e32 v38, 0x3d372713, v34
	v_mul_f32_e32 v39, 0x3d372713, v35
	v_mul_f32_e32 v40, 0x3d372713, v36
	v_mul_f32_e32 v41, 0x3d372713, v37
	v_mul_f32_e32 v42, 0x3fcc422a, v34
	v_mul_f32_e32 v43, 0x3fcc422a, v35
	v_mul_f32_e32 v44, 0x3fcc422a, v36
	v_mul_f32_e32 v45, 0x3fcc422a, v37
	v_fma_f32 v38, v38, v34, 1.0
	v_fma_f32 v39, v39, v35, 1.0
	v_fma_f32 v40, v40, v36, 1.0
	v_fma_f32 v41, v41, v37, 1.0
	v_mul_f32_e32 v42, v42, v38
	v_mul_f32_e32 v43, v43, v39
	v_mul_f32_e32 v44, v44, v40
	v_mul_f32_e32 v45, v45, v41
	v_mul_f32_e32 v42, 0xbfb8aa3b, v42
	v_mul_f32_e32 v43, 0xbfb8aa3b, v43
	v_mul_f32_e32 v44, 0xbfb8aa3b, v44
	v_mul_f32_e32 v45, 0xbfb8aa3b, v45
	v_exp_f32_e32 v42, v42
	v_exp_f32_e32 v43, v43
	v_exp_f32_e32 v44, v44
	v_exp_f32_e32 v45, v45
	v_add_f32_e32 v42, 1.0, v42
	v_add_f32_e32 v43, 1.0, v43
	v_add_f32_e32 v44, 1.0, v44
	v_add_f32_e32 v45, 1.0, v45
	v_rcp_f32_e32 v42, v42
	v_rcp_f32_e32 v43, v43
	v_rcp_f32_e32 v44, v44
	v_rcp_f32_e32 v45, v45
	v_mul_f32_e32 v34, v42, v34
	v_mul_f32_e32 v35, v43, v35
	v_mul_f32_e32 v36, v44, v36
	v_mul_f32_e32 v37, v45, v37
	v_add_f32_e32 v46, v198, v6
	v_add_f32_e32 v47, v198, v7
	v_add_f32_e32 v48, v198, v8
	v_add_f32_e32 v49, v198, v9
	v_mul_f32_e32 v46, v46, v34
	v_mul_f32_e32 v47, v47, v35
	v_mul_f32_e32 v48, v48, v36
	v_mul_f32_e32 v49, v49, v37
	v_cvt_pk_bf16_f32 v50, v46, v47
	v_cvt_pk_bf16_f32 v51, v48, v49
	global_store_dwordx2 v189, v[50:51], s[12:13] offset:32
	v_lshlrev_b32_e32 v34, 16, v222
	v_and_b32_e32 v35, 0xffff0000, v222
	v_lshlrev_b32_e32 v36, 16, v223
	v_and_b32_e32 v37, 0xffff0000, v223
	v_mul_f32_e32 v38, 0x3d372713, v34
	v_mul_f32_e32 v39, 0x3d372713, v35
	v_mul_f32_e32 v40, 0x3d372713, v36
	v_mul_f32_e32 v41, 0x3d372713, v37
	v_mul_f32_e32 v42, 0x3fcc422a, v34
	v_mul_f32_e32 v43, 0x3fcc422a, v35
	v_mul_f32_e32 v44, 0x3fcc422a, v36
	v_mul_f32_e32 v45, 0x3fcc422a, v37
	v_fma_f32 v38, v38, v34, 1.0
	v_fma_f32 v39, v39, v35, 1.0
	v_fma_f32 v40, v40, v36, 1.0
	v_fma_f32 v41, v41, v37, 1.0
	v_mul_f32_e32 v42, v42, v38
	v_mul_f32_e32 v43, v43, v39
	v_mul_f32_e32 v44, v44, v40
	v_mul_f32_e32 v45, v45, v41
	v_mul_f32_e32 v42, 0xbfb8aa3b, v42
	v_mul_f32_e32 v43, 0xbfb8aa3b, v43
	v_mul_f32_e32 v44, 0xbfb8aa3b, v44
	v_mul_f32_e32 v45, 0xbfb8aa3b, v45
	v_exp_f32_e32 v42, v42
	v_exp_f32_e32 v43, v43
	v_exp_f32_e32 v44, v44
	v_exp_f32_e32 v45, v45
	v_add_f32_e32 v42, 1.0, v42
	v_add_f32_e32 v43, 1.0, v43
	v_add_f32_e32 v44, 1.0, v44
	v_add_f32_e32 v45, 1.0, v45
	v_rcp_f32_e32 v42, v42
	v_rcp_f32_e32 v43, v43
	v_rcp_f32_e32 v44, v44
	v_rcp_f32_e32 v45, v45
	v_mul_f32_e32 v34, v42, v34
	v_mul_f32_e32 v35, v43, v35
	v_mul_f32_e32 v36, v44, v36
	v_mul_f32_e32 v37, v45, v37
	v_add_f32_e32 v46, v198, v10
	v_add_f32_e32 v47, v198, v11
	v_add_f32_e32 v48, v198, v12
	v_add_f32_e32 v49, v198, v13
	v_mul_f32_e32 v46, v46, v34
	v_mul_f32_e32 v47, v47, v35
	v_mul_f32_e32 v48, v48, v36
	v_mul_f32_e32 v49, v49, v37
	v_cvt_pk_bf16_f32 v50, v46, v47
	v_cvt_pk_bf16_f32 v51, v48, v49
	global_store_dwordx2 v189, v[50:51], s[12:13] offset:64
	v_lshlrev_b32_e32 v34, 16, v224
	v_and_b32_e32 v35, 0xffff0000, v224
	v_lshlrev_b32_e32 v36, 16, v225
	v_and_b32_e32 v37, 0xffff0000, v225
	v_mul_f32_e32 v38, 0x3d372713, v34
	v_mul_f32_e32 v39, 0x3d372713, v35
	v_mul_f32_e32 v40, 0x3d372713, v36
	v_mul_f32_e32 v41, 0x3d372713, v37
	v_mul_f32_e32 v42, 0x3fcc422a, v34
	v_mul_f32_e32 v43, 0x3fcc422a, v35
	v_mul_f32_e32 v44, 0x3fcc422a, v36
	v_mul_f32_e32 v45, 0x3fcc422a, v37
	v_fma_f32 v38, v38, v34, 1.0
	v_fma_f32 v39, v39, v35, 1.0
	v_fma_f32 v40, v40, v36, 1.0
	v_fma_f32 v41, v41, v37, 1.0
	v_mul_f32_e32 v42, v42, v38
	v_mul_f32_e32 v43, v43, v39
	v_mul_f32_e32 v44, v44, v40
	v_mul_f32_e32 v45, v45, v41
	v_mul_f32_e32 v42, 0xbfb8aa3b, v42
	v_mul_f32_e32 v43, 0xbfb8aa3b, v43
	v_mul_f32_e32 v44, 0xbfb8aa3b, v44
	v_mul_f32_e32 v45, 0xbfb8aa3b, v45
	v_exp_f32_e32 v42, v42
	v_exp_f32_e32 v43, v43
; __device__ __forceinline__ unsigned cvt_pk_bf16(float lo, float hi) { unsigned r; asm volatile("v_cvt_pk_bf16_f32 %0, %1, %2" : "=v"(r) : "v"(lo), "v"(hi)); return r; }
; __device__ __forceinline__ float bf_lo(unsigned w) { return __uint_as_float(w << 16); }
; __device__ __forceinline__ float bf_hi(unsigned w) { return __uint_as_float(w & 0xffff0000u); }
; __device__ __forceinline__ float gelu_f(float x) { const float y2 = 1.5957691216057308f * x * (1.0f + 0.044715f * x * x); return x * sigmoid_f(y2); }
; __device__ __forceinline__ void p2_block(LAS unsigned char* lds, const bf16_t* __restrict__ PROJ, bf16_t* __restrict__ ATT, bf16_t* __restrict__ SGU, const float* __restrict__ qn, const float* __restrict__ kn, ...
;     ...
;         const float bias = bsp[gg * 128 + irow];
;         const size_t grow = (size_t)b * pg8::SEQ + n * 128 + irow;
;         const bf16_t* up = PROJ + grow * pg8::IN_W + pg8::C_U + gg * 128 + 4 * fq; bf16_t* op = SGU + grow * 1024 + gg * 128 + 4 * fq;
; #pragma unroll
;         for (int dt = 0; dt < 8; ++dt) { const u32x2 uw = *(const u32x2*)(up + 16 * dt);
;             const float u0 = gelu_f(bf_lo(uw.x)), u1 = gelu_f(bf_hi(uw.x)), u2 = gelu_f(bf_lo(uw.y)), u3 = gelu_f(bf_hi(uw.y));
;             u32x2 ow; ow.x = cvt_pk_bf16(u0 * (acc[dt][0] + bias), u1 * (acc[dt][1] + bias)); ow.y = cvt_pk_bf16(u2 * (acc[dt][2] + bias), u3 * (acc[dt][3] + bias)); *(u32x2*)(op + 16 * dt) = ow; }
	v_exp_f32_e32 v44, v44
	v_exp_f32_e32 v45, v45
	v_add_f32_e32 v42, 1.0, v42
	v_add_f32_e32 v43, 1.0, v43
	v_add_f32_e32 v44, 1.0, v44
	v_add_f32_e32 v45, 1.0, v45
	v_rcp_f32_e32 v42, v42
	v_rcp_f32_e32 v43, v43
	v_rcp_f32_e32 v44, v44
	v_rcp_f32_e32 v45, v45
	v_mul_f32_e32 v34, v42, v34
	v_mul_f32_e32 v35, v43, v35
	v_mul_f32_e32 v36, v44, v36
	v_mul_f32_e32 v37, v45, v37
	v_add_f32_e32 v46, v198, v14
	v_add_f32_e32 v47, v198, v15
	v_add_f32_e32 v48, v198, v16
	v_add_f32_e32 v49, v198, v17
	v_mul_f32_e32 v46, v46, v34
	v_mul_f32_e32 v47, v47, v35
	v_mul_f32_e32 v48, v48, v36
	v_mul_f32_e32 v49, v49, v37
	v_cvt_pk_bf16_f32 v50, v46, v47
	v_cvt_pk_bf16_f32 v51, v48, v49
	global_store_dwordx2 v189, v[50:51], s[12:13] offset:96
	v_lshlrev_b32_e32 v34, 16, v226
	v_and_b32_e32 v35, 0xffff0000, v226
	v_lshlrev_b32_e32 v36, 16, v227
	v_and_b32_e32 v37, 0xffff0000, v227
	v_mul_f32_e32 v38, 0x3d372713, v34
	v_mul_f32_e32 v39, 0x3d372713, v35
	v_mul_f32_e32 v40, 0x3d372713, v36
	v_mul_f32_e32 v41, 0x3d372713, v37
	v_mul_f32_e32 v42, 0x3fcc422a, v34
	v_mul_f32_e32 v43, 0x3fcc422a, v35
	v_mul_f32_e32 v44, 0x3fcc422a, v36
	v_mul_f32_e32 v45, 0x3fcc422a, v37
	v_fma_f32 v38, v38, v34, 1.0
	v_fma_f32 v39, v39, v35, 1.0
	v_fma_f32 v40, v40, v36, 1.0
	v_fma_f32 v41, v41, v37, 1.0
	v_mul_f32_e32 v42, v42, v38
	v_mul_f32_e32 v43, v43, v39
	v_mul_f32_e32 v44, v44, v40
	v_mul_f32_e32 v45, v45, v41
	v_mul_f32_e32 v42, 0xbfb8aa3b, v42
	v_mul_f32_e32 v43, 0xbfb8aa3b, v43
	v_mul_f32_e32 v44, 0xbfb8aa3b, v44
	v_mul_f32_e32 v45, 0xbfb8aa3b, v45
	v_exp_f32_e32 v42, v42
	v_exp_f32_e32 v43, v43
	v_exp_f32_e32 v44, v44
	v_exp_f32_e32 v45, v45
	v_add_f32_e32 v42, 1.0, v42
	v_add_f32_e32 v43, 1.0, v43
	v_add_f32_e32 v44, 1.0, v44
	v_add_f32_e32 v45, 1.0, v45
	v_rcp_f32_e32 v42, v42
	v_rcp_f32_e32 v43, v43
	v_rcp_f32_e32 v44, v44
	v_rcp_f32_e32 v45, v45
	v_mul_f32_e32 v34, v42, v34
	v_mul_f32_e32 v35, v43, v35
	v_mul_f32_e32 v36, v44, v36
	v_mul_f32_e32 v37, v45, v37
	v_add_f32_e32 v46, v198, v18
	v_add_f32_e32 v47, v198, v19
	v_add_f32_e32 v48, v198, v20
	v_add_f32_e32 v49, v198, v21
	v_mul_f32_e32 v46, v46, v34
	v_mul_f32_e32 v47, v47, v35
	v_mul_f32_e32 v48, v48, v36
	v_mul_f32_e32 v49, v49, v37
	v_cvt_pk_bf16_f32 v50, v46, v47
	v_cvt_pk_bf16_f32 v51, v48, v49
	global_store_dwordx2 v189, v[50:51], s[12:13] offset:128
	v_lshlrev_b32_e32 v34, 16, v228
	v_and_b32_e32 v35, 0xffff0000, v228
	v_lshlrev_b32_e32 v36, 16, v229
	v_and_b32_e32 v37, 0xffff0000, v229
	v_mul_f32_e32 v38, 0x3d372713, v34
	v_mul_f32_e32 v39, 0x3d372713, v35
	v_mul_f32_e32 v40, 0x3d372713, v36
	v_mul_f32_e32 v41, 0x3d372713, v37
	v_mul_f32_e32 v42, 0x3fcc422a, v34
	v_mul_f32_e32 v43, 0x3fcc422a, v35
	v_mul_f32_e32 v44, 0x3fcc422a, v36
	v_mul_f32_e32 v45, 0x3fcc422a, v37
	v_fma_f32 v38, v38, v34, 1.0
	v_fma_f32 v39, v39, v35, 1.0
	v_fma_f32 v40, v40, v36, 1.0
	v_fma_f32 v41, v41, v37, 1.0
	v_mul_f32_e32 v42, v42, v38
	v_mul_f32_e32 v43, v43, v39
	v_mul_f32_e32 v44, v44, v40
	v_mul_f32_e32 v45, v45, v41
	v_mul_f32_e32 v42, 0xbfb8aa3b, v42
	v_mul_f32_e32 v43, 0xbfb8aa3b, v43
	v_mul_f32_e32 v44, 0xbfb8aa3b, v44
	v_mul_f32_e32 v45, 0xbfb8aa3b, v45
	v_exp_f32_e32 v42, v42
	v_exp_f32_e32 v43, v43
	v_exp_f32_e32 v44, v44
	v_exp_f32_e32 v45, v45
	v_add_f32_e32 v42, 1.0, v42
	v_add_f32_e32 v43, 1.0, v43
	v_add_f32_e32 v44, 1.0, v44
	v_add_f32_e32 v45, 1.0, v45
	v_rcp_f32_e32 v42, v42
	v_rcp_f32_e32 v43, v43
	v_rcp_f32_e32 v44, v44
	v_rcp_f32_e32 v45, v45
	v_mul_f32_e32 v34, v42, v34
	v_mul_f32_e32 v35, v43, v35
	v_mul_f32_e32 v36, v44, v36
	v_mul_f32_e32 v37, v45, v37
	v_add_f32_e32 v46, v198, v22
	v_add_f32_e32 v47, v198, v23
	v_add_f32_e32 v48, v198, v24
	v_add_f32_e32 v49, v198, v25
	v_mul_f32_e32 v46, v46, v34
	v_mul_f32_e32 v47, v47, v35
	v_mul_f32_e32 v48, v48, v36
	v_mul_f32_e32 v49, v49, v37
	v_cvt_pk_bf16_f32 v50, v46, v47
	v_cvt_pk_bf16_f32 v51, v48, v49
	global_store_dwordx2 v189, v[50:51], s[12:13] offset:160
	v_lshlrev_b32_e32 v34, 16, v230
	v_and_b32_e32 v35, 0xffff0000, v230
	v_lshlrev_b32_e32 v36, 16, v231
	v_and_b32_e32 v37, 0xffff0000, v231
	v_mul_f32_e32 v38, 0x3d372713, v34
	v_mul_f32_e32 v39, 0x3d372713, v35
	v_mul_f32_e32 v40, 0x3d372713, v36
	v_mul_f32_e32 v41, 0x3d372713, v37
	v_mul_f32_e32 v42, 0x3fcc422a, v34
	v_mul_f32_e32 v43, 0x3fcc422a, v35
	v_mul_f32_e32 v44, 0x3fcc422a, v36
	v_mul_f32_e32 v45, 0x3fcc422a, v37
	v_fma_f32 v38, v38, v34, 1.0
	v_fma_f32 v39, v39, v35, 1.0
	v_fma_f32 v40, v40, v36, 1.0
	v_fma_f32 v41, v41, v37, 1.0
	v_mul_f32_e32 v42, v42, v38
	v_mul_f32_e32 v43, v43, v39
	v_mul_f32_e32 v44, v44, v40
	v_mul_f32_e32 v45, v45, v41
	v_mul_f32_e32 v42, 0xbfb8aa3b, v42
	v_mul_f32_e32 v43, 0xbfb8aa3b, v43
	v_mul_f32_e32 v44, 0xbfb8aa3b, v44
	v_mul_f32_e32 v45, 0xbfb8aa3b, v45
	v_exp_f32_e32 v42, v42
	v_exp_f32_e32 v43, v43
	v_exp_f32_e32 v44, v44
	v_exp_f32_e32 v45, v45
	v_add_f32_e32 v42, 1.0, v42
	v_add_f32_e32 v43, 1.0, v43
	v_add_f32_e32 v44, 1.0, v44
	v_add_f32_e32 v45, 1.0, v45
	v_rcp_f32_e32 v42, v42
	v_rcp_f32_e32 v43, v43
	v_rcp_f32_e32 v44, v44
	v_rcp_f32_e32 v45, v45
	v_mul_f32_e32 v34, v42, v34
	v_mul_f32_e32 v35, v43, v35
	v_mul_f32_e32 v36, v44, v36
	v_mul_f32_e32 v37, v45, v37
	v_add_f32_e32 v46, v198, v26
	v_add_f32_e32 v47, v198, v27
	v_add_f32_e32 v48, v198, v28
	v_add_f32_e32 v49, v198, v29
	v_mul_f32_e32 v46, v46, v34
	v_mul_f32_e32 v47, v47, v35
	v_mul_f32_e32 v48, v48, v36
	v_mul_f32_e32 v49, v49, v37
	v_cvt_pk_bf16_f32 v50, v46, v47
	v_cvt_pk_bf16_f32 v51, v48, v49
	global_store_dwordx2 v189, v[50:51], s[12:13] offset:192
	v_lshlrev_b32_e32 v34, 16, v232
	v_and_b32_e32 v35, 0xffff0000, v232
	v_lshlrev_b32_e32 v36, 16, v233
	v_and_b32_e32 v37, 0xffff0000, v233
; __device__ __forceinline__ unsigned cvt_pk_bf16(float lo, float hi) { unsigned r; asm volatile("v_cvt_pk_bf16_f32 %0, %1, %2" : "=v"(r) : "v"(lo), "v"(hi)); return r; }
; __device__ __forceinline__ float bf_lo(unsigned w) { return __uint_as_float(w << 16); }
; __device__ __forceinline__ float bf_hi(unsigned w) { return __uint_as_float(w & 0xffff0000u); }
; __device__ __forceinline__ float gelu_f(float x) { const float y2 = 1.5957691216057308f * x * (1.0f + 0.044715f * x * x); return x * sigmoid_f(y2); }
; __device__ __forceinline__ void p2_block(LAS unsigned char* lds, const bf16_t* __restrict__ PROJ, bf16_t* __restrict__ ATT, bf16_t* __restrict__ SGU, const float* __restrict__ qn, const float* __restrict__ kn, ...
;     ...
;         const float bias = bsp[gg * 128 + irow];
;         const size_t grow = (size_t)b * pg8::SEQ + n * 128 + irow;
;         const bf16_t* up = PROJ + grow * pg8::IN_W + pg8::C_U + gg * 128 + 4 * fq; bf16_t* op = SGU + grow * 1024 + gg * 128 + 4 * fq;
; #pragma unroll
;         for (int dt = 0; dt < 8; ++dt) { const u32x2 uw = *(const u32x2*)(up + 16 * dt);
;             const float u0 = gelu_f(bf_lo(uw.x)), u1 = gelu_f(bf_hi(uw.x)), u2 = gelu_f(bf_lo(uw.y)), u3 = gelu_f(bf_hi(uw.y));
;             u32x2 ow; ow.x = cvt_pk_bf16(u0 * (acc[dt][0] + bias), u1 * (acc[dt][1] + bias)); ow.y = cvt_pk_bf16(u2 * (acc[dt][2] + bias), u3 * (acc[dt][3] + bias)); *(u32x2*)(op + 16 * dt) = ow; }
	v_mul_f32_e32 v38, 0x3d372713, v34
	v_mul_f32_e32 v39, 0x3d372713, v35
	v_mul_f32_e32 v40, 0x3d372713, v36
	v_mul_f32_e32 v41, 0x3d372713, v37
	v_mul_f32_e32 v42, 0x3fcc422a, v34
	v_mul_f32_e32 v43, 0x3fcc422a, v35
	v_mul_f32_e32 v44, 0x3fcc422a, v36
	v_mul_f32_e32 v45, 0x3fcc422a, v37
	v_fma_f32 v38, v38, v34, 1.0
	v_fma_f32 v39, v39, v35, 1.0
	v_fma_f32 v40, v40, v36, 1.0
	v_fma_f32 v41, v41, v37, 1.0
	v_mul_f32_e32 v42, v42, v38
	v_mul_f32_e32 v43, v43, v39
	v_mul_f32_e32 v44, v44, v40
	v_mul_f32_e32 v45, v45, v41
	v_mul_f32_e32 v42, 0xbfb8aa3b, v42
	v_mul_f32_e32 v43, 0xbfb8aa3b, v43
	v_mul_f32_e32 v44, 0xbfb8aa3b, v44
	v_mul_f32_e32 v45, 0xbfb8aa3b, v45
	v_exp_f32_e32 v42, v42
	v_exp_f32_e32 v43, v43
	v_exp_f32_e32 v44, v44
	v_exp_f32_e32 v45, v45
	v_add_f32_e32 v42, 1.0, v42
	v_add_f32_e32 v43, 1.0, v43
	v_add_f32_e32 v44, 1.0, v44
	v_add_f32_e32 v45, 1.0, v45
	v_rcp_f32_e32 v42, v42
	v_rcp_f32_e32 v43, v43
	v_rcp_f32_e32 v44, v44
	v_rcp_f32_e32 v45, v45
	v_mul_f32_e32 v34, v42, v34
	v_mul_f32_e32 v35, v43, v35
	v_mul_f32_e32 v36, v44, v36
	v_mul_f32_e32 v37, v45, v37
	v_add_f32_e32 v46, v198, v30
	v_add_f32_e32 v47, v198, v31
	v_add_f32_e32 v48, v198, v32
	v_add_f32_e32 v49, v198, v33
	v_mul_f32_e32 v46, v46, v34
	v_mul_f32_e32 v47, v47, v35
	v_mul_f32_e32 v48, v48, v36
	v_mul_f32_e32 v49, v49, v37
	v_cvt_pk_bf16_f32 v50, v46, v47
	v_cvt_pk_bf16_f32 v51, v48, v49
	global_store_dwordx2 v189, v[50:51], s[12:13] offset:224
	v_lshlrev_b32_e32 v34, 16, v234
	v_and_b32_e32 v35, 0xffff0000, v234
	v_lshlrev_b32_e32 v36, 16, v235
	v_and_b32_e32 v37, 0xffff0000, v235
	v_mul_f32_e32 v38, 0x3d372713, v34
	v_mul_f32_e32 v39, 0x3d372713, v35
	v_mul_f32_e32 v40, 0x3d372713, v36
	v_mul_f32_e32 v41, 0x3d372713, v37
	v_mul_f32_e32 v42, 0x3fcc422a, v34
	v_mul_f32_e32 v43, 0x3fcc422a, v35
	v_mul_f32_e32 v44, 0x3fcc422a, v36
	v_mul_f32_e32 v45, 0x3fcc422a, v37
	v_fma_f32 v38, v38, v34, 1.0
	v_fma_f32 v39, v39, v35, 1.0
	v_fma_f32 v40, v40, v36, 1.0
	v_fma_f32 v41, v41, v37, 1.0
	v_mul_f32_e32 v42, v42, v38
	v_mul_f32_e32 v43, v43, v39
	v_mul_f32_e32 v44, v44, v40
	v_mul_f32_e32 v45, v45, v41
	v_mul_f32_e32 v42, 0xbfb8aa3b, v42
	v_mul_f32_e32 v43, 0xbfb8aa3b, v43
	v_mul_f32_e32 v44, 0xbfb8aa3b, v44
	v_mul_f32_e32 v45, 0xbfb8aa3b, v45
	v_exp_f32_e32 v42, v42
	v_exp_f32_e32 v43, v43
	v_exp_f32_e32 v44, v44
	v_exp_f32_e32 v45, v45
	v_add_f32_e32 v42, 1.0, v42
	v_add_f32_e32 v43, 1.0, v43
	v_add_f32_e32 v44, 1.0, v44
	v_add_f32_e32 v45, 1.0, v45
	v_rcp_f32_e32 v42, v42
	v_rcp_f32_e32 v43, v43
	v_rcp_f32_e32 v44, v44
	v_rcp_f32_e32 v45, v45
	v_mul_f32_e32 v34, v42, v34
	v_mul_f32_e32 v35, v43, v35
	v_mul_f32_e32 v36, v44, v36
	v_mul_f32_e32 v37, v45, v37
	v_add_f32_e32 v46, v199, v114
	v_add_f32_e32 v47, v199, v115
	v_add_f32_e32 v48, v199, v116
	v_add_f32_e32 v49, v199, v117
	v_mul_f32_e32 v46, v46, v34
	v_mul_f32_e32 v47, v47, v35
	v_mul_f32_e32 v48, v48, v36
	v_mul_f32_e32 v49, v49, v37
	v_cvt_pk_bf16_f32 v50, v46, v47
	v_cvt_pk_bf16_f32 v51, v48, v49
	global_store_dwordx2 v189, v[50:51], s[12:13] offset:256
	v_lshlrev_b32_e32 v34, 16, v236
	v_and_b32_e32 v35, 0xffff0000, v236
	v_lshlrev_b32_e32 v36, 16, v237
	v_and_b32_e32 v37, 0xffff0000, v237
	v_mul_f32_e32 v38, 0x3d372713, v34
	v_mul_f32_e32 v39, 0x3d372713, v35
	v_mul_f32_e32 v40, 0x3d372713, v36
	v_mul_f32_e32 v41, 0x3d372713, v37
	v_mul_f32_e32 v42, 0x3fcc422a, v34
	v_mul_f32_e32 v43, 0x3fcc422a, v35
	v_mul_f32_e32 v44, 0x3fcc422a, v36
	v_mul_f32_e32 v45, 0x3fcc422a, v37
	v_fma_f32 v38, v38, v34, 1.0
	v_fma_f32 v39, v39, v35, 1.0
	v_fma_f32 v40, v40, v36, 1.0
	v_fma_f32 v41, v41, v37, 1.0
	v_mul_f32_e32 v42, v42, v38
	v_mul_f32_e32 v43, v43, v39
	v_mul_f32_e32 v44, v44, v40
	v_mul_f32_e32 v45, v45, v41
	v_mul_f32_e32 v42, 0xbfb8aa3b, v42
	v_mul_f32_e32 v43, 0xbfb8aa3b, v43
	v_mul_f32_e32 v44, 0xbfb8aa3b, v44
	v_mul_f32_e32 v45, 0xbfb8aa3b, v45
	v_exp_f32_e32 v42, v42
	v_exp_f32_e32 v43, v43
	v_exp_f32_e32 v44, v44
	v_exp_f32_e32 v45, v45
	v_add_f32_e32 v42, 1.0, v42
	v_add_f32_e32 v43, 1.0, v43
	v_add_f32_e32 v44, 1.0, v44
	v_add_f32_e32 v45, 1.0, v45
	v_rcp_f32_e32 v42, v42
	v_rcp_f32_e32 v43, v43
	v_rcp_f32_e32 v44, v44
	v_rcp_f32_e32 v45, v45
	v_mul_f32_e32 v34, v42, v34
	v_mul_f32_e32 v35, v43, v35
	v_mul_f32_e32 v36, v44, v36
	v_mul_f32_e32 v37, v45, v37
	v_add_f32_e32 v46, v199, v118
	v_add_f32_e32 v47, v199, v119
	v_add_f32_e32 v48, v199, v120
	v_add_f32_e32 v49, v199, v121
	v_mul_f32_e32 v46, v46, v34
	v_mul_f32_e32 v47, v47, v35
	v_mul_f32_e32 v48, v48, v36
	v_mul_f32_e32 v49, v49, v37
	v_cvt_pk_bf16_f32 v50, v46, v47
	v_cvt_pk_bf16_f32 v51, v48, v49
	global_store_dwordx2 v189, v[50:51], s[12:13] offset:288
	v_lshlrev_b32_e32 v34, 16, v238
	v_and_b32_e32 v35, 0xffff0000, v238
	v_lshlrev_b32_e32 v36, 16, v239
	v_and_b32_e32 v37, 0xffff0000, v239
	v_mul_f32_e32 v38, 0x3d372713, v34
	v_mul_f32_e32 v39, 0x3d372713, v35
	v_mul_f32_e32 v40, 0x3d372713, v36
	v_mul_f32_e32 v41, 0x3d372713, v37
	v_mul_f32_e32 v42, 0x3fcc422a, v34
	v_mul_f32_e32 v43, 0x3fcc422a, v35
	v_mul_f32_e32 v44, 0x3fcc422a, v36
	v_mul_f32_e32 v45, 0x3fcc422a, v37
	v_fma_f32 v38, v38, v34, 1.0
	v_fma_f32 v39, v39, v35, 1.0
	v_fma_f32 v40, v40, v36, 1.0
	v_fma_f32 v41, v41, v37, 1.0
	v_mul_f32_e32 v42, v42, v38
	v_mul_f32_e32 v43, v43, v39
	v_mul_f32_e32 v44, v44, v40
	v_mul_f32_e32 v45, v45, v41
	v_mul_f32_e32 v42, 0xbfb8aa3b, v42
	v_mul_f32_e32 v43, 0xbfb8aa3b, v43
	v_mul_f32_e32 v44, 0xbfb8aa3b, v44
	v_mul_f32_e32 v45, 0xbfb8aa3b, v45
	v_exp_f32_e32 v42, v42
	v_exp_f32_e32 v43, v43
	v_exp_f32_e32 v44, v44
	v_exp_f32_e32 v45, v45
	v_add_f32_e32 v42, 1.0, v42
	v_add_f32_e32 v43, 1.0, v43
	v_add_f32_e32 v44, 1.0, v44
; __device__ __forceinline__ unsigned cvt_pk_bf16(float lo, float hi) { unsigned r; asm volatile("v_cvt_pk_bf16_f32 %0, %1, %2" : "=v"(r) : "v"(lo), "v"(hi)); return r; }
; __device__ __forceinline__ float bf_lo(unsigned w) { return __uint_as_float(w << 16); }
; __device__ __forceinline__ float bf_hi(unsigned w) { return __uint_as_float(w & 0xffff0000u); }
; __device__ __forceinline__ float gelu_f(float x) { const float y2 = 1.5957691216057308f * x * (1.0f + 0.044715f * x * x); return x * sigmoid_f(y2); }
; __device__ __forceinline__ void p2_block(LAS unsigned char* lds, const bf16_t* __restrict__ PROJ, bf16_t* __restrict__ ATT, bf16_t* __restrict__ SGU, const float* __restrict__ qn, const float* __restrict__ kn, ...
;     ...
;         const float bias = bsp[gg * 128 + irow];
;         const size_t grow = (size_t)b * pg8::SEQ + n * 128 + irow;
;         const bf16_t* up = PROJ + grow * pg8::IN_W + pg8::C_U + gg * 128 + 4 * fq; bf16_t* op = SGU + grow * 1024 + gg * 128 + 4 * fq;
; #pragma unroll
;         for (int dt = 0; dt < 8; ++dt) { const u32x2 uw = *(const u32x2*)(up + 16 * dt);
;             const float u0 = gelu_f(bf_lo(uw.x)), u1 = gelu_f(bf_hi(uw.x)), u2 = gelu_f(bf_lo(uw.y)), u3 = gelu_f(bf_hi(uw.y));
;             u32x2 ow; ow.x = cvt_pk_bf16(u0 * (acc[dt][0] + bias), u1 * (acc[dt][1] + bias)); ow.y = cvt_pk_bf16(u2 * (acc[dt][2] + bias), u3 * (acc[dt][3] + bias)); *(u32x2*)(op + 16 * dt) = ow; }
	v_add_f32_e32 v45, 1.0, v45
	v_rcp_f32_e32 v42, v42
	v_rcp_f32_e32 v43, v43
	v_rcp_f32_e32 v44, v44
	v_rcp_f32_e32 v45, v45
	v_mul_f32_e32 v34, v42, v34
	v_mul_f32_e32 v35, v43, v35
	v_mul_f32_e32 v36, v44, v36
	v_mul_f32_e32 v37, v45, v37
	v_add_f32_e32 v46, v199, v122
	v_add_f32_e32 v47, v199, v123
	v_add_f32_e32 v48, v199, v124
	v_add_f32_e32 v49, v199, v125
	v_mul_f32_e32 v46, v46, v34
	v_mul_f32_e32 v47, v47, v35
	v_mul_f32_e32 v48, v48, v36
	v_mul_f32_e32 v49, v49, v37
	v_cvt_pk_bf16_f32 v50, v46, v47
	v_cvt_pk_bf16_f32 v51, v48, v49
	global_store_dwordx2 v189, v[50:51], s[12:13] offset:320
	v_lshlrev_b32_e32 v34, 16, v240
	v_and_b32_e32 v35, 0xffff0000, v240
	v_lshlrev_b32_e32 v36, 16, v241
	v_and_b32_e32 v37, 0xffff0000, v241
	v_mul_f32_e32 v38, 0x3d372713, v34
	v_mul_f32_e32 v39, 0x3d372713, v35
	v_mul_f32_e32 v40, 0x3d372713, v36
	v_mul_f32_e32 v41, 0x3d372713, v37
	v_mul_f32_e32 v42, 0x3fcc422a, v34
	v_mul_f32_e32 v43, 0x3fcc422a, v35
	v_mul_f32_e32 v44, 0x3fcc422a, v36
	v_mul_f32_e32 v45, 0x3fcc422a, v37
	v_fma_f32 v38, v38, v34, 1.0
	v_fma_f32 v39, v39, v35, 1.0
	v_fma_f32 v40, v40, v36, 1.0
	v_fma_f32 v41, v41, v37, 1.0
	v_mul_f32_e32 v42, v42, v38
	v_mul_f32_e32 v43, v43, v39
	v_mul_f32_e32 v44, v44, v40
	v_mul_f32_e32 v45, v45, v41
	v_mul_f32_e32 v42, 0xbfb8aa3b, v42
	v_mul_f32_e32 v43, 0xbfb8aa3b, v43
	v_mul_f32_e32 v44, 0xbfb8aa3b, v44
	v_mul_f32_e32 v45, 0xbfb8aa3b, v45
	v_exp_f32_e32 v42, v42
	v_exp_f32_e32 v43, v43
	v_exp_f32_e32 v44, v44
	v_exp_f32_e32 v45, v45
	v_add_f32_e32 v42, 1.0, v42
	v_add_f32_e32 v43, 1.0, v43
	v_add_f32_e32 v44, 1.0, v44
	v_add_f32_e32 v45, 1.0, v45
	v_rcp_f32_e32 v42, v42
	v_rcp_f32_e32 v43, v43
	v_rcp_f32_e32 v44, v44
	v_rcp_f32_e32 v45, v45
	v_mul_f32_e32 v34, v42, v34
	v_mul_f32_e32 v35, v43, v35
	v_mul_f32_e32 v36, v44, v36
	v_mul_f32_e32 v37, v45, v37
	v_add_f32_e32 v46, v199, v126
	v_add_f32_e32 v47, v199, v127
	v_add_f32_e32 v48, v199, v128
	v_add_f32_e32 v49, v199, v129
	v_mul_f32_e32 v46, v46, v34
	v_mul_f32_e32 v47, v47, v35
	v_mul_f32_e32 v48, v48, v36
	v_mul_f32_e32 v49, v49, v37
	v_cvt_pk_bf16_f32 v50, v46, v47
	v_cvt_pk_bf16_f32 v51, v48, v49
	global_store_dwordx2 v189, v[50:51], s[12:13] offset:352
	v_lshlrev_b32_e32 v34, 16, v242
	v_and_b32_e32 v35, 0xffff0000, v242
	v_lshlrev_b32_e32 v36, 16, v243
	v_and_b32_e32 v37, 0xffff0000, v243
	v_mul_f32_e32 v38, 0x3d372713, v34
	v_mul_f32_e32 v39, 0x3d372713, v35
	v_mul_f32_e32 v40, 0x3d372713, v36
	v_mul_f32_e32 v41, 0x3d372713, v37
	v_mul_f32_e32 v42, 0x3fcc422a, v34
	v_mul_f32_e32 v43, 0x3fcc422a, v35
	v_mul_f32_e32 v44, 0x3fcc422a, v36
	v_mul_f32_e32 v45, 0x3fcc422a, v37
	v_fma_f32 v38, v38, v34, 1.0
	v_fma_f32 v39, v39, v35, 1.0
	v_fma_f32 v40, v40, v36, 1.0
	v_fma_f32 v41, v41, v37, 1.0
	v_mul_f32_e32 v42, v42, v38
	v_mul_f32_e32 v43, v43, v39
	v_mul_f32_e32 v44, v44, v40
	v_mul_f32_e32 v45, v45, v41
	v_mul_f32_e32 v42, 0xbfb8aa3b, v42
	v_mul_f32_e32 v43, 0xbfb8aa3b, v43
	v_mul_f32_e32 v44, 0xbfb8aa3b, v44
	v_mul_f32_e32 v45, 0xbfb8aa3b, v45
	v_exp_f32_e32 v42, v42
	v_exp_f32_e32 v43, v43
	v_exp_f32_e32 v44, v44
	v_exp_f32_e32 v45, v45
	v_add_f32_e32 v42, 1.0, v42
	v_add_f32_e32 v43, 1.0, v43
	v_add_f32_e32 v44, 1.0, v44
	v_add_f32_e32 v45, 1.0, v45
	v_rcp_f32_e32 v42, v42
	v_rcp_f32_e32 v43, v43
	v_rcp_f32_e32 v44, v44
	v_rcp_f32_e32 v45, v45
	v_mul_f32_e32 v34, v42, v34
	v_mul_f32_e32 v35, v43, v35
	v_mul_f32_e32 v36, v44, v36
	v_mul_f32_e32 v37, v45, v37
	v_add_f32_e32 v46, v199, v130
	v_add_f32_e32 v47, v199, v131
	v_add_f32_e32 v48, v199, v132
	v_add_f32_e32 v49, v199, v133
	v_mul_f32_e32 v46, v46, v34
	v_mul_f32_e32 v47, v47, v35
	v_mul_f32_e32 v48, v48, v36
	v_mul_f32_e32 v49, v49, v37
	v_cvt_pk_bf16_f32 v50, v46, v47
	v_cvt_pk_bf16_f32 v51, v48, v49
	global_store_dwordx2 v189, v[50:51], s[12:13] offset:384
	v_lshlrev_b32_e32 v34, 16, v244
	v_and_b32_e32 v35, 0xffff0000, v244
	v_lshlrev_b32_e32 v36, 16, v245
	v_and_b32_e32 v37, 0xffff0000, v245
	v_mul_f32_e32 v38, 0x3d372713, v34
	v_mul_f32_e32 v39, 0x3d372713, v35
	v_mul_f32_e32 v40, 0x3d372713, v36
	v_mul_f32_e32 v41, 0x3d372713, v37
	v_mul_f32_e32 v42, 0x3fcc422a, v34
	v_mul_f32_e32 v43, 0x3fcc422a, v35
	v_mul_f32_e32 v44, 0x3fcc422a, v36
	v_mul_f32_e32 v45, 0x3fcc422a, v37
	v_fma_f32 v38, v38, v34, 1.0
	v_fma_f32 v39, v39, v35, 1.0
	v_fma_f32 v40, v40, v36, 1.0
	v_fma_f32 v41, v41, v37, 1.0
; __device__ __forceinline__ unsigned cvt_pk_bf16(float lo, float hi) { unsigned r; asm volatile("v_cvt_pk_bf16_f32 %0, %1, %2" : "=v"(r) : "v"(lo), "v"(hi)); return r; }
; __device__ __forceinline__ float bf_lo(unsigned w) { return __uint_as_float(w << 16); }
; __device__ __forceinline__ float bf_hi(unsigned w) { return __uint_as_float(w & 0xffff0000u); }
; __device__ __forceinline__ float gelu_f(float x) { const float y2 = 1.5957691216057308f * x * (1.0f + 0.044715f * x * x); return x * sigmoid_f(y2); }
; __device__ __forceinline__ void p2_block(LAS unsigned char* lds, const bf16_t* __restrict__ PROJ, bf16_t* __restrict__ ATT, bf16_t* __restrict__ SGU, const float* __restrict__ qn, const float* __restrict__ kn, ...
;     ...
;         const float bias = bsp[gg * 128 + irow];
;         const size_t grow = (size_t)b * pg8::SEQ + n * 128 + irow;
;         const bf16_t* up = PROJ + grow * pg8::IN_W + pg8::C_U + gg * 128 + 4 * fq; bf16_t* op = SGU + grow * 1024 + gg * 128 + 4 * fq;
; #pragma unroll
;         for (int dt = 0; dt < 8; ++dt) { const u32x2 uw = *(const u32x2*)(up + 16 * dt);
;             const float u0 = gelu_f(bf_lo(uw.x)), u1 = gelu_f(bf_hi(uw.x)), u2 = gelu_f(bf_lo(uw.y)), u3 = gelu_f(bf_hi(uw.y));
;             u32x2 ow; ow.x = cvt_pk_bf16(u0 * (acc[dt][0] + bias), u1 * (acc[dt][1] + bias)); ow.y = cvt_pk_bf16(u2 * (acc[dt][2] + bias), u3 * (acc[dt][3] + bias)); *(u32x2*)(op + 16 * dt) = ow; }
;     }
;     __syncthreads();
	v_mul_f32_e32 v42, v42, v38
	v_mul_f32_e32 v43, v43, v39
	v_mul_f32_e32 v44, v44, v40
	v_mul_f32_e32 v45, v45, v41
	v_mul_f32_e32 v42, 0xbfb8aa3b, v42
	v_mul_f32_e32 v43, 0xbfb8aa3b, v43
	v_mul_f32_e32 v44, 0xbfb8aa3b, v44
	v_mul_f32_e32 v45, 0xbfb8aa3b, v45
	v_exp_f32_e32 v42, v42
	v_exp_f32_e32 v43, v43
	v_exp_f32_e32 v44, v44
	v_exp_f32_e32 v45, v45
	v_add_f32_e32 v42, 1.0, v42
	v_add_f32_e32 v43, 1.0, v43
	v_add_f32_e32 v44, 1.0, v44
	v_add_f32_e32 v45, 1.0, v45
	v_rcp_f32_e32 v42, v42
	v_rcp_f32_e32 v43, v43
	v_rcp_f32_e32 v44, v44
	v_rcp_f32_e32 v45, v45
	v_mul_f32_e32 v34, v42, v34
	v_mul_f32_e32 v35, v43, v35
	v_mul_f32_e32 v36, v44, v36
	v_mul_f32_e32 v37, v45, v37
	v_add_f32_e32 v46, v199, v134
	v_add_f32_e32 v47, v199, v135
	v_add_f32_e32 v48, v199, v136
	v_add_f32_e32 v49, v199, v137
	v_mul_f32_e32 v46, v46, v34
	v_mul_f32_e32 v47, v47, v35
	v_mul_f32_e32 v48, v48, v36
	v_mul_f32_e32 v49, v49, v37
	v_cvt_pk_bf16_f32 v50, v46, v47
	v_cvt_pk_bf16_f32 v51, v48, v49
	global_store_dwordx2 v189, v[50:51], s[12:13] offset:416
	v_lshlrev_b32_e32 v34, 16, v200
	v_and_b32_e32 v35, 0xffff0000, v200
	v_lshlrev_b32_e32 v36, 16, v201
	v_and_b32_e32 v37, 0xffff0000, v201
	v_mul_f32_e32 v38, 0x3d372713, v34
	v_mul_f32_e32 v39, 0x3d372713, v35
	v_mul_f32_e32 v40, 0x3d372713, v36
	v_mul_f32_e32 v41, 0x3d372713, v37
	v_mul_f32_e32 v42, 0x3fcc422a, v34
	v_mul_f32_e32 v43, 0x3fcc422a, v35
	v_mul_f32_e32 v44, 0x3fcc422a, v36
	v_mul_f32_e32 v45, 0x3fcc422a, v37
	v_fma_f32 v38, v38, v34, 1.0
	v_fma_f32 v39, v39, v35, 1.0
	v_fma_f32 v40, v40, v36, 1.0
	v_fma_f32 v41, v41, v37, 1.0
	v_mul_f32_e32 v42, v42, v38
	v_mul_f32_e32 v43, v43, v39
	v_mul_f32_e32 v44, v44, v40
	v_mul_f32_e32 v45, v45, v41
	v_mul_f32_e32 v42, 0xbfb8aa3b, v42
	v_mul_f32_e32 v43, 0xbfb8aa3b, v43
	v_mul_f32_e32 v44, 0xbfb8aa3b, v44
	v_mul_f32_e32 v45, 0xbfb8aa3b, v45
	v_exp_f32_e32 v42, v42
	v_exp_f32_e32 v43, v43
	v_exp_f32_e32 v44, v44
	v_exp_f32_e32 v45, v45
	v_add_f32_e32 v42, 1.0, v42
	v_add_f32_e32 v43, 1.0, v43
	v_add_f32_e32 v44, 1.0, v44
	v_add_f32_e32 v45, 1.0, v45
	v_rcp_f32_e32 v42, v42
	v_rcp_f32_e32 v43, v43
	v_rcp_f32_e32 v44, v44
	v_rcp_f32_e32 v45, v45
	v_mul_f32_e32 v34, v42, v34
	v_mul_f32_e32 v35, v43, v35
	v_mul_f32_e32 v36, v44, v36
	v_mul_f32_e32 v37, v45, v37
	v_add_f32_e32 v46, v199, v138
	v_add_f32_e32 v47, v199, v139
	v_add_f32_e32 v48, v199, v140
	v_add_f32_e32 v49, v199, v141
	v_mul_f32_e32 v46, v46, v34
	v_mul_f32_e32 v47, v47, v35
	v_mul_f32_e32 v48, v48, v36
	v_mul_f32_e32 v49, v49, v37
	v_cvt_pk_bf16_f32 v50, v46, v47
	v_cvt_pk_bf16_f32 v51, v48, v49
	global_store_dwordx2 v189, v[50:51], s[12:13] offset:448
	v_lshlrev_b32_e32 v34, 16, v202
	v_and_b32_e32 v35, 0xffff0000, v202
	v_lshlrev_b32_e32 v36, 16, v203
	v_and_b32_e32 v37, 0xffff0000, v203
	v_mul_f32_e32 v38, 0x3d372713, v34
	v_mul_f32_e32 v39, 0x3d372713, v35
	v_mul_f32_e32 v40, 0x3d372713, v36
	v_mul_f32_e32 v41, 0x3d372713, v37
	v_mul_f32_e32 v42, 0x3fcc422a, v34
	v_mul_f32_e32 v43, 0x3fcc422a, v35
	v_mul_f32_e32 v44, 0x3fcc422a, v36
	v_mul_f32_e32 v45, 0x3fcc422a, v37
	v_fma_f32 v38, v38, v34, 1.0
	v_fma_f32 v39, v39, v35, 1.0
	v_fma_f32 v40, v40, v36, 1.0
	v_fma_f32 v41, v41, v37, 1.0
	v_mul_f32_e32 v42, v42, v38
	v_mul_f32_e32 v43, v43, v39
	v_mul_f32_e32 v44, v44, v40
	v_mul_f32_e32 v45, v45, v41
	v_mul_f32_e32 v42, 0xbfb8aa3b, v42
	v_mul_f32_e32 v43, 0xbfb8aa3b, v43
	v_mul_f32_e32 v44, 0xbfb8aa3b, v44
	v_mul_f32_e32 v45, 0xbfb8aa3b, v45
	v_exp_f32_e32 v42, v42
	v_exp_f32_e32 v43, v43
	v_exp_f32_e32 v44, v44
	v_exp_f32_e32 v45, v45
	v_add_f32_e32 v42, 1.0, v42
	v_add_f32_e32 v43, 1.0, v43
	v_add_f32_e32 v44, 1.0, v44
	v_add_f32_e32 v45, 1.0, v45
	v_rcp_f32_e32 v42, v42
	v_rcp_f32_e32 v43, v43
	v_rcp_f32_e32 v44, v44
	v_rcp_f32_e32 v45, v45
	v_mul_f32_e32 v34, v42, v34
	v_mul_f32_e32 v35, v43, v35
	v_mul_f32_e32 v36, v44, v36
	v_mul_f32_e32 v37, v45, v37
	v_add_f32_e32 v46, v199, v160
	v_add_f32_e32 v47, v199, v161
	v_add_f32_e32 v48, v199, v162
	v_add_f32_e32 v49, v199, v163
	v_mul_f32_e32 v46, v46, v34
	v_mul_f32_e32 v47, v47, v35
	v_mul_f32_e32 v48, v48, v36
	v_mul_f32_e32 v49, v49, v37
	v_cvt_pk_bf16_f32 v50, v46, v47
	v_cvt_pk_bf16_f32 v51, v48, v49
	global_store_dwordx2 v189, v[50:51], s[12:13] offset:480
	s_add_i32 s2, s2, s3
	s_cmpk_lt_i32 s2, 0x100
	s_waitcnt lgkmcnt(0)
	s_barrier
	s_cbranch_scc1 .LBB0_330
